# K-loops: s_setprio 1 issued ahead of the s_waitcnt that precedes the barrier (hidden under the wait) instead of between the wait and the barrier
# baseline (speedup 1.0000x reference)
.LBB0_175:
	s_ashr_i32 s57, s56, 31
	s_lshl_b64 s[52:53], s[56:57], 20
	v_readlane_b32 s66, v254, 17
	v_readlane_b32 s67, v254, 18
	s_add_u32 s66, s66, s52
	s_addc_u32 s67, s67, s53
	s_and_b64 s[52:53], s[6:7], exec
	s_cselect_b32 s11, s67, s9
	s_cselect_b32 s13, s66, s8
	s_ashr_i32 s61, s60, 31
	s_lshl_b64 s[52:53], s[60:61], 20
	v_readlane_b32 s68, v254, 21
	v_readlane_b32 s69, v254, 22
	s_add_u32 s88, s68, s52
	s_addc_u32 s89, s69, s53
	s_and_b64 s[52:53], s[6:7], exec
	s_cselect_b32 s57, s89, s15
	s_cselect_b32 s61, s88, s14
	s_add_u32 s8, s8, 0x80080
	s_addc_u32 s9, s9, 0
	s_add_u32 s68, s14, 0x100
	s_addc_u32 s69, s15, 0
	s_mov_b32 s90, -2
	s_add_u32 s14, s8, 0xfff80080
	s_addc_u32 s15, s9, -1
	s_add_i32 s91, 0, 0x10000
	s_cmp_eq_u32 s90, 28
	s_cselect_b32 s53, s11, s15
	s_cselect_b32 s52, s13, s14
	v_add_u32_e32 v14, s91, v188
	s_cselect_b32 s15, s57, s69
	s_cselect_b32 s14, s61, s68
	s_add_i32 s96, 0, 0x14000
	ds_read_b128 v[6:9], v14
	ds_read_b128 v[10:13], v14 offset:1024
	ds_read_b128 v[140:143], v14 offset:2048
	ds_read_b128 v[144:147], v14 offset:3072
	v_add_u32_e32 v14, s96, v188
	ds_read_b128 v[148:151], v14
	ds_read_b128 v[152:155], v14 offset:1024
	ds_read_b128 v[180:183], v14 offset:2048
	ds_read_b128 v[208:211], v14 offset:3072
	v_lshl_add_u64 v[14:15], s[8:9], 0, v[176:177]
	s_add_i32 m0, s40, 0xc000
	ds_read_b128 v[212:215], v206
	ds_read_b128 v[216:219], v206 offset:1024
	ds_read_b128 v[220:223], v206 offset:2048
	ds_read_b128 v[224:227], v206 offset:3072
	ds_read_b128 v[238:241], v206 offset:4096
	ds_read_b128 v[242:245], v206 offset:5120
	ds_read_b128 v[246:249], v206 offset:6144
	ds_read_b128 v[250:253], v206 offset:7168
	global_load_lds_dwordx4 v[14:15], off
	s_add_i32 m0, s40, 0xe000
	v_lshl_add_u64 v[14:15], s[8:9], 0, v[178:179]
	global_load_lds_dwordx4 v[14:15], off
	s_setprio 1
	s_waitcnt vmcnt(8) lgkmcnt(0)
	s_barrier
	v_mfma_f32_16x16x32_bf16 v[136:139], v[6:9], v[212:215], 0
	v_mfma_f32_16x16x32_bf16 v[104:107], v[140:143], v[212:215], 0
	v_mfma_f32_16x16x32_bf16 v[132:135], v[6:9], v[220:223], 0
	v_mfma_f32_16x16x32_bf16 v[100:103], v[140:143], v[220:223], 0
	v_mfma_f32_16x16x32_bf16 v[128:131], v[6:9], v[238:241], 0
	v_mfma_f32_16x16x32_bf16 v[96:99], v[140:143], v[238:241], 0
	v_mfma_f32_16x16x32_bf16 v[124:127], v[6:9], v[246:249], 0
	v_mfma_f32_16x16x32_bf16 v[92:95], v[140:143], v[246:249], 0
	v_mfma_f32_16x16x32_bf16 v[136:139], v[10:13], v[216:219], v[136:139]
	v_mfma_f32_16x16x32_bf16 v[104:107], v[144:147], v[216:219], v[104:107]
	v_mfma_f32_16x16x32_bf16 v[132:135], v[10:13], v[224:227], v[132:135]
	v_mfma_f32_16x16x32_bf16 v[100:103], v[144:147], v[224:227], v[100:103]
	v_mfma_f32_16x16x32_bf16 v[128:131], v[10:13], v[242:245], v[128:131]
	v_mfma_f32_16x16x32_bf16 v[96:99], v[144:147], v[242:245], v[96:99]
	v_mfma_f32_16x16x32_bf16 v[124:127], v[10:13], v[250:253], v[124:127]
	v_mfma_f32_16x16x32_bf16 v[92:95], v[144:147], v[250:253], v[92:95]
	s_setprio 0
	s_setprio 1
	v_mfma_f32_16x16x32_bf16 v[72:75], v[148:151], v[212:215], 0
	v_mfma_f32_16x16x32_bf16 v[40:43], v[180:183], v[212:215], 0
	v_mfma_f32_16x16x32_bf16 v[68:71], v[148:151], v[220:223], 0
	v_mfma_f32_16x16x32_bf16 v[36:39], v[180:183], v[220:223], 0
	v_mfma_f32_16x16x32_bf16 v[64:67], v[148:151], v[238:241], 0
	v_mfma_f32_16x16x32_bf16 v[32:35], v[180:183], v[238:241], 0
	v_mfma_f32_16x16x32_bf16 v[60:63], v[148:151], v[246:249], 0
	v_mfma_f32_16x16x32_bf16 v[28:31], v[180:183], v[246:249], 0
	v_mfma_f32_16x16x32_bf16 v[72:75], v[152:155], v[216:219], v[72:75]
	v_mfma_f32_16x16x32_bf16 v[40:43], v[208:211], v[216:219], v[40:43]
	v_mfma_f32_16x16x32_bf16 v[68:71], v[152:155], v[224:227], v[68:71]
	v_mfma_f32_16x16x32_bf16 v[36:39], v[208:211], v[224:227], v[36:39]
	v_mfma_f32_16x16x32_bf16 v[64:67], v[152:155], v[242:245], v[64:67]
	v_mfma_f32_16x16x32_bf16 v[32:35], v[208:211], v[242:245], v[32:35]
	v_mfma_f32_16x16x32_bf16 v[60:63], v[152:155], v[250:253], v[60:63]
	v_mfma_f32_16x16x32_bf16 v[28:31], v[208:211], v[250:253], v[28:31]
	s_barrier
	s_setprio 0
	s_add_i32 s91, s91, s33
	v_lshl_add_u64 v[156:157], s[14:15], 0, v[160:161]
	s_mov_b32 m0, s91
	ds_read_b128 v[212:215], v206 offset:16384
	ds_read_b128 v[216:219], v206 offset:17408
	ds_read_b128 v[220:223], v206 offset:18432
	ds_read_b128 v[224:227], v206 offset:19456
	ds_read_b128 v[238:241], v206 offset:20480
	ds_read_b128 v[242:245], v206 offset:21504
	ds_read_b128 v[246:249], v206 offset:22528
	ds_read_b128 v[250:253], v206 offset:23552
	global_load_lds_dwordx4 v[156:157], off
	s_add_i32 m0, s91, 0x2000
	s_add_u32 vcc_lo, s14, 0x80000
	v_lshl_add_u64 v[184:185], s[14:15], 0, v[164:165]
	s_addc_u32 vcc_hi, s15, 0
	s_add_i32 s91, s96, s33
	global_load_lds_dwordx4 v[184:185], off
	v_lshl_add_u64 v[14:15], vcc, 0, v[160:161]
	s_mov_b32 m0, s91
	v_lshl_add_u64 v[196:197], s[52:53], 0, v[158:159]
	global_load_lds_dwordx4 v[14:15], off
	v_lshl_add_u64 v[14:15], vcc, 0, v[164:165]
	s_add_i32 m0, s91, 0x2000
	v_lshl_add_u64 v[198:199], s[52:53], 0, v[162:163]
	global_load_lds_dwordx4 v[14:15], off
	s_mov_b32 m0, s40
	s_nop 0
	global_load_lds_dwordx4 v[196:197], off
	s_mov_b32 m0, s41
	s_nop 0
	global_load_lds_dwordx4 v[198:199], off
	s_setprio 1
	s_waitcnt vmcnt(8) lgkmcnt(0)
	s_barrier
	v_mfma_f32_16x16x32_bf16 v[120:123], v[6:9], v[212:215], 0
	v_mfma_f32_16x16x32_bf16 v[88:91], v[140:143], v[212:215], 0
	v_mfma_f32_16x16x32_bf16 v[116:119], v[6:9], v[220:223], 0
	v_mfma_f32_16x16x32_bf16 v[84:87], v[140:143], v[220:223], 0
	v_mfma_f32_16x16x32_bf16 v[112:115], v[6:9], v[238:241], 0
	v_mfma_f32_16x16x32_bf16 v[80:83], v[140:143], v[238:241], 0
	v_mfma_f32_16x16x32_bf16 v[6:9], v[6:9], v[246:249], 0
	v_mfma_f32_16x16x32_bf16 v[120:123], v[10:13], v[216:219], v[120:123]
	v_mfma_f32_16x16x32_bf16 v[88:91], v[144:147], v[216:219], v[88:91]
	v_mfma_f32_16x16x32_bf16 v[116:119], v[10:13], v[224:227], v[116:119]
	v_mfma_f32_16x16x32_bf16 v[84:87], v[144:147], v[224:227], v[84:87]
	v_mfma_f32_16x16x32_bf16 v[112:115], v[10:13], v[242:245], v[112:115]
	v_mfma_f32_16x16x32_bf16 v[80:83], v[144:147], v[242:245], v[80:83]
	v_mfma_f32_16x16x32_bf16 v[6:9], v[10:13], v[250:253], v[6:9]
	v_mfma_f32_16x16x32_bf16 v[10:13], v[140:143], v[246:249], 0
	v_mfma_f32_16x16x32_bf16 v[10:13], v[144:147], v[250:253], v[10:13]
	s_setprio 0
	s_setprio 1
	v_mfma_f32_16x16x32_bf16 v[56:59], v[148:151], v[212:215], 0
	v_mfma_f32_16x16x32_bf16 v[24:27], v[180:183], v[212:215], 0
	v_mfma_f32_16x16x32_bf16 v[52:55], v[148:151], v[220:223], 0
	v_mfma_f32_16x16x32_bf16 v[20:23], v[180:183], v[220:223], 0
	v_mfma_f32_16x16x32_bf16 v[48:51], v[148:151], v[238:241], 0
	v_mfma_f32_16x16x32_bf16 v[14:17], v[180:183], v[238:241], 0
	v_mfma_f32_16x16x32_bf16 v[44:47], v[148:151], v[246:249], 0
	v_mfma_f32_16x16x32_bf16 v[2:5], v[180:183], v[246:249], 0
	v_mfma_f32_16x16x32_bf16 v[56:59], v[152:155], v[216:219], v[56:59]
	v_mfma_f32_16x16x32_bf16 v[24:27], v[208:211], v[216:219], v[24:27]
	v_mfma_f32_16x16x32_bf16 v[52:55], v[152:155], v[224:227], v[52:55]
	v_mfma_f32_16x16x32_bf16 v[20:23], v[208:211], v[224:227], v[20:23]
	v_mfma_f32_16x16x32_bf16 v[48:51], v[152:155], v[242:245], v[48:51]
	v_mfma_f32_16x16x32_bf16 v[14:17], v[208:211], v[242:245], v[14:17]
	v_mfma_f32_16x16x32_bf16 v[44:47], v[152:155], v[250:253], v[44:47]
	v_mfma_f32_16x16x32_bf16 v[2:5], v[208:211], v[250:253], v[2:5]
	s_barrier
	s_setprio 0
	s_add_i32 s91, 0, 0x18000
	v_add_u32_e32 v18, s91, v188
	s_add_i32 s96, 0, 0x1c000
	ds_read_b128 v[76:79], v18
	ds_read_b128 v[108:111], v18 offset:1024
	ds_read_b128 v[140:143], v18 offset:2048
	ds_read_b128 v[144:147], v18 offset:3072
	v_add_u32_e32 v18, s96, v188
	ds_read_b128 v[148:151], v18
	ds_read_b128 v[152:155], v18 offset:1024
	ds_read_b128 v[180:183], v18 offset:2048
	ds_read_b128 v[208:211], v18 offset:3072
	s_add_u32 s52, s52, 0x80000
	s_addc_u32 s53, s53, 0
	s_mov_b32 m0, s42
	v_lshl_add_u64 v[18:19], s[52:53], 0, v[158:159]
	ds_read_b128 v[212:215], v206 offset:32768
	ds_read_b128 v[216:219], v206 offset:33792
	ds_read_b128 v[220:223], v206 offset:34816
	ds_read_b128 v[224:227], v206 offset:35840
	ds_read_b128 v[238:241], v206 offset:36864
	ds_read_b128 v[242:245], v206 offset:37888
	ds_read_b128 v[246:249], v206 offset:38912
	ds_read_b128 v[250:253], v206 offset:39936
	global_load_lds_dwordx4 v[18:19], off
	s_mov_b32 m0, s43
	v_lshl_add_u64 v[18:19], s[52:53], 0, v[162:163]
	global_load_lds_dwordx4 v[18:19], off
	s_setprio 1
	s_waitcnt vmcnt(8) lgkmcnt(0)
	s_barrier
	v_mfma_f32_16x16x32_bf16 v[136:139], v[76:79], v[212:215], v[136:139]
	v_mfma_f32_16x16x32_bf16 v[104:107], v[140:143], v[212:215], v[104:107]
	v_mfma_f32_16x16x32_bf16 v[132:135], v[76:79], v[220:223], v[132:135]
	v_mfma_f32_16x16x32_bf16 v[100:103], v[140:143], v[220:223], v[100:103]
	v_mfma_f32_16x16x32_bf16 v[128:131], v[76:79], v[238:241], v[128:131]
	v_mfma_f32_16x16x32_bf16 v[96:99], v[140:143], v[238:241], v[96:99]
	v_mfma_f32_16x16x32_bf16 v[124:127], v[76:79], v[246:249], v[124:127]
	v_mfma_f32_16x16x32_bf16 v[92:95], v[140:143], v[246:249], v[92:95]
	v_mfma_f32_16x16x32_bf16 v[136:139], v[108:111], v[216:219], v[136:139]
	v_mfma_f32_16x16x32_bf16 v[104:107], v[144:147], v[216:219], v[104:107]
	v_mfma_f32_16x16x32_bf16 v[132:135], v[108:111], v[224:227], v[132:135]
	v_mfma_f32_16x16x32_bf16 v[100:103], v[144:147], v[224:227], v[100:103]
	v_mfma_f32_16x16x32_bf16 v[128:131], v[108:111], v[242:245], v[128:131]
	v_mfma_f32_16x16x32_bf16 v[96:99], v[144:147], v[242:245], v[96:99]
	v_mfma_f32_16x16x32_bf16 v[124:127], v[108:111], v[250:253], v[124:127]
	v_mfma_f32_16x16x32_bf16 v[92:95], v[144:147], v[250:253], v[92:95]
	s_setprio 0
	s_setprio 1
	v_mfma_f32_16x16x32_bf16 v[72:75], v[148:151], v[212:215], v[72:75]
	v_mfma_f32_16x16x32_bf16 v[40:43], v[180:183], v[212:215], v[40:43]
	v_mfma_f32_16x16x32_bf16 v[68:71], v[148:151], v[220:223], v[68:71]
	v_mfma_f32_16x16x32_bf16 v[36:39], v[180:183], v[220:223], v[36:39]
	v_mfma_f32_16x16x32_bf16 v[64:67], v[148:151], v[238:241], v[64:67]
	v_mfma_f32_16x16x32_bf16 v[32:35], v[180:183], v[238:241], v[32:35]
	v_mfma_f32_16x16x32_bf16 v[60:63], v[148:151], v[246:249], v[60:63]
	v_mfma_f32_16x16x32_bf16 v[28:31], v[180:183], v[246:249], v[28:31]
	v_mfma_f32_16x16x32_bf16 v[72:75], v[152:155], v[216:219], v[72:75]
	v_mfma_f32_16x16x32_bf16 v[40:43], v[208:211], v[216:219], v[40:43]
	v_mfma_f32_16x16x32_bf16 v[68:71], v[152:155], v[224:227], v[68:71]
	v_mfma_f32_16x16x32_bf16 v[36:39], v[208:211], v[224:227], v[36:39]
	v_mfma_f32_16x16x32_bf16 v[64:67], v[152:155], v[242:245], v[64:67]
	v_mfma_f32_16x16x32_bf16 v[32:35], v[208:211], v[242:245], v[32:35]
	v_mfma_f32_16x16x32_bf16 v[60:63], v[152:155], v[250:253], v[60:63]
	v_mfma_f32_16x16x32_bf16 v[28:31], v[208:211], v[250:253], v[28:31]
	s_barrier
	s_setprio 0
	s_add_i32 s52, s91, s33
	v_lshl_add_u64 v[18:19], v[156:157], 0, s[58:59]
	s_mov_b32 m0, s52
	ds_read_b128 v[212:215], v206 offset:49152
	ds_read_b128 v[216:219], v206 offset:50176
	ds_read_b128 v[220:223], v206 offset:51200
	ds_read_b128 v[224:227], v206 offset:52224
	ds_read_b128 v[238:241], v206 offset:53248
	ds_read_b128 v[242:245], v206 offset:54272
	ds_read_b128 v[246:249], v206 offset:55296
	ds_read_b128 v[250:253], v206 offset:56320
	global_load_lds_dwordx4 v[18:19], off
	s_add_i32 m0, s52, 0x2000
	s_add_u32 s14, s14, 0x80080
	v_lshl_add_u64 v[18:19], v[184:185], 0, s[58:59]
	s_addc_u32 s15, s15, 0
	s_add_i32 s52, s96, s33
	global_load_lds_dwordx4 v[18:19], off
	s_mov_b32 m0, s52
	v_lshl_add_u64 v[18:19], s[14:15], 0, v[160:161]
	global_load_lds_dwordx4 v[18:19], off
	s_add_i32 m0, s52, 0x2000
	v_lshl_add_u64 v[18:19], s[14:15], 0, v[164:165]
	global_load_lds_dwordx4 v[18:19], off
	s_mov_b32 m0, s55
	v_lshl_add_u64 v[18:19], v[196:197], 0, s[58:59]
	global_load_lds_dwordx4 v[18:19], off
	s_mov_b32 m0, s77
	v_lshl_add_u64 v[18:19], v[198:199], 0, s[58:59]
	global_load_lds_dwordx4 v[18:19], off
	s_setprio 1
	s_waitcnt vmcnt(8) lgkmcnt(0)
	s_barrier
	v_mfma_f32_16x16x32_bf16 v[120:123], v[76:79], v[212:215], v[120:123]
	v_mfma_f32_16x16x32_bf16 v[116:119], v[76:79], v[220:223], v[116:119]
	v_mfma_f32_16x16x32_bf16 v[112:115], v[76:79], v[238:241], v[112:115]
	v_mfma_f32_16x16x32_bf16 v[6:9], v[76:79], v[246:249], v[6:9]
	v_mfma_f32_16x16x32_bf16 v[120:123], v[108:111], v[216:219], v[120:123]
	v_mfma_f32_16x16x32_bf16 v[88:91], v[140:143], v[212:215], v[88:91]
	v_mfma_f32_16x16x32_bf16 v[116:119], v[108:111], v[224:227], v[116:119]
	v_mfma_f32_16x16x32_bf16 v[84:87], v[140:143], v[220:223], v[84:87]
	v_mfma_f32_16x16x32_bf16 v[112:115], v[108:111], v[242:245], v[112:115]
	v_mfma_f32_16x16x32_bf16 v[80:83], v[140:143], v[238:241], v[80:83]
	v_mfma_f32_16x16x32_bf16 v[108:111], v[108:111], v[250:253], v[6:9]
	v_mfma_f32_16x16x32_bf16 v[6:9], v[140:143], v[246:249], v[10:13]
	v_mfma_f32_16x16x32_bf16 v[88:91], v[144:147], v[216:219], v[88:91]
	v_mfma_f32_16x16x32_bf16 v[84:87], v[144:147], v[224:227], v[84:87]
	v_mfma_f32_16x16x32_bf16 v[80:83], v[144:147], v[242:245], v[80:83]
	v_mfma_f32_16x16x32_bf16 v[76:79], v[144:147], v[250:253], v[6:9]
	s_setprio 0
	s_setprio 1
	v_mfma_f32_16x16x32_bf16 v[6:9], v[148:151], v[212:215], v[56:59]
	v_mfma_f32_16x16x32_bf16 v[56:59], v[152:155], v[216:219], v[6:9]
	v_mfma_f32_16x16x32_bf16 v[6:9], v[180:183], v[212:215], v[24:27]
	v_mfma_f32_16x16x32_bf16 v[24:27], v[208:211], v[216:219], v[6:9]
	v_mfma_f32_16x16x32_bf16 v[6:9], v[148:151], v[220:223], v[52:55]
	v_mfma_f32_16x16x32_bf16 v[52:55], v[152:155], v[224:227], v[6:9]
	v_mfma_f32_16x16x32_bf16 v[6:9], v[180:183], v[220:223], v[20:23]
	v_mfma_f32_16x16x32_bf16 v[20:23], v[208:211], v[224:227], v[6:9]
	v_mfma_f32_16x16x32_bf16 v[6:9], v[148:151], v[238:241], v[48:51]
	v_mfma_f32_16x16x32_bf16 v[48:51], v[152:155], v[242:245], v[6:9]
	v_mfma_f32_16x16x32_bf16 v[6:9], v[180:183], v[238:241], v[14:17]
	v_mfma_f32_16x16x32_bf16 v[16:19], v[208:211], v[242:245], v[6:9]
	v_mfma_f32_16x16x32_bf16 v[6:9], v[148:151], v[246:249], v[44:47]
	v_mfma_f32_16x16x32_bf16 v[2:5], v[180:183], v[246:249], v[2:5]
	v_mfma_f32_16x16x32_bf16 v[44:47], v[152:155], v[250:253], v[6:9]
	v_mfma_f32_16x16x32_bf16 v[2:5], v[208:211], v[250:253], v[2:5]
	s_barrier
	s_setprio 0
	s_add_i32 s90, s90, 2
	s_add_u32 s8, s8, 0x100
	s_addc_u32 s9, s9, 0
	s_add_u32 s68, s68, 0x100
	s_addc_u32 s69, s69, 0
	s_cmp_gt_u32 s90, 29
	s_cbranch_scc1 .Lpeel_done_0
.LBB0_176:
	s_add_u32 s14, s8, 0xfff80080
	s_addc_u32 s15, s9, -1
	s_add_i32 s91, 0, 0x10000
	s_cmp_eq_u32 s90, 28
	s_cselect_b32 s53, s11, s15
	s_cselect_b32 s52, s13, s14
	v_add_u32_e32 v14, s91, v188
	s_cselect_b32 s15, s57, s69
	s_cselect_b32 s14, s61, s68
	s_add_i32 s96, 0, 0x14000
	ds_read_b128 v[6:9], v14
	ds_read_b128 v[10:13], v14 offset:1024
	ds_read_b128 v[140:143], v14 offset:2048
	ds_read_b128 v[144:147], v14 offset:3072
	v_add_u32_e32 v14, s96, v188
	ds_read_b128 v[148:151], v14
	ds_read_b128 v[152:155], v14 offset:1024
	ds_read_b128 v[180:183], v14 offset:2048
	ds_read_b128 v[208:211], v14 offset:3072
	v_lshl_add_u64 v[14:15], s[8:9], 0, v[176:177]
	s_add_i32 m0, s40, 0xc000
	ds_read_b128 v[212:215], v206
	ds_read_b128 v[216:219], v206 offset:1024
	ds_read_b128 v[220:223], v206 offset:2048
	ds_read_b128 v[224:227], v206 offset:3072
	ds_read_b128 v[238:241], v206 offset:4096
	ds_read_b128 v[242:245], v206 offset:5120
	ds_read_b128 v[246:249], v206 offset:6144
	ds_read_b128 v[250:253], v206 offset:7168
	global_load_lds_dwordx4 v[14:15], off
	s_add_i32 m0, s40, 0xe000
	v_lshl_add_u64 v[14:15], s[8:9], 0, v[178:179]
	global_load_lds_dwordx4 v[14:15], off
	s_setprio 1
	s_waitcnt vmcnt(8) lgkmcnt(0)
	s_barrier
	v_mfma_f32_16x16x32_bf16 v[136:139], v[6:9], v[212:215], v[136:139]
	v_mfma_f32_16x16x32_bf16 v[104:107], v[140:143], v[212:215], v[104:107]
	v_mfma_f32_16x16x32_bf16 v[132:135], v[6:9], v[220:223], v[132:135]
	v_mfma_f32_16x16x32_bf16 v[100:103], v[140:143], v[220:223], v[100:103]
	v_mfma_f32_16x16x32_bf16 v[128:131], v[6:9], v[238:241], v[128:131]
	v_mfma_f32_16x16x32_bf16 v[96:99], v[140:143], v[238:241], v[96:99]
	v_mfma_f32_16x16x32_bf16 v[124:127], v[6:9], v[246:249], v[124:127]
	v_mfma_f32_16x16x32_bf16 v[92:95], v[140:143], v[246:249], v[92:95]
	v_mfma_f32_16x16x32_bf16 v[136:139], v[10:13], v[216:219], v[136:139]
	v_mfma_f32_16x16x32_bf16 v[104:107], v[144:147], v[216:219], v[104:107]
	v_mfma_f32_16x16x32_bf16 v[132:135], v[10:13], v[224:227], v[132:135]
	v_mfma_f32_16x16x32_bf16 v[100:103], v[144:147], v[224:227], v[100:103]
	v_mfma_f32_16x16x32_bf16 v[128:131], v[10:13], v[242:245], v[128:131]
	v_mfma_f32_16x16x32_bf16 v[96:99], v[144:147], v[242:245], v[96:99]
	v_mfma_f32_16x16x32_bf16 v[124:127], v[10:13], v[250:253], v[124:127]
	v_mfma_f32_16x16x32_bf16 v[92:95], v[144:147], v[250:253], v[92:95]
	s_setprio 0
	s_setprio 1
	v_mfma_f32_16x16x32_bf16 v[72:75], v[148:151], v[212:215], v[72:75]
	v_mfma_f32_16x16x32_bf16 v[40:43], v[180:183], v[212:215], v[40:43]
	v_mfma_f32_16x16x32_bf16 v[68:71], v[148:151], v[220:223], v[68:71]
	v_mfma_f32_16x16x32_bf16 v[36:39], v[180:183], v[220:223], v[36:39]
	v_mfma_f32_16x16x32_bf16 v[64:67], v[148:151], v[238:241], v[64:67]
	v_mfma_f32_16x16x32_bf16 v[32:35], v[180:183], v[238:241], v[32:35]
	v_mfma_f32_16x16x32_bf16 v[60:63], v[148:151], v[246:249], v[60:63]
	v_mfma_f32_16x16x32_bf16 v[28:31], v[180:183], v[246:249], v[28:31]
	v_mfma_f32_16x16x32_bf16 v[72:75], v[152:155], v[216:219], v[72:75]
	v_mfma_f32_16x16x32_bf16 v[40:43], v[208:211], v[216:219], v[40:43]
	v_mfma_f32_16x16x32_bf16 v[68:71], v[152:155], v[224:227], v[68:71]
	v_mfma_f32_16x16x32_bf16 v[36:39], v[208:211], v[224:227], v[36:39]
	v_mfma_f32_16x16x32_bf16 v[64:67], v[152:155], v[242:245], v[64:67]
	v_mfma_f32_16x16x32_bf16 v[32:35], v[208:211], v[242:245], v[32:35]
	v_mfma_f32_16x16x32_bf16 v[60:63], v[152:155], v[250:253], v[60:63]
	v_mfma_f32_16x16x32_bf16 v[28:31], v[208:211], v[250:253], v[28:31]
	s_setprio 0
	s_barrier
	s_add_i32 s91, s91, s33
	v_lshl_add_u64 v[156:157], s[14:15], 0, v[160:161]
	s_mov_b32 m0, s91
	ds_read_b128 v[212:215], v206 offset:16384
	ds_read_b128 v[216:219], v206 offset:17408
	ds_read_b128 v[220:223], v206 offset:18432
	ds_read_b128 v[224:227], v206 offset:19456
	ds_read_b128 v[238:241], v206 offset:20480
	ds_read_b128 v[242:245], v206 offset:21504
	ds_read_b128 v[246:249], v206 offset:22528
	ds_read_b128 v[250:253], v206 offset:23552
	global_load_lds_dwordx4 v[156:157], off
	s_add_i32 m0, s91, 0x2000
	s_add_u32 vcc_lo, s14, 0x80000
	v_lshl_add_u64 v[184:185], s[14:15], 0, v[164:165]
	s_addc_u32 vcc_hi, s15, 0
	s_add_i32 s91, s96, s33
	global_load_lds_dwordx4 v[184:185], off
	v_lshl_add_u64 v[14:15], vcc, 0, v[160:161]
	s_mov_b32 m0, s91
	v_lshl_add_u64 v[196:197], s[52:53], 0, v[158:159]
	global_load_lds_dwordx4 v[14:15], off
	v_lshl_add_u64 v[14:15], vcc, 0, v[164:165]
	s_add_i32 m0, s91, 0x2000
	v_lshl_add_u64 v[198:199], s[52:53], 0, v[162:163]
	global_load_lds_dwordx4 v[14:15], off
	s_mov_b32 m0, s40
	s_nop 0
	global_load_lds_dwordx4 v[196:197], off
	s_mov_b32 m0, s41
	s_nop 0
	global_load_lds_dwordx4 v[198:199], off
	s_setprio 1
	s_waitcnt vmcnt(8) lgkmcnt(0)
	s_barrier
	v_mfma_f32_16x16x32_bf16 v[120:123], v[6:9], v[212:215], v[120:123]
	v_mfma_f32_16x16x32_bf16 v[88:91], v[140:143], v[212:215], v[88:91]
	v_mfma_f32_16x16x32_bf16 v[116:119], v[6:9], v[220:223], v[116:119]
	v_mfma_f32_16x16x32_bf16 v[84:87], v[140:143], v[220:223], v[84:87]
	v_mfma_f32_16x16x32_bf16 v[112:115], v[6:9], v[238:241], v[112:115]
	v_mfma_f32_16x16x32_bf16 v[80:83], v[140:143], v[238:241], v[80:83]
	v_mfma_f32_16x16x32_bf16 v[6:9], v[6:9], v[246:249], v[108:111]
	v_mfma_f32_16x16x32_bf16 v[120:123], v[10:13], v[216:219], v[120:123]
	v_mfma_f32_16x16x32_bf16 v[88:91], v[144:147], v[216:219], v[88:91]
	v_mfma_f32_16x16x32_bf16 v[116:119], v[10:13], v[224:227], v[116:119]
	v_mfma_f32_16x16x32_bf16 v[84:87], v[144:147], v[224:227], v[84:87]
	v_mfma_f32_16x16x32_bf16 v[112:115], v[10:13], v[242:245], v[112:115]
	v_mfma_f32_16x16x32_bf16 v[80:83], v[144:147], v[242:245], v[80:83]
	v_mfma_f32_16x16x32_bf16 v[6:9], v[10:13], v[250:253], v[6:9]
	v_mfma_f32_16x16x32_bf16 v[10:13], v[140:143], v[246:249], v[76:79]
	v_mfma_f32_16x16x32_bf16 v[10:13], v[144:147], v[250:253], v[10:13]
	s_setprio 0
	s_setprio 1
	v_mfma_f32_16x16x32_bf16 v[56:59], v[148:151], v[212:215], v[56:59]
	v_mfma_f32_16x16x32_bf16 v[24:27], v[180:183], v[212:215], v[24:27]
	v_mfma_f32_16x16x32_bf16 v[52:55], v[148:151], v[220:223], v[52:55]
	v_mfma_f32_16x16x32_bf16 v[20:23], v[180:183], v[220:223], v[20:23]
	v_mfma_f32_16x16x32_bf16 v[48:51], v[148:151], v[238:241], v[48:51]
	v_mfma_f32_16x16x32_bf16 v[14:17], v[180:183], v[238:241], v[16:19]
	v_mfma_f32_16x16x32_bf16 v[44:47], v[148:151], v[246:249], v[44:47]
	v_mfma_f32_16x16x32_bf16 v[2:5], v[180:183], v[246:249], v[2:5]
	v_mfma_f32_16x16x32_bf16 v[56:59], v[152:155], v[216:219], v[56:59]
	v_mfma_f32_16x16x32_bf16 v[24:27], v[208:211], v[216:219], v[24:27]
	v_mfma_f32_16x16x32_bf16 v[52:55], v[152:155], v[224:227], v[52:55]
	v_mfma_f32_16x16x32_bf16 v[20:23], v[208:211], v[224:227], v[20:23]
	v_mfma_f32_16x16x32_bf16 v[48:51], v[152:155], v[242:245], v[48:51]
	v_mfma_f32_16x16x32_bf16 v[14:17], v[208:211], v[242:245], v[14:17]
	v_mfma_f32_16x16x32_bf16 v[44:47], v[152:155], v[250:253], v[44:47]
	v_mfma_f32_16x16x32_bf16 v[2:5], v[208:211], v[250:253], v[2:5]
	s_setprio 0
	s_barrier
	s_add_i32 s91, 0, 0x18000
	v_add_u32_e32 v18, s91, v188
	s_add_i32 s96, 0, 0x1c000
	ds_read_b128 v[76:79], v18
	ds_read_b128 v[108:111], v18 offset:1024
	ds_read_b128 v[140:143], v18 offset:2048
	ds_read_b128 v[144:147], v18 offset:3072
	v_add_u32_e32 v18, s96, v188
	ds_read_b128 v[148:151], v18
	ds_read_b128 v[152:155], v18 offset:1024
	ds_read_b128 v[180:183], v18 offset:2048
	ds_read_b128 v[208:211], v18 offset:3072
	s_add_u32 s52, s52, 0x80000
	s_addc_u32 s53, s53, 0
	s_mov_b32 m0, s42
	v_lshl_add_u64 v[18:19], s[52:53], 0, v[158:159]
	ds_read_b128 v[212:215], v206 offset:32768
	ds_read_b128 v[216:219], v206 offset:33792
	ds_read_b128 v[220:223], v206 offset:34816
	ds_read_b128 v[224:227], v206 offset:35840
	ds_read_b128 v[238:241], v206 offset:36864
	ds_read_b128 v[242:245], v206 offset:37888
	ds_read_b128 v[246:249], v206 offset:38912
	ds_read_b128 v[250:253], v206 offset:39936
	global_load_lds_dwordx4 v[18:19], off
	s_mov_b32 m0, s43
	v_lshl_add_u64 v[18:19], s[52:53], 0, v[162:163]
	global_load_lds_dwordx4 v[18:19], off
	s_setprio 1
	s_waitcnt vmcnt(8) lgkmcnt(0)
	s_barrier
	v_mfma_f32_16x16x32_bf16 v[136:139], v[76:79], v[212:215], v[136:139]
	v_mfma_f32_16x16x32_bf16 v[104:107], v[140:143], v[212:215], v[104:107]
	v_mfma_f32_16x16x32_bf16 v[132:135], v[76:79], v[220:223], v[132:135]
	v_mfma_f32_16x16x32_bf16 v[100:103], v[140:143], v[220:223], v[100:103]
	v_mfma_f32_16x16x32_bf16 v[128:131], v[76:79], v[238:241], v[128:131]
	v_mfma_f32_16x16x32_bf16 v[96:99], v[140:143], v[238:241], v[96:99]
	v_mfma_f32_16x16x32_bf16 v[124:127], v[76:79], v[246:249], v[124:127]
	v_mfma_f32_16x16x32_bf16 v[92:95], v[140:143], v[246:249], v[92:95]
	v_mfma_f32_16x16x32_bf16 v[136:139], v[108:111], v[216:219], v[136:139]
	v_mfma_f32_16x16x32_bf16 v[104:107], v[144:147], v[216:219], v[104:107]
	v_mfma_f32_16x16x32_bf16 v[132:135], v[108:111], v[224:227], v[132:135]
	v_mfma_f32_16x16x32_bf16 v[100:103], v[144:147], v[224:227], v[100:103]
	v_mfma_f32_16x16x32_bf16 v[128:131], v[108:111], v[242:245], v[128:131]
	v_mfma_f32_16x16x32_bf16 v[96:99], v[144:147], v[242:245], v[96:99]
	v_mfma_f32_16x16x32_bf16 v[124:127], v[108:111], v[250:253], v[124:127]
	v_mfma_f32_16x16x32_bf16 v[92:95], v[144:147], v[250:253], v[92:95]
	s_setprio 0
	s_setprio 1
	v_mfma_f32_16x16x32_bf16 v[72:75], v[148:151], v[212:215], v[72:75]
	v_mfma_f32_16x16x32_bf16 v[40:43], v[180:183], v[212:215], v[40:43]
	v_mfma_f32_16x16x32_bf16 v[68:71], v[148:151], v[220:223], v[68:71]
	v_mfma_f32_16x16x32_bf16 v[36:39], v[180:183], v[220:223], v[36:39]
	v_mfma_f32_16x16x32_bf16 v[64:67], v[148:151], v[238:241], v[64:67]
	v_mfma_f32_16x16x32_bf16 v[32:35], v[180:183], v[238:241], v[32:35]
	v_mfma_f32_16x16x32_bf16 v[60:63], v[148:151], v[246:249], v[60:63]
	v_mfma_f32_16x16x32_bf16 v[28:31], v[180:183], v[246:249], v[28:31]
	v_mfma_f32_16x16x32_bf16 v[72:75], v[152:155], v[216:219], v[72:75]
	v_mfma_f32_16x16x32_bf16 v[40:43], v[208:211], v[216:219], v[40:43]
	v_mfma_f32_16x16x32_bf16 v[68:71], v[152:155], v[224:227], v[68:71]
	v_mfma_f32_16x16x32_bf16 v[36:39], v[208:211], v[224:227], v[36:39]
	v_mfma_f32_16x16x32_bf16 v[64:67], v[152:155], v[242:245], v[64:67]
	v_mfma_f32_16x16x32_bf16 v[32:35], v[208:211], v[242:245], v[32:35]
	v_mfma_f32_16x16x32_bf16 v[60:63], v[152:155], v[250:253], v[60:63]
	v_mfma_f32_16x16x32_bf16 v[28:31], v[208:211], v[250:253], v[28:31]
	s_setprio 0
	s_barrier
	s_add_i32 s52, s91, s33
	v_lshl_add_u64 v[18:19], v[156:157], 0, s[58:59]
	s_mov_b32 m0, s52
	ds_read_b128 v[212:215], v206 offset:49152
	ds_read_b128 v[216:219], v206 offset:50176
	ds_read_b128 v[220:223], v206 offset:51200
	ds_read_b128 v[224:227], v206 offset:52224
	ds_read_b128 v[238:241], v206 offset:53248
	ds_read_b128 v[242:245], v206 offset:54272
	ds_read_b128 v[246:249], v206 offset:55296
	ds_read_b128 v[250:253], v206 offset:56320
	global_load_lds_dwordx4 v[18:19], off
	s_add_i32 m0, s52, 0x2000
	s_add_u32 s14, s14, 0x80080
	v_lshl_add_u64 v[18:19], v[184:185], 0, s[58:59]
	s_addc_u32 s15, s15, 0
	s_add_i32 s52, s96, s33
	global_load_lds_dwordx4 v[18:19], off
	s_mov_b32 m0, s52
	v_lshl_add_u64 v[18:19], s[14:15], 0, v[160:161]
	global_load_lds_dwordx4 v[18:19], off
	s_add_i32 m0, s52, 0x2000
	v_lshl_add_u64 v[18:19], s[14:15], 0, v[164:165]
	global_load_lds_dwordx4 v[18:19], off
	s_mov_b32 m0, s55
	v_lshl_add_u64 v[18:19], v[196:197], 0, s[58:59]
	global_load_lds_dwordx4 v[18:19], off
	s_mov_b32 m0, s77
	v_lshl_add_u64 v[18:19], v[198:199], 0, s[58:59]
	global_load_lds_dwordx4 v[18:19], off
	s_setprio 1
	s_waitcnt vmcnt(8) lgkmcnt(0)
	s_barrier
	v_mfma_f32_16x16x32_bf16 v[120:123], v[76:79], v[212:215], v[120:123]
	v_mfma_f32_16x16x32_bf16 v[116:119], v[76:79], v[220:223], v[116:119]
	v_mfma_f32_16x16x32_bf16 v[112:115], v[76:79], v[238:241], v[112:115]
	v_mfma_f32_16x16x32_bf16 v[6:9], v[76:79], v[246:249], v[6:9]
	v_mfma_f32_16x16x32_bf16 v[120:123], v[108:111], v[216:219], v[120:123]
	v_mfma_f32_16x16x32_bf16 v[88:91], v[140:143], v[212:215], v[88:91]
	v_mfma_f32_16x16x32_bf16 v[116:119], v[108:111], v[224:227], v[116:119]
	v_mfma_f32_16x16x32_bf16 v[84:87], v[140:143], v[220:223], v[84:87]
	v_mfma_f32_16x16x32_bf16 v[112:115], v[108:111], v[242:245], v[112:115]
	v_mfma_f32_16x16x32_bf16 v[80:83], v[140:143], v[238:241], v[80:83]
	v_mfma_f32_16x16x32_bf16 v[108:111], v[108:111], v[250:253], v[6:9]
	v_mfma_f32_16x16x32_bf16 v[6:9], v[140:143], v[246:249], v[10:13]
	v_mfma_f32_16x16x32_bf16 v[88:91], v[144:147], v[216:219], v[88:91]
	v_mfma_f32_16x16x32_bf16 v[84:87], v[144:147], v[224:227], v[84:87]
	v_mfma_f32_16x16x32_bf16 v[80:83], v[144:147], v[242:245], v[80:83]
	v_mfma_f32_16x16x32_bf16 v[76:79], v[144:147], v[250:253], v[6:9]
	s_setprio 0
	s_setprio 1
	v_mfma_f32_16x16x32_bf16 v[6:9], v[148:151], v[212:215], v[56:59]
	v_mfma_f32_16x16x32_bf16 v[56:59], v[152:155], v[216:219], v[6:9]
	v_mfma_f32_16x16x32_bf16 v[6:9], v[180:183], v[212:215], v[24:27]
	v_mfma_f32_16x16x32_bf16 v[24:27], v[208:211], v[216:219], v[6:9]
	v_mfma_f32_16x16x32_bf16 v[6:9], v[148:151], v[220:223], v[52:55]
	v_mfma_f32_16x16x32_bf16 v[52:55], v[152:155], v[224:227], v[6:9]
	v_mfma_f32_16x16x32_bf16 v[6:9], v[180:183], v[220:223], v[20:23]
	v_mfma_f32_16x16x32_bf16 v[20:23], v[208:211], v[224:227], v[6:9]
	v_mfma_f32_16x16x32_bf16 v[6:9], v[148:151], v[238:241], v[48:51]
	v_mfma_f32_16x16x32_bf16 v[48:51], v[152:155], v[242:245], v[6:9]
	v_mfma_f32_16x16x32_bf16 v[6:9], v[180:183], v[238:241], v[14:17]
	v_mfma_f32_16x16x32_bf16 v[16:19], v[208:211], v[242:245], v[6:9]
	v_mfma_f32_16x16x32_bf16 v[6:9], v[148:151], v[246:249], v[44:47]
	v_mfma_f32_16x16x32_bf16 v[2:5], v[180:183], v[246:249], v[2:5]
	v_mfma_f32_16x16x32_bf16 v[44:47], v[152:155], v[250:253], v[6:9]
	v_mfma_f32_16x16x32_bf16 v[2:5], v[208:211], v[250:253], v[2:5]
	s_setprio 0
	s_barrier
	s_add_i32 s90, s90, 2
	s_add_u32 s8, s8, 0x100
	s_addc_u32 s9, s9, 0
	s_add_u32 s68, s68, 0x100
	s_addc_u32 s69, s69, 0
	s_cmp_gt_u32 s90, 29
	s_cbranch_scc0 .LBB0_176

.LBB0_671:
	s_ashr_i32 s11, s10, 31
	s_lshl_b64 s[12:13], s[10:11], 20
	v_readlane_b32 s14, v254, 17
	v_readlane_b32 s15, v254, 18
	s_add_u32 s12, s14, s12
	s_addc_u32 s13, s15, s13
	s_and_b64 s[14:15], s[4:5], exec
	s_cselect_b32 s11, s13, s23
	s_cselect_b32 s18, s12, s22
	s_ashr_i32 s9, s8, 31
	s_lshl_b64 s[14:15], s[8:9], 20
	v_readlane_b32 s26, v254, 44
	v_readlane_b32 s27, v254, 45
	s_add_u32 s14, s26, s14
	s_addc_u32 s15, s27, s15
	s_and_b64 s[26:27], s[4:5], exec
	s_cselect_b32 s9, s15, s25
	s_cselect_b32 s19, s14, s24
	s_add_u32 s22, s22, 0x80080
	s_addc_u32 s23, s23, 0
	s_add_u32 s21, s24, 0x100
	s_addc_u32 s33, s25, 0
	s_mov_b32 s40, -2
	v_readlane_b32 s41, v255, 49
	s_nop 3
	s_cmp_eq_u32 s41, 2
	v_writelane_b32 v255, 2, 49
	s_cbranch_scc0 .Ltrip0_strict_1
	s_add_u32 s24, s22, 0xfff80080
	s_addc_u32 s25, s23, -1
	s_add_i32 s41, 0, 0x10000
	s_cmp_eq_u32 s40, 28
	s_cselect_b32 s27, s11, s25
	s_cselect_b32 s26, s18, s24
	s_cselect_b32 s25, s9, s33
	s_cselect_b32 s24, s19, s21
	s_add_i32 s46, 0, 0x14000
	v_add_u32_e32 v142, s41, v214
	v_add_u32_e32 v158, s46, v214
	ds_read_b128 v[130:133], v142
	ds_read_b128 v[134:137], v142 offset:1024
	ds_read_b128 v[138:141], v142 offset:2048
	ds_read_b128 v[142:145], v142 offset:3072
	ds_read_b128 v[146:149], v158
	ds_read_b128 v[150:153], v158 offset:1024
	ds_read_b128 v[154:157], v158 offset:2048
	ds_read_b128 v[158:161], v158 offset:3072
	v_lshl_add_u64 v[212:213], s[22:23], 0, v[182:183]
	s_add_i32 m0, s17, 0xc000
	ds_read_b128 v[162:165], v216
	ds_read_b128 v[166:169], v216 offset:1024
	ds_read_b128 v[170:173], v216 offset:2048
	ds_read_b128 v[186:189], v216 offset:3072
	ds_read_b128 v[196:199], v216 offset:4096
	ds_read_b128 v[200:203], v216 offset:5120
	ds_read_b128 v[204:207], v216 offset:6144
	ds_read_b128 v[208:211], v216 offset:7168
	global_load_lds_dwordx4 v[212:213], off
	s_add_i32 m0, s17, 0xe000
	v_lshl_add_u64 v[212:213], s[22:23], 0, v[184:185]
	global_load_lds_dwordx4 v[212:213], off
	s_setprio 1
	s_waitcnt vmcnt(24) lgkmcnt(0)
	s_barrier
	v_mfma_f32_16x16x32_bf16 v[126:129], v[130:133], v[162:165], 0
	v_mfma_f32_16x16x32_bf16 v[122:125], v[138:141], v[162:165], 0
	v_mfma_f32_16x16x32_bf16 v[110:113], v[130:133], v[170:173], 0
	v_mfma_f32_16x16x32_bf16 v[106:109], v[138:141], v[170:173], 0
	v_mfma_f32_16x16x32_bf16 v[94:97], v[130:133], v[196:199], 0
	v_mfma_f32_16x16x32_bf16 v[90:93], v[138:141], v[196:199], 0
	v_mfma_f32_16x16x32_bf16 v[78:81], v[130:133], v[204:207], 0
	v_mfma_f32_16x16x32_bf16 v[74:77], v[138:141], v[204:207], 0
	v_mfma_f32_16x16x32_bf16 v[126:129], v[134:137], v[166:169], v[126:129]
	v_mfma_f32_16x16x32_bf16 v[122:125], v[142:145], v[166:169], v[122:125]
	v_mfma_f32_16x16x32_bf16 v[110:113], v[134:137], v[186:189], v[110:113]
	v_mfma_f32_16x16x32_bf16 v[106:109], v[142:145], v[186:189], v[106:109]
	v_mfma_f32_16x16x32_bf16 v[94:97], v[134:137], v[200:203], v[94:97]
	v_mfma_f32_16x16x32_bf16 v[90:93], v[142:145], v[200:203], v[90:93]
	v_mfma_f32_16x16x32_bf16 v[78:81], v[134:137], v[208:211], v[78:81]
	v_mfma_f32_16x16x32_bf16 v[74:77], v[142:145], v[208:211], v[74:77]
	s_setprio 0
	s_setprio 1
	v_mfma_f32_16x16x32_bf16 v[118:121], v[146:149], v[162:165], 0
	v_mfma_f32_16x16x32_bf16 v[114:117], v[154:157], v[162:165], 0
	v_mfma_f32_16x16x32_bf16 v[102:105], v[146:149], v[170:173], 0
	v_mfma_f32_16x16x32_bf16 v[98:101], v[154:157], v[170:173], 0
	v_mfma_f32_16x16x32_bf16 v[86:89], v[146:149], v[196:199], 0
	v_mfma_f32_16x16x32_bf16 v[82:85], v[154:157], v[196:199], 0
	v_mfma_f32_16x16x32_bf16 v[70:73], v[146:149], v[204:207], 0
	v_mfma_f32_16x16x32_bf16 v[66:69], v[154:157], v[204:207], 0
	v_mfma_f32_16x16x32_bf16 v[118:121], v[150:153], v[166:169], v[118:121]
	v_mfma_f32_16x16x32_bf16 v[114:117], v[158:161], v[166:169], v[114:117]
	v_mfma_f32_16x16x32_bf16 v[102:105], v[150:153], v[186:189], v[102:105]
	v_mfma_f32_16x16x32_bf16 v[98:101], v[158:161], v[186:189], v[98:101]
	v_mfma_f32_16x16x32_bf16 v[86:89], v[150:153], v[200:203], v[86:89]
	v_mfma_f32_16x16x32_bf16 v[82:85], v[158:161], v[200:203], v[82:85]
	v_mfma_f32_16x16x32_bf16 v[70:73], v[150:153], v[208:211], v[70:73]
	v_mfma_f32_16x16x32_bf16 v[66:69], v[158:161], v[208:211], v[66:69]
	s_barrier
	s_setprio 0
	s_add_i32 s41, s41, s29
	v_lshl_add_u64 v[212:213], s[24:25], 0, v[178:179]
	s_mov_b32 m0, s41
	ds_read_b128 v[162:165], v216 offset:16384
	ds_read_b128 v[166:169], v216 offset:17408
	ds_read_b128 v[170:173], v216 offset:18432
	ds_read_b128 v[186:189], v216 offset:19456
	ds_read_b128 v[196:199], v216 offset:20480
	ds_read_b128 v[200:203], v216 offset:21504
	ds_read_b128 v[204:207], v216 offset:22528
	ds_read_b128 v[208:211], v216 offset:23552
	global_load_lds_dwordx4 v[212:213], off
	s_add_i32 m0, s41, 0x2000
	s_add_u32 s42, s24, 0x80000
	v_lshl_add_u64 v[218:219], s[24:25], 0, v[174:175]
	s_addc_u32 s43, s25, 0
	s_add_i32 s41, s46, s29
	global_load_lds_dwordx4 v[218:219], off
	v_lshl_add_u64 v[220:221], s[42:43], 0, v[178:179]
	s_mov_b32 m0, s41
	v_lshl_add_u64 v[222:223], s[26:27], 0, v[176:177]
	global_load_lds_dwordx4 v[220:221], off
	s_add_i32 m0, s41, 0x2000
	v_lshl_add_u64 v[220:221], s[42:43], 0, v[174:175]
	global_load_lds_dwordx4 v[220:221], off
	s_mov_b32 m0, s17
	v_lshl_add_u64 v[220:221], s[26:27], 0, v[180:181]
	global_load_lds_dwordx4 v[220:221], off
	s_mov_b32 m0, s31
	s_nop 0
	global_load_lds_dwordx4 v[222:223], off
	s_setprio 1
	s_waitcnt vmcnt(24) lgkmcnt(0)
	s_barrier
	v_mfma_f32_16x16x32_bf16 v[62:65], v[130:133], v[162:165], 0
	v_mfma_f32_16x16x32_bf16 v[58:61], v[138:141], v[162:165], 0
	v_mfma_f32_16x16x32_bf16 v[46:49], v[130:133], v[170:173], 0
	v_mfma_f32_16x16x32_bf16 v[42:45], v[138:141], v[170:173], 0
	v_mfma_f32_16x16x32_bf16 v[30:33], v[130:133], v[196:199], 0
	v_mfma_f32_16x16x32_bf16 v[26:29], v[138:141], v[196:199], 0
	v_mfma_f32_16x16x32_bf16 v[14:17], v[130:133], v[204:207], 0
	v_mfma_f32_16x16x32_bf16 v[10:13], v[138:141], v[204:207], 0
	v_mfma_f32_16x16x32_bf16 v[62:65], v[134:137], v[166:169], v[62:65]
	v_mfma_f32_16x16x32_bf16 v[58:61], v[142:145], v[166:169], v[58:61]
	v_mfma_f32_16x16x32_bf16 v[46:49], v[134:137], v[186:189], v[46:49]
	v_mfma_f32_16x16x32_bf16 v[42:45], v[142:145], v[186:189], v[42:45]
	v_mfma_f32_16x16x32_bf16 v[30:33], v[134:137], v[200:203], v[30:33]
	v_mfma_f32_16x16x32_bf16 v[26:29], v[142:145], v[200:203], v[26:29]
	v_mfma_f32_16x16x32_bf16 v[14:17], v[134:137], v[208:211], v[14:17]
	v_mfma_f32_16x16x32_bf16 v[10:13], v[142:145], v[208:211], v[10:13]
	s_setprio 0
	s_setprio 1
	v_mfma_f32_16x16x32_bf16 v[54:57], v[146:149], v[162:165], 0
	v_mfma_f32_16x16x32_bf16 v[50:53], v[154:157], v[162:165], 0
	v_mfma_f32_16x16x32_bf16 v[38:41], v[146:149], v[170:173], 0
	v_mfma_f32_16x16x32_bf16 v[34:37], v[154:157], v[170:173], 0
	v_mfma_f32_16x16x32_bf16 v[22:25], v[146:149], v[196:199], 0
	v_mfma_f32_16x16x32_bf16 v[18:21], v[154:157], v[196:199], 0
	v_mfma_f32_16x16x32_bf16 v[6:9], v[146:149], v[204:207], 0
	v_mfma_f32_16x16x32_bf16 v[2:5], v[154:157], v[204:207], 0
	v_mfma_f32_16x16x32_bf16 v[54:57], v[150:153], v[166:169], v[54:57]
	v_mfma_f32_16x16x32_bf16 v[50:53], v[158:161], v[166:169], v[50:53]
	v_mfma_f32_16x16x32_bf16 v[38:41], v[150:153], v[186:189], v[38:41]
	v_mfma_f32_16x16x32_bf16 v[34:37], v[158:161], v[186:189], v[34:37]
	v_mfma_f32_16x16x32_bf16 v[22:25], v[150:153], v[200:203], v[22:25]
	v_mfma_f32_16x16x32_bf16 v[18:21], v[158:161], v[200:203], v[18:21]
	v_mfma_f32_16x16x32_bf16 v[6:9], v[150:153], v[208:211], v[6:9]
	v_mfma_f32_16x16x32_bf16 v[2:5], v[158:161], v[208:211], v[2:5]
	s_barrier
	s_setprio 0
	s_add_i32 s41, 0, 0x18000
	s_add_i32 s42, 0, 0x1c000
	v_add_u32_e32 v142, s41, v214
	v_add_u32_e32 v158, s42, v214
	ds_read_b128 v[130:133], v142
	ds_read_b128 v[134:137], v142 offset:1024
	ds_read_b128 v[138:141], v142 offset:2048
	ds_read_b128 v[142:145], v142 offset:3072
	ds_read_b128 v[146:149], v158
	ds_read_b128 v[150:153], v158 offset:1024
	ds_read_b128 v[154:157], v158 offset:2048
	ds_read_b128 v[158:161], v158 offset:3072
	s_add_u32 s26, s26, 0x80000
	s_addc_u32 s27, s27, 0
	s_mov_b32 m0, s34
	v_lshl_add_u64 v[224:225], s[26:27], 0, v[180:181]
	ds_read_b128 v[162:165], v216 offset:32768
	ds_read_b128 v[166:169], v216 offset:33792
	ds_read_b128 v[170:173], v216 offset:34816
	ds_read_b128 v[186:189], v216 offset:35840
	ds_read_b128 v[196:199], v216 offset:36864
	ds_read_b128 v[200:203], v216 offset:37888
	ds_read_b128 v[204:207], v216 offset:38912
	ds_read_b128 v[208:211], v216 offset:39936
	global_load_lds_dwordx4 v[224:225], off
	s_mov_b32 m0, s35
	v_lshl_add_u64 v[224:225], s[26:27], 0, v[176:177]
	global_load_lds_dwordx4 v[224:225], off
	s_setprio 1
	s_waitcnt vmcnt(8) lgkmcnt(0)
	s_barrier
	v_mfma_f32_16x16x32_bf16 v[126:129], v[130:133], v[162:165], v[126:129]
	v_mfma_f32_16x16x32_bf16 v[122:125], v[138:141], v[162:165], v[122:125]
	v_mfma_f32_16x16x32_bf16 v[110:113], v[130:133], v[170:173], v[110:113]
	v_mfma_f32_16x16x32_bf16 v[106:109], v[138:141], v[170:173], v[106:109]
	v_mfma_f32_16x16x32_bf16 v[94:97], v[130:133], v[196:199], v[94:97]
	v_mfma_f32_16x16x32_bf16 v[90:93], v[138:141], v[196:199], v[90:93]
	v_mfma_f32_16x16x32_bf16 v[78:81], v[130:133], v[204:207], v[78:81]
	v_mfma_f32_16x16x32_bf16 v[74:77], v[138:141], v[204:207], v[74:77]
	v_mfma_f32_16x16x32_bf16 v[126:129], v[134:137], v[166:169], v[126:129]
	v_mfma_f32_16x16x32_bf16 v[122:125], v[142:145], v[166:169], v[122:125]
	v_mfma_f32_16x16x32_bf16 v[110:113], v[134:137], v[186:189], v[110:113]
	v_mfma_f32_16x16x32_bf16 v[106:109], v[142:145], v[186:189], v[106:109]
	v_mfma_f32_16x16x32_bf16 v[94:97], v[134:137], v[200:203], v[94:97]
	v_mfma_f32_16x16x32_bf16 v[90:93], v[142:145], v[200:203], v[90:93]
	v_mfma_f32_16x16x32_bf16 v[78:81], v[134:137], v[208:211], v[78:81]
	v_mfma_f32_16x16x32_bf16 v[74:77], v[142:145], v[208:211], v[74:77]
	s_setprio 0
	s_setprio 1
	v_mfma_f32_16x16x32_bf16 v[118:121], v[146:149], v[162:165], v[118:121]
	v_mfma_f32_16x16x32_bf16 v[114:117], v[154:157], v[162:165], v[114:117]
	v_mfma_f32_16x16x32_bf16 v[102:105], v[146:149], v[170:173], v[102:105]
	v_mfma_f32_16x16x32_bf16 v[98:101], v[154:157], v[170:173], v[98:101]
	v_mfma_f32_16x16x32_bf16 v[86:89], v[146:149], v[196:199], v[86:89]
	v_mfma_f32_16x16x32_bf16 v[82:85], v[154:157], v[196:199], v[82:85]
	v_mfma_f32_16x16x32_bf16 v[70:73], v[146:149], v[204:207], v[70:73]
	v_mfma_f32_16x16x32_bf16 v[66:69], v[154:157], v[204:207], v[66:69]
	v_mfma_f32_16x16x32_bf16 v[118:121], v[150:153], v[166:169], v[118:121]
	v_mfma_f32_16x16x32_bf16 v[114:117], v[158:161], v[166:169], v[114:117]
	v_mfma_f32_16x16x32_bf16 v[102:105], v[150:153], v[186:189], v[102:105]
	v_mfma_f32_16x16x32_bf16 v[98:101], v[158:161], v[186:189], v[98:101]
	v_mfma_f32_16x16x32_bf16 v[86:89], v[150:153], v[200:203], v[86:89]
	v_mfma_f32_16x16x32_bf16 v[82:85], v[158:161], v[200:203], v[82:85]
	v_mfma_f32_16x16x32_bf16 v[70:73], v[150:153], v[208:211], v[70:73]
	v_mfma_f32_16x16x32_bf16 v[66:69], v[158:161], v[208:211], v[66:69]
	s_barrier
	s_setprio 0
	s_add_i32 s26, s41, s29
	v_lshl_add_u64 v[212:213], v[212:213], 0, s[58:59]
	s_mov_b32 m0, s26
	ds_read_b128 v[162:165], v216 offset:49152
	ds_read_b128 v[166:169], v216 offset:50176
	ds_read_b128 v[170:173], v216 offset:51200
	ds_read_b128 v[186:189], v216 offset:52224
	ds_read_b128 v[196:199], v216 offset:53248
	ds_read_b128 v[200:203], v216 offset:54272
	ds_read_b128 v[204:207], v216 offset:55296
	ds_read_b128 v[208:211], v216 offset:56320
	global_load_lds_dwordx4 v[212:213], off
	s_add_i32 m0, s26, 0x2000
	s_add_u32 s24, s24, 0x80080
	v_lshl_add_u64 v[212:213], v[218:219], 0, s[58:59]
	s_addc_u32 s25, s25, 0
	s_add_i32 s26, s42, s29
	global_load_lds_dwordx4 v[212:213], off
	s_mov_b32 m0, s26
	v_lshl_add_u64 v[212:213], s[24:25], 0, v[178:179]
	global_load_lds_dwordx4 v[212:213], off
	s_add_i32 m0, s26, 0x2000
	v_lshl_add_u64 v[212:213], s[24:25], 0, v[174:175]
	global_load_lds_dwordx4 v[212:213], off
	s_mov_b32 m0, s38
	v_lshl_add_u64 v[212:213], v[220:221], 0, s[58:59]
	global_load_lds_dwordx4 v[212:213], off
	s_mov_b32 m0, s39
	v_lshl_add_u64 v[212:213], v[222:223], 0, s[58:59]
	global_load_lds_dwordx4 v[212:213], off
	s_setprio 1
	s_waitcnt vmcnt(8) lgkmcnt(0)
	s_barrier
	v_mfma_f32_16x16x32_bf16 v[62:65], v[130:133], v[162:165], v[62:65]
	v_mfma_f32_16x16x32_bf16 v[58:61], v[138:141], v[162:165], v[58:61]
	v_mfma_f32_16x16x32_bf16 v[46:49], v[130:133], v[170:173], v[46:49]
	v_mfma_f32_16x16x32_bf16 v[42:45], v[138:141], v[170:173], v[42:45]
	v_mfma_f32_16x16x32_bf16 v[30:33], v[130:133], v[196:199], v[30:33]
	v_mfma_f32_16x16x32_bf16 v[26:29], v[138:141], v[196:199], v[26:29]
	v_mfma_f32_16x16x32_bf16 v[14:17], v[130:133], v[204:207], v[14:17]
	v_mfma_f32_16x16x32_bf16 v[10:13], v[138:141], v[204:207], v[10:13]
	v_mfma_f32_16x16x32_bf16 v[62:65], v[134:137], v[166:169], v[62:65]
	v_mfma_f32_16x16x32_bf16 v[58:61], v[142:145], v[166:169], v[58:61]
	v_mfma_f32_16x16x32_bf16 v[46:49], v[134:137], v[186:189], v[46:49]
	v_mfma_f32_16x16x32_bf16 v[42:45], v[142:145], v[186:189], v[42:45]
	v_mfma_f32_16x16x32_bf16 v[30:33], v[134:137], v[200:203], v[30:33]
	v_mfma_f32_16x16x32_bf16 v[26:29], v[142:145], v[200:203], v[26:29]
	v_mfma_f32_16x16x32_bf16 v[14:17], v[134:137], v[208:211], v[14:17]
	v_mfma_f32_16x16x32_bf16 v[10:13], v[142:145], v[208:211], v[10:13]
	s_setprio 0
	s_setprio 1
	v_mfma_f32_16x16x32_bf16 v[54:57], v[146:149], v[162:165], v[54:57]
	v_mfma_f32_16x16x32_bf16 v[50:53], v[154:157], v[162:165], v[50:53]
	v_mfma_f32_16x16x32_bf16 v[38:41], v[146:149], v[170:173], v[38:41]
	v_mfma_f32_16x16x32_bf16 v[34:37], v[154:157], v[170:173], v[34:37]
	v_mfma_f32_16x16x32_bf16 v[22:25], v[146:149], v[196:199], v[22:25]
	v_mfma_f32_16x16x32_bf16 v[18:21], v[154:157], v[196:199], v[18:21]
	v_mfma_f32_16x16x32_bf16 v[6:9], v[146:149], v[204:207], v[6:9]
	v_mfma_f32_16x16x32_bf16 v[2:5], v[154:157], v[204:207], v[2:5]
	v_mfma_f32_16x16x32_bf16 v[54:57], v[150:153], v[166:169], v[54:57]
	v_mfma_f32_16x16x32_bf16 v[50:53], v[158:161], v[166:169], v[50:53]
	v_mfma_f32_16x16x32_bf16 v[38:41], v[150:153], v[186:189], v[38:41]
	v_mfma_f32_16x16x32_bf16 v[34:37], v[158:161], v[186:189], v[34:37]
	v_mfma_f32_16x16x32_bf16 v[22:25], v[150:153], v[200:203], v[22:25]
	v_mfma_f32_16x16x32_bf16 v[18:21], v[158:161], v[200:203], v[18:21]
	v_mfma_f32_16x16x32_bf16 v[6:9], v[150:153], v[208:211], v[6:9]
	v_mfma_f32_16x16x32_bf16 v[2:5], v[158:161], v[208:211], v[2:5]
	s_barrier
	s_setprio 0
	s_add_i32 s40, s40, 2
	s_add_u32 s22, s22, 0x100
	s_addc_u32 s23, s23, 0
	s_add_u32 s21, s21, 0x100
	s_addc_u32 s33, s33, 0
	s_cmp_gt_u32 s40, 29
	s_cbranch_scc1 .Lpeel_done_1
	s_branch .LBB0_672
.Ltrip0_strict_1:
	s_add_u32 s24, s22, 0xfff80080
	s_addc_u32 s25, s23, -1
	s_add_i32 s41, 0, 0x10000
	s_cmp_eq_u32 s40, 28
	s_cselect_b32 s27, s11, s25
	s_cselect_b32 s26, s18, s24
	s_cselect_b32 s25, s9, s33
	s_cselect_b32 s24, s19, s21
	s_add_i32 s46, 0, 0x14000
	v_add_u32_e32 v142, s41, v214
	v_add_u32_e32 v158, s46, v214
	ds_read_b128 v[130:133], v142
	ds_read_b128 v[134:137], v142 offset:1024
	ds_read_b128 v[138:141], v142 offset:2048
	ds_read_b128 v[142:145], v142 offset:3072
	ds_read_b128 v[146:149], v158
	ds_read_b128 v[150:153], v158 offset:1024
	ds_read_b128 v[154:157], v158 offset:2048
	ds_read_b128 v[158:161], v158 offset:3072
	v_lshl_add_u64 v[212:213], s[22:23], 0, v[182:183]
	s_add_i32 m0, s17, 0xc000
	ds_read_b128 v[162:165], v216
	ds_read_b128 v[166:169], v216 offset:1024
	ds_read_b128 v[170:173], v216 offset:2048
	ds_read_b128 v[186:189], v216 offset:3072
	ds_read_b128 v[196:199], v216 offset:4096
	ds_read_b128 v[200:203], v216 offset:5120
	ds_read_b128 v[204:207], v216 offset:6144
	ds_read_b128 v[208:211], v216 offset:7168
	global_load_lds_dwordx4 v[212:213], off
	s_add_i32 m0, s17, 0xe000
	v_lshl_add_u64 v[212:213], s[22:23], 0, v[184:185]
	global_load_lds_dwordx4 v[212:213], off
	s_setprio 1
	s_waitcnt vmcnt(8) lgkmcnt(0)
	s_barrier
	v_mfma_f32_16x16x32_bf16 v[126:129], v[130:133], v[162:165], 0
	v_mfma_f32_16x16x32_bf16 v[122:125], v[138:141], v[162:165], 0
	v_mfma_f32_16x16x32_bf16 v[110:113], v[130:133], v[170:173], 0
	v_mfma_f32_16x16x32_bf16 v[106:109], v[138:141], v[170:173], 0
	v_mfma_f32_16x16x32_bf16 v[94:97], v[130:133], v[196:199], 0
	v_mfma_f32_16x16x32_bf16 v[90:93], v[138:141], v[196:199], 0
	v_mfma_f32_16x16x32_bf16 v[78:81], v[130:133], v[204:207], 0
	v_mfma_f32_16x16x32_bf16 v[74:77], v[138:141], v[204:207], 0
	v_mfma_f32_16x16x32_bf16 v[126:129], v[134:137], v[166:169], v[126:129]
	v_mfma_f32_16x16x32_bf16 v[122:125], v[142:145], v[166:169], v[122:125]
	v_mfma_f32_16x16x32_bf16 v[110:113], v[134:137], v[186:189], v[110:113]
	v_mfma_f32_16x16x32_bf16 v[106:109], v[142:145], v[186:189], v[106:109]
	v_mfma_f32_16x16x32_bf16 v[94:97], v[134:137], v[200:203], v[94:97]
	v_mfma_f32_16x16x32_bf16 v[90:93], v[142:145], v[200:203], v[90:93]
	v_mfma_f32_16x16x32_bf16 v[78:81], v[134:137], v[208:211], v[78:81]
	v_mfma_f32_16x16x32_bf16 v[74:77], v[142:145], v[208:211], v[74:77]
	s_setprio 0
	s_setprio 1
	v_mfma_f32_16x16x32_bf16 v[118:121], v[146:149], v[162:165], 0
	v_mfma_f32_16x16x32_bf16 v[114:117], v[154:157], v[162:165], 0
	v_mfma_f32_16x16x32_bf16 v[102:105], v[146:149], v[170:173], 0
	v_mfma_f32_16x16x32_bf16 v[98:101], v[154:157], v[170:173], 0
	v_mfma_f32_16x16x32_bf16 v[86:89], v[146:149], v[196:199], 0
	v_mfma_f32_16x16x32_bf16 v[82:85], v[154:157], v[196:199], 0
	v_mfma_f32_16x16x32_bf16 v[70:73], v[146:149], v[204:207], 0
	v_mfma_f32_16x16x32_bf16 v[66:69], v[154:157], v[204:207], 0
	v_mfma_f32_16x16x32_bf16 v[118:121], v[150:153], v[166:169], v[118:121]
	v_mfma_f32_16x16x32_bf16 v[114:117], v[158:161], v[166:169], v[114:117]
	v_mfma_f32_16x16x32_bf16 v[102:105], v[150:153], v[186:189], v[102:105]
	v_mfma_f32_16x16x32_bf16 v[98:101], v[158:161], v[186:189], v[98:101]
	v_mfma_f32_16x16x32_bf16 v[86:89], v[150:153], v[200:203], v[86:89]
	v_mfma_f32_16x16x32_bf16 v[82:85], v[158:161], v[200:203], v[82:85]
	v_mfma_f32_16x16x32_bf16 v[70:73], v[150:153], v[208:211], v[70:73]
	v_mfma_f32_16x16x32_bf16 v[66:69], v[158:161], v[208:211], v[66:69]
	s_barrier
	s_setprio 0
	s_add_i32 s41, s41, s29
	v_lshl_add_u64 v[212:213], s[24:25], 0, v[178:179]
	s_mov_b32 m0, s41
	ds_read_b128 v[162:165], v216 offset:16384
	ds_read_b128 v[166:169], v216 offset:17408
	ds_read_b128 v[170:173], v216 offset:18432
	ds_read_b128 v[186:189], v216 offset:19456
	ds_read_b128 v[196:199], v216 offset:20480
	ds_read_b128 v[200:203], v216 offset:21504
	ds_read_b128 v[204:207], v216 offset:22528
	ds_read_b128 v[208:211], v216 offset:23552
	global_load_lds_dwordx4 v[212:213], off
	s_add_i32 m0, s41, 0x2000
	s_add_u32 s42, s24, 0x80000
	v_lshl_add_u64 v[218:219], s[24:25], 0, v[174:175]
	s_addc_u32 s43, s25, 0
	s_add_i32 s41, s46, s29
	global_load_lds_dwordx4 v[218:219], off
	v_lshl_add_u64 v[220:221], s[42:43], 0, v[178:179]
	s_mov_b32 m0, s41
	v_lshl_add_u64 v[222:223], s[26:27], 0, v[176:177]
	global_load_lds_dwordx4 v[220:221], off
	s_add_i32 m0, s41, 0x2000
	v_lshl_add_u64 v[220:221], s[42:43], 0, v[174:175]
	global_load_lds_dwordx4 v[220:221], off
	s_mov_b32 m0, s17
	v_lshl_add_u64 v[220:221], s[26:27], 0, v[180:181]
	global_load_lds_dwordx4 v[220:221], off
	s_mov_b32 m0, s31
	s_nop 0
	global_load_lds_dwordx4 v[222:223], off
	s_setprio 1
	s_waitcnt vmcnt(8) lgkmcnt(0)
	s_barrier
	v_mfma_f32_16x16x32_bf16 v[62:65], v[130:133], v[162:165], 0
	v_mfma_f32_16x16x32_bf16 v[58:61], v[138:141], v[162:165], 0
	v_mfma_f32_16x16x32_bf16 v[46:49], v[130:133], v[170:173], 0
	v_mfma_f32_16x16x32_bf16 v[42:45], v[138:141], v[170:173], 0
	v_mfma_f32_16x16x32_bf16 v[30:33], v[130:133], v[196:199], 0
	v_mfma_f32_16x16x32_bf16 v[26:29], v[138:141], v[196:199], 0
	v_mfma_f32_16x16x32_bf16 v[14:17], v[130:133], v[204:207], 0
	v_mfma_f32_16x16x32_bf16 v[10:13], v[138:141], v[204:207], 0
	v_mfma_f32_16x16x32_bf16 v[62:65], v[134:137], v[166:169], v[62:65]
	v_mfma_f32_16x16x32_bf16 v[58:61], v[142:145], v[166:169], v[58:61]
	v_mfma_f32_16x16x32_bf16 v[46:49], v[134:137], v[186:189], v[46:49]
	v_mfma_f32_16x16x32_bf16 v[42:45], v[142:145], v[186:189], v[42:45]
	v_mfma_f32_16x16x32_bf16 v[30:33], v[134:137], v[200:203], v[30:33]
	v_mfma_f32_16x16x32_bf16 v[26:29], v[142:145], v[200:203], v[26:29]
	v_mfma_f32_16x16x32_bf16 v[14:17], v[134:137], v[208:211], v[14:17]
	v_mfma_f32_16x16x32_bf16 v[10:13], v[142:145], v[208:211], v[10:13]
	s_setprio 0
	s_setprio 1
	v_mfma_f32_16x16x32_bf16 v[54:57], v[146:149], v[162:165], 0
	v_mfma_f32_16x16x32_bf16 v[50:53], v[154:157], v[162:165], 0
	v_mfma_f32_16x16x32_bf16 v[38:41], v[146:149], v[170:173], 0
	v_mfma_f32_16x16x32_bf16 v[34:37], v[154:157], v[170:173], 0
	v_mfma_f32_16x16x32_bf16 v[22:25], v[146:149], v[196:199], 0
	v_mfma_f32_16x16x32_bf16 v[18:21], v[154:157], v[196:199], 0
	v_mfma_f32_16x16x32_bf16 v[6:9], v[146:149], v[204:207], 0
	v_mfma_f32_16x16x32_bf16 v[2:5], v[154:157], v[204:207], 0
	v_mfma_f32_16x16x32_bf16 v[54:57], v[150:153], v[166:169], v[54:57]
	v_mfma_f32_16x16x32_bf16 v[50:53], v[158:161], v[166:169], v[50:53]
	v_mfma_f32_16x16x32_bf16 v[38:41], v[150:153], v[186:189], v[38:41]
	v_mfma_f32_16x16x32_bf16 v[34:37], v[158:161], v[186:189], v[34:37]
	v_mfma_f32_16x16x32_bf16 v[22:25], v[150:153], v[200:203], v[22:25]
	v_mfma_f32_16x16x32_bf16 v[18:21], v[158:161], v[200:203], v[18:21]
	v_mfma_f32_16x16x32_bf16 v[6:9], v[150:153], v[208:211], v[6:9]
	v_mfma_f32_16x16x32_bf16 v[2:5], v[158:161], v[208:211], v[2:5]
	s_barrier
	s_setprio 0
	s_add_i32 s41, 0, 0x18000
	s_add_i32 s42, 0, 0x1c000
	v_add_u32_e32 v142, s41, v214
	v_add_u32_e32 v158, s42, v214
	ds_read_b128 v[130:133], v142
	ds_read_b128 v[134:137], v142 offset:1024
	ds_read_b128 v[138:141], v142 offset:2048
	ds_read_b128 v[142:145], v142 offset:3072
	ds_read_b128 v[146:149], v158
	ds_read_b128 v[150:153], v158 offset:1024
	ds_read_b128 v[154:157], v158 offset:2048
	ds_read_b128 v[158:161], v158 offset:3072
	s_add_u32 s26, s26, 0x80000
	s_addc_u32 s27, s27, 0
	s_mov_b32 m0, s34
	v_lshl_add_u64 v[224:225], s[26:27], 0, v[180:181]
	ds_read_b128 v[162:165], v216 offset:32768
	ds_read_b128 v[166:169], v216 offset:33792
	ds_read_b128 v[170:173], v216 offset:34816
	ds_read_b128 v[186:189], v216 offset:35840
	ds_read_b128 v[196:199], v216 offset:36864
	ds_read_b128 v[200:203], v216 offset:37888
	ds_read_b128 v[204:207], v216 offset:38912
	ds_read_b128 v[208:211], v216 offset:39936
	global_load_lds_dwordx4 v[224:225], off
	s_mov_b32 m0, s35
	v_lshl_add_u64 v[224:225], s[26:27], 0, v[176:177]
	global_load_lds_dwordx4 v[224:225], off
	s_setprio 1
	s_waitcnt vmcnt(8) lgkmcnt(0)
	s_barrier
	v_mfma_f32_16x16x32_bf16 v[126:129], v[130:133], v[162:165], v[126:129]
	v_mfma_f32_16x16x32_bf16 v[122:125], v[138:141], v[162:165], v[122:125]
	v_mfma_f32_16x16x32_bf16 v[110:113], v[130:133], v[170:173], v[110:113]
	v_mfma_f32_16x16x32_bf16 v[106:109], v[138:141], v[170:173], v[106:109]
	v_mfma_f32_16x16x32_bf16 v[94:97], v[130:133], v[196:199], v[94:97]
	v_mfma_f32_16x16x32_bf16 v[90:93], v[138:141], v[196:199], v[90:93]
	v_mfma_f32_16x16x32_bf16 v[78:81], v[130:133], v[204:207], v[78:81]
	v_mfma_f32_16x16x32_bf16 v[74:77], v[138:141], v[204:207], v[74:77]
	v_mfma_f32_16x16x32_bf16 v[126:129], v[134:137], v[166:169], v[126:129]
	v_mfma_f32_16x16x32_bf16 v[122:125], v[142:145], v[166:169], v[122:125]
	v_mfma_f32_16x16x32_bf16 v[110:113], v[134:137], v[186:189], v[110:113]
	v_mfma_f32_16x16x32_bf16 v[106:109], v[142:145], v[186:189], v[106:109]
	v_mfma_f32_16x16x32_bf16 v[94:97], v[134:137], v[200:203], v[94:97]
	v_mfma_f32_16x16x32_bf16 v[90:93], v[142:145], v[200:203], v[90:93]
	v_mfma_f32_16x16x32_bf16 v[78:81], v[134:137], v[208:211], v[78:81]
	v_mfma_f32_16x16x32_bf16 v[74:77], v[142:145], v[208:211], v[74:77]
	s_setprio 0
	s_setprio 1
	v_mfma_f32_16x16x32_bf16 v[118:121], v[146:149], v[162:165], v[118:121]
	v_mfma_f32_16x16x32_bf16 v[114:117], v[154:157], v[162:165], v[114:117]
	v_mfma_f32_16x16x32_bf16 v[102:105], v[146:149], v[170:173], v[102:105]
	v_mfma_f32_16x16x32_bf16 v[98:101], v[154:157], v[170:173], v[98:101]
	v_mfma_f32_16x16x32_bf16 v[86:89], v[146:149], v[196:199], v[86:89]
	v_mfma_f32_16x16x32_bf16 v[82:85], v[154:157], v[196:199], v[82:85]
	v_mfma_f32_16x16x32_bf16 v[70:73], v[146:149], v[204:207], v[70:73]
	v_mfma_f32_16x16x32_bf16 v[66:69], v[154:157], v[204:207], v[66:69]
	v_mfma_f32_16x16x32_bf16 v[118:121], v[150:153], v[166:169], v[118:121]
	v_mfma_f32_16x16x32_bf16 v[114:117], v[158:161], v[166:169], v[114:117]
	v_mfma_f32_16x16x32_bf16 v[102:105], v[150:153], v[186:189], v[102:105]
	v_mfma_f32_16x16x32_bf16 v[98:101], v[158:161], v[186:189], v[98:101]
	v_mfma_f32_16x16x32_bf16 v[86:89], v[150:153], v[200:203], v[86:89]
	v_mfma_f32_16x16x32_bf16 v[82:85], v[158:161], v[200:203], v[82:85]
	v_mfma_f32_16x16x32_bf16 v[70:73], v[150:153], v[208:211], v[70:73]
	v_mfma_f32_16x16x32_bf16 v[66:69], v[158:161], v[208:211], v[66:69]
	s_barrier
	s_setprio 0
	s_add_i32 s26, s41, s29
	v_lshl_add_u64 v[212:213], v[212:213], 0, s[58:59]
	s_mov_b32 m0, s26
	ds_read_b128 v[162:165], v216 offset:49152
	ds_read_b128 v[166:169], v216 offset:50176
	ds_read_b128 v[170:173], v216 offset:51200
	ds_read_b128 v[186:189], v216 offset:52224
	ds_read_b128 v[196:199], v216 offset:53248
	ds_read_b128 v[200:203], v216 offset:54272
	ds_read_b128 v[204:207], v216 offset:55296
	ds_read_b128 v[208:211], v216 offset:56320
	global_load_lds_dwordx4 v[212:213], off
	s_add_i32 m0, s26, 0x2000
	s_add_u32 s24, s24, 0x80080
	v_lshl_add_u64 v[212:213], v[218:219], 0, s[58:59]
	s_addc_u32 s25, s25, 0
	s_add_i32 s26, s42, s29
	global_load_lds_dwordx4 v[212:213], off
	s_mov_b32 m0, s26
	v_lshl_add_u64 v[212:213], s[24:25], 0, v[178:179]
	global_load_lds_dwordx4 v[212:213], off
	s_add_i32 m0, s26, 0x2000
	v_lshl_add_u64 v[212:213], s[24:25], 0, v[174:175]
	global_load_lds_dwordx4 v[212:213], off
	s_mov_b32 m0, s38
	v_lshl_add_u64 v[212:213], v[220:221], 0, s[58:59]
	global_load_lds_dwordx4 v[212:213], off
	s_mov_b32 m0, s39
	v_lshl_add_u64 v[212:213], v[222:223], 0, s[58:59]
	global_load_lds_dwordx4 v[212:213], off
	s_setprio 1
	s_waitcnt vmcnt(8) lgkmcnt(0)
	s_barrier
	v_mfma_f32_16x16x32_bf16 v[62:65], v[130:133], v[162:165], v[62:65]
	v_mfma_f32_16x16x32_bf16 v[58:61], v[138:141], v[162:165], v[58:61]
	v_mfma_f32_16x16x32_bf16 v[46:49], v[130:133], v[170:173], v[46:49]
	v_mfma_f32_16x16x32_bf16 v[42:45], v[138:141], v[170:173], v[42:45]
	v_mfma_f32_16x16x32_bf16 v[30:33], v[130:133], v[196:199], v[30:33]
	v_mfma_f32_16x16x32_bf16 v[26:29], v[138:141], v[196:199], v[26:29]
	v_mfma_f32_16x16x32_bf16 v[14:17], v[130:133], v[204:207], v[14:17]
	v_mfma_f32_16x16x32_bf16 v[10:13], v[138:141], v[204:207], v[10:13]
	v_mfma_f32_16x16x32_bf16 v[62:65], v[134:137], v[166:169], v[62:65]
	v_mfma_f32_16x16x32_bf16 v[58:61], v[142:145], v[166:169], v[58:61]
	v_mfma_f32_16x16x32_bf16 v[46:49], v[134:137], v[186:189], v[46:49]
	v_mfma_f32_16x16x32_bf16 v[42:45], v[142:145], v[186:189], v[42:45]
	v_mfma_f32_16x16x32_bf16 v[30:33], v[134:137], v[200:203], v[30:33]
	v_mfma_f32_16x16x32_bf16 v[26:29], v[142:145], v[200:203], v[26:29]
	v_mfma_f32_16x16x32_bf16 v[14:17], v[134:137], v[208:211], v[14:17]
	v_mfma_f32_16x16x32_bf16 v[10:13], v[142:145], v[208:211], v[10:13]
	s_setprio 0
	s_setprio 1
	v_mfma_f32_16x16x32_bf16 v[54:57], v[146:149], v[162:165], v[54:57]
	v_mfma_f32_16x16x32_bf16 v[50:53], v[154:157], v[162:165], v[50:53]
	v_mfma_f32_16x16x32_bf16 v[38:41], v[146:149], v[170:173], v[38:41]
	v_mfma_f32_16x16x32_bf16 v[34:37], v[154:157], v[170:173], v[34:37]
	v_mfma_f32_16x16x32_bf16 v[22:25], v[146:149], v[196:199], v[22:25]
	v_mfma_f32_16x16x32_bf16 v[18:21], v[154:157], v[196:199], v[18:21]
	v_mfma_f32_16x16x32_bf16 v[6:9], v[146:149], v[204:207], v[6:9]
	v_mfma_f32_16x16x32_bf16 v[2:5], v[154:157], v[204:207], v[2:5]
	v_mfma_f32_16x16x32_bf16 v[54:57], v[150:153], v[166:169], v[54:57]
	v_mfma_f32_16x16x32_bf16 v[50:53], v[158:161], v[166:169], v[50:53]
	v_mfma_f32_16x16x32_bf16 v[38:41], v[150:153], v[186:189], v[38:41]
	v_mfma_f32_16x16x32_bf16 v[34:37], v[158:161], v[186:189], v[34:37]
	v_mfma_f32_16x16x32_bf16 v[22:25], v[150:153], v[200:203], v[22:25]
	v_mfma_f32_16x16x32_bf16 v[18:21], v[158:161], v[200:203], v[18:21]
	v_mfma_f32_16x16x32_bf16 v[6:9], v[150:153], v[208:211], v[6:9]
	v_mfma_f32_16x16x32_bf16 v[2:5], v[158:161], v[208:211], v[2:5]
	s_barrier
	s_setprio 0
	s_add_i32 s40, s40, 2
	s_add_u32 s22, s22, 0x100
	s_addc_u32 s23, s23, 0
	s_add_u32 s21, s21, 0x100
	s_addc_u32 s33, s33, 0
	s_cmp_gt_u32 s40, 29
	s_cbranch_scc1 .Lpeel_done_1
.LBB0_672:
	s_add_u32 s24, s22, 0xfff80080
	s_addc_u32 s25, s23, -1
	s_add_i32 s41, 0, 0x10000
	s_cmp_eq_u32 s40, 28
	s_cselect_b32 s27, s11, s25
	s_cselect_b32 s26, s18, s24
	s_cselect_b32 s25, s9, s33
	s_cselect_b32 s24, s19, s21
	s_add_i32 s46, 0, 0x14000
	v_add_u32_e32 v142, s41, v214
	v_add_u32_e32 v158, s46, v214
	ds_read_b128 v[130:133], v142
	ds_read_b128 v[134:137], v142 offset:1024
	ds_read_b128 v[138:141], v142 offset:2048
	ds_read_b128 v[142:145], v142 offset:3072
	ds_read_b128 v[146:149], v158
	ds_read_b128 v[150:153], v158 offset:1024
	ds_read_b128 v[154:157], v158 offset:2048
	ds_read_b128 v[158:161], v158 offset:3072
	v_lshl_add_u64 v[212:213], s[22:23], 0, v[182:183]
	s_add_i32 m0, s17, 0xc000
	ds_read_b128 v[162:165], v216
	ds_read_b128 v[166:169], v216 offset:1024
	ds_read_b128 v[170:173], v216 offset:2048
	ds_read_b128 v[186:189], v216 offset:3072
	ds_read_b128 v[196:199], v216 offset:4096
	ds_read_b128 v[200:203], v216 offset:5120
	ds_read_b128 v[204:207], v216 offset:6144
	ds_read_b128 v[208:211], v216 offset:7168
	global_load_lds_dwordx4 v[212:213], off
	s_add_i32 m0, s17, 0xe000
	v_lshl_add_u64 v[212:213], s[22:23], 0, v[184:185]
	global_load_lds_dwordx4 v[212:213], off
	s_setprio 1
	s_waitcnt vmcnt(8) lgkmcnt(0)
	s_barrier
	v_mfma_f32_16x16x32_bf16 v[126:129], v[130:133], v[162:165], v[126:129]
	v_mfma_f32_16x16x32_bf16 v[122:125], v[138:141], v[162:165], v[122:125]
	v_mfma_f32_16x16x32_bf16 v[110:113], v[130:133], v[170:173], v[110:113]
	v_mfma_f32_16x16x32_bf16 v[106:109], v[138:141], v[170:173], v[106:109]
	v_mfma_f32_16x16x32_bf16 v[94:97], v[130:133], v[196:199], v[94:97]
	v_mfma_f32_16x16x32_bf16 v[90:93], v[138:141], v[196:199], v[90:93]
	v_mfma_f32_16x16x32_bf16 v[78:81], v[130:133], v[204:207], v[78:81]
	v_mfma_f32_16x16x32_bf16 v[74:77], v[138:141], v[204:207], v[74:77]
	v_mfma_f32_16x16x32_bf16 v[126:129], v[134:137], v[166:169], v[126:129]
	v_mfma_f32_16x16x32_bf16 v[122:125], v[142:145], v[166:169], v[122:125]
	v_mfma_f32_16x16x32_bf16 v[110:113], v[134:137], v[186:189], v[110:113]
	v_mfma_f32_16x16x32_bf16 v[106:109], v[142:145], v[186:189], v[106:109]
	v_mfma_f32_16x16x32_bf16 v[94:97], v[134:137], v[200:203], v[94:97]
	v_mfma_f32_16x16x32_bf16 v[90:93], v[142:145], v[200:203], v[90:93]
	v_mfma_f32_16x16x32_bf16 v[78:81], v[134:137], v[208:211], v[78:81]
	v_mfma_f32_16x16x32_bf16 v[74:77], v[142:145], v[208:211], v[74:77]
	s_setprio 0
	s_setprio 1
	v_mfma_f32_16x16x32_bf16 v[118:121], v[146:149], v[162:165], v[118:121]
	v_mfma_f32_16x16x32_bf16 v[114:117], v[154:157], v[162:165], v[114:117]
	v_mfma_f32_16x16x32_bf16 v[102:105], v[146:149], v[170:173], v[102:105]
	v_mfma_f32_16x16x32_bf16 v[98:101], v[154:157], v[170:173], v[98:101]
	v_mfma_f32_16x16x32_bf16 v[86:89], v[146:149], v[196:199], v[86:89]
	v_mfma_f32_16x16x32_bf16 v[82:85], v[154:157], v[196:199], v[82:85]
	v_mfma_f32_16x16x32_bf16 v[70:73], v[146:149], v[204:207], v[70:73]
	v_mfma_f32_16x16x32_bf16 v[66:69], v[154:157], v[204:207], v[66:69]
	v_mfma_f32_16x16x32_bf16 v[118:121], v[150:153], v[166:169], v[118:121]
	v_mfma_f32_16x16x32_bf16 v[114:117], v[158:161], v[166:169], v[114:117]
	v_mfma_f32_16x16x32_bf16 v[102:105], v[150:153], v[186:189], v[102:105]
	v_mfma_f32_16x16x32_bf16 v[98:101], v[158:161], v[186:189], v[98:101]
	v_mfma_f32_16x16x32_bf16 v[86:89], v[150:153], v[200:203], v[86:89]
	v_mfma_f32_16x16x32_bf16 v[82:85], v[158:161], v[200:203], v[82:85]
	v_mfma_f32_16x16x32_bf16 v[70:73], v[150:153], v[208:211], v[70:73]
	v_mfma_f32_16x16x32_bf16 v[66:69], v[158:161], v[208:211], v[66:69]
	s_setprio 0
	s_barrier
	s_add_i32 s41, s41, s29
	v_lshl_add_u64 v[212:213], s[24:25], 0, v[178:179]
	s_mov_b32 m0, s41
	ds_read_b128 v[162:165], v216 offset:16384
	ds_read_b128 v[166:169], v216 offset:17408
	ds_read_b128 v[170:173], v216 offset:18432
	ds_read_b128 v[186:189], v216 offset:19456
	ds_read_b128 v[196:199], v216 offset:20480
	ds_read_b128 v[200:203], v216 offset:21504
	ds_read_b128 v[204:207], v216 offset:22528
	ds_read_b128 v[208:211], v216 offset:23552
	global_load_lds_dwordx4 v[212:213], off
	s_add_i32 m0, s41, 0x2000
	s_add_u32 s42, s24, 0x80000
	v_lshl_add_u64 v[218:219], s[24:25], 0, v[174:175]
	s_addc_u32 s43, s25, 0
	s_add_i32 s41, s46, s29
	global_load_lds_dwordx4 v[218:219], off
	v_lshl_add_u64 v[220:221], s[42:43], 0, v[178:179]
	s_mov_b32 m0, s41
	v_lshl_add_u64 v[222:223], s[26:27], 0, v[176:177]
	global_load_lds_dwordx4 v[220:221], off
	s_add_i32 m0, s41, 0x2000
	v_lshl_add_u64 v[220:221], s[42:43], 0, v[174:175]
	global_load_lds_dwordx4 v[220:221], off
	s_mov_b32 m0, s17
	v_lshl_add_u64 v[220:221], s[26:27], 0, v[180:181]
	global_load_lds_dwordx4 v[220:221], off
	s_mov_b32 m0, s31
	s_nop 0
	global_load_lds_dwordx4 v[222:223], off
	s_setprio 1
	s_waitcnt vmcnt(8) lgkmcnt(0)
	s_barrier
	v_mfma_f32_16x16x32_bf16 v[62:65], v[130:133], v[162:165], v[62:65]
	v_mfma_f32_16x16x32_bf16 v[58:61], v[138:141], v[162:165], v[58:61]
	v_mfma_f32_16x16x32_bf16 v[46:49], v[130:133], v[170:173], v[46:49]
	v_mfma_f32_16x16x32_bf16 v[42:45], v[138:141], v[170:173], v[42:45]
	v_mfma_f32_16x16x32_bf16 v[30:33], v[130:133], v[196:199], v[30:33]
	v_mfma_f32_16x16x32_bf16 v[26:29], v[138:141], v[196:199], v[26:29]
	v_mfma_f32_16x16x32_bf16 v[14:17], v[130:133], v[204:207], v[14:17]
	v_mfma_f32_16x16x32_bf16 v[10:13], v[138:141], v[204:207], v[10:13]
	v_mfma_f32_16x16x32_bf16 v[62:65], v[134:137], v[166:169], v[62:65]
	v_mfma_f32_16x16x32_bf16 v[58:61], v[142:145], v[166:169], v[58:61]
	v_mfma_f32_16x16x32_bf16 v[46:49], v[134:137], v[186:189], v[46:49]
	v_mfma_f32_16x16x32_bf16 v[42:45], v[142:145], v[186:189], v[42:45]
	v_mfma_f32_16x16x32_bf16 v[30:33], v[134:137], v[200:203], v[30:33]
	v_mfma_f32_16x16x32_bf16 v[26:29], v[142:145], v[200:203], v[26:29]
	v_mfma_f32_16x16x32_bf16 v[14:17], v[134:137], v[208:211], v[14:17]
	v_mfma_f32_16x16x32_bf16 v[10:13], v[142:145], v[208:211], v[10:13]
	s_setprio 0
	s_setprio 1
	v_mfma_f32_16x16x32_bf16 v[54:57], v[146:149], v[162:165], v[54:57]
	v_mfma_f32_16x16x32_bf16 v[50:53], v[154:157], v[162:165], v[50:53]
	v_mfma_f32_16x16x32_bf16 v[38:41], v[146:149], v[170:173], v[38:41]
	v_mfma_f32_16x16x32_bf16 v[34:37], v[154:157], v[170:173], v[34:37]
	v_mfma_f32_16x16x32_bf16 v[22:25], v[146:149], v[196:199], v[22:25]
	v_mfma_f32_16x16x32_bf16 v[18:21], v[154:157], v[196:199], v[18:21]
	v_mfma_f32_16x16x32_bf16 v[6:9], v[146:149], v[204:207], v[6:9]
	v_mfma_f32_16x16x32_bf16 v[2:5], v[154:157], v[204:207], v[2:5]
	v_mfma_f32_16x16x32_bf16 v[54:57], v[150:153], v[166:169], v[54:57]
	v_mfma_f32_16x16x32_bf16 v[50:53], v[158:161], v[166:169], v[50:53]
	v_mfma_f32_16x16x32_bf16 v[38:41], v[150:153], v[186:189], v[38:41]
	v_mfma_f32_16x16x32_bf16 v[34:37], v[158:161], v[186:189], v[34:37]
	v_mfma_f32_16x16x32_bf16 v[22:25], v[150:153], v[200:203], v[22:25]
	v_mfma_f32_16x16x32_bf16 v[18:21], v[158:161], v[200:203], v[18:21]
	v_mfma_f32_16x16x32_bf16 v[6:9], v[150:153], v[208:211], v[6:9]
	v_mfma_f32_16x16x32_bf16 v[2:5], v[158:161], v[208:211], v[2:5]
	s_setprio 0
	s_barrier
	s_add_i32 s41, 0, 0x18000
	s_add_i32 s42, 0, 0x1c000
	v_add_u32_e32 v142, s41, v214
	v_add_u32_e32 v158, s42, v214
	ds_read_b128 v[130:133], v142
	ds_read_b128 v[134:137], v142 offset:1024
	ds_read_b128 v[138:141], v142 offset:2048
	ds_read_b128 v[142:145], v142 offset:3072
	ds_read_b128 v[146:149], v158
	ds_read_b128 v[150:153], v158 offset:1024
	ds_read_b128 v[154:157], v158 offset:2048
	ds_read_b128 v[158:161], v158 offset:3072
	s_add_u32 s26, s26, 0x80000
	s_addc_u32 s27, s27, 0
	s_mov_b32 m0, s34
	v_lshl_add_u64 v[224:225], s[26:27], 0, v[180:181]
	ds_read_b128 v[162:165], v216 offset:32768
	ds_read_b128 v[166:169], v216 offset:33792
	ds_read_b128 v[170:173], v216 offset:34816
	ds_read_b128 v[186:189], v216 offset:35840
	ds_read_b128 v[196:199], v216 offset:36864
	ds_read_b128 v[200:203], v216 offset:37888
	ds_read_b128 v[204:207], v216 offset:38912
	ds_read_b128 v[208:211], v216 offset:39936
	global_load_lds_dwordx4 v[224:225], off
	s_mov_b32 m0, s35
	v_lshl_add_u64 v[224:225], s[26:27], 0, v[176:177]
	global_load_lds_dwordx4 v[224:225], off
	s_setprio 1
	s_waitcnt vmcnt(8) lgkmcnt(0)
	s_barrier
	v_mfma_f32_16x16x32_bf16 v[126:129], v[130:133], v[162:165], v[126:129]
	v_mfma_f32_16x16x32_bf16 v[122:125], v[138:141], v[162:165], v[122:125]
	v_mfma_f32_16x16x32_bf16 v[110:113], v[130:133], v[170:173], v[110:113]
	v_mfma_f32_16x16x32_bf16 v[106:109], v[138:141], v[170:173], v[106:109]
	v_mfma_f32_16x16x32_bf16 v[94:97], v[130:133], v[196:199], v[94:97]
	v_mfma_f32_16x16x32_bf16 v[90:93], v[138:141], v[196:199], v[90:93]
	v_mfma_f32_16x16x32_bf16 v[78:81], v[130:133], v[204:207], v[78:81]
	v_mfma_f32_16x16x32_bf16 v[74:77], v[138:141], v[204:207], v[74:77]
	v_mfma_f32_16x16x32_bf16 v[126:129], v[134:137], v[166:169], v[126:129]
	v_mfma_f32_16x16x32_bf16 v[122:125], v[142:145], v[166:169], v[122:125]
	v_mfma_f32_16x16x32_bf16 v[110:113], v[134:137], v[186:189], v[110:113]
	v_mfma_f32_16x16x32_bf16 v[106:109], v[142:145], v[186:189], v[106:109]
	v_mfma_f32_16x16x32_bf16 v[94:97], v[134:137], v[200:203], v[94:97]
	v_mfma_f32_16x16x32_bf16 v[90:93], v[142:145], v[200:203], v[90:93]
	v_mfma_f32_16x16x32_bf16 v[78:81], v[134:137], v[208:211], v[78:81]
	v_mfma_f32_16x16x32_bf16 v[74:77], v[142:145], v[208:211], v[74:77]
	s_setprio 0
	s_setprio 1
	v_mfma_f32_16x16x32_bf16 v[118:121], v[146:149], v[162:165], v[118:121]
	v_mfma_f32_16x16x32_bf16 v[114:117], v[154:157], v[162:165], v[114:117]
	v_mfma_f32_16x16x32_bf16 v[102:105], v[146:149], v[170:173], v[102:105]
	v_mfma_f32_16x16x32_bf16 v[98:101], v[154:157], v[170:173], v[98:101]
	v_mfma_f32_16x16x32_bf16 v[86:89], v[146:149], v[196:199], v[86:89]
	v_mfma_f32_16x16x32_bf16 v[82:85], v[154:157], v[196:199], v[82:85]
	v_mfma_f32_16x16x32_bf16 v[70:73], v[146:149], v[204:207], v[70:73]
	v_mfma_f32_16x16x32_bf16 v[66:69], v[154:157], v[204:207], v[66:69]
	v_mfma_f32_16x16x32_bf16 v[118:121], v[150:153], v[166:169], v[118:121]
	v_mfma_f32_16x16x32_bf16 v[114:117], v[158:161], v[166:169], v[114:117]
	v_mfma_f32_16x16x32_bf16 v[102:105], v[150:153], v[186:189], v[102:105]
	v_mfma_f32_16x16x32_bf16 v[98:101], v[158:161], v[186:189], v[98:101]
	v_mfma_f32_16x16x32_bf16 v[86:89], v[150:153], v[200:203], v[86:89]
	v_mfma_f32_16x16x32_bf16 v[82:85], v[158:161], v[200:203], v[82:85]
	v_mfma_f32_16x16x32_bf16 v[70:73], v[150:153], v[208:211], v[70:73]
	v_mfma_f32_16x16x32_bf16 v[66:69], v[158:161], v[208:211], v[66:69]
	s_setprio 0
	s_barrier
	s_add_i32 s26, s41, s29
	v_lshl_add_u64 v[212:213], v[212:213], 0, s[58:59]
	s_mov_b32 m0, s26
	ds_read_b128 v[162:165], v216 offset:49152
	ds_read_b128 v[166:169], v216 offset:50176
	ds_read_b128 v[170:173], v216 offset:51200
	ds_read_b128 v[186:189], v216 offset:52224
	ds_read_b128 v[196:199], v216 offset:53248
	ds_read_b128 v[200:203], v216 offset:54272
	ds_read_b128 v[204:207], v216 offset:55296
	ds_read_b128 v[208:211], v216 offset:56320
	global_load_lds_dwordx4 v[212:213], off
	s_add_i32 m0, s26, 0x2000
	s_add_u32 s24, s24, 0x80080
	v_lshl_add_u64 v[212:213], v[218:219], 0, s[58:59]
	s_addc_u32 s25, s25, 0
	s_add_i32 s26, s42, s29
	global_load_lds_dwordx4 v[212:213], off
	s_mov_b32 m0, s26
	v_lshl_add_u64 v[212:213], s[24:25], 0, v[178:179]
	global_load_lds_dwordx4 v[212:213], off
	s_add_i32 m0, s26, 0x2000
	v_lshl_add_u64 v[212:213], s[24:25], 0, v[174:175]
	global_load_lds_dwordx4 v[212:213], off
	s_mov_b32 m0, s38
	v_lshl_add_u64 v[212:213], v[220:221], 0, s[58:59]
	global_load_lds_dwordx4 v[212:213], off
	s_mov_b32 m0, s39
	v_lshl_add_u64 v[212:213], v[222:223], 0, s[58:59]
	global_load_lds_dwordx4 v[212:213], off
	s_setprio 1
	s_waitcnt vmcnt(8) lgkmcnt(0)
	s_barrier
	v_mfma_f32_16x16x32_bf16 v[62:65], v[130:133], v[162:165], v[62:65]
	v_mfma_f32_16x16x32_bf16 v[58:61], v[138:141], v[162:165], v[58:61]
	v_mfma_f32_16x16x32_bf16 v[46:49], v[130:133], v[170:173], v[46:49]
	v_mfma_f32_16x16x32_bf16 v[42:45], v[138:141], v[170:173], v[42:45]
	v_mfma_f32_16x16x32_bf16 v[30:33], v[130:133], v[196:199], v[30:33]
	v_mfma_f32_16x16x32_bf16 v[26:29], v[138:141], v[196:199], v[26:29]
	v_mfma_f32_16x16x32_bf16 v[14:17], v[130:133], v[204:207], v[14:17]
	v_mfma_f32_16x16x32_bf16 v[10:13], v[138:141], v[204:207], v[10:13]
	v_mfma_f32_16x16x32_bf16 v[62:65], v[134:137], v[166:169], v[62:65]
	v_mfma_f32_16x16x32_bf16 v[58:61], v[142:145], v[166:169], v[58:61]
	v_mfma_f32_16x16x32_bf16 v[46:49], v[134:137], v[186:189], v[46:49]
	v_mfma_f32_16x16x32_bf16 v[42:45], v[142:145], v[186:189], v[42:45]
	v_mfma_f32_16x16x32_bf16 v[30:33], v[134:137], v[200:203], v[30:33]
	v_mfma_f32_16x16x32_bf16 v[26:29], v[142:145], v[200:203], v[26:29]
	v_mfma_f32_16x16x32_bf16 v[14:17], v[134:137], v[208:211], v[14:17]
	v_mfma_f32_16x16x32_bf16 v[10:13], v[142:145], v[208:211], v[10:13]
	s_setprio 0
	s_setprio 1
	v_mfma_f32_16x16x32_bf16 v[54:57], v[146:149], v[162:165], v[54:57]
	v_mfma_f32_16x16x32_bf16 v[50:53], v[154:157], v[162:165], v[50:53]
	v_mfma_f32_16x16x32_bf16 v[38:41], v[146:149], v[170:173], v[38:41]
	v_mfma_f32_16x16x32_bf16 v[34:37], v[154:157], v[170:173], v[34:37]
	v_mfma_f32_16x16x32_bf16 v[22:25], v[146:149], v[196:199], v[22:25]
	v_mfma_f32_16x16x32_bf16 v[18:21], v[154:157], v[196:199], v[18:21]
	v_mfma_f32_16x16x32_bf16 v[6:9], v[146:149], v[204:207], v[6:9]
	v_mfma_f32_16x16x32_bf16 v[2:5], v[154:157], v[204:207], v[2:5]
	v_mfma_f32_16x16x32_bf16 v[54:57], v[150:153], v[166:169], v[54:57]
	v_mfma_f32_16x16x32_bf16 v[50:53], v[158:161], v[166:169], v[50:53]
	v_mfma_f32_16x16x32_bf16 v[38:41], v[150:153], v[186:189], v[38:41]
	v_mfma_f32_16x16x32_bf16 v[34:37], v[158:161], v[186:189], v[34:37]
	v_mfma_f32_16x16x32_bf16 v[22:25], v[150:153], v[200:203], v[22:25]
	v_mfma_f32_16x16x32_bf16 v[18:21], v[158:161], v[200:203], v[18:21]
	v_mfma_f32_16x16x32_bf16 v[6:9], v[150:153], v[208:211], v[6:9]
	v_mfma_f32_16x16x32_bf16 v[2:5], v[158:161], v[208:211], v[2:5]
	s_setprio 0
	s_barrier
	s_add_i32 s40, s40, 2
	s_add_u32 s22, s22, 0x100
	s_addc_u32 s23, s23, 0
	s_add_u32 s21, s21, 0x100
	s_addc_u32 s33, s33, 0
	s_cmp_gt_u32 s40, 29
	s_cbranch_scc0 .LBB0_672

.LBB0_747:
	s_ashr_i32 s9, s8, 31
	s_lshl_b64 s[10:11], s[8:9], 20
	s_add_u32 s10, s69, s10
	s_addc_u32 s11, s77, s11
	s_and_b64 s[12:13], s[4:5], exec
	s_cselect_b32 s9, s11, s17
	s_cselect_b32 s31, s10, s16
	s_ashr_i32 s7, s6, 31
	s_lshl_b64 s[12:13], s[6:7], 20
	v_readlane_b32 s22, v254, 42
	v_readlane_b32 s23, v254, 43
	s_add_u32 s12, s22, s12
	s_addc_u32 s13, s23, s13
	s_and_b64 s[22:23], s[4:5], exec
	s_cselect_b32 s7, s13, s21
	s_cselect_b32 s33, s12, s20
	s_add_u32 s16, s16, 0x80080
	s_addc_u32 s17, s17, 0
	s_add_u32 s34, s20, 0x100
	s_addc_u32 s35, s21, 0
	s_mov_b32 s36, -2
	v_readlane_b32 s37, v255, 49
	s_nop 3
	s_cmp_eq_u32 s37, 3
	v_writelane_b32 v255, 3, 49
	s_cbranch_scc0 .Ltrip0_strict_2
	s_add_u32 s20, s16, 0xfff80080
	s_addc_u32 s21, s17, -1
	s_add_i32 s37, 0, 0x10000
	s_cmp_eq_u32 s36, 28
	s_cselect_b32 s23, s9, s21
	s_cselect_b32 s22, s31, s20
	s_cselect_b32 s21, s7, s35
	s_cselect_b32 s20, s33, s34
	s_add_i32 s40, 0, 0x14000
	v_add_u32_e32 v142, s37, v238
	v_add_u32_e32 v158, s40, v238
	ds_read_b128 v[130:133], v142
	ds_read_b128 v[134:137], v142 offset:1024
	ds_read_b128 v[138:141], v142 offset:2048
	ds_read_b128 v[142:145], v142 offset:3072
	ds_read_b128 v[146:149], v158
	ds_read_b128 v[150:153], v158 offset:1024
	ds_read_b128 v[154:157], v158 offset:2048
	ds_read_b128 v[158:161], v158 offset:3072
	v_lshl_add_u64 v[210:211], s[16:17], 0, v[206:207]
	s_add_i32 m0, s25, 0xc000
	ds_read_b128 v[162:165], v240
	ds_read_b128 v[166:169], v240 offset:1024
	ds_read_b128 v[170:173], v240 offset:2048
	ds_read_b128 v[174:177], v240 offset:3072
	ds_read_b128 v[178:181], v240 offset:4096
	ds_read_b128 v[182:185], v240 offset:5120
	ds_read_b128 v[186:189], v240 offset:6144
	ds_read_b128 v[196:199], v240 offset:7168
	global_load_lds_dwordx4 v[210:211], off
	s_add_i32 m0, s25, 0xe000
	v_lshl_add_u64 v[210:211], s[16:17], 0, v[208:209]
	global_load_lds_dwordx4 v[210:211], off
	s_setprio 1
	s_waitcnt vmcnt(24) lgkmcnt(0)
	s_barrier
	v_mfma_f32_16x16x32_bf16 v[126:129], v[130:133], v[162:165], 0
	v_mfma_f32_16x16x32_bf16 v[122:125], v[138:141], v[162:165], 0
	v_mfma_f32_16x16x32_bf16 v[110:113], v[130:133], v[170:173], 0
	v_mfma_f32_16x16x32_bf16 v[106:109], v[138:141], v[170:173], 0
	v_mfma_f32_16x16x32_bf16 v[98:101], v[130:133], v[178:181], 0
	v_mfma_f32_16x16x32_bf16 v[90:93], v[138:141], v[178:181], 0
	v_mfma_f32_16x16x32_bf16 v[82:85], v[130:133], v[186:189], 0
	v_mfma_f32_16x16x32_bf16 v[74:77], v[138:141], v[186:189], 0
	v_mfma_f32_16x16x32_bf16 v[126:129], v[134:137], v[166:169], v[126:129]
	v_mfma_f32_16x16x32_bf16 v[122:125], v[142:145], v[166:169], v[122:125]
	v_mfma_f32_16x16x32_bf16 v[110:113], v[134:137], v[174:177], v[110:113]
	v_mfma_f32_16x16x32_bf16 v[106:109], v[142:145], v[174:177], v[106:109]
	v_mfma_f32_16x16x32_bf16 v[98:101], v[134:137], v[182:185], v[98:101]
	v_mfma_f32_16x16x32_bf16 v[90:93], v[142:145], v[182:185], v[90:93]
	v_mfma_f32_16x16x32_bf16 v[82:85], v[134:137], v[196:199], v[82:85]
	v_mfma_f32_16x16x32_bf16 v[74:77], v[142:145], v[196:199], v[74:77]
	s_setprio 0
	s_setprio 1
	v_mfma_f32_16x16x32_bf16 v[118:121], v[146:149], v[162:165], 0
	v_mfma_f32_16x16x32_bf16 v[114:117], v[154:157], v[162:165], 0
	v_mfma_f32_16x16x32_bf16 v[102:105], v[146:149], v[170:173], 0
	v_mfma_f32_16x16x32_bf16 v[94:97], v[154:157], v[170:173], 0
	v_mfma_f32_16x16x32_bf16 v[86:89], v[146:149], v[178:181], 0
	v_mfma_f32_16x16x32_bf16 v[78:81], v[154:157], v[178:181], 0
	v_mfma_f32_16x16x32_bf16 v[70:73], v[146:149], v[186:189], 0
	v_mfma_f32_16x16x32_bf16 v[66:69], v[154:157], v[186:189], 0
	v_mfma_f32_16x16x32_bf16 v[118:121], v[150:153], v[166:169], v[118:121]
	v_mfma_f32_16x16x32_bf16 v[114:117], v[158:161], v[166:169], v[114:117]
	v_mfma_f32_16x16x32_bf16 v[102:105], v[150:153], v[174:177], v[102:105]
	v_mfma_f32_16x16x32_bf16 v[94:97], v[158:161], v[174:177], v[94:97]
	v_mfma_f32_16x16x32_bf16 v[86:89], v[150:153], v[182:185], v[86:89]
	v_mfma_f32_16x16x32_bf16 v[78:81], v[158:161], v[182:185], v[78:81]
	v_mfma_f32_16x16x32_bf16 v[70:73], v[150:153], v[196:199], v[70:73]
	v_mfma_f32_16x16x32_bf16 v[66:69], v[158:161], v[196:199], v[66:69]
	s_barrier
	s_setprio 0
	s_add_i32 s37, s37, s24
	v_lshl_add_u64 v[210:211], s[20:21], 0, v[190:191]
	s_mov_b32 m0, s37
	ds_read_b128 v[162:165], v240 offset:16384
	ds_read_b128 v[166:169], v240 offset:17408
	ds_read_b128 v[170:173], v240 offset:18432
	ds_read_b128 v[174:177], v240 offset:19456
	ds_read_b128 v[178:181], v240 offset:20480
	ds_read_b128 v[182:185], v240 offset:21504
	ds_read_b128 v[186:189], v240 offset:22528
	ds_read_b128 v[196:199], v240 offset:23552
	global_load_lds_dwordx4 v[210:211], off
	s_add_i32 m0, s37, 0x2000
	s_add_u32 s38, s20, 0x80000
	v_lshl_add_u64 v[212:213], s[20:21], 0, v[204:205]
	s_addc_u32 s39, s21, 0
	s_add_i32 s37, s40, s24
	global_load_lds_dwordx4 v[212:213], off
	v_lshl_add_u64 v[214:215], s[38:39], 0, v[190:191]
	s_mov_b32 m0, s37
	v_lshl_add_u64 v[216:217], s[22:23], 0, v[202:203]
	global_load_lds_dwordx4 v[214:215], off
	s_add_i32 m0, s37, 0x2000
	v_lshl_add_u64 v[214:215], s[38:39], 0, v[204:205]
	global_load_lds_dwordx4 v[214:215], off
	s_mov_b32 m0, s25
	v_lshl_add_u64 v[214:215], s[22:23], 0, v[200:201]
	global_load_lds_dwordx4 v[214:215], off
	s_mov_b32 m0, s26
	s_nop 0
	global_load_lds_dwordx4 v[216:217], off
	s_setprio 1
	s_waitcnt vmcnt(24) lgkmcnt(0)
	s_barrier
	v_mfma_f32_16x16x32_bf16 v[62:65], v[130:133], v[162:165], 0
	v_mfma_f32_16x16x32_bf16 v[58:61], v[138:141], v[162:165], 0
	v_mfma_f32_16x16x32_bf16 v[50:53], v[130:133], v[170:173], 0
	v_mfma_f32_16x16x32_bf16 v[42:45], v[138:141], v[170:173], 0
	v_mfma_f32_16x16x32_bf16 v[34:37], v[130:133], v[178:181], 0
	v_mfma_f32_16x16x32_bf16 v[26:29], v[138:141], v[178:181], 0
	v_mfma_f32_16x16x32_bf16 v[18:21], v[130:133], v[186:189], 0
	v_mfma_f32_16x16x32_bf16 v[10:13], v[138:141], v[186:189], 0
	v_mfma_f32_16x16x32_bf16 v[62:65], v[134:137], v[166:169], v[62:65]
	v_mfma_f32_16x16x32_bf16 v[58:61], v[142:145], v[166:169], v[58:61]
	v_mfma_f32_16x16x32_bf16 v[50:53], v[134:137], v[174:177], v[50:53]
	v_mfma_f32_16x16x32_bf16 v[42:45], v[142:145], v[174:177], v[42:45]
	v_mfma_f32_16x16x32_bf16 v[34:37], v[134:137], v[182:185], v[34:37]
	v_mfma_f32_16x16x32_bf16 v[26:29], v[142:145], v[182:185], v[26:29]
	v_mfma_f32_16x16x32_bf16 v[18:21], v[134:137], v[196:199], v[18:21]
	v_mfma_f32_16x16x32_bf16 v[10:13], v[142:145], v[196:199], v[10:13]
	s_setprio 0
	s_setprio 1
	v_mfma_f32_16x16x32_bf16 v[54:57], v[146:149], v[162:165], 0
	v_mfma_f32_16x16x32_bf16 v[46:49], v[154:157], v[162:165], 0
	v_mfma_f32_16x16x32_bf16 v[38:41], v[146:149], v[170:173], 0
	v_mfma_f32_16x16x32_bf16 v[30:33], v[154:157], v[170:173], 0
	v_mfma_f32_16x16x32_bf16 v[22:25], v[146:149], v[178:181], 0
	v_mfma_f32_16x16x32_bf16 v[14:17], v[154:157], v[178:181], 0
	v_mfma_f32_16x16x32_bf16 v[6:9], v[146:149], v[186:189], 0
	v_mfma_f32_16x16x32_bf16 v[2:5], v[154:157], v[186:189], 0
	v_mfma_f32_16x16x32_bf16 v[54:57], v[150:153], v[166:169], v[54:57]
	v_mfma_f32_16x16x32_bf16 v[46:49], v[158:161], v[166:169], v[46:49]
	v_mfma_f32_16x16x32_bf16 v[38:41], v[150:153], v[174:177], v[38:41]
	v_mfma_f32_16x16x32_bf16 v[30:33], v[158:161], v[174:177], v[30:33]
	v_mfma_f32_16x16x32_bf16 v[22:25], v[150:153], v[182:185], v[22:25]
	v_mfma_f32_16x16x32_bf16 v[14:17], v[158:161], v[182:185], v[14:17]
	v_mfma_f32_16x16x32_bf16 v[6:9], v[150:153], v[196:199], v[6:9]
	v_mfma_f32_16x16x32_bf16 v[2:5], v[158:161], v[196:199], v[2:5]
	s_barrier
	s_setprio 0
	s_add_i32 s37, 0, 0x18000
	s_add_i32 s38, 0, 0x1c000
	v_add_u32_e32 v142, s37, v238
	v_add_u32_e32 v158, s38, v238
	ds_read_b128 v[130:133], v142
	ds_read_b128 v[134:137], v142 offset:1024
	ds_read_b128 v[138:141], v142 offset:2048
	ds_read_b128 v[142:145], v142 offset:3072
	ds_read_b128 v[146:149], v158
	ds_read_b128 v[150:153], v158 offset:1024
	ds_read_b128 v[154:157], v158 offset:2048
	ds_read_b128 v[158:161], v158 offset:3072
	s_add_u32 s22, s22, 0x80000
	s_addc_u32 s23, s23, 0
	s_mov_b32 m0, s27
	v_lshl_add_u64 v[218:219], s[22:23], 0, v[200:201]
	ds_read_b128 v[162:165], v240 offset:32768
	ds_read_b128 v[166:169], v240 offset:33792
	ds_read_b128 v[170:173], v240 offset:34816
	ds_read_b128 v[174:177], v240 offset:35840
	ds_read_b128 v[178:181], v240 offset:36864
	ds_read_b128 v[182:185], v240 offset:37888
	ds_read_b128 v[186:189], v240 offset:38912
	ds_read_b128 v[196:199], v240 offset:39936
	global_load_lds_dwordx4 v[218:219], off
	s_mov_b32 m0, s28
	v_lshl_add_u64 v[218:219], s[22:23], 0, v[202:203]
	global_load_lds_dwordx4 v[218:219], off
	s_setprio 1
	s_waitcnt vmcnt(8) lgkmcnt(0)
	s_barrier
	v_mfma_f32_16x16x32_bf16 v[126:129], v[130:133], v[162:165], v[126:129]
	v_mfma_f32_16x16x32_bf16 v[122:125], v[138:141], v[162:165], v[122:125]
	v_mfma_f32_16x16x32_bf16 v[110:113], v[130:133], v[170:173], v[110:113]
	v_mfma_f32_16x16x32_bf16 v[106:109], v[138:141], v[170:173], v[106:109]
	v_mfma_f32_16x16x32_bf16 v[98:101], v[130:133], v[178:181], v[98:101]
	v_mfma_f32_16x16x32_bf16 v[90:93], v[138:141], v[178:181], v[90:93]
	v_mfma_f32_16x16x32_bf16 v[82:85], v[130:133], v[186:189], v[82:85]
	v_mfma_f32_16x16x32_bf16 v[74:77], v[138:141], v[186:189], v[74:77]
	v_mfma_f32_16x16x32_bf16 v[126:129], v[134:137], v[166:169], v[126:129]
	v_mfma_f32_16x16x32_bf16 v[122:125], v[142:145], v[166:169], v[122:125]
	v_mfma_f32_16x16x32_bf16 v[110:113], v[134:137], v[174:177], v[110:113]
	v_mfma_f32_16x16x32_bf16 v[106:109], v[142:145], v[174:177], v[106:109]
	v_mfma_f32_16x16x32_bf16 v[98:101], v[134:137], v[182:185], v[98:101]
	v_mfma_f32_16x16x32_bf16 v[90:93], v[142:145], v[182:185], v[90:93]
	v_mfma_f32_16x16x32_bf16 v[82:85], v[134:137], v[196:199], v[82:85]
	v_mfma_f32_16x16x32_bf16 v[74:77], v[142:145], v[196:199], v[74:77]
	s_setprio 0
	s_setprio 1
	v_mfma_f32_16x16x32_bf16 v[118:121], v[146:149], v[162:165], v[118:121]
	v_mfma_f32_16x16x32_bf16 v[114:117], v[154:157], v[162:165], v[114:117]
	v_mfma_f32_16x16x32_bf16 v[102:105], v[146:149], v[170:173], v[102:105]
	v_mfma_f32_16x16x32_bf16 v[94:97], v[154:157], v[170:173], v[94:97]
	v_mfma_f32_16x16x32_bf16 v[86:89], v[146:149], v[178:181], v[86:89]
	v_mfma_f32_16x16x32_bf16 v[78:81], v[154:157], v[178:181], v[78:81]
	v_mfma_f32_16x16x32_bf16 v[70:73], v[146:149], v[186:189], v[70:73]
	v_mfma_f32_16x16x32_bf16 v[66:69], v[154:157], v[186:189], v[66:69]
	v_mfma_f32_16x16x32_bf16 v[118:121], v[150:153], v[166:169], v[118:121]
	v_mfma_f32_16x16x32_bf16 v[114:117], v[158:161], v[166:169], v[114:117]
	v_mfma_f32_16x16x32_bf16 v[102:105], v[150:153], v[174:177], v[102:105]
	v_mfma_f32_16x16x32_bf16 v[94:97], v[158:161], v[174:177], v[94:97]
	v_mfma_f32_16x16x32_bf16 v[86:89], v[150:153], v[182:185], v[86:89]
	v_mfma_f32_16x16x32_bf16 v[78:81], v[158:161], v[182:185], v[78:81]
	v_mfma_f32_16x16x32_bf16 v[70:73], v[150:153], v[196:199], v[70:73]
	v_mfma_f32_16x16x32_bf16 v[66:69], v[158:161], v[196:199], v[66:69]
	s_barrier
	s_setprio 0
	s_add_i32 s22, s37, s24
	v_lshl_add_u64 v[210:211], v[210:211], 0, s[58:59]
	s_mov_b32 m0, s22
	ds_read_b128 v[162:165], v240 offset:49152
	ds_read_b128 v[166:169], v240 offset:50176
	ds_read_b128 v[170:173], v240 offset:51200
	ds_read_b128 v[174:177], v240 offset:52224
	ds_read_b128 v[178:181], v240 offset:53248
	ds_read_b128 v[182:185], v240 offset:54272
	ds_read_b128 v[186:189], v240 offset:55296
	ds_read_b128 v[196:199], v240 offset:56320
	global_load_lds_dwordx4 v[210:211], off
	s_add_i32 m0, s22, 0x2000
	s_add_u32 s20, s20, 0x80080
	v_lshl_add_u64 v[210:211], v[212:213], 0, s[58:59]
	s_addc_u32 s21, s21, 0
	s_add_i32 s22, s38, s24
	global_load_lds_dwordx4 v[210:211], off
	s_mov_b32 m0, s22
	v_lshl_add_u64 v[210:211], s[20:21], 0, v[190:191]
	global_load_lds_dwordx4 v[210:211], off
	s_add_i32 m0, s22, 0x2000
	v_lshl_add_u64 v[210:211], s[20:21], 0, v[204:205]
	global_load_lds_dwordx4 v[210:211], off
	s_mov_b32 m0, s29
	v_lshl_add_u64 v[210:211], v[214:215], 0, s[58:59]
	global_load_lds_dwordx4 v[210:211], off
	s_mov_b32 m0, s30
	v_lshl_add_u64 v[210:211], v[216:217], 0, s[58:59]
	global_load_lds_dwordx4 v[210:211], off
	s_setprio 1
	s_waitcnt vmcnt(8) lgkmcnt(0)
	s_barrier
	v_mfma_f32_16x16x32_bf16 v[62:65], v[130:133], v[162:165], v[62:65]
	v_mfma_f32_16x16x32_bf16 v[58:61], v[138:141], v[162:165], v[58:61]
	v_mfma_f32_16x16x32_bf16 v[50:53], v[130:133], v[170:173], v[50:53]
	v_mfma_f32_16x16x32_bf16 v[42:45], v[138:141], v[170:173], v[42:45]
	v_mfma_f32_16x16x32_bf16 v[34:37], v[130:133], v[178:181], v[34:37]
	v_mfma_f32_16x16x32_bf16 v[26:29], v[138:141], v[178:181], v[26:29]
	v_mfma_f32_16x16x32_bf16 v[18:21], v[130:133], v[186:189], v[18:21]
	v_mfma_f32_16x16x32_bf16 v[10:13], v[138:141], v[186:189], v[10:13]
	v_mfma_f32_16x16x32_bf16 v[62:65], v[134:137], v[166:169], v[62:65]
	v_mfma_f32_16x16x32_bf16 v[58:61], v[142:145], v[166:169], v[58:61]
	v_mfma_f32_16x16x32_bf16 v[50:53], v[134:137], v[174:177], v[50:53]
	v_mfma_f32_16x16x32_bf16 v[42:45], v[142:145], v[174:177], v[42:45]
	v_mfma_f32_16x16x32_bf16 v[34:37], v[134:137], v[182:185], v[34:37]
	v_mfma_f32_16x16x32_bf16 v[26:29], v[142:145], v[182:185], v[26:29]
	v_mfma_f32_16x16x32_bf16 v[18:21], v[134:137], v[196:199], v[18:21]
	v_mfma_f32_16x16x32_bf16 v[10:13], v[142:145], v[196:199], v[10:13]
	s_setprio 0
	s_setprio 1
	v_mfma_f32_16x16x32_bf16 v[54:57], v[146:149], v[162:165], v[54:57]
	v_mfma_f32_16x16x32_bf16 v[46:49], v[154:157], v[162:165], v[46:49]
	v_mfma_f32_16x16x32_bf16 v[38:41], v[146:149], v[170:173], v[38:41]
	v_mfma_f32_16x16x32_bf16 v[30:33], v[154:157], v[170:173], v[30:33]
	v_mfma_f32_16x16x32_bf16 v[22:25], v[146:149], v[178:181], v[22:25]
	v_mfma_f32_16x16x32_bf16 v[14:17], v[154:157], v[178:181], v[14:17]
	v_mfma_f32_16x16x32_bf16 v[6:9], v[146:149], v[186:189], v[6:9]
	v_mfma_f32_16x16x32_bf16 v[2:5], v[154:157], v[186:189], v[2:5]
	v_mfma_f32_16x16x32_bf16 v[54:57], v[150:153], v[166:169], v[54:57]
	v_mfma_f32_16x16x32_bf16 v[46:49], v[158:161], v[166:169], v[46:49]
	v_mfma_f32_16x16x32_bf16 v[38:41], v[150:153], v[174:177], v[38:41]
	v_mfma_f32_16x16x32_bf16 v[30:33], v[158:161], v[174:177], v[30:33]
	v_mfma_f32_16x16x32_bf16 v[22:25], v[150:153], v[182:185], v[22:25]
	v_mfma_f32_16x16x32_bf16 v[14:17], v[158:161], v[182:185], v[14:17]
	v_mfma_f32_16x16x32_bf16 v[6:9], v[150:153], v[196:199], v[6:9]
	v_mfma_f32_16x16x32_bf16 v[2:5], v[158:161], v[196:199], v[2:5]
	s_barrier
	s_setprio 0
	s_add_i32 s36, s36, 2
	s_add_u32 s16, s16, 0x100
	s_addc_u32 s17, s17, 0
	s_add_u32 s34, s34, 0x100
	s_addc_u32 s35, s35, 0
	s_cmp_gt_u32 s36, 29
	s_cbranch_scc1 .Lpeel_done_2
	s_branch .LBB0_748
.Ltrip0_strict_2:
	s_add_u32 s20, s16, 0xfff80080
	s_addc_u32 s21, s17, -1
	s_add_i32 s37, 0, 0x10000
	s_cmp_eq_u32 s36, 28
	s_cselect_b32 s23, s9, s21
	s_cselect_b32 s22, s31, s20
	s_cselect_b32 s21, s7, s35
	s_cselect_b32 s20, s33, s34
	s_add_i32 s40, 0, 0x14000
	v_add_u32_e32 v142, s37, v238
	v_add_u32_e32 v158, s40, v238
	ds_read_b128 v[130:133], v142
	ds_read_b128 v[134:137], v142 offset:1024
	ds_read_b128 v[138:141], v142 offset:2048
	ds_read_b128 v[142:145], v142 offset:3072
	ds_read_b128 v[146:149], v158
	ds_read_b128 v[150:153], v158 offset:1024
	ds_read_b128 v[154:157], v158 offset:2048
	ds_read_b128 v[158:161], v158 offset:3072
	v_lshl_add_u64 v[210:211], s[16:17], 0, v[206:207]
	s_add_i32 m0, s25, 0xc000
	ds_read_b128 v[162:165], v240
	ds_read_b128 v[166:169], v240 offset:1024
	ds_read_b128 v[170:173], v240 offset:2048
	ds_read_b128 v[174:177], v240 offset:3072
	ds_read_b128 v[178:181], v240 offset:4096
	ds_read_b128 v[182:185], v240 offset:5120
	ds_read_b128 v[186:189], v240 offset:6144
	ds_read_b128 v[196:199], v240 offset:7168
	global_load_lds_dwordx4 v[210:211], off
	s_add_i32 m0, s25, 0xe000
	v_lshl_add_u64 v[210:211], s[16:17], 0, v[208:209]
	global_load_lds_dwordx4 v[210:211], off
	s_setprio 1
	s_waitcnt vmcnt(8) lgkmcnt(0)
	s_barrier
	v_mfma_f32_16x16x32_bf16 v[126:129], v[130:133], v[162:165], 0
	v_mfma_f32_16x16x32_bf16 v[122:125], v[138:141], v[162:165], 0
	v_mfma_f32_16x16x32_bf16 v[110:113], v[130:133], v[170:173], 0
	v_mfma_f32_16x16x32_bf16 v[106:109], v[138:141], v[170:173], 0
	v_mfma_f32_16x16x32_bf16 v[98:101], v[130:133], v[178:181], 0
	v_mfma_f32_16x16x32_bf16 v[90:93], v[138:141], v[178:181], 0
	v_mfma_f32_16x16x32_bf16 v[82:85], v[130:133], v[186:189], 0
	v_mfma_f32_16x16x32_bf16 v[74:77], v[138:141], v[186:189], 0
	v_mfma_f32_16x16x32_bf16 v[126:129], v[134:137], v[166:169], v[126:129]
	v_mfma_f32_16x16x32_bf16 v[122:125], v[142:145], v[166:169], v[122:125]
	v_mfma_f32_16x16x32_bf16 v[110:113], v[134:137], v[174:177], v[110:113]
	v_mfma_f32_16x16x32_bf16 v[106:109], v[142:145], v[174:177], v[106:109]
	v_mfma_f32_16x16x32_bf16 v[98:101], v[134:137], v[182:185], v[98:101]
	v_mfma_f32_16x16x32_bf16 v[90:93], v[142:145], v[182:185], v[90:93]
	v_mfma_f32_16x16x32_bf16 v[82:85], v[134:137], v[196:199], v[82:85]
	v_mfma_f32_16x16x32_bf16 v[74:77], v[142:145], v[196:199], v[74:77]
	s_setprio 0
	s_setprio 1
	v_mfma_f32_16x16x32_bf16 v[118:121], v[146:149], v[162:165], 0
	v_mfma_f32_16x16x32_bf16 v[114:117], v[154:157], v[162:165], 0
	v_mfma_f32_16x16x32_bf16 v[102:105], v[146:149], v[170:173], 0
	v_mfma_f32_16x16x32_bf16 v[94:97], v[154:157], v[170:173], 0
	v_mfma_f32_16x16x32_bf16 v[86:89], v[146:149], v[178:181], 0
	v_mfma_f32_16x16x32_bf16 v[78:81], v[154:157], v[178:181], 0
	v_mfma_f32_16x16x32_bf16 v[70:73], v[146:149], v[186:189], 0
	v_mfma_f32_16x16x32_bf16 v[66:69], v[154:157], v[186:189], 0
	v_mfma_f32_16x16x32_bf16 v[118:121], v[150:153], v[166:169], v[118:121]
	v_mfma_f32_16x16x32_bf16 v[114:117], v[158:161], v[166:169], v[114:117]
	v_mfma_f32_16x16x32_bf16 v[102:105], v[150:153], v[174:177], v[102:105]
	v_mfma_f32_16x16x32_bf16 v[94:97], v[158:161], v[174:177], v[94:97]
	v_mfma_f32_16x16x32_bf16 v[86:89], v[150:153], v[182:185], v[86:89]
	v_mfma_f32_16x16x32_bf16 v[78:81], v[158:161], v[182:185], v[78:81]
	v_mfma_f32_16x16x32_bf16 v[70:73], v[150:153], v[196:199], v[70:73]
	v_mfma_f32_16x16x32_bf16 v[66:69], v[158:161], v[196:199], v[66:69]
	s_barrier
	s_setprio 0
	s_add_i32 s37, s37, s24
	v_lshl_add_u64 v[210:211], s[20:21], 0, v[190:191]
	s_mov_b32 m0, s37
	ds_read_b128 v[162:165], v240 offset:16384
	ds_read_b128 v[166:169], v240 offset:17408
	ds_read_b128 v[170:173], v240 offset:18432
	ds_read_b128 v[174:177], v240 offset:19456
	ds_read_b128 v[178:181], v240 offset:20480
	ds_read_b128 v[182:185], v240 offset:21504
	ds_read_b128 v[186:189], v240 offset:22528
	ds_read_b128 v[196:199], v240 offset:23552
	global_load_lds_dwordx4 v[210:211], off
	s_add_i32 m0, s37, 0x2000
	s_add_u32 s38, s20, 0x80000
	v_lshl_add_u64 v[212:213], s[20:21], 0, v[204:205]
	s_addc_u32 s39, s21, 0
	s_add_i32 s37, s40, s24
	global_load_lds_dwordx4 v[212:213], off
	v_lshl_add_u64 v[214:215], s[38:39], 0, v[190:191]
	s_mov_b32 m0, s37
	v_lshl_add_u64 v[216:217], s[22:23], 0, v[202:203]
	global_load_lds_dwordx4 v[214:215], off
	s_add_i32 m0, s37, 0x2000
	v_lshl_add_u64 v[214:215], s[38:39], 0, v[204:205]
	global_load_lds_dwordx4 v[214:215], off
	s_mov_b32 m0, s25
	v_lshl_add_u64 v[214:215], s[22:23], 0, v[200:201]
	global_load_lds_dwordx4 v[214:215], off
	s_mov_b32 m0, s26
	s_nop 0
	global_load_lds_dwordx4 v[216:217], off
	s_setprio 1
	s_waitcnt vmcnt(8) lgkmcnt(0)
	s_barrier
	v_mfma_f32_16x16x32_bf16 v[62:65], v[130:133], v[162:165], 0
	v_mfma_f32_16x16x32_bf16 v[58:61], v[138:141], v[162:165], 0
	v_mfma_f32_16x16x32_bf16 v[50:53], v[130:133], v[170:173], 0
	v_mfma_f32_16x16x32_bf16 v[42:45], v[138:141], v[170:173], 0
	v_mfma_f32_16x16x32_bf16 v[34:37], v[130:133], v[178:181], 0
	v_mfma_f32_16x16x32_bf16 v[26:29], v[138:141], v[178:181], 0
	v_mfma_f32_16x16x32_bf16 v[18:21], v[130:133], v[186:189], 0
	v_mfma_f32_16x16x32_bf16 v[10:13], v[138:141], v[186:189], 0
	v_mfma_f32_16x16x32_bf16 v[62:65], v[134:137], v[166:169], v[62:65]
	v_mfma_f32_16x16x32_bf16 v[58:61], v[142:145], v[166:169], v[58:61]
	v_mfma_f32_16x16x32_bf16 v[50:53], v[134:137], v[174:177], v[50:53]
	v_mfma_f32_16x16x32_bf16 v[42:45], v[142:145], v[174:177], v[42:45]
	v_mfma_f32_16x16x32_bf16 v[34:37], v[134:137], v[182:185], v[34:37]
	v_mfma_f32_16x16x32_bf16 v[26:29], v[142:145], v[182:185], v[26:29]
	v_mfma_f32_16x16x32_bf16 v[18:21], v[134:137], v[196:199], v[18:21]
	v_mfma_f32_16x16x32_bf16 v[10:13], v[142:145], v[196:199], v[10:13]
	s_setprio 0
	s_setprio 1
	v_mfma_f32_16x16x32_bf16 v[54:57], v[146:149], v[162:165], 0
	v_mfma_f32_16x16x32_bf16 v[46:49], v[154:157], v[162:165], 0
	v_mfma_f32_16x16x32_bf16 v[38:41], v[146:149], v[170:173], 0
	v_mfma_f32_16x16x32_bf16 v[30:33], v[154:157], v[170:173], 0
	v_mfma_f32_16x16x32_bf16 v[22:25], v[146:149], v[178:181], 0
	v_mfma_f32_16x16x32_bf16 v[14:17], v[154:157], v[178:181], 0
	v_mfma_f32_16x16x32_bf16 v[6:9], v[146:149], v[186:189], 0
	v_mfma_f32_16x16x32_bf16 v[2:5], v[154:157], v[186:189], 0
	v_mfma_f32_16x16x32_bf16 v[54:57], v[150:153], v[166:169], v[54:57]
	v_mfma_f32_16x16x32_bf16 v[46:49], v[158:161], v[166:169], v[46:49]
	v_mfma_f32_16x16x32_bf16 v[38:41], v[150:153], v[174:177], v[38:41]
	v_mfma_f32_16x16x32_bf16 v[30:33], v[158:161], v[174:177], v[30:33]
	v_mfma_f32_16x16x32_bf16 v[22:25], v[150:153], v[182:185], v[22:25]
	v_mfma_f32_16x16x32_bf16 v[14:17], v[158:161], v[182:185], v[14:17]
	v_mfma_f32_16x16x32_bf16 v[6:9], v[150:153], v[196:199], v[6:9]
	v_mfma_f32_16x16x32_bf16 v[2:5], v[158:161], v[196:199], v[2:5]
	s_barrier
	s_setprio 0
	s_add_i32 s37, 0, 0x18000
	s_add_i32 s38, 0, 0x1c000
	v_add_u32_e32 v142, s37, v238
	v_add_u32_e32 v158, s38, v238
	ds_read_b128 v[130:133], v142
	ds_read_b128 v[134:137], v142 offset:1024
	ds_read_b128 v[138:141], v142 offset:2048
	ds_read_b128 v[142:145], v142 offset:3072
	ds_read_b128 v[146:149], v158
	ds_read_b128 v[150:153], v158 offset:1024
	ds_read_b128 v[154:157], v158 offset:2048
	ds_read_b128 v[158:161], v158 offset:3072
	s_add_u32 s22, s22, 0x80000
	s_addc_u32 s23, s23, 0
	s_mov_b32 m0, s27
	v_lshl_add_u64 v[218:219], s[22:23], 0, v[200:201]
	ds_read_b128 v[162:165], v240 offset:32768
	ds_read_b128 v[166:169], v240 offset:33792
	ds_read_b128 v[170:173], v240 offset:34816
	ds_read_b128 v[174:177], v240 offset:35840
	ds_read_b128 v[178:181], v240 offset:36864
	ds_read_b128 v[182:185], v240 offset:37888
	ds_read_b128 v[186:189], v240 offset:38912
	ds_read_b128 v[196:199], v240 offset:39936
	global_load_lds_dwordx4 v[218:219], off
	s_mov_b32 m0, s28
	v_lshl_add_u64 v[218:219], s[22:23], 0, v[202:203]
	global_load_lds_dwordx4 v[218:219], off
	s_setprio 1
	s_waitcnt vmcnt(8) lgkmcnt(0)
	s_barrier
	v_mfma_f32_16x16x32_bf16 v[126:129], v[130:133], v[162:165], v[126:129]
	v_mfma_f32_16x16x32_bf16 v[122:125], v[138:141], v[162:165], v[122:125]
	v_mfma_f32_16x16x32_bf16 v[110:113], v[130:133], v[170:173], v[110:113]
	v_mfma_f32_16x16x32_bf16 v[106:109], v[138:141], v[170:173], v[106:109]
	v_mfma_f32_16x16x32_bf16 v[98:101], v[130:133], v[178:181], v[98:101]
	v_mfma_f32_16x16x32_bf16 v[90:93], v[138:141], v[178:181], v[90:93]
	v_mfma_f32_16x16x32_bf16 v[82:85], v[130:133], v[186:189], v[82:85]
	v_mfma_f32_16x16x32_bf16 v[74:77], v[138:141], v[186:189], v[74:77]
	v_mfma_f32_16x16x32_bf16 v[126:129], v[134:137], v[166:169], v[126:129]
	v_mfma_f32_16x16x32_bf16 v[122:125], v[142:145], v[166:169], v[122:125]
	v_mfma_f32_16x16x32_bf16 v[110:113], v[134:137], v[174:177], v[110:113]
	v_mfma_f32_16x16x32_bf16 v[106:109], v[142:145], v[174:177], v[106:109]
	v_mfma_f32_16x16x32_bf16 v[98:101], v[134:137], v[182:185], v[98:101]
	v_mfma_f32_16x16x32_bf16 v[90:93], v[142:145], v[182:185], v[90:93]
	v_mfma_f32_16x16x32_bf16 v[82:85], v[134:137], v[196:199], v[82:85]
	v_mfma_f32_16x16x32_bf16 v[74:77], v[142:145], v[196:199], v[74:77]
	s_setprio 0
	s_setprio 1
	v_mfma_f32_16x16x32_bf16 v[118:121], v[146:149], v[162:165], v[118:121]
	v_mfma_f32_16x16x32_bf16 v[114:117], v[154:157], v[162:165], v[114:117]
	v_mfma_f32_16x16x32_bf16 v[102:105], v[146:149], v[170:173], v[102:105]
	v_mfma_f32_16x16x32_bf16 v[94:97], v[154:157], v[170:173], v[94:97]
	v_mfma_f32_16x16x32_bf16 v[86:89], v[146:149], v[178:181], v[86:89]
	v_mfma_f32_16x16x32_bf16 v[78:81], v[154:157], v[178:181], v[78:81]
	v_mfma_f32_16x16x32_bf16 v[70:73], v[146:149], v[186:189], v[70:73]
	v_mfma_f32_16x16x32_bf16 v[66:69], v[154:157], v[186:189], v[66:69]
	v_mfma_f32_16x16x32_bf16 v[118:121], v[150:153], v[166:169], v[118:121]
	v_mfma_f32_16x16x32_bf16 v[114:117], v[158:161], v[166:169], v[114:117]
	v_mfma_f32_16x16x32_bf16 v[102:105], v[150:153], v[174:177], v[102:105]
	v_mfma_f32_16x16x32_bf16 v[94:97], v[158:161], v[174:177], v[94:97]
	v_mfma_f32_16x16x32_bf16 v[86:89], v[150:153], v[182:185], v[86:89]
	v_mfma_f32_16x16x32_bf16 v[78:81], v[158:161], v[182:185], v[78:81]
	v_mfma_f32_16x16x32_bf16 v[70:73], v[150:153], v[196:199], v[70:73]
	v_mfma_f32_16x16x32_bf16 v[66:69], v[158:161], v[196:199], v[66:69]
	s_barrier
	s_setprio 0
	s_add_i32 s22, s37, s24
	v_lshl_add_u64 v[210:211], v[210:211], 0, s[58:59]
	s_mov_b32 m0, s22
	ds_read_b128 v[162:165], v240 offset:49152
	ds_read_b128 v[166:169], v240 offset:50176
	ds_read_b128 v[170:173], v240 offset:51200
	ds_read_b128 v[174:177], v240 offset:52224
	ds_read_b128 v[178:181], v240 offset:53248
	ds_read_b128 v[182:185], v240 offset:54272
	ds_read_b128 v[186:189], v240 offset:55296
	ds_read_b128 v[196:199], v240 offset:56320
	global_load_lds_dwordx4 v[210:211], off
	s_add_i32 m0, s22, 0x2000
	s_add_u32 s20, s20, 0x80080
	v_lshl_add_u64 v[210:211], v[212:213], 0, s[58:59]
	s_addc_u32 s21, s21, 0
	s_add_i32 s22, s38, s24
	global_load_lds_dwordx4 v[210:211], off
	s_mov_b32 m0, s22
	v_lshl_add_u64 v[210:211], s[20:21], 0, v[190:191]
	global_load_lds_dwordx4 v[210:211], off
	s_add_i32 m0, s22, 0x2000
	v_lshl_add_u64 v[210:211], s[20:21], 0, v[204:205]
	global_load_lds_dwordx4 v[210:211], off
	s_mov_b32 m0, s29
	v_lshl_add_u64 v[210:211], v[214:215], 0, s[58:59]
	global_load_lds_dwordx4 v[210:211], off
	s_mov_b32 m0, s30
	v_lshl_add_u64 v[210:211], v[216:217], 0, s[58:59]
	global_load_lds_dwordx4 v[210:211], off
	s_setprio 1
	s_waitcnt vmcnt(8) lgkmcnt(0)
	s_barrier
	v_mfma_f32_16x16x32_bf16 v[62:65], v[130:133], v[162:165], v[62:65]
	v_mfma_f32_16x16x32_bf16 v[58:61], v[138:141], v[162:165], v[58:61]
	v_mfma_f32_16x16x32_bf16 v[50:53], v[130:133], v[170:173], v[50:53]
	v_mfma_f32_16x16x32_bf16 v[42:45], v[138:141], v[170:173], v[42:45]
	v_mfma_f32_16x16x32_bf16 v[34:37], v[130:133], v[178:181], v[34:37]
	v_mfma_f32_16x16x32_bf16 v[26:29], v[138:141], v[178:181], v[26:29]
	v_mfma_f32_16x16x32_bf16 v[18:21], v[130:133], v[186:189], v[18:21]
	v_mfma_f32_16x16x32_bf16 v[10:13], v[138:141], v[186:189], v[10:13]
	v_mfma_f32_16x16x32_bf16 v[62:65], v[134:137], v[166:169], v[62:65]
	v_mfma_f32_16x16x32_bf16 v[58:61], v[142:145], v[166:169], v[58:61]
	v_mfma_f32_16x16x32_bf16 v[50:53], v[134:137], v[174:177], v[50:53]
	v_mfma_f32_16x16x32_bf16 v[42:45], v[142:145], v[174:177], v[42:45]
	v_mfma_f32_16x16x32_bf16 v[34:37], v[134:137], v[182:185], v[34:37]
	v_mfma_f32_16x16x32_bf16 v[26:29], v[142:145], v[182:185], v[26:29]
	v_mfma_f32_16x16x32_bf16 v[18:21], v[134:137], v[196:199], v[18:21]
	v_mfma_f32_16x16x32_bf16 v[10:13], v[142:145], v[196:199], v[10:13]
	s_setprio 0
	s_setprio 1
	v_mfma_f32_16x16x32_bf16 v[54:57], v[146:149], v[162:165], v[54:57]
	v_mfma_f32_16x16x32_bf16 v[46:49], v[154:157], v[162:165], v[46:49]
	v_mfma_f32_16x16x32_bf16 v[38:41], v[146:149], v[170:173], v[38:41]
	v_mfma_f32_16x16x32_bf16 v[30:33], v[154:157], v[170:173], v[30:33]
	v_mfma_f32_16x16x32_bf16 v[22:25], v[146:149], v[178:181], v[22:25]
	v_mfma_f32_16x16x32_bf16 v[14:17], v[154:157], v[178:181], v[14:17]
	v_mfma_f32_16x16x32_bf16 v[6:9], v[146:149], v[186:189], v[6:9]
	v_mfma_f32_16x16x32_bf16 v[2:5], v[154:157], v[186:189], v[2:5]
	v_mfma_f32_16x16x32_bf16 v[54:57], v[150:153], v[166:169], v[54:57]
	v_mfma_f32_16x16x32_bf16 v[46:49], v[158:161], v[166:169], v[46:49]
	v_mfma_f32_16x16x32_bf16 v[38:41], v[150:153], v[174:177], v[38:41]
	v_mfma_f32_16x16x32_bf16 v[30:33], v[158:161], v[174:177], v[30:33]
	v_mfma_f32_16x16x32_bf16 v[22:25], v[150:153], v[182:185], v[22:25]
	v_mfma_f32_16x16x32_bf16 v[14:17], v[158:161], v[182:185], v[14:17]
	v_mfma_f32_16x16x32_bf16 v[6:9], v[150:153], v[196:199], v[6:9]
	v_mfma_f32_16x16x32_bf16 v[2:5], v[158:161], v[196:199], v[2:5]
	s_barrier
	s_setprio 0
	s_add_i32 s36, s36, 2
	s_add_u32 s16, s16, 0x100
	s_addc_u32 s17, s17, 0
	s_add_u32 s34, s34, 0x100
	s_addc_u32 s35, s35, 0
	s_cmp_gt_u32 s36, 29
	s_cbranch_scc1 .Lpeel_done_2
.LBB0_748:
	s_add_u32 s20, s16, 0xfff80080
	s_addc_u32 s21, s17, -1
	s_add_i32 s37, 0, 0x10000
	s_cmp_eq_u32 s36, 28
	s_cselect_b32 s23, s9, s21
	s_cselect_b32 s22, s31, s20
	s_cselect_b32 s21, s7, s35
	s_cselect_b32 s20, s33, s34
	s_add_i32 s40, 0, 0x14000
	v_add_u32_e32 v142, s37, v238
	v_add_u32_e32 v158, s40, v238
	ds_read_b128 v[130:133], v142
	ds_read_b128 v[134:137], v142 offset:1024
	ds_read_b128 v[138:141], v142 offset:2048
	ds_read_b128 v[142:145], v142 offset:3072
	ds_read_b128 v[146:149], v158
	ds_read_b128 v[150:153], v158 offset:1024
	ds_read_b128 v[154:157], v158 offset:2048
	ds_read_b128 v[158:161], v158 offset:3072
	v_lshl_add_u64 v[210:211], s[16:17], 0, v[206:207]
	s_add_i32 m0, s25, 0xc000
	ds_read_b128 v[162:165], v240
	ds_read_b128 v[166:169], v240 offset:1024
	ds_read_b128 v[170:173], v240 offset:2048
	ds_read_b128 v[174:177], v240 offset:3072
	ds_read_b128 v[178:181], v240 offset:4096
	ds_read_b128 v[182:185], v240 offset:5120
	ds_read_b128 v[186:189], v240 offset:6144
	ds_read_b128 v[196:199], v240 offset:7168
	global_load_lds_dwordx4 v[210:211], off
	s_add_i32 m0, s25, 0xe000
	v_lshl_add_u64 v[210:211], s[16:17], 0, v[208:209]
	global_load_lds_dwordx4 v[210:211], off
	s_setprio 1
	s_waitcnt vmcnt(8) lgkmcnt(0)
	s_barrier
	v_mfma_f32_16x16x32_bf16 v[126:129], v[130:133], v[162:165], v[126:129]
	v_mfma_f32_16x16x32_bf16 v[122:125], v[138:141], v[162:165], v[122:125]
	v_mfma_f32_16x16x32_bf16 v[110:113], v[130:133], v[170:173], v[110:113]
	v_mfma_f32_16x16x32_bf16 v[106:109], v[138:141], v[170:173], v[106:109]
	v_mfma_f32_16x16x32_bf16 v[98:101], v[130:133], v[178:181], v[98:101]
	v_mfma_f32_16x16x32_bf16 v[90:93], v[138:141], v[178:181], v[90:93]
	v_mfma_f32_16x16x32_bf16 v[82:85], v[130:133], v[186:189], v[82:85]
	v_mfma_f32_16x16x32_bf16 v[74:77], v[138:141], v[186:189], v[74:77]
	v_mfma_f32_16x16x32_bf16 v[126:129], v[134:137], v[166:169], v[126:129]
	v_mfma_f32_16x16x32_bf16 v[122:125], v[142:145], v[166:169], v[122:125]
	v_mfma_f32_16x16x32_bf16 v[110:113], v[134:137], v[174:177], v[110:113]
	v_mfma_f32_16x16x32_bf16 v[106:109], v[142:145], v[174:177], v[106:109]
	v_mfma_f32_16x16x32_bf16 v[98:101], v[134:137], v[182:185], v[98:101]
	v_mfma_f32_16x16x32_bf16 v[90:93], v[142:145], v[182:185], v[90:93]
	v_mfma_f32_16x16x32_bf16 v[82:85], v[134:137], v[196:199], v[82:85]
	v_mfma_f32_16x16x32_bf16 v[74:77], v[142:145], v[196:199], v[74:77]
	s_setprio 0
	s_setprio 1
	v_mfma_f32_16x16x32_bf16 v[118:121], v[146:149], v[162:165], v[118:121]
	v_mfma_f32_16x16x32_bf16 v[114:117], v[154:157], v[162:165], v[114:117]
	v_mfma_f32_16x16x32_bf16 v[102:105], v[146:149], v[170:173], v[102:105]
	v_mfma_f32_16x16x32_bf16 v[94:97], v[154:157], v[170:173], v[94:97]
	v_mfma_f32_16x16x32_bf16 v[86:89], v[146:149], v[178:181], v[86:89]
	v_mfma_f32_16x16x32_bf16 v[78:81], v[154:157], v[178:181], v[78:81]
	v_mfma_f32_16x16x32_bf16 v[70:73], v[146:149], v[186:189], v[70:73]
	v_mfma_f32_16x16x32_bf16 v[66:69], v[154:157], v[186:189], v[66:69]
	v_mfma_f32_16x16x32_bf16 v[118:121], v[150:153], v[166:169], v[118:121]
	v_mfma_f32_16x16x32_bf16 v[114:117], v[158:161], v[166:169], v[114:117]
	v_mfma_f32_16x16x32_bf16 v[102:105], v[150:153], v[174:177], v[102:105]
	v_mfma_f32_16x16x32_bf16 v[94:97], v[158:161], v[174:177], v[94:97]
	v_mfma_f32_16x16x32_bf16 v[86:89], v[150:153], v[182:185], v[86:89]
	v_mfma_f32_16x16x32_bf16 v[78:81], v[158:161], v[182:185], v[78:81]
	v_mfma_f32_16x16x32_bf16 v[70:73], v[150:153], v[196:199], v[70:73]
	v_mfma_f32_16x16x32_bf16 v[66:69], v[158:161], v[196:199], v[66:69]
	s_setprio 0
	s_barrier
	s_add_i32 s37, s37, s24
	v_lshl_add_u64 v[210:211], s[20:21], 0, v[190:191]
	s_mov_b32 m0, s37
	ds_read_b128 v[162:165], v240 offset:16384
	ds_read_b128 v[166:169], v240 offset:17408
	ds_read_b128 v[170:173], v240 offset:18432
	ds_read_b128 v[174:177], v240 offset:19456
	ds_read_b128 v[178:181], v240 offset:20480
	ds_read_b128 v[182:185], v240 offset:21504
	ds_read_b128 v[186:189], v240 offset:22528
	ds_read_b128 v[196:199], v240 offset:23552
	global_load_lds_dwordx4 v[210:211], off
	s_add_i32 m0, s37, 0x2000
	s_add_u32 s38, s20, 0x80000
	v_lshl_add_u64 v[212:213], s[20:21], 0, v[204:205]
	s_addc_u32 s39, s21, 0
	s_add_i32 s37, s40, s24
	global_load_lds_dwordx4 v[212:213], off
	v_lshl_add_u64 v[214:215], s[38:39], 0, v[190:191]
	s_mov_b32 m0, s37
	v_lshl_add_u64 v[216:217], s[22:23], 0, v[202:203]
	global_load_lds_dwordx4 v[214:215], off
	s_add_i32 m0, s37, 0x2000
	v_lshl_add_u64 v[214:215], s[38:39], 0, v[204:205]
	global_load_lds_dwordx4 v[214:215], off
	s_mov_b32 m0, s25
	v_lshl_add_u64 v[214:215], s[22:23], 0, v[200:201]
	global_load_lds_dwordx4 v[214:215], off
	s_mov_b32 m0, s26
	s_nop 0
	global_load_lds_dwordx4 v[216:217], off
	s_setprio 1
	s_waitcnt vmcnt(8) lgkmcnt(0)
	s_barrier
	v_mfma_f32_16x16x32_bf16 v[62:65], v[130:133], v[162:165], v[62:65]
	v_mfma_f32_16x16x32_bf16 v[58:61], v[138:141], v[162:165], v[58:61]
	v_mfma_f32_16x16x32_bf16 v[50:53], v[130:133], v[170:173], v[50:53]
	v_mfma_f32_16x16x32_bf16 v[42:45], v[138:141], v[170:173], v[42:45]
	v_mfma_f32_16x16x32_bf16 v[34:37], v[130:133], v[178:181], v[34:37]
	v_mfma_f32_16x16x32_bf16 v[26:29], v[138:141], v[178:181], v[26:29]
	v_mfma_f32_16x16x32_bf16 v[18:21], v[130:133], v[186:189], v[18:21]
	v_mfma_f32_16x16x32_bf16 v[10:13], v[138:141], v[186:189], v[10:13]
	v_mfma_f32_16x16x32_bf16 v[62:65], v[134:137], v[166:169], v[62:65]
	v_mfma_f32_16x16x32_bf16 v[58:61], v[142:145], v[166:169], v[58:61]
	v_mfma_f32_16x16x32_bf16 v[50:53], v[134:137], v[174:177], v[50:53]
	v_mfma_f32_16x16x32_bf16 v[42:45], v[142:145], v[174:177], v[42:45]
	v_mfma_f32_16x16x32_bf16 v[34:37], v[134:137], v[182:185], v[34:37]
	v_mfma_f32_16x16x32_bf16 v[26:29], v[142:145], v[182:185], v[26:29]
	v_mfma_f32_16x16x32_bf16 v[18:21], v[134:137], v[196:199], v[18:21]
	v_mfma_f32_16x16x32_bf16 v[10:13], v[142:145], v[196:199], v[10:13]
	s_setprio 0
	s_setprio 1
	v_mfma_f32_16x16x32_bf16 v[54:57], v[146:149], v[162:165], v[54:57]
	v_mfma_f32_16x16x32_bf16 v[46:49], v[154:157], v[162:165], v[46:49]
	v_mfma_f32_16x16x32_bf16 v[38:41], v[146:149], v[170:173], v[38:41]
	v_mfma_f32_16x16x32_bf16 v[30:33], v[154:157], v[170:173], v[30:33]
	v_mfma_f32_16x16x32_bf16 v[22:25], v[146:149], v[178:181], v[22:25]
	v_mfma_f32_16x16x32_bf16 v[14:17], v[154:157], v[178:181], v[14:17]
	v_mfma_f32_16x16x32_bf16 v[6:9], v[146:149], v[186:189], v[6:9]
	v_mfma_f32_16x16x32_bf16 v[2:5], v[154:157], v[186:189], v[2:5]
	v_mfma_f32_16x16x32_bf16 v[54:57], v[150:153], v[166:169], v[54:57]
	v_mfma_f32_16x16x32_bf16 v[46:49], v[158:161], v[166:169], v[46:49]
	v_mfma_f32_16x16x32_bf16 v[38:41], v[150:153], v[174:177], v[38:41]
	v_mfma_f32_16x16x32_bf16 v[30:33], v[158:161], v[174:177], v[30:33]
	v_mfma_f32_16x16x32_bf16 v[22:25], v[150:153], v[182:185], v[22:25]
	v_mfma_f32_16x16x32_bf16 v[14:17], v[158:161], v[182:185], v[14:17]
	v_mfma_f32_16x16x32_bf16 v[6:9], v[150:153], v[196:199], v[6:9]
	v_mfma_f32_16x16x32_bf16 v[2:5], v[158:161], v[196:199], v[2:5]
	s_setprio 0
	s_barrier
	s_add_i32 s37, 0, 0x18000
	s_add_i32 s38, 0, 0x1c000
	v_add_u32_e32 v142, s37, v238
	v_add_u32_e32 v158, s38, v238
	ds_read_b128 v[130:133], v142
	ds_read_b128 v[134:137], v142 offset:1024
	ds_read_b128 v[138:141], v142 offset:2048
	ds_read_b128 v[142:145], v142 offset:3072
	ds_read_b128 v[146:149], v158
	ds_read_b128 v[150:153], v158 offset:1024
	ds_read_b128 v[154:157], v158 offset:2048
	ds_read_b128 v[158:161], v158 offset:3072
	s_add_u32 s22, s22, 0x80000
	s_addc_u32 s23, s23, 0
	s_mov_b32 m0, s27
	v_lshl_add_u64 v[218:219], s[22:23], 0, v[200:201]
	ds_read_b128 v[162:165], v240 offset:32768
	ds_read_b128 v[166:169], v240 offset:33792
	ds_read_b128 v[170:173], v240 offset:34816
	ds_read_b128 v[174:177], v240 offset:35840
	ds_read_b128 v[178:181], v240 offset:36864
	ds_read_b128 v[182:185], v240 offset:37888
	ds_read_b128 v[186:189], v240 offset:38912
	ds_read_b128 v[196:199], v240 offset:39936
	global_load_lds_dwordx4 v[218:219], off
	s_mov_b32 m0, s28
	v_lshl_add_u64 v[218:219], s[22:23], 0, v[202:203]
	global_load_lds_dwordx4 v[218:219], off
	s_setprio 1
	s_waitcnt vmcnt(8) lgkmcnt(0)
	s_barrier
	v_mfma_f32_16x16x32_bf16 v[126:129], v[130:133], v[162:165], v[126:129]
	v_mfma_f32_16x16x32_bf16 v[122:125], v[138:141], v[162:165], v[122:125]
	v_mfma_f32_16x16x32_bf16 v[110:113], v[130:133], v[170:173], v[110:113]
	v_mfma_f32_16x16x32_bf16 v[106:109], v[138:141], v[170:173], v[106:109]
	v_mfma_f32_16x16x32_bf16 v[98:101], v[130:133], v[178:181], v[98:101]
	v_mfma_f32_16x16x32_bf16 v[90:93], v[138:141], v[178:181], v[90:93]
	v_mfma_f32_16x16x32_bf16 v[82:85], v[130:133], v[186:189], v[82:85]
	v_mfma_f32_16x16x32_bf16 v[74:77], v[138:141], v[186:189], v[74:77]
	v_mfma_f32_16x16x32_bf16 v[126:129], v[134:137], v[166:169], v[126:129]
	v_mfma_f32_16x16x32_bf16 v[122:125], v[142:145], v[166:169], v[122:125]
	v_mfma_f32_16x16x32_bf16 v[110:113], v[134:137], v[174:177], v[110:113]
	v_mfma_f32_16x16x32_bf16 v[106:109], v[142:145], v[174:177], v[106:109]
	v_mfma_f32_16x16x32_bf16 v[98:101], v[134:137], v[182:185], v[98:101]
	v_mfma_f32_16x16x32_bf16 v[90:93], v[142:145], v[182:185], v[90:93]
	v_mfma_f32_16x16x32_bf16 v[82:85], v[134:137], v[196:199], v[82:85]
	v_mfma_f32_16x16x32_bf16 v[74:77], v[142:145], v[196:199], v[74:77]
	s_setprio 0
	s_setprio 1
	v_mfma_f32_16x16x32_bf16 v[118:121], v[146:149], v[162:165], v[118:121]
	v_mfma_f32_16x16x32_bf16 v[114:117], v[154:157], v[162:165], v[114:117]
	v_mfma_f32_16x16x32_bf16 v[102:105], v[146:149], v[170:173], v[102:105]
	v_mfma_f32_16x16x32_bf16 v[94:97], v[154:157], v[170:173], v[94:97]
	v_mfma_f32_16x16x32_bf16 v[86:89], v[146:149], v[178:181], v[86:89]
	v_mfma_f32_16x16x32_bf16 v[78:81], v[154:157], v[178:181], v[78:81]
	v_mfma_f32_16x16x32_bf16 v[70:73], v[146:149], v[186:189], v[70:73]
	v_mfma_f32_16x16x32_bf16 v[66:69], v[154:157], v[186:189], v[66:69]
	v_mfma_f32_16x16x32_bf16 v[118:121], v[150:153], v[166:169], v[118:121]
	v_mfma_f32_16x16x32_bf16 v[114:117], v[158:161], v[166:169], v[114:117]
	v_mfma_f32_16x16x32_bf16 v[102:105], v[150:153], v[174:177], v[102:105]
	v_mfma_f32_16x16x32_bf16 v[94:97], v[158:161], v[174:177], v[94:97]
	v_mfma_f32_16x16x32_bf16 v[86:89], v[150:153], v[182:185], v[86:89]
	v_mfma_f32_16x16x32_bf16 v[78:81], v[158:161], v[182:185], v[78:81]
	v_mfma_f32_16x16x32_bf16 v[70:73], v[150:153], v[196:199], v[70:73]
	v_mfma_f32_16x16x32_bf16 v[66:69], v[158:161], v[196:199], v[66:69]
	s_setprio 0
	s_barrier
	s_add_i32 s22, s37, s24
	v_lshl_add_u64 v[210:211], v[210:211], 0, s[58:59]
	s_mov_b32 m0, s22
	ds_read_b128 v[162:165], v240 offset:49152
	ds_read_b128 v[166:169], v240 offset:50176
	ds_read_b128 v[170:173], v240 offset:51200
	ds_read_b128 v[174:177], v240 offset:52224
	ds_read_b128 v[178:181], v240 offset:53248
	ds_read_b128 v[182:185], v240 offset:54272
	ds_read_b128 v[186:189], v240 offset:55296
	ds_read_b128 v[196:199], v240 offset:56320
	global_load_lds_dwordx4 v[210:211], off
	s_add_i32 m0, s22, 0x2000
	s_add_u32 s20, s20, 0x80080
	v_lshl_add_u64 v[210:211], v[212:213], 0, s[58:59]
	s_addc_u32 s21, s21, 0
	s_add_i32 s22, s38, s24
	global_load_lds_dwordx4 v[210:211], off
	s_mov_b32 m0, s22
	v_lshl_add_u64 v[210:211], s[20:21], 0, v[190:191]
	global_load_lds_dwordx4 v[210:211], off
	s_add_i32 m0, s22, 0x2000
	v_lshl_add_u64 v[210:211], s[20:21], 0, v[204:205]
	global_load_lds_dwordx4 v[210:211], off
	s_mov_b32 m0, s29
	v_lshl_add_u64 v[210:211], v[214:215], 0, s[58:59]
	global_load_lds_dwordx4 v[210:211], off
	s_mov_b32 m0, s30
	v_lshl_add_u64 v[210:211], v[216:217], 0, s[58:59]
	global_load_lds_dwordx4 v[210:211], off
	s_setprio 1
	s_waitcnt vmcnt(8) lgkmcnt(0)
	s_barrier
	v_mfma_f32_16x16x32_bf16 v[62:65], v[130:133], v[162:165], v[62:65]
	v_mfma_f32_16x16x32_bf16 v[58:61], v[138:141], v[162:165], v[58:61]
	v_mfma_f32_16x16x32_bf16 v[50:53], v[130:133], v[170:173], v[50:53]
	v_mfma_f32_16x16x32_bf16 v[42:45], v[138:141], v[170:173], v[42:45]
	v_mfma_f32_16x16x32_bf16 v[34:37], v[130:133], v[178:181], v[34:37]
	v_mfma_f32_16x16x32_bf16 v[26:29], v[138:141], v[178:181], v[26:29]
	v_mfma_f32_16x16x32_bf16 v[18:21], v[130:133], v[186:189], v[18:21]
	v_mfma_f32_16x16x32_bf16 v[10:13], v[138:141], v[186:189], v[10:13]
	v_mfma_f32_16x16x32_bf16 v[62:65], v[134:137], v[166:169], v[62:65]
	v_mfma_f32_16x16x32_bf16 v[58:61], v[142:145], v[166:169], v[58:61]
	v_mfma_f32_16x16x32_bf16 v[50:53], v[134:137], v[174:177], v[50:53]
	v_mfma_f32_16x16x32_bf16 v[42:45], v[142:145], v[174:177], v[42:45]
	v_mfma_f32_16x16x32_bf16 v[34:37], v[134:137], v[182:185], v[34:37]
	v_mfma_f32_16x16x32_bf16 v[26:29], v[142:145], v[182:185], v[26:29]
	v_mfma_f32_16x16x32_bf16 v[18:21], v[134:137], v[196:199], v[18:21]
	v_mfma_f32_16x16x32_bf16 v[10:13], v[142:145], v[196:199], v[10:13]
	s_setprio 0
	s_setprio 1
	v_mfma_f32_16x16x32_bf16 v[54:57], v[146:149], v[162:165], v[54:57]
	v_mfma_f32_16x16x32_bf16 v[46:49], v[154:157], v[162:165], v[46:49]
	v_mfma_f32_16x16x32_bf16 v[38:41], v[146:149], v[170:173], v[38:41]
	v_mfma_f32_16x16x32_bf16 v[30:33], v[154:157], v[170:173], v[30:33]
	v_mfma_f32_16x16x32_bf16 v[22:25], v[146:149], v[178:181], v[22:25]
	v_mfma_f32_16x16x32_bf16 v[14:17], v[154:157], v[178:181], v[14:17]
	v_mfma_f32_16x16x32_bf16 v[6:9], v[146:149], v[186:189], v[6:9]
	v_mfma_f32_16x16x32_bf16 v[2:5], v[154:157], v[186:189], v[2:5]
	v_mfma_f32_16x16x32_bf16 v[54:57], v[150:153], v[166:169], v[54:57]
	v_mfma_f32_16x16x32_bf16 v[46:49], v[158:161], v[166:169], v[46:49]
	v_mfma_f32_16x16x32_bf16 v[38:41], v[150:153], v[174:177], v[38:41]
	v_mfma_f32_16x16x32_bf16 v[30:33], v[158:161], v[174:177], v[30:33]
	v_mfma_f32_16x16x32_bf16 v[22:25], v[150:153], v[182:185], v[22:25]
	v_mfma_f32_16x16x32_bf16 v[14:17], v[158:161], v[182:185], v[14:17]
	v_mfma_f32_16x16x32_bf16 v[6:9], v[150:153], v[196:199], v[6:9]
	v_mfma_f32_16x16x32_bf16 v[2:5], v[158:161], v[196:199], v[2:5]
	s_setprio 0
	s_barrier
	s_add_i32 s36, s36, 2
	s_add_u32 s16, s16, 0x100
	s_addc_u32 s17, s17, 0
	s_add_u32 s34, s34, 0x100
	s_addc_u32 s35, s35, 0
	s_cmp_gt_u32 s36, 29
	s_cbranch_scc0 .LBB0_748

.LBB0_771:
	s_ashr_i32 s17, s16, 31
	s_lshl_b64 s[20:21], s[16:17], 20
	v_readlane_b32 s0, v254, 60
	s_add_u32 s20, s0, s20
	v_readlane_b32 s0, v254, 61
	s_addc_u32 s21, s0, s21
	s_and_b64 s[22:23], s[6:7], exec
	s_cselect_b32 s17, s21, s27
	s_cselect_b32 s40, s20, s26
	s_ashr_i32 s15, s14, 31
	s_lshl_b64 s[22:23], s[14:15], 20
	v_readlane_b32 s0, v254, 40
	v_readlane_b32 s1, v254, 41
	s_add_u32 s22, s0, s22
	s_addc_u32 s23, s1, s23
	s_and_b64 s[30:31], s[6:7], exec
	s_cselect_b32 s15, s23, s29
	s_cselect_b32 s41, s22, s28
	s_add_u32 s26, s26, 0x80080
	s_addc_u32 s27, s27, 0
	s_add_u32 s42, s28, 0x100
	s_addc_u32 s43, s29, 0
	s_mov_b32 s46, -2
	v_readlane_b32 s47, v255, 49
	s_nop 3
	s_cmp_eq_u32 s47, 4
	v_writelane_b32 v255, 4, 49
	s_cbranch_scc0 .Ltrip0_strict_3
	s_add_u32 s28, s26, 0xfff80080
	s_addc_u32 s29, s27, -1
	s_add_i32 s47, 0, 0x10000
	s_cmp_eq_u32 s46, 28
	s_cselect_b32 s31, s17, s29
	s_cselect_b32 s30, s40, s28
	s_cselect_b32 s29, s15, s43
	s_cselect_b32 s28, s41, s42
	s_add_i32 s55, 0, 0x14000
	v_add_u32_e32 v142, s47, v220
	v_add_u32_e32 v158, s55, v220
	ds_read_b128 v[130:133], v142
	ds_read_b128 v[134:137], v142 offset:1024
	ds_read_b128 v[138:141], v142 offset:2048
	ds_read_b128 v[142:145], v142 offset:3072
	ds_read_b128 v[146:149], v158
	ds_read_b128 v[150:153], v158 offset:1024
	ds_read_b128 v[154:157], v158 offset:2048
	ds_read_b128 v[158:161], v158 offset:3072
	v_lshl_add_u64 v[210:211], s[26:27], 0, v[202:203]
	s_add_i32 m0, s34, 0xc000
	ds_read_b128 v[162:165], v222
	ds_read_b128 v[166:169], v222 offset:1024
	ds_read_b128 v[170:173], v222 offset:2048
	ds_read_b128 v[174:177], v222 offset:3072
	ds_read_b128 v[178:181], v222 offset:4096
	ds_read_b128 v[182:185], v222 offset:5120
	ds_read_b128 v[196:199], v222 offset:6144
	ds_read_b128 v[206:209], v222 offset:7168
	global_load_lds_dwordx4 v[210:211], off
	s_add_i32 m0, s34, 0xe000
	v_lshl_add_u64 v[210:211], s[26:27], 0, v[204:205]
	global_load_lds_dwordx4 v[210:211], off
	s_setprio 1
	s_waitcnt vmcnt(24) lgkmcnt(0)
	s_barrier
	v_mfma_f32_16x16x32_bf16 v[126:129], v[130:133], v[162:165], 0
	v_mfma_f32_16x16x32_bf16 v[122:125], v[138:141], v[162:165], 0
	v_mfma_f32_16x16x32_bf16 v[110:113], v[130:133], v[170:173], 0
	v_mfma_f32_16x16x32_bf16 v[106:109], v[138:141], v[170:173], 0
	v_mfma_f32_16x16x32_bf16 v[94:97], v[130:133], v[178:181], 0
	v_mfma_f32_16x16x32_bf16 v[90:93], v[138:141], v[178:181], 0
	v_mfma_f32_16x16x32_bf16 v[78:81], v[130:133], v[196:199], 0
	v_mfma_f32_16x16x32_bf16 v[74:77], v[138:141], v[196:199], 0
	v_mfma_f32_16x16x32_bf16 v[126:129], v[134:137], v[166:169], v[126:129]
	v_mfma_f32_16x16x32_bf16 v[122:125], v[142:145], v[166:169], v[122:125]
	v_mfma_f32_16x16x32_bf16 v[110:113], v[134:137], v[174:177], v[110:113]
	v_mfma_f32_16x16x32_bf16 v[106:109], v[142:145], v[174:177], v[106:109]
	v_mfma_f32_16x16x32_bf16 v[94:97], v[134:137], v[182:185], v[94:97]
	v_mfma_f32_16x16x32_bf16 v[90:93], v[142:145], v[182:185], v[90:93]
	v_mfma_f32_16x16x32_bf16 v[78:81], v[134:137], v[206:209], v[78:81]
	v_mfma_f32_16x16x32_bf16 v[74:77], v[142:145], v[206:209], v[74:77]
	s_setprio 0
	s_setprio 1
	v_mfma_f32_16x16x32_bf16 v[118:121], v[146:149], v[162:165], 0
	v_mfma_f32_16x16x32_bf16 v[114:117], v[154:157], v[162:165], 0
	v_mfma_f32_16x16x32_bf16 v[102:105], v[146:149], v[170:173], 0
	v_mfma_f32_16x16x32_bf16 v[98:101], v[154:157], v[170:173], 0
	v_mfma_f32_16x16x32_bf16 v[86:89], v[146:149], v[178:181], 0
	v_mfma_f32_16x16x32_bf16 v[82:85], v[154:157], v[178:181], 0
	v_mfma_f32_16x16x32_bf16 v[70:73], v[146:149], v[196:199], 0
	v_mfma_f32_16x16x32_bf16 v[66:69], v[154:157], v[196:199], 0
	v_mfma_f32_16x16x32_bf16 v[118:121], v[150:153], v[166:169], v[118:121]
	v_mfma_f32_16x16x32_bf16 v[114:117], v[158:161], v[166:169], v[114:117]
	v_mfma_f32_16x16x32_bf16 v[102:105], v[150:153], v[174:177], v[102:105]
	v_mfma_f32_16x16x32_bf16 v[98:101], v[158:161], v[174:177], v[98:101]
	v_mfma_f32_16x16x32_bf16 v[86:89], v[150:153], v[182:185], v[86:89]
	v_mfma_f32_16x16x32_bf16 v[82:85], v[158:161], v[182:185], v[82:85]
	v_mfma_f32_16x16x32_bf16 v[70:73], v[150:153], v[206:209], v[70:73]
	v_mfma_f32_16x16x32_bf16 v[66:69], v[158:161], v[206:209], v[66:69]
	s_barrier
	s_setprio 0
	s_add_i32 s47, s47, s33
	v_lshl_add_u64 v[210:211], s[28:29], 0, v[190:191]
	s_mov_b32 m0, s47
	ds_read_b128 v[162:165], v222 offset:16384
	ds_read_b128 v[166:169], v222 offset:17408
	ds_read_b128 v[170:173], v222 offset:18432
	ds_read_b128 v[174:177], v222 offset:19456
	ds_read_b128 v[178:181], v222 offset:20480
	ds_read_b128 v[182:185], v222 offset:21504
	ds_read_b128 v[196:199], v222 offset:22528
	ds_read_b128 v[206:209], v222 offset:23552
	global_load_lds_dwordx4 v[210:211], off
	s_add_i32 m0, s47, 0x2000
	s_add_u32 s52, s28, 0x80000
	v_lshl_add_u64 v[212:213], s[28:29], 0, v[200:201]
	s_addc_u32 s53, s29, 0
	s_add_i32 s47, s55, s33
	global_load_lds_dwordx4 v[212:213], off
	v_lshl_add_u64 v[214:215], s[52:53], 0, v[190:191]
	s_mov_b32 m0, s47
	v_lshl_add_u64 v[216:217], s[30:31], 0, v[188:189]
	global_load_lds_dwordx4 v[214:215], off
	s_add_i32 m0, s47, 0x2000
	v_lshl_add_u64 v[214:215], s[52:53], 0, v[200:201]
	global_load_lds_dwordx4 v[214:215], off
	s_mov_b32 m0, s34
	v_lshl_add_u64 v[214:215], s[30:31], 0, v[186:187]
	global_load_lds_dwordx4 v[214:215], off
	s_mov_b32 m0, s35
	s_nop 0
	global_load_lds_dwordx4 v[216:217], off
	s_setprio 1
	s_waitcnt vmcnt(24) lgkmcnt(0)
	s_barrier
	v_mfma_f32_16x16x32_bf16 v[62:65], v[130:133], v[162:165], 0
	v_mfma_f32_16x16x32_bf16 v[58:61], v[138:141], v[162:165], 0
	v_mfma_f32_16x16x32_bf16 v[46:49], v[130:133], v[170:173], 0
	v_mfma_f32_16x16x32_bf16 v[42:45], v[138:141], v[170:173], 0
	v_mfma_f32_16x16x32_bf16 v[30:33], v[130:133], v[178:181], 0
	v_mfma_f32_16x16x32_bf16 v[26:29], v[138:141], v[178:181], 0
	v_mfma_f32_16x16x32_bf16 v[14:17], v[130:133], v[196:199], 0
	v_mfma_f32_16x16x32_bf16 v[10:13], v[138:141], v[196:199], 0
	v_mfma_f32_16x16x32_bf16 v[62:65], v[134:137], v[166:169], v[62:65]
	v_mfma_f32_16x16x32_bf16 v[58:61], v[142:145], v[166:169], v[58:61]
	v_mfma_f32_16x16x32_bf16 v[46:49], v[134:137], v[174:177], v[46:49]
	v_mfma_f32_16x16x32_bf16 v[42:45], v[142:145], v[174:177], v[42:45]
	v_mfma_f32_16x16x32_bf16 v[30:33], v[134:137], v[182:185], v[30:33]
	v_mfma_f32_16x16x32_bf16 v[26:29], v[142:145], v[182:185], v[26:29]
	v_mfma_f32_16x16x32_bf16 v[14:17], v[134:137], v[206:209], v[14:17]
	v_mfma_f32_16x16x32_bf16 v[10:13], v[142:145], v[206:209], v[10:13]
	s_setprio 0
	s_setprio 1
	v_mfma_f32_16x16x32_bf16 v[54:57], v[146:149], v[162:165], 0
	v_mfma_f32_16x16x32_bf16 v[50:53], v[154:157], v[162:165], 0
	v_mfma_f32_16x16x32_bf16 v[38:41], v[146:149], v[170:173], 0
	v_mfma_f32_16x16x32_bf16 v[34:37], v[154:157], v[170:173], 0
	v_mfma_f32_16x16x32_bf16 v[22:25], v[146:149], v[178:181], 0
	v_mfma_f32_16x16x32_bf16 v[18:21], v[154:157], v[178:181], 0
	v_mfma_f32_16x16x32_bf16 v[6:9], v[146:149], v[196:199], 0
	v_mfma_f32_16x16x32_bf16 v[2:5], v[154:157], v[196:199], 0
	v_mfma_f32_16x16x32_bf16 v[54:57], v[150:153], v[166:169], v[54:57]
	v_mfma_f32_16x16x32_bf16 v[50:53], v[158:161], v[166:169], v[50:53]
	v_mfma_f32_16x16x32_bf16 v[38:41], v[150:153], v[174:177], v[38:41]
	v_mfma_f32_16x16x32_bf16 v[34:37], v[158:161], v[174:177], v[34:37]
	v_mfma_f32_16x16x32_bf16 v[22:25], v[150:153], v[182:185], v[22:25]
	v_mfma_f32_16x16x32_bf16 v[18:21], v[158:161], v[182:185], v[18:21]
	v_mfma_f32_16x16x32_bf16 v[6:9], v[150:153], v[206:209], v[6:9]
	v_mfma_f32_16x16x32_bf16 v[2:5], v[158:161], v[206:209], v[2:5]
	s_barrier
	s_setprio 0
	s_add_i32 s47, 0, 0x18000
	s_add_i32 s52, 0, 0x1c000
	v_add_u32_e32 v142, s47, v220
	v_add_u32_e32 v158, s52, v220
	ds_read_b128 v[130:133], v142
	ds_read_b128 v[134:137], v142 offset:1024
	ds_read_b128 v[138:141], v142 offset:2048
	ds_read_b128 v[142:145], v142 offset:3072
	ds_read_b128 v[146:149], v158
	ds_read_b128 v[150:153], v158 offset:1024
	ds_read_b128 v[154:157], v158 offset:2048
	ds_read_b128 v[158:161], v158 offset:3072
	s_add_u32 s30, s30, 0x80000
	s_addc_u32 s31, s31, 0
	s_mov_b32 m0, s36
	v_lshl_add_u64 v[218:219], s[30:31], 0, v[186:187]
	ds_read_b128 v[162:165], v222 offset:32768
	ds_read_b128 v[166:169], v222 offset:33792
	ds_read_b128 v[170:173], v222 offset:34816
	ds_read_b128 v[174:177], v222 offset:35840
	ds_read_b128 v[178:181], v222 offset:36864
	ds_read_b128 v[182:185], v222 offset:37888
	ds_read_b128 v[196:199], v222 offset:38912
	ds_read_b128 v[206:209], v222 offset:39936
	global_load_lds_dwordx4 v[218:219], off
	s_mov_b32 m0, s37
	v_lshl_add_u64 v[218:219], s[30:31], 0, v[188:189]
	global_load_lds_dwordx4 v[218:219], off
	s_setprio 1
	s_waitcnt vmcnt(8) lgkmcnt(0)
	s_barrier
	v_mfma_f32_16x16x32_bf16 v[126:129], v[130:133], v[162:165], v[126:129]
	v_mfma_f32_16x16x32_bf16 v[122:125], v[138:141], v[162:165], v[122:125]
	v_mfma_f32_16x16x32_bf16 v[110:113], v[130:133], v[170:173], v[110:113]
	v_mfma_f32_16x16x32_bf16 v[106:109], v[138:141], v[170:173], v[106:109]
	v_mfma_f32_16x16x32_bf16 v[94:97], v[130:133], v[178:181], v[94:97]
	v_mfma_f32_16x16x32_bf16 v[90:93], v[138:141], v[178:181], v[90:93]
	v_mfma_f32_16x16x32_bf16 v[78:81], v[130:133], v[196:199], v[78:81]
	v_mfma_f32_16x16x32_bf16 v[74:77], v[138:141], v[196:199], v[74:77]
	v_mfma_f32_16x16x32_bf16 v[126:129], v[134:137], v[166:169], v[126:129]
	v_mfma_f32_16x16x32_bf16 v[122:125], v[142:145], v[166:169], v[122:125]
	v_mfma_f32_16x16x32_bf16 v[110:113], v[134:137], v[174:177], v[110:113]
	v_mfma_f32_16x16x32_bf16 v[106:109], v[142:145], v[174:177], v[106:109]
	v_mfma_f32_16x16x32_bf16 v[94:97], v[134:137], v[182:185], v[94:97]
	v_mfma_f32_16x16x32_bf16 v[90:93], v[142:145], v[182:185], v[90:93]
	v_mfma_f32_16x16x32_bf16 v[78:81], v[134:137], v[206:209], v[78:81]
	v_mfma_f32_16x16x32_bf16 v[74:77], v[142:145], v[206:209], v[74:77]
	s_setprio 0
	s_setprio 1
	v_mfma_f32_16x16x32_bf16 v[118:121], v[146:149], v[162:165], v[118:121]
	v_mfma_f32_16x16x32_bf16 v[114:117], v[154:157], v[162:165], v[114:117]
	v_mfma_f32_16x16x32_bf16 v[102:105], v[146:149], v[170:173], v[102:105]
	v_mfma_f32_16x16x32_bf16 v[98:101], v[154:157], v[170:173], v[98:101]
	v_mfma_f32_16x16x32_bf16 v[86:89], v[146:149], v[178:181], v[86:89]
	v_mfma_f32_16x16x32_bf16 v[82:85], v[154:157], v[178:181], v[82:85]
	v_mfma_f32_16x16x32_bf16 v[70:73], v[146:149], v[196:199], v[70:73]
	v_mfma_f32_16x16x32_bf16 v[66:69], v[154:157], v[196:199], v[66:69]
	v_mfma_f32_16x16x32_bf16 v[118:121], v[150:153], v[166:169], v[118:121]
	v_mfma_f32_16x16x32_bf16 v[114:117], v[158:161], v[166:169], v[114:117]
	v_mfma_f32_16x16x32_bf16 v[102:105], v[150:153], v[174:177], v[102:105]
	v_mfma_f32_16x16x32_bf16 v[98:101], v[158:161], v[174:177], v[98:101]
	v_mfma_f32_16x16x32_bf16 v[86:89], v[150:153], v[182:185], v[86:89]
	v_mfma_f32_16x16x32_bf16 v[82:85], v[158:161], v[182:185], v[82:85]
	v_mfma_f32_16x16x32_bf16 v[70:73], v[150:153], v[206:209], v[70:73]
	v_mfma_f32_16x16x32_bf16 v[66:69], v[158:161], v[206:209], v[66:69]
	s_barrier
	s_setprio 0
	s_add_i32 s30, s47, s33
	v_lshl_add_u64 v[210:211], v[210:211], 0, s[58:59]
	s_mov_b32 m0, s30
	ds_read_b128 v[162:165], v222 offset:49152
	ds_read_b128 v[166:169], v222 offset:50176
	ds_read_b128 v[170:173], v222 offset:51200
	ds_read_b128 v[174:177], v222 offset:52224
	ds_read_b128 v[178:181], v222 offset:53248
	ds_read_b128 v[182:185], v222 offset:54272
	ds_read_b128 v[196:199], v222 offset:55296
	ds_read_b128 v[206:209], v222 offset:56320
	global_load_lds_dwordx4 v[210:211], off
	s_add_i32 m0, s30, 0x2000
	s_add_u32 s28, s28, 0x80080
	v_lshl_add_u64 v[210:211], v[212:213], 0, s[58:59]
	s_addc_u32 s29, s29, 0
	s_add_i32 s30, s52, s33
	global_load_lds_dwordx4 v[210:211], off
	s_mov_b32 m0, s30
	v_lshl_add_u64 v[210:211], s[28:29], 0, v[190:191]
	global_load_lds_dwordx4 v[210:211], off
	s_add_i32 m0, s30, 0x2000
	v_lshl_add_u64 v[210:211], s[28:29], 0, v[200:201]
	global_load_lds_dwordx4 v[210:211], off
	s_mov_b32 m0, s38
	v_lshl_add_u64 v[210:211], v[214:215], 0, s[58:59]
	global_load_lds_dwordx4 v[210:211], off
	s_mov_b32 m0, s39
	v_lshl_add_u64 v[210:211], v[216:217], 0, s[58:59]
	global_load_lds_dwordx4 v[210:211], off
	s_setprio 1
	s_waitcnt vmcnt(8) lgkmcnt(0)
	s_barrier
	v_mfma_f32_16x16x32_bf16 v[62:65], v[130:133], v[162:165], v[62:65]
	v_mfma_f32_16x16x32_bf16 v[58:61], v[138:141], v[162:165], v[58:61]
	v_mfma_f32_16x16x32_bf16 v[46:49], v[130:133], v[170:173], v[46:49]
	v_mfma_f32_16x16x32_bf16 v[42:45], v[138:141], v[170:173], v[42:45]
	v_mfma_f32_16x16x32_bf16 v[30:33], v[130:133], v[178:181], v[30:33]
	v_mfma_f32_16x16x32_bf16 v[26:29], v[138:141], v[178:181], v[26:29]
	v_mfma_f32_16x16x32_bf16 v[14:17], v[130:133], v[196:199], v[14:17]
	v_mfma_f32_16x16x32_bf16 v[10:13], v[138:141], v[196:199], v[10:13]
	v_mfma_f32_16x16x32_bf16 v[62:65], v[134:137], v[166:169], v[62:65]
	v_mfma_f32_16x16x32_bf16 v[58:61], v[142:145], v[166:169], v[58:61]
	v_mfma_f32_16x16x32_bf16 v[46:49], v[134:137], v[174:177], v[46:49]
	v_mfma_f32_16x16x32_bf16 v[42:45], v[142:145], v[174:177], v[42:45]
	v_mfma_f32_16x16x32_bf16 v[30:33], v[134:137], v[182:185], v[30:33]
	v_mfma_f32_16x16x32_bf16 v[26:29], v[142:145], v[182:185], v[26:29]
	v_mfma_f32_16x16x32_bf16 v[14:17], v[134:137], v[206:209], v[14:17]
	v_mfma_f32_16x16x32_bf16 v[10:13], v[142:145], v[206:209], v[10:13]
	s_setprio 0
	s_setprio 1
	v_mfma_f32_16x16x32_bf16 v[54:57], v[146:149], v[162:165], v[54:57]
	v_mfma_f32_16x16x32_bf16 v[50:53], v[154:157], v[162:165], v[50:53]
	v_mfma_f32_16x16x32_bf16 v[38:41], v[146:149], v[170:173], v[38:41]
	v_mfma_f32_16x16x32_bf16 v[34:37], v[154:157], v[170:173], v[34:37]
	v_mfma_f32_16x16x32_bf16 v[22:25], v[146:149], v[178:181], v[22:25]
	v_mfma_f32_16x16x32_bf16 v[18:21], v[154:157], v[178:181], v[18:21]
	v_mfma_f32_16x16x32_bf16 v[6:9], v[146:149], v[196:199], v[6:9]
	v_mfma_f32_16x16x32_bf16 v[2:5], v[154:157], v[196:199], v[2:5]
	v_mfma_f32_16x16x32_bf16 v[54:57], v[150:153], v[166:169], v[54:57]
	v_mfma_f32_16x16x32_bf16 v[50:53], v[158:161], v[166:169], v[50:53]
	v_mfma_f32_16x16x32_bf16 v[38:41], v[150:153], v[174:177], v[38:41]
	v_mfma_f32_16x16x32_bf16 v[34:37], v[158:161], v[174:177], v[34:37]
	v_mfma_f32_16x16x32_bf16 v[22:25], v[150:153], v[182:185], v[22:25]
	v_mfma_f32_16x16x32_bf16 v[18:21], v[158:161], v[182:185], v[18:21]
	v_mfma_f32_16x16x32_bf16 v[6:9], v[150:153], v[206:209], v[6:9]
	v_mfma_f32_16x16x32_bf16 v[2:5], v[158:161], v[206:209], v[2:5]
	s_barrier
	s_setprio 0
	s_add_i32 s46, s46, 2
	s_add_u32 s26, s26, 0x100
	s_addc_u32 s27, s27, 0
	s_add_u32 s42, s42, 0x100
	s_addc_u32 s43, s43, 0
	s_cmp_gt_u32 s46, 29
	s_cbranch_scc1 .Lpeel_done_3
	s_branch .LBB0_772
.Ltrip0_strict_3:
	s_add_u32 s28, s26, 0xfff80080
	s_addc_u32 s29, s27, -1
	s_add_i32 s47, 0, 0x10000
	s_cmp_eq_u32 s46, 28
	s_cselect_b32 s31, s17, s29
	s_cselect_b32 s30, s40, s28
	s_cselect_b32 s29, s15, s43
	s_cselect_b32 s28, s41, s42
	s_add_i32 s55, 0, 0x14000
	v_add_u32_e32 v142, s47, v220
	v_add_u32_e32 v158, s55, v220
	ds_read_b128 v[130:133], v142
	ds_read_b128 v[134:137], v142 offset:1024
	ds_read_b128 v[138:141], v142 offset:2048
	ds_read_b128 v[142:145], v142 offset:3072
	ds_read_b128 v[146:149], v158
	ds_read_b128 v[150:153], v158 offset:1024
	ds_read_b128 v[154:157], v158 offset:2048
	ds_read_b128 v[158:161], v158 offset:3072
	v_lshl_add_u64 v[210:211], s[26:27], 0, v[202:203]
	s_add_i32 m0, s34, 0xc000
	ds_read_b128 v[162:165], v222
	ds_read_b128 v[166:169], v222 offset:1024
	ds_read_b128 v[170:173], v222 offset:2048
	ds_read_b128 v[174:177], v222 offset:3072
	ds_read_b128 v[178:181], v222 offset:4096
	ds_read_b128 v[182:185], v222 offset:5120
	ds_read_b128 v[196:199], v222 offset:6144
	ds_read_b128 v[206:209], v222 offset:7168
	global_load_lds_dwordx4 v[210:211], off
	s_add_i32 m0, s34, 0xe000
	v_lshl_add_u64 v[210:211], s[26:27], 0, v[204:205]
	global_load_lds_dwordx4 v[210:211], off
	s_setprio 1
	s_waitcnt vmcnt(8) lgkmcnt(0)
	s_barrier
	v_mfma_f32_16x16x32_bf16 v[126:129], v[130:133], v[162:165], 0
	v_mfma_f32_16x16x32_bf16 v[122:125], v[138:141], v[162:165], 0
	v_mfma_f32_16x16x32_bf16 v[110:113], v[130:133], v[170:173], 0
	v_mfma_f32_16x16x32_bf16 v[106:109], v[138:141], v[170:173], 0
	v_mfma_f32_16x16x32_bf16 v[94:97], v[130:133], v[178:181], 0
	v_mfma_f32_16x16x32_bf16 v[90:93], v[138:141], v[178:181], 0
	v_mfma_f32_16x16x32_bf16 v[78:81], v[130:133], v[196:199], 0
	v_mfma_f32_16x16x32_bf16 v[74:77], v[138:141], v[196:199], 0
	v_mfma_f32_16x16x32_bf16 v[126:129], v[134:137], v[166:169], v[126:129]
	v_mfma_f32_16x16x32_bf16 v[122:125], v[142:145], v[166:169], v[122:125]
	v_mfma_f32_16x16x32_bf16 v[110:113], v[134:137], v[174:177], v[110:113]
	v_mfma_f32_16x16x32_bf16 v[106:109], v[142:145], v[174:177], v[106:109]
	v_mfma_f32_16x16x32_bf16 v[94:97], v[134:137], v[182:185], v[94:97]
	v_mfma_f32_16x16x32_bf16 v[90:93], v[142:145], v[182:185], v[90:93]
	v_mfma_f32_16x16x32_bf16 v[78:81], v[134:137], v[206:209], v[78:81]
	v_mfma_f32_16x16x32_bf16 v[74:77], v[142:145], v[206:209], v[74:77]
	s_setprio 0
	s_setprio 1
	v_mfma_f32_16x16x32_bf16 v[118:121], v[146:149], v[162:165], 0
	v_mfma_f32_16x16x32_bf16 v[114:117], v[154:157], v[162:165], 0
	v_mfma_f32_16x16x32_bf16 v[102:105], v[146:149], v[170:173], 0
	v_mfma_f32_16x16x32_bf16 v[98:101], v[154:157], v[170:173], 0
	v_mfma_f32_16x16x32_bf16 v[86:89], v[146:149], v[178:181], 0
	v_mfma_f32_16x16x32_bf16 v[82:85], v[154:157], v[178:181], 0
	v_mfma_f32_16x16x32_bf16 v[70:73], v[146:149], v[196:199], 0
	v_mfma_f32_16x16x32_bf16 v[66:69], v[154:157], v[196:199], 0
	v_mfma_f32_16x16x32_bf16 v[118:121], v[150:153], v[166:169], v[118:121]
	v_mfma_f32_16x16x32_bf16 v[114:117], v[158:161], v[166:169], v[114:117]
	v_mfma_f32_16x16x32_bf16 v[102:105], v[150:153], v[174:177], v[102:105]
	v_mfma_f32_16x16x32_bf16 v[98:101], v[158:161], v[174:177], v[98:101]
	v_mfma_f32_16x16x32_bf16 v[86:89], v[150:153], v[182:185], v[86:89]
	v_mfma_f32_16x16x32_bf16 v[82:85], v[158:161], v[182:185], v[82:85]
	v_mfma_f32_16x16x32_bf16 v[70:73], v[150:153], v[206:209], v[70:73]
	v_mfma_f32_16x16x32_bf16 v[66:69], v[158:161], v[206:209], v[66:69]
	s_barrier
	s_setprio 0
	s_add_i32 s47, s47, s33
	v_lshl_add_u64 v[210:211], s[28:29], 0, v[190:191]
	s_mov_b32 m0, s47
	ds_read_b128 v[162:165], v222 offset:16384
	ds_read_b128 v[166:169], v222 offset:17408
	ds_read_b128 v[170:173], v222 offset:18432
	ds_read_b128 v[174:177], v222 offset:19456
	ds_read_b128 v[178:181], v222 offset:20480
	ds_read_b128 v[182:185], v222 offset:21504
	ds_read_b128 v[196:199], v222 offset:22528
	ds_read_b128 v[206:209], v222 offset:23552
	global_load_lds_dwordx4 v[210:211], off
	s_add_i32 m0, s47, 0x2000
	s_add_u32 s52, s28, 0x80000
	v_lshl_add_u64 v[212:213], s[28:29], 0, v[200:201]
	s_addc_u32 s53, s29, 0
	s_add_i32 s47, s55, s33
	global_load_lds_dwordx4 v[212:213], off
	v_lshl_add_u64 v[214:215], s[52:53], 0, v[190:191]
	s_mov_b32 m0, s47
	v_lshl_add_u64 v[216:217], s[30:31], 0, v[188:189]
	global_load_lds_dwordx4 v[214:215], off
	s_add_i32 m0, s47, 0x2000
	v_lshl_add_u64 v[214:215], s[52:53], 0, v[200:201]
	global_load_lds_dwordx4 v[214:215], off
	s_mov_b32 m0, s34
	v_lshl_add_u64 v[214:215], s[30:31], 0, v[186:187]
	global_load_lds_dwordx4 v[214:215], off
	s_mov_b32 m0, s35
	s_nop 0
	global_load_lds_dwordx4 v[216:217], off
	s_setprio 1
	s_waitcnt vmcnt(8) lgkmcnt(0)
	s_barrier
	v_mfma_f32_16x16x32_bf16 v[62:65], v[130:133], v[162:165], 0
	v_mfma_f32_16x16x32_bf16 v[58:61], v[138:141], v[162:165], 0
	v_mfma_f32_16x16x32_bf16 v[46:49], v[130:133], v[170:173], 0
	v_mfma_f32_16x16x32_bf16 v[42:45], v[138:141], v[170:173], 0
	v_mfma_f32_16x16x32_bf16 v[30:33], v[130:133], v[178:181], 0
	v_mfma_f32_16x16x32_bf16 v[26:29], v[138:141], v[178:181], 0
	v_mfma_f32_16x16x32_bf16 v[14:17], v[130:133], v[196:199], 0
	v_mfma_f32_16x16x32_bf16 v[10:13], v[138:141], v[196:199], 0
	v_mfma_f32_16x16x32_bf16 v[62:65], v[134:137], v[166:169], v[62:65]
	v_mfma_f32_16x16x32_bf16 v[58:61], v[142:145], v[166:169], v[58:61]
	v_mfma_f32_16x16x32_bf16 v[46:49], v[134:137], v[174:177], v[46:49]
	v_mfma_f32_16x16x32_bf16 v[42:45], v[142:145], v[174:177], v[42:45]
	v_mfma_f32_16x16x32_bf16 v[30:33], v[134:137], v[182:185], v[30:33]
	v_mfma_f32_16x16x32_bf16 v[26:29], v[142:145], v[182:185], v[26:29]
	v_mfma_f32_16x16x32_bf16 v[14:17], v[134:137], v[206:209], v[14:17]
	v_mfma_f32_16x16x32_bf16 v[10:13], v[142:145], v[206:209], v[10:13]
	s_setprio 0
	s_setprio 1
	v_mfma_f32_16x16x32_bf16 v[54:57], v[146:149], v[162:165], 0
	v_mfma_f32_16x16x32_bf16 v[50:53], v[154:157], v[162:165], 0
	v_mfma_f32_16x16x32_bf16 v[38:41], v[146:149], v[170:173], 0
	v_mfma_f32_16x16x32_bf16 v[34:37], v[154:157], v[170:173], 0
	v_mfma_f32_16x16x32_bf16 v[22:25], v[146:149], v[178:181], 0
	v_mfma_f32_16x16x32_bf16 v[18:21], v[154:157], v[178:181], 0
	v_mfma_f32_16x16x32_bf16 v[6:9], v[146:149], v[196:199], 0
	v_mfma_f32_16x16x32_bf16 v[2:5], v[154:157], v[196:199], 0
	v_mfma_f32_16x16x32_bf16 v[54:57], v[150:153], v[166:169], v[54:57]
	v_mfma_f32_16x16x32_bf16 v[50:53], v[158:161], v[166:169], v[50:53]
	v_mfma_f32_16x16x32_bf16 v[38:41], v[150:153], v[174:177], v[38:41]
	v_mfma_f32_16x16x32_bf16 v[34:37], v[158:161], v[174:177], v[34:37]
	v_mfma_f32_16x16x32_bf16 v[22:25], v[150:153], v[182:185], v[22:25]
	v_mfma_f32_16x16x32_bf16 v[18:21], v[158:161], v[182:185], v[18:21]
	v_mfma_f32_16x16x32_bf16 v[6:9], v[150:153], v[206:209], v[6:9]
	v_mfma_f32_16x16x32_bf16 v[2:5], v[158:161], v[206:209], v[2:5]
	s_barrier
	s_setprio 0
	s_add_i32 s47, 0, 0x18000
	s_add_i32 s52, 0, 0x1c000
	v_add_u32_e32 v142, s47, v220
	v_add_u32_e32 v158, s52, v220
	ds_read_b128 v[130:133], v142
	ds_read_b128 v[134:137], v142 offset:1024
	ds_read_b128 v[138:141], v142 offset:2048
	ds_read_b128 v[142:145], v142 offset:3072
	ds_read_b128 v[146:149], v158
	ds_read_b128 v[150:153], v158 offset:1024
	ds_read_b128 v[154:157], v158 offset:2048
	ds_read_b128 v[158:161], v158 offset:3072
	s_add_u32 s30, s30, 0x80000
	s_addc_u32 s31, s31, 0
	s_mov_b32 m0, s36
	v_lshl_add_u64 v[218:219], s[30:31], 0, v[186:187]
	ds_read_b128 v[162:165], v222 offset:32768
	ds_read_b128 v[166:169], v222 offset:33792
	ds_read_b128 v[170:173], v222 offset:34816
	ds_read_b128 v[174:177], v222 offset:35840
	ds_read_b128 v[178:181], v222 offset:36864
	ds_read_b128 v[182:185], v222 offset:37888
	ds_read_b128 v[196:199], v222 offset:38912
	ds_read_b128 v[206:209], v222 offset:39936
	global_load_lds_dwordx4 v[218:219], off
	s_mov_b32 m0, s37
	v_lshl_add_u64 v[218:219], s[30:31], 0, v[188:189]
	global_load_lds_dwordx4 v[218:219], off
	s_setprio 1
	s_waitcnt vmcnt(8) lgkmcnt(0)
	s_barrier
	v_mfma_f32_16x16x32_bf16 v[126:129], v[130:133], v[162:165], v[126:129]
	v_mfma_f32_16x16x32_bf16 v[122:125], v[138:141], v[162:165], v[122:125]
	v_mfma_f32_16x16x32_bf16 v[110:113], v[130:133], v[170:173], v[110:113]
	v_mfma_f32_16x16x32_bf16 v[106:109], v[138:141], v[170:173], v[106:109]
	v_mfma_f32_16x16x32_bf16 v[94:97], v[130:133], v[178:181], v[94:97]
	v_mfma_f32_16x16x32_bf16 v[90:93], v[138:141], v[178:181], v[90:93]
	v_mfma_f32_16x16x32_bf16 v[78:81], v[130:133], v[196:199], v[78:81]
	v_mfma_f32_16x16x32_bf16 v[74:77], v[138:141], v[196:199], v[74:77]
	v_mfma_f32_16x16x32_bf16 v[126:129], v[134:137], v[166:169], v[126:129]
	v_mfma_f32_16x16x32_bf16 v[122:125], v[142:145], v[166:169], v[122:125]
	v_mfma_f32_16x16x32_bf16 v[110:113], v[134:137], v[174:177], v[110:113]
	v_mfma_f32_16x16x32_bf16 v[106:109], v[142:145], v[174:177], v[106:109]
	v_mfma_f32_16x16x32_bf16 v[94:97], v[134:137], v[182:185], v[94:97]
	v_mfma_f32_16x16x32_bf16 v[90:93], v[142:145], v[182:185], v[90:93]
	v_mfma_f32_16x16x32_bf16 v[78:81], v[134:137], v[206:209], v[78:81]
	v_mfma_f32_16x16x32_bf16 v[74:77], v[142:145], v[206:209], v[74:77]
	s_setprio 0
	s_setprio 1
	v_mfma_f32_16x16x32_bf16 v[118:121], v[146:149], v[162:165], v[118:121]
	v_mfma_f32_16x16x32_bf16 v[114:117], v[154:157], v[162:165], v[114:117]
	v_mfma_f32_16x16x32_bf16 v[102:105], v[146:149], v[170:173], v[102:105]
	v_mfma_f32_16x16x32_bf16 v[98:101], v[154:157], v[170:173], v[98:101]
	v_mfma_f32_16x16x32_bf16 v[86:89], v[146:149], v[178:181], v[86:89]
	v_mfma_f32_16x16x32_bf16 v[82:85], v[154:157], v[178:181], v[82:85]
	v_mfma_f32_16x16x32_bf16 v[70:73], v[146:149], v[196:199], v[70:73]
	v_mfma_f32_16x16x32_bf16 v[66:69], v[154:157], v[196:199], v[66:69]
	v_mfma_f32_16x16x32_bf16 v[118:121], v[150:153], v[166:169], v[118:121]
	v_mfma_f32_16x16x32_bf16 v[114:117], v[158:161], v[166:169], v[114:117]
	v_mfma_f32_16x16x32_bf16 v[102:105], v[150:153], v[174:177], v[102:105]
	v_mfma_f32_16x16x32_bf16 v[98:101], v[158:161], v[174:177], v[98:101]
	v_mfma_f32_16x16x32_bf16 v[86:89], v[150:153], v[182:185], v[86:89]
	v_mfma_f32_16x16x32_bf16 v[82:85], v[158:161], v[182:185], v[82:85]
	v_mfma_f32_16x16x32_bf16 v[70:73], v[150:153], v[206:209], v[70:73]
	v_mfma_f32_16x16x32_bf16 v[66:69], v[158:161], v[206:209], v[66:69]
	s_barrier
	s_setprio 0
	s_add_i32 s30, s47, s33
	v_lshl_add_u64 v[210:211], v[210:211], 0, s[58:59]
	s_mov_b32 m0, s30
	ds_read_b128 v[162:165], v222 offset:49152
	ds_read_b128 v[166:169], v222 offset:50176
	ds_read_b128 v[170:173], v222 offset:51200
	ds_read_b128 v[174:177], v222 offset:52224
	ds_read_b128 v[178:181], v222 offset:53248
	ds_read_b128 v[182:185], v222 offset:54272
	ds_read_b128 v[196:199], v222 offset:55296
	ds_read_b128 v[206:209], v222 offset:56320
	global_load_lds_dwordx4 v[210:211], off
	s_add_i32 m0, s30, 0x2000
	s_add_u32 s28, s28, 0x80080
	v_lshl_add_u64 v[210:211], v[212:213], 0, s[58:59]
	s_addc_u32 s29, s29, 0
	s_add_i32 s30, s52, s33
	global_load_lds_dwordx4 v[210:211], off
	s_mov_b32 m0, s30
	v_lshl_add_u64 v[210:211], s[28:29], 0, v[190:191]
	global_load_lds_dwordx4 v[210:211], off
	s_add_i32 m0, s30, 0x2000
	v_lshl_add_u64 v[210:211], s[28:29], 0, v[200:201]
	global_load_lds_dwordx4 v[210:211], off
	s_mov_b32 m0, s38
	v_lshl_add_u64 v[210:211], v[214:215], 0, s[58:59]
	global_load_lds_dwordx4 v[210:211], off
	s_mov_b32 m0, s39
	v_lshl_add_u64 v[210:211], v[216:217], 0, s[58:59]
	global_load_lds_dwordx4 v[210:211], off
	s_setprio 1
	s_waitcnt vmcnt(8) lgkmcnt(0)
	s_barrier
	v_mfma_f32_16x16x32_bf16 v[62:65], v[130:133], v[162:165], v[62:65]
	v_mfma_f32_16x16x32_bf16 v[58:61], v[138:141], v[162:165], v[58:61]
	v_mfma_f32_16x16x32_bf16 v[46:49], v[130:133], v[170:173], v[46:49]
	v_mfma_f32_16x16x32_bf16 v[42:45], v[138:141], v[170:173], v[42:45]
	v_mfma_f32_16x16x32_bf16 v[30:33], v[130:133], v[178:181], v[30:33]
	v_mfma_f32_16x16x32_bf16 v[26:29], v[138:141], v[178:181], v[26:29]
	v_mfma_f32_16x16x32_bf16 v[14:17], v[130:133], v[196:199], v[14:17]
	v_mfma_f32_16x16x32_bf16 v[10:13], v[138:141], v[196:199], v[10:13]
	v_mfma_f32_16x16x32_bf16 v[62:65], v[134:137], v[166:169], v[62:65]
	v_mfma_f32_16x16x32_bf16 v[58:61], v[142:145], v[166:169], v[58:61]
	v_mfma_f32_16x16x32_bf16 v[46:49], v[134:137], v[174:177], v[46:49]
	v_mfma_f32_16x16x32_bf16 v[42:45], v[142:145], v[174:177], v[42:45]
	v_mfma_f32_16x16x32_bf16 v[30:33], v[134:137], v[182:185], v[30:33]
	v_mfma_f32_16x16x32_bf16 v[26:29], v[142:145], v[182:185], v[26:29]
	v_mfma_f32_16x16x32_bf16 v[14:17], v[134:137], v[206:209], v[14:17]
	v_mfma_f32_16x16x32_bf16 v[10:13], v[142:145], v[206:209], v[10:13]
	s_setprio 0
	s_setprio 1
	v_mfma_f32_16x16x32_bf16 v[54:57], v[146:149], v[162:165], v[54:57]
	v_mfma_f32_16x16x32_bf16 v[50:53], v[154:157], v[162:165], v[50:53]
	v_mfma_f32_16x16x32_bf16 v[38:41], v[146:149], v[170:173], v[38:41]
	v_mfma_f32_16x16x32_bf16 v[34:37], v[154:157], v[170:173], v[34:37]
	v_mfma_f32_16x16x32_bf16 v[22:25], v[146:149], v[178:181], v[22:25]
	v_mfma_f32_16x16x32_bf16 v[18:21], v[154:157], v[178:181], v[18:21]
	v_mfma_f32_16x16x32_bf16 v[6:9], v[146:149], v[196:199], v[6:9]
	v_mfma_f32_16x16x32_bf16 v[2:5], v[154:157], v[196:199], v[2:5]
	v_mfma_f32_16x16x32_bf16 v[54:57], v[150:153], v[166:169], v[54:57]
	v_mfma_f32_16x16x32_bf16 v[50:53], v[158:161], v[166:169], v[50:53]
	v_mfma_f32_16x16x32_bf16 v[38:41], v[150:153], v[174:177], v[38:41]
	v_mfma_f32_16x16x32_bf16 v[34:37], v[158:161], v[174:177], v[34:37]
	v_mfma_f32_16x16x32_bf16 v[22:25], v[150:153], v[182:185], v[22:25]
	v_mfma_f32_16x16x32_bf16 v[18:21], v[158:161], v[182:185], v[18:21]
	v_mfma_f32_16x16x32_bf16 v[6:9], v[150:153], v[206:209], v[6:9]
	v_mfma_f32_16x16x32_bf16 v[2:5], v[158:161], v[206:209], v[2:5]
	s_barrier
	s_setprio 0
	s_add_i32 s46, s46, 2
	s_add_u32 s26, s26, 0x100
	s_addc_u32 s27, s27, 0
	s_add_u32 s42, s42, 0x100
	s_addc_u32 s43, s43, 0
	s_cmp_gt_u32 s46, 29
	s_cbranch_scc1 .Lpeel_done_3
.LBB0_772:
	s_add_u32 s28, s26, 0xfff80080
	s_addc_u32 s29, s27, -1
	s_add_i32 s47, 0, 0x10000
	s_cmp_eq_u32 s46, 28
	s_cselect_b32 s31, s17, s29
	s_cselect_b32 s30, s40, s28
	s_cselect_b32 s29, s15, s43
	s_cselect_b32 s28, s41, s42
	s_add_i32 s55, 0, 0x14000
	v_add_u32_e32 v142, s47, v220
	v_add_u32_e32 v158, s55, v220
	ds_read_b128 v[130:133], v142
	ds_read_b128 v[134:137], v142 offset:1024
	ds_read_b128 v[138:141], v142 offset:2048
	ds_read_b128 v[142:145], v142 offset:3072
	ds_read_b128 v[146:149], v158
	ds_read_b128 v[150:153], v158 offset:1024
	ds_read_b128 v[154:157], v158 offset:2048
	ds_read_b128 v[158:161], v158 offset:3072
	v_lshl_add_u64 v[210:211], s[26:27], 0, v[202:203]
	s_add_i32 m0, s34, 0xc000
	ds_read_b128 v[162:165], v222
	ds_read_b128 v[166:169], v222 offset:1024
	ds_read_b128 v[170:173], v222 offset:2048
	ds_read_b128 v[174:177], v222 offset:3072
	ds_read_b128 v[178:181], v222 offset:4096
	ds_read_b128 v[182:185], v222 offset:5120
	ds_read_b128 v[196:199], v222 offset:6144
	ds_read_b128 v[206:209], v222 offset:7168
	global_load_lds_dwordx4 v[210:211], off
	s_add_i32 m0, s34, 0xe000
	v_lshl_add_u64 v[210:211], s[26:27], 0, v[204:205]
	global_load_lds_dwordx4 v[210:211], off
	s_setprio 1
	s_waitcnt vmcnt(8) lgkmcnt(0)
	s_barrier
	v_mfma_f32_16x16x32_bf16 v[126:129], v[130:133], v[162:165], v[126:129]
	v_mfma_f32_16x16x32_bf16 v[122:125], v[138:141], v[162:165], v[122:125]
	v_mfma_f32_16x16x32_bf16 v[110:113], v[130:133], v[170:173], v[110:113]
	v_mfma_f32_16x16x32_bf16 v[106:109], v[138:141], v[170:173], v[106:109]
	v_mfma_f32_16x16x32_bf16 v[94:97], v[130:133], v[178:181], v[94:97]
	v_mfma_f32_16x16x32_bf16 v[90:93], v[138:141], v[178:181], v[90:93]
	v_mfma_f32_16x16x32_bf16 v[78:81], v[130:133], v[196:199], v[78:81]
	v_mfma_f32_16x16x32_bf16 v[74:77], v[138:141], v[196:199], v[74:77]
	v_mfma_f32_16x16x32_bf16 v[126:129], v[134:137], v[166:169], v[126:129]
	v_mfma_f32_16x16x32_bf16 v[122:125], v[142:145], v[166:169], v[122:125]
	v_mfma_f32_16x16x32_bf16 v[110:113], v[134:137], v[174:177], v[110:113]
	v_mfma_f32_16x16x32_bf16 v[106:109], v[142:145], v[174:177], v[106:109]
	v_mfma_f32_16x16x32_bf16 v[94:97], v[134:137], v[182:185], v[94:97]
	v_mfma_f32_16x16x32_bf16 v[90:93], v[142:145], v[182:185], v[90:93]
	v_mfma_f32_16x16x32_bf16 v[78:81], v[134:137], v[206:209], v[78:81]
	v_mfma_f32_16x16x32_bf16 v[74:77], v[142:145], v[206:209], v[74:77]
	s_setprio 0
	s_setprio 1
	v_mfma_f32_16x16x32_bf16 v[118:121], v[146:149], v[162:165], v[118:121]
	v_mfma_f32_16x16x32_bf16 v[114:117], v[154:157], v[162:165], v[114:117]
	v_mfma_f32_16x16x32_bf16 v[102:105], v[146:149], v[170:173], v[102:105]
	v_mfma_f32_16x16x32_bf16 v[98:101], v[154:157], v[170:173], v[98:101]
	v_mfma_f32_16x16x32_bf16 v[86:89], v[146:149], v[178:181], v[86:89]
	v_mfma_f32_16x16x32_bf16 v[82:85], v[154:157], v[178:181], v[82:85]
	v_mfma_f32_16x16x32_bf16 v[70:73], v[146:149], v[196:199], v[70:73]
	v_mfma_f32_16x16x32_bf16 v[66:69], v[154:157], v[196:199], v[66:69]
	v_mfma_f32_16x16x32_bf16 v[118:121], v[150:153], v[166:169], v[118:121]
	v_mfma_f32_16x16x32_bf16 v[114:117], v[158:161], v[166:169], v[114:117]
	v_mfma_f32_16x16x32_bf16 v[102:105], v[150:153], v[174:177], v[102:105]
	v_mfma_f32_16x16x32_bf16 v[98:101], v[158:161], v[174:177], v[98:101]
	v_mfma_f32_16x16x32_bf16 v[86:89], v[150:153], v[182:185], v[86:89]
	v_mfma_f32_16x16x32_bf16 v[82:85], v[158:161], v[182:185], v[82:85]
	v_mfma_f32_16x16x32_bf16 v[70:73], v[150:153], v[206:209], v[70:73]
	v_mfma_f32_16x16x32_bf16 v[66:69], v[158:161], v[206:209], v[66:69]
	s_setprio 0
	s_barrier
	s_add_i32 s47, s47, s33
	v_lshl_add_u64 v[210:211], s[28:29], 0, v[190:191]
	s_mov_b32 m0, s47
	ds_read_b128 v[162:165], v222 offset:16384
	ds_read_b128 v[166:169], v222 offset:17408
	ds_read_b128 v[170:173], v222 offset:18432
	ds_read_b128 v[174:177], v222 offset:19456
	ds_read_b128 v[178:181], v222 offset:20480
	ds_read_b128 v[182:185], v222 offset:21504
	ds_read_b128 v[196:199], v222 offset:22528
	ds_read_b128 v[206:209], v222 offset:23552
	global_load_lds_dwordx4 v[210:211], off
	s_add_i32 m0, s47, 0x2000
	s_add_u32 s52, s28, 0x80000
	v_lshl_add_u64 v[212:213], s[28:29], 0, v[200:201]
	s_addc_u32 s53, s29, 0
	s_add_i32 s47, s55, s33
	global_load_lds_dwordx4 v[212:213], off
	v_lshl_add_u64 v[214:215], s[52:53], 0, v[190:191]
	s_mov_b32 m0, s47
	v_lshl_add_u64 v[216:217], s[30:31], 0, v[188:189]
	global_load_lds_dwordx4 v[214:215], off
	s_add_i32 m0, s47, 0x2000
	v_lshl_add_u64 v[214:215], s[52:53], 0, v[200:201]
	global_load_lds_dwordx4 v[214:215], off
	s_mov_b32 m0, s34
	v_lshl_add_u64 v[214:215], s[30:31], 0, v[186:187]
	global_load_lds_dwordx4 v[214:215], off
	s_mov_b32 m0, s35
	s_nop 0
	global_load_lds_dwordx4 v[216:217], off
	s_setprio 1
	s_waitcnt vmcnt(8) lgkmcnt(0)
	s_barrier
	v_mfma_f32_16x16x32_bf16 v[62:65], v[130:133], v[162:165], v[62:65]
	v_mfma_f32_16x16x32_bf16 v[58:61], v[138:141], v[162:165], v[58:61]
	v_mfma_f32_16x16x32_bf16 v[46:49], v[130:133], v[170:173], v[46:49]
	v_mfma_f32_16x16x32_bf16 v[42:45], v[138:141], v[170:173], v[42:45]
	v_mfma_f32_16x16x32_bf16 v[30:33], v[130:133], v[178:181], v[30:33]
	v_mfma_f32_16x16x32_bf16 v[26:29], v[138:141], v[178:181], v[26:29]
	v_mfma_f32_16x16x32_bf16 v[14:17], v[130:133], v[196:199], v[14:17]
	v_mfma_f32_16x16x32_bf16 v[10:13], v[138:141], v[196:199], v[10:13]
	v_mfma_f32_16x16x32_bf16 v[62:65], v[134:137], v[166:169], v[62:65]
	v_mfma_f32_16x16x32_bf16 v[58:61], v[142:145], v[166:169], v[58:61]
	v_mfma_f32_16x16x32_bf16 v[46:49], v[134:137], v[174:177], v[46:49]
	v_mfma_f32_16x16x32_bf16 v[42:45], v[142:145], v[174:177], v[42:45]
	v_mfma_f32_16x16x32_bf16 v[30:33], v[134:137], v[182:185], v[30:33]
	v_mfma_f32_16x16x32_bf16 v[26:29], v[142:145], v[182:185], v[26:29]
	v_mfma_f32_16x16x32_bf16 v[14:17], v[134:137], v[206:209], v[14:17]
	v_mfma_f32_16x16x32_bf16 v[10:13], v[142:145], v[206:209], v[10:13]
	s_setprio 0
	s_setprio 1
	v_mfma_f32_16x16x32_bf16 v[54:57], v[146:149], v[162:165], v[54:57]
	v_mfma_f32_16x16x32_bf16 v[50:53], v[154:157], v[162:165], v[50:53]
	v_mfma_f32_16x16x32_bf16 v[38:41], v[146:149], v[170:173], v[38:41]
	v_mfma_f32_16x16x32_bf16 v[34:37], v[154:157], v[170:173], v[34:37]
	v_mfma_f32_16x16x32_bf16 v[22:25], v[146:149], v[178:181], v[22:25]
	v_mfma_f32_16x16x32_bf16 v[18:21], v[154:157], v[178:181], v[18:21]
	v_mfma_f32_16x16x32_bf16 v[6:9], v[146:149], v[196:199], v[6:9]
	v_mfma_f32_16x16x32_bf16 v[2:5], v[154:157], v[196:199], v[2:5]
	v_mfma_f32_16x16x32_bf16 v[54:57], v[150:153], v[166:169], v[54:57]
	v_mfma_f32_16x16x32_bf16 v[50:53], v[158:161], v[166:169], v[50:53]
	v_mfma_f32_16x16x32_bf16 v[38:41], v[150:153], v[174:177], v[38:41]
	v_mfma_f32_16x16x32_bf16 v[34:37], v[158:161], v[174:177], v[34:37]
	v_mfma_f32_16x16x32_bf16 v[22:25], v[150:153], v[182:185], v[22:25]
	v_mfma_f32_16x16x32_bf16 v[18:21], v[158:161], v[182:185], v[18:21]
	v_mfma_f32_16x16x32_bf16 v[6:9], v[150:153], v[206:209], v[6:9]
	v_mfma_f32_16x16x32_bf16 v[2:5], v[158:161], v[206:209], v[2:5]
	s_setprio 0
	s_barrier
	s_add_i32 s47, 0, 0x18000
	s_add_i32 s52, 0, 0x1c000
	v_add_u32_e32 v142, s47, v220
	v_add_u32_e32 v158, s52, v220
	ds_read_b128 v[130:133], v142
	ds_read_b128 v[134:137], v142 offset:1024
	ds_read_b128 v[138:141], v142 offset:2048
	ds_read_b128 v[142:145], v142 offset:3072
	ds_read_b128 v[146:149], v158
	ds_read_b128 v[150:153], v158 offset:1024
	ds_read_b128 v[154:157], v158 offset:2048
	ds_read_b128 v[158:161], v158 offset:3072
	s_add_u32 s30, s30, 0x80000
	s_addc_u32 s31, s31, 0
	s_mov_b32 m0, s36
	v_lshl_add_u64 v[218:219], s[30:31], 0, v[186:187]
	ds_read_b128 v[162:165], v222 offset:32768
	ds_read_b128 v[166:169], v222 offset:33792
	ds_read_b128 v[170:173], v222 offset:34816
	ds_read_b128 v[174:177], v222 offset:35840
	ds_read_b128 v[178:181], v222 offset:36864
	ds_read_b128 v[182:185], v222 offset:37888
	ds_read_b128 v[196:199], v222 offset:38912
	ds_read_b128 v[206:209], v222 offset:39936
	global_load_lds_dwordx4 v[218:219], off
	s_mov_b32 m0, s37
	v_lshl_add_u64 v[218:219], s[30:31], 0, v[188:189]
	global_load_lds_dwordx4 v[218:219], off
	s_setprio 1
	s_waitcnt vmcnt(8) lgkmcnt(0)
	s_barrier
	v_mfma_f32_16x16x32_bf16 v[126:129], v[130:133], v[162:165], v[126:129]
	v_mfma_f32_16x16x32_bf16 v[122:125], v[138:141], v[162:165], v[122:125]
	v_mfma_f32_16x16x32_bf16 v[110:113], v[130:133], v[170:173], v[110:113]
	v_mfma_f32_16x16x32_bf16 v[106:109], v[138:141], v[170:173], v[106:109]
	v_mfma_f32_16x16x32_bf16 v[94:97], v[130:133], v[178:181], v[94:97]
	v_mfma_f32_16x16x32_bf16 v[90:93], v[138:141], v[178:181], v[90:93]
	v_mfma_f32_16x16x32_bf16 v[78:81], v[130:133], v[196:199], v[78:81]
	v_mfma_f32_16x16x32_bf16 v[74:77], v[138:141], v[196:199], v[74:77]
	v_mfma_f32_16x16x32_bf16 v[126:129], v[134:137], v[166:169], v[126:129]
	v_mfma_f32_16x16x32_bf16 v[122:125], v[142:145], v[166:169], v[122:125]
	v_mfma_f32_16x16x32_bf16 v[110:113], v[134:137], v[174:177], v[110:113]
	v_mfma_f32_16x16x32_bf16 v[106:109], v[142:145], v[174:177], v[106:109]
	v_mfma_f32_16x16x32_bf16 v[94:97], v[134:137], v[182:185], v[94:97]
	v_mfma_f32_16x16x32_bf16 v[90:93], v[142:145], v[182:185], v[90:93]
	v_mfma_f32_16x16x32_bf16 v[78:81], v[134:137], v[206:209], v[78:81]
	v_mfma_f32_16x16x32_bf16 v[74:77], v[142:145], v[206:209], v[74:77]
	s_setprio 0
	s_setprio 1
	v_mfma_f32_16x16x32_bf16 v[118:121], v[146:149], v[162:165], v[118:121]
	v_mfma_f32_16x16x32_bf16 v[114:117], v[154:157], v[162:165], v[114:117]
	v_mfma_f32_16x16x32_bf16 v[102:105], v[146:149], v[170:173], v[102:105]
	v_mfma_f32_16x16x32_bf16 v[98:101], v[154:157], v[170:173], v[98:101]
	v_mfma_f32_16x16x32_bf16 v[86:89], v[146:149], v[178:181], v[86:89]
	v_mfma_f32_16x16x32_bf16 v[82:85], v[154:157], v[178:181], v[82:85]
	v_mfma_f32_16x16x32_bf16 v[70:73], v[146:149], v[196:199], v[70:73]
	v_mfma_f32_16x16x32_bf16 v[66:69], v[154:157], v[196:199], v[66:69]
	v_mfma_f32_16x16x32_bf16 v[118:121], v[150:153], v[166:169], v[118:121]
	v_mfma_f32_16x16x32_bf16 v[114:117], v[158:161], v[166:169], v[114:117]
	v_mfma_f32_16x16x32_bf16 v[102:105], v[150:153], v[174:177], v[102:105]
	v_mfma_f32_16x16x32_bf16 v[98:101], v[158:161], v[174:177], v[98:101]
	v_mfma_f32_16x16x32_bf16 v[86:89], v[150:153], v[182:185], v[86:89]
	v_mfma_f32_16x16x32_bf16 v[82:85], v[158:161], v[182:185], v[82:85]
	v_mfma_f32_16x16x32_bf16 v[70:73], v[150:153], v[206:209], v[70:73]
	v_mfma_f32_16x16x32_bf16 v[66:69], v[158:161], v[206:209], v[66:69]
	s_setprio 0
	s_barrier
	s_add_i32 s30, s47, s33
	v_lshl_add_u64 v[210:211], v[210:211], 0, s[58:59]
	s_mov_b32 m0, s30
	ds_read_b128 v[162:165], v222 offset:49152
	ds_read_b128 v[166:169], v222 offset:50176
	ds_read_b128 v[170:173], v222 offset:51200
	ds_read_b128 v[174:177], v222 offset:52224
	ds_read_b128 v[178:181], v222 offset:53248
	ds_read_b128 v[182:185], v222 offset:54272
	ds_read_b128 v[196:199], v222 offset:55296
	ds_read_b128 v[206:209], v222 offset:56320
	global_load_lds_dwordx4 v[210:211], off
	s_add_i32 m0, s30, 0x2000
	s_add_u32 s28, s28, 0x80080
	v_lshl_add_u64 v[210:211], v[212:213], 0, s[58:59]
	s_addc_u32 s29, s29, 0
	s_add_i32 s30, s52, s33
	global_load_lds_dwordx4 v[210:211], off
	s_mov_b32 m0, s30
	v_lshl_add_u64 v[210:211], s[28:29], 0, v[190:191]
	global_load_lds_dwordx4 v[210:211], off
	s_add_i32 m0, s30, 0x2000
	v_lshl_add_u64 v[210:211], s[28:29], 0, v[200:201]
	global_load_lds_dwordx4 v[210:211], off
	s_mov_b32 m0, s38
	v_lshl_add_u64 v[210:211], v[214:215], 0, s[58:59]
	global_load_lds_dwordx4 v[210:211], off
	s_mov_b32 m0, s39
	v_lshl_add_u64 v[210:211], v[216:217], 0, s[58:59]
	global_load_lds_dwordx4 v[210:211], off
	s_setprio 1
	s_waitcnt vmcnt(8) lgkmcnt(0)
	s_barrier
	v_mfma_f32_16x16x32_bf16 v[62:65], v[130:133], v[162:165], v[62:65]
	v_mfma_f32_16x16x32_bf16 v[58:61], v[138:141], v[162:165], v[58:61]
	v_mfma_f32_16x16x32_bf16 v[46:49], v[130:133], v[170:173], v[46:49]
	v_mfma_f32_16x16x32_bf16 v[42:45], v[138:141], v[170:173], v[42:45]
	v_mfma_f32_16x16x32_bf16 v[30:33], v[130:133], v[178:181], v[30:33]
	v_mfma_f32_16x16x32_bf16 v[26:29], v[138:141], v[178:181], v[26:29]
	v_mfma_f32_16x16x32_bf16 v[14:17], v[130:133], v[196:199], v[14:17]
	v_mfma_f32_16x16x32_bf16 v[10:13], v[138:141], v[196:199], v[10:13]
	v_mfma_f32_16x16x32_bf16 v[62:65], v[134:137], v[166:169], v[62:65]
	v_mfma_f32_16x16x32_bf16 v[58:61], v[142:145], v[166:169], v[58:61]
	v_mfma_f32_16x16x32_bf16 v[46:49], v[134:137], v[174:177], v[46:49]
	v_mfma_f32_16x16x32_bf16 v[42:45], v[142:145], v[174:177], v[42:45]
	v_mfma_f32_16x16x32_bf16 v[30:33], v[134:137], v[182:185], v[30:33]
	v_mfma_f32_16x16x32_bf16 v[26:29], v[142:145], v[182:185], v[26:29]
	v_mfma_f32_16x16x32_bf16 v[14:17], v[134:137], v[206:209], v[14:17]
	v_mfma_f32_16x16x32_bf16 v[10:13], v[142:145], v[206:209], v[10:13]
	s_setprio 0
	s_setprio 1
	v_mfma_f32_16x16x32_bf16 v[54:57], v[146:149], v[162:165], v[54:57]
	v_mfma_f32_16x16x32_bf16 v[50:53], v[154:157], v[162:165], v[50:53]
	v_mfma_f32_16x16x32_bf16 v[38:41], v[146:149], v[170:173], v[38:41]
	v_mfma_f32_16x16x32_bf16 v[34:37], v[154:157], v[170:173], v[34:37]
	v_mfma_f32_16x16x32_bf16 v[22:25], v[146:149], v[178:181], v[22:25]
	v_mfma_f32_16x16x32_bf16 v[18:21], v[154:157], v[178:181], v[18:21]
	v_mfma_f32_16x16x32_bf16 v[6:9], v[146:149], v[196:199], v[6:9]
	v_mfma_f32_16x16x32_bf16 v[2:5], v[154:157], v[196:199], v[2:5]
	v_mfma_f32_16x16x32_bf16 v[54:57], v[150:153], v[166:169], v[54:57]
	v_mfma_f32_16x16x32_bf16 v[50:53], v[158:161], v[166:169], v[50:53]
	v_mfma_f32_16x16x32_bf16 v[38:41], v[150:153], v[174:177], v[38:41]
	v_mfma_f32_16x16x32_bf16 v[34:37], v[158:161], v[174:177], v[34:37]
	v_mfma_f32_16x16x32_bf16 v[22:25], v[150:153], v[182:185], v[22:25]
	v_mfma_f32_16x16x32_bf16 v[18:21], v[158:161], v[182:185], v[18:21]
	v_mfma_f32_16x16x32_bf16 v[6:9], v[150:153], v[206:209], v[6:9]
	v_mfma_f32_16x16x32_bf16 v[2:5], v[158:161], v[206:209], v[2:5]
	s_setprio 0
	s_barrier
	s_add_i32 s46, s46, 2
	s_add_u32 s26, s26, 0x100
	s_addc_u32 s27, s27, 0
	s_add_u32 s42, s42, 0x100
	s_addc_u32 s43, s43, 0
	s_cmp_gt_u32 s46, 29
	s_cbranch_scc0 .LBB0_772

.LBB0_799:
	s_ashr_i32 s11, s10, 31
	s_lshl_b64 s[14:15], s[10:11], 20
	s_add_u32 s14, s69, s14
	s_addc_u32 s15, s77, s15
	s_and_b64 s[16:17], s[12:13], exec
	s_cselect_b32 s11, s15, s25
	s_cselect_b32 s21, s14, s24
	s_ashr_i32 s9, s8, 31
	s_lshl_b64 s[16:17], s[8:9], 20
	v_readlane_b32 s0, v254, 42
	v_readlane_b32 s1, v254, 43
	s_add_u32 s16, s0, s16
	s_addc_u32 s17, s1, s17
	s_and_b64 s[28:29], s[12:13], exec
	s_cselect_b32 s9, s17, s27
	s_cselect_b32 s47, s16, s26
	s_add_u32 s24, s24, 0x80080
	s_addc_u32 s25, s25, 0
	s_add_u32 s52, s26, 0x100
	s_addc_u32 s53, s27, 0
	s_mov_b32 s55, -2
	v_readlane_b32 s56, v255, 49
	s_nop 3
	s_cmp_eq_u32 s56, 5
	v_writelane_b32 v255, 5, 49
	s_cbranch_scc0 .Ltrip0_strict_4
	s_add_u32 s26, s24, 0xfff80080
	s_addc_u32 s27, s25, -1
	s_add_i32 s56, 0, 0x10000
	s_cmp_eq_u32 s55, 28
	s_cselect_b32 s29, s11, s27
	s_cselect_b32 s28, s21, s26
	s_cselect_b32 s27, s9, s53
	s_cselect_b32 s26, s47, s52
	s_add_i32 s60, 0, 0x14000
	v_add_u32_e32 v142, s56, v238
	v_add_u32_e32 v158, s60, v238
	ds_read_b128 v[130:133], v142
	ds_read_b128 v[134:137], v142 offset:1024
	ds_read_b128 v[138:141], v142 offset:2048
	ds_read_b128 v[142:145], v142 offset:3072
	ds_read_b128 v[146:149], v158
	ds_read_b128 v[150:153], v158 offset:1024
	ds_read_b128 v[154:157], v158 offset:2048
	ds_read_b128 v[158:161], v158 offset:3072
	v_lshl_add_u64 v[210:211], s[24:25], 0, v[206:207]
	s_add_i32 m0, s23, 0xc000
	ds_read_b128 v[162:165], v240
	ds_read_b128 v[166:169], v240 offset:1024
	ds_read_b128 v[170:173], v240 offset:2048
	ds_read_b128 v[174:177], v240 offset:3072
	ds_read_b128 v[178:181], v240 offset:4096
	ds_read_b128 v[182:185], v240 offset:5120
	ds_read_b128 v[186:189], v240 offset:6144
	ds_read_b128 v[196:199], v240 offset:7168
	global_load_lds_dwordx4 v[210:211], off
	s_add_i32 m0, s23, 0xe000
	v_lshl_add_u64 v[210:211], s[24:25], 0, v[208:209]
	global_load_lds_dwordx4 v[210:211], off
	s_setprio 1
	s_waitcnt vmcnt(24) lgkmcnt(0)
	s_barrier
	v_mfma_f32_16x16x32_bf16 v[126:129], v[130:133], v[162:165], 0
	v_mfma_f32_16x16x32_bf16 v[122:125], v[138:141], v[162:165], 0
	v_mfma_f32_16x16x32_bf16 v[110:113], v[130:133], v[170:173], 0
	v_mfma_f32_16x16x32_bf16 v[106:109], v[138:141], v[170:173], 0
	v_mfma_f32_16x16x32_bf16 v[98:101], v[130:133], v[178:181], 0
	v_mfma_f32_16x16x32_bf16 v[90:93], v[138:141], v[178:181], 0
	v_mfma_f32_16x16x32_bf16 v[82:85], v[130:133], v[186:189], 0
	v_mfma_f32_16x16x32_bf16 v[74:77], v[138:141], v[186:189], 0
	v_mfma_f32_16x16x32_bf16 v[126:129], v[134:137], v[166:169], v[126:129]
	v_mfma_f32_16x16x32_bf16 v[122:125], v[142:145], v[166:169], v[122:125]
	v_mfma_f32_16x16x32_bf16 v[110:113], v[134:137], v[174:177], v[110:113]
	v_mfma_f32_16x16x32_bf16 v[106:109], v[142:145], v[174:177], v[106:109]
	v_mfma_f32_16x16x32_bf16 v[98:101], v[134:137], v[182:185], v[98:101]
	v_mfma_f32_16x16x32_bf16 v[90:93], v[142:145], v[182:185], v[90:93]
	v_mfma_f32_16x16x32_bf16 v[82:85], v[134:137], v[196:199], v[82:85]
	v_mfma_f32_16x16x32_bf16 v[74:77], v[142:145], v[196:199], v[74:77]
	s_setprio 0
	s_setprio 1
	v_mfma_f32_16x16x32_bf16 v[118:121], v[146:149], v[162:165], 0
	v_mfma_f32_16x16x32_bf16 v[114:117], v[154:157], v[162:165], 0
	v_mfma_f32_16x16x32_bf16 v[102:105], v[146:149], v[170:173], 0
	v_mfma_f32_16x16x32_bf16 v[94:97], v[154:157], v[170:173], 0
	v_mfma_f32_16x16x32_bf16 v[86:89], v[146:149], v[178:181], 0
	v_mfma_f32_16x16x32_bf16 v[78:81], v[154:157], v[178:181], 0
	v_mfma_f32_16x16x32_bf16 v[70:73], v[146:149], v[186:189], 0
	v_mfma_f32_16x16x32_bf16 v[66:69], v[154:157], v[186:189], 0
	v_mfma_f32_16x16x32_bf16 v[118:121], v[150:153], v[166:169], v[118:121]
	v_mfma_f32_16x16x32_bf16 v[114:117], v[158:161], v[166:169], v[114:117]
	v_mfma_f32_16x16x32_bf16 v[102:105], v[150:153], v[174:177], v[102:105]
	v_mfma_f32_16x16x32_bf16 v[94:97], v[158:161], v[174:177], v[94:97]
	v_mfma_f32_16x16x32_bf16 v[86:89], v[150:153], v[182:185], v[86:89]
	v_mfma_f32_16x16x32_bf16 v[78:81], v[158:161], v[182:185], v[78:81]
	v_mfma_f32_16x16x32_bf16 v[70:73], v[150:153], v[196:199], v[70:73]
	v_mfma_f32_16x16x32_bf16 v[66:69], v[158:161], v[196:199], v[66:69]
	s_barrier
	s_setprio 0
	s_add_i32 s56, s56, s34
	v_lshl_add_u64 v[210:211], s[26:27], 0, v[190:191]
	s_mov_b32 m0, s56
	ds_read_b128 v[162:165], v240 offset:16384
	ds_read_b128 v[166:169], v240 offset:17408
	ds_read_b128 v[170:173], v240 offset:18432
	ds_read_b128 v[174:177], v240 offset:19456
	ds_read_b128 v[178:181], v240 offset:20480
	ds_read_b128 v[182:185], v240 offset:21504
	ds_read_b128 v[186:189], v240 offset:22528
	ds_read_b128 v[196:199], v240 offset:23552
	global_load_lds_dwordx4 v[210:211], off
	s_add_i32 m0, s56, 0x2000
	s_add_u32 s56, s26, 0x80000
	v_lshl_add_u64 v[212:213], s[26:27], 0, v[204:205]
	s_addc_u32 s57, s27, 0
	s_add_i32 s60, s60, s34
	global_load_lds_dwordx4 v[212:213], off
	v_lshl_add_u64 v[214:215], s[56:57], 0, v[190:191]
	s_mov_b32 m0, s60
	v_lshl_add_u64 v[216:217], s[28:29], 0, v[202:203]
	global_load_lds_dwordx4 v[214:215], off
	s_add_i32 m0, s60, 0x2000
	v_lshl_add_u64 v[214:215], s[56:57], 0, v[204:205]
	global_load_lds_dwordx4 v[214:215], off
	s_mov_b32 m0, s23
	v_lshl_add_u64 v[214:215], s[28:29], 0, v[200:201]
	global_load_lds_dwordx4 v[214:215], off
	s_mov_b32 m0, s35
	s_nop 0
	global_load_lds_dwordx4 v[216:217], off
	s_setprio 1
	s_waitcnt vmcnt(24) lgkmcnt(0)
	s_barrier
	v_mfma_f32_16x16x32_bf16 v[62:65], v[130:133], v[162:165], 0
	v_mfma_f32_16x16x32_bf16 v[58:61], v[138:141], v[162:165], 0
	v_mfma_f32_16x16x32_bf16 v[50:53], v[130:133], v[170:173], 0
	v_mfma_f32_16x16x32_bf16 v[42:45], v[138:141], v[170:173], 0
	v_mfma_f32_16x16x32_bf16 v[34:37], v[130:133], v[178:181], 0
	v_mfma_f32_16x16x32_bf16 v[26:29], v[138:141], v[178:181], 0
	v_mfma_f32_16x16x32_bf16 v[18:21], v[130:133], v[186:189], 0
	v_mfma_f32_16x16x32_bf16 v[10:13], v[138:141], v[186:189], 0
	v_mfma_f32_16x16x32_bf16 v[62:65], v[134:137], v[166:169], v[62:65]
	v_mfma_f32_16x16x32_bf16 v[58:61], v[142:145], v[166:169], v[58:61]
	v_mfma_f32_16x16x32_bf16 v[50:53], v[134:137], v[174:177], v[50:53]
	v_mfma_f32_16x16x32_bf16 v[42:45], v[142:145], v[174:177], v[42:45]
	v_mfma_f32_16x16x32_bf16 v[34:37], v[134:137], v[182:185], v[34:37]
	v_mfma_f32_16x16x32_bf16 v[26:29], v[142:145], v[182:185], v[26:29]
	v_mfma_f32_16x16x32_bf16 v[18:21], v[134:137], v[196:199], v[18:21]
	v_mfma_f32_16x16x32_bf16 v[10:13], v[142:145], v[196:199], v[10:13]
	s_setprio 0
	s_setprio 1
	v_mfma_f32_16x16x32_bf16 v[54:57], v[146:149], v[162:165], 0
	v_mfma_f32_16x16x32_bf16 v[46:49], v[154:157], v[162:165], 0
	v_mfma_f32_16x16x32_bf16 v[38:41], v[146:149], v[170:173], 0
	v_mfma_f32_16x16x32_bf16 v[30:33], v[154:157], v[170:173], 0
	v_mfma_f32_16x16x32_bf16 v[22:25], v[146:149], v[178:181], 0
	v_mfma_f32_16x16x32_bf16 v[14:17], v[154:157], v[178:181], 0
	v_mfma_f32_16x16x32_bf16 v[6:9], v[146:149], v[186:189], 0
	v_mfma_f32_16x16x32_bf16 v[2:5], v[154:157], v[186:189], 0
	v_mfma_f32_16x16x32_bf16 v[54:57], v[150:153], v[166:169], v[54:57]
	v_mfma_f32_16x16x32_bf16 v[46:49], v[158:161], v[166:169], v[46:49]
	v_mfma_f32_16x16x32_bf16 v[38:41], v[150:153], v[174:177], v[38:41]
	v_mfma_f32_16x16x32_bf16 v[30:33], v[158:161], v[174:177], v[30:33]
	v_mfma_f32_16x16x32_bf16 v[22:25], v[150:153], v[182:185], v[22:25]
	v_mfma_f32_16x16x32_bf16 v[14:17], v[158:161], v[182:185], v[14:17]
	v_mfma_f32_16x16x32_bf16 v[6:9], v[150:153], v[196:199], v[6:9]
	v_mfma_f32_16x16x32_bf16 v[2:5], v[158:161], v[196:199], v[2:5]
	s_barrier
	s_setprio 0
	s_add_i32 s56, 0, 0x18000
	s_add_i32 s57, 0, 0x1c000
	v_add_u32_e32 v142, s56, v238
	v_add_u32_e32 v158, s57, v238
	ds_read_b128 v[130:133], v142
	ds_read_b128 v[134:137], v142 offset:1024
	ds_read_b128 v[138:141], v142 offset:2048
	ds_read_b128 v[142:145], v142 offset:3072
	ds_read_b128 v[146:149], v158
	ds_read_b128 v[150:153], v158 offset:1024
	ds_read_b128 v[154:157], v158 offset:2048
	ds_read_b128 v[158:161], v158 offset:3072
	s_add_u32 s28, s28, 0x80000
	s_addc_u32 s29, s29, 0
	s_mov_b32 m0, s41
	v_lshl_add_u64 v[218:219], s[28:29], 0, v[200:201]
	ds_read_b128 v[162:165], v240 offset:32768
	ds_read_b128 v[166:169], v240 offset:33792
	ds_read_b128 v[170:173], v240 offset:34816
	ds_read_b128 v[174:177], v240 offset:35840
	ds_read_b128 v[178:181], v240 offset:36864
	ds_read_b128 v[182:185], v240 offset:37888
	ds_read_b128 v[186:189], v240 offset:38912
	ds_read_b128 v[196:199], v240 offset:39936
	global_load_lds_dwordx4 v[218:219], off
	s_mov_b32 m0, s42
	v_lshl_add_u64 v[218:219], s[28:29], 0, v[202:203]
	global_load_lds_dwordx4 v[218:219], off
	s_setprio 1
	s_waitcnt vmcnt(8) lgkmcnt(0)
	s_barrier
	v_mfma_f32_16x16x32_bf16 v[126:129], v[130:133], v[162:165], v[126:129]
	v_mfma_f32_16x16x32_bf16 v[122:125], v[138:141], v[162:165], v[122:125]
	v_mfma_f32_16x16x32_bf16 v[110:113], v[130:133], v[170:173], v[110:113]
	v_mfma_f32_16x16x32_bf16 v[106:109], v[138:141], v[170:173], v[106:109]
	v_mfma_f32_16x16x32_bf16 v[98:101], v[130:133], v[178:181], v[98:101]
	v_mfma_f32_16x16x32_bf16 v[90:93], v[138:141], v[178:181], v[90:93]
	v_mfma_f32_16x16x32_bf16 v[82:85], v[130:133], v[186:189], v[82:85]
	v_mfma_f32_16x16x32_bf16 v[74:77], v[138:141], v[186:189], v[74:77]
	v_mfma_f32_16x16x32_bf16 v[126:129], v[134:137], v[166:169], v[126:129]
	v_mfma_f32_16x16x32_bf16 v[122:125], v[142:145], v[166:169], v[122:125]
	v_mfma_f32_16x16x32_bf16 v[110:113], v[134:137], v[174:177], v[110:113]
	v_mfma_f32_16x16x32_bf16 v[106:109], v[142:145], v[174:177], v[106:109]
	v_mfma_f32_16x16x32_bf16 v[98:101], v[134:137], v[182:185], v[98:101]
	v_mfma_f32_16x16x32_bf16 v[90:93], v[142:145], v[182:185], v[90:93]
	v_mfma_f32_16x16x32_bf16 v[82:85], v[134:137], v[196:199], v[82:85]
	v_mfma_f32_16x16x32_bf16 v[74:77], v[142:145], v[196:199], v[74:77]
	s_setprio 0
	s_setprio 1
	v_mfma_f32_16x16x32_bf16 v[118:121], v[146:149], v[162:165], v[118:121]
	v_mfma_f32_16x16x32_bf16 v[114:117], v[154:157], v[162:165], v[114:117]
	v_mfma_f32_16x16x32_bf16 v[102:105], v[146:149], v[170:173], v[102:105]
	v_mfma_f32_16x16x32_bf16 v[94:97], v[154:157], v[170:173], v[94:97]
	v_mfma_f32_16x16x32_bf16 v[86:89], v[146:149], v[178:181], v[86:89]
	v_mfma_f32_16x16x32_bf16 v[78:81], v[154:157], v[178:181], v[78:81]
	v_mfma_f32_16x16x32_bf16 v[70:73], v[146:149], v[186:189], v[70:73]
	v_mfma_f32_16x16x32_bf16 v[66:69], v[154:157], v[186:189], v[66:69]
	v_mfma_f32_16x16x32_bf16 v[118:121], v[150:153], v[166:169], v[118:121]
	v_mfma_f32_16x16x32_bf16 v[114:117], v[158:161], v[166:169], v[114:117]
	v_mfma_f32_16x16x32_bf16 v[102:105], v[150:153], v[174:177], v[102:105]
	v_mfma_f32_16x16x32_bf16 v[94:97], v[158:161], v[174:177], v[94:97]
	v_mfma_f32_16x16x32_bf16 v[86:89], v[150:153], v[182:185], v[86:89]
	v_mfma_f32_16x16x32_bf16 v[78:81], v[158:161], v[182:185], v[78:81]
	v_mfma_f32_16x16x32_bf16 v[70:73], v[150:153], v[196:199], v[70:73]
	v_mfma_f32_16x16x32_bf16 v[66:69], v[158:161], v[196:199], v[66:69]
	s_barrier
	s_setprio 0
	s_add_i32 s28, s56, s34
	v_lshl_add_u64 v[210:211], v[210:211], 0, s[58:59]
	s_mov_b32 m0, s28
	ds_read_b128 v[162:165], v240 offset:49152
	ds_read_b128 v[166:169], v240 offset:50176
	ds_read_b128 v[170:173], v240 offset:51200
	ds_read_b128 v[174:177], v240 offset:52224
	ds_read_b128 v[178:181], v240 offset:53248
	ds_read_b128 v[182:185], v240 offset:54272
	ds_read_b128 v[186:189], v240 offset:55296
	ds_read_b128 v[196:199], v240 offset:56320
	global_load_lds_dwordx4 v[210:211], off
	s_add_i32 m0, s28, 0x2000
	s_add_u32 s26, s26, 0x80080
	v_lshl_add_u64 v[210:211], v[212:213], 0, s[58:59]
	s_addc_u32 s27, s27, 0
	s_add_i32 s28, s57, s34
	global_load_lds_dwordx4 v[210:211], off
	s_mov_b32 m0, s28
	v_lshl_add_u64 v[210:211], s[26:27], 0, v[190:191]
	global_load_lds_dwordx4 v[210:211], off
	s_add_i32 m0, s28, 0x2000
	v_lshl_add_u64 v[210:211], s[26:27], 0, v[204:205]
	global_load_lds_dwordx4 v[210:211], off
	s_mov_b32 m0, s43
	v_lshl_add_u64 v[210:211], v[214:215], 0, s[58:59]
	global_load_lds_dwordx4 v[210:211], off
	s_mov_b32 m0, s46
	v_lshl_add_u64 v[210:211], v[216:217], 0, s[58:59]
	global_load_lds_dwordx4 v[210:211], off
	s_setprio 1
	s_waitcnt vmcnt(8) lgkmcnt(0)
	s_barrier
	v_mfma_f32_16x16x32_bf16 v[62:65], v[130:133], v[162:165], v[62:65]
	v_mfma_f32_16x16x32_bf16 v[58:61], v[138:141], v[162:165], v[58:61]
	v_mfma_f32_16x16x32_bf16 v[50:53], v[130:133], v[170:173], v[50:53]
	v_mfma_f32_16x16x32_bf16 v[42:45], v[138:141], v[170:173], v[42:45]
	v_mfma_f32_16x16x32_bf16 v[34:37], v[130:133], v[178:181], v[34:37]
	v_mfma_f32_16x16x32_bf16 v[26:29], v[138:141], v[178:181], v[26:29]
	v_mfma_f32_16x16x32_bf16 v[18:21], v[130:133], v[186:189], v[18:21]
	v_mfma_f32_16x16x32_bf16 v[10:13], v[138:141], v[186:189], v[10:13]
	v_mfma_f32_16x16x32_bf16 v[62:65], v[134:137], v[166:169], v[62:65]
	v_mfma_f32_16x16x32_bf16 v[58:61], v[142:145], v[166:169], v[58:61]
	v_mfma_f32_16x16x32_bf16 v[50:53], v[134:137], v[174:177], v[50:53]
	v_mfma_f32_16x16x32_bf16 v[42:45], v[142:145], v[174:177], v[42:45]
	v_mfma_f32_16x16x32_bf16 v[34:37], v[134:137], v[182:185], v[34:37]
	v_mfma_f32_16x16x32_bf16 v[26:29], v[142:145], v[182:185], v[26:29]
	v_mfma_f32_16x16x32_bf16 v[18:21], v[134:137], v[196:199], v[18:21]
	v_mfma_f32_16x16x32_bf16 v[10:13], v[142:145], v[196:199], v[10:13]
	s_setprio 0
	s_setprio 1
	v_mfma_f32_16x16x32_bf16 v[54:57], v[146:149], v[162:165], v[54:57]
	v_mfma_f32_16x16x32_bf16 v[46:49], v[154:157], v[162:165], v[46:49]
	v_mfma_f32_16x16x32_bf16 v[38:41], v[146:149], v[170:173], v[38:41]
	v_mfma_f32_16x16x32_bf16 v[30:33], v[154:157], v[170:173], v[30:33]
	v_mfma_f32_16x16x32_bf16 v[22:25], v[146:149], v[178:181], v[22:25]
	v_mfma_f32_16x16x32_bf16 v[14:17], v[154:157], v[178:181], v[14:17]
	v_mfma_f32_16x16x32_bf16 v[6:9], v[146:149], v[186:189], v[6:9]
	v_mfma_f32_16x16x32_bf16 v[2:5], v[154:157], v[186:189], v[2:5]
	v_mfma_f32_16x16x32_bf16 v[54:57], v[150:153], v[166:169], v[54:57]
	v_mfma_f32_16x16x32_bf16 v[46:49], v[158:161], v[166:169], v[46:49]
	v_mfma_f32_16x16x32_bf16 v[38:41], v[150:153], v[174:177], v[38:41]
	v_mfma_f32_16x16x32_bf16 v[30:33], v[158:161], v[174:177], v[30:33]
	v_mfma_f32_16x16x32_bf16 v[22:25], v[150:153], v[182:185], v[22:25]
	v_mfma_f32_16x16x32_bf16 v[14:17], v[158:161], v[182:185], v[14:17]
	v_mfma_f32_16x16x32_bf16 v[6:9], v[150:153], v[196:199], v[6:9]
	v_mfma_f32_16x16x32_bf16 v[2:5], v[158:161], v[196:199], v[2:5]
	s_barrier
	s_setprio 0
	s_add_i32 s55, s55, 2
	s_add_u32 s24, s24, 0x100
	s_addc_u32 s25, s25, 0
	s_add_u32 s52, s52, 0x100
	s_addc_u32 s53, s53, 0
	s_cmp_gt_u32 s55, 29
	s_cbranch_scc1 .Lpeel_done_4
	s_branch .LBB0_800
.Ltrip0_strict_4:
	s_add_u32 s26, s24, 0xfff80080
	s_addc_u32 s27, s25, -1
	s_add_i32 s56, 0, 0x10000
	s_cmp_eq_u32 s55, 28
	s_cselect_b32 s29, s11, s27
	s_cselect_b32 s28, s21, s26
	s_cselect_b32 s27, s9, s53
	s_cselect_b32 s26, s47, s52
	s_add_i32 s60, 0, 0x14000
	v_add_u32_e32 v142, s56, v238
	v_add_u32_e32 v158, s60, v238
	ds_read_b128 v[130:133], v142
	ds_read_b128 v[134:137], v142 offset:1024
	ds_read_b128 v[138:141], v142 offset:2048
	ds_read_b128 v[142:145], v142 offset:3072
	ds_read_b128 v[146:149], v158
	ds_read_b128 v[150:153], v158 offset:1024
	ds_read_b128 v[154:157], v158 offset:2048
	ds_read_b128 v[158:161], v158 offset:3072
	v_lshl_add_u64 v[210:211], s[24:25], 0, v[206:207]
	s_add_i32 m0, s23, 0xc000
	ds_read_b128 v[162:165], v240
	ds_read_b128 v[166:169], v240 offset:1024
	ds_read_b128 v[170:173], v240 offset:2048
	ds_read_b128 v[174:177], v240 offset:3072
	ds_read_b128 v[178:181], v240 offset:4096
	ds_read_b128 v[182:185], v240 offset:5120
	ds_read_b128 v[186:189], v240 offset:6144
	ds_read_b128 v[196:199], v240 offset:7168
	global_load_lds_dwordx4 v[210:211], off
	s_add_i32 m0, s23, 0xe000
	v_lshl_add_u64 v[210:211], s[24:25], 0, v[208:209]
	global_load_lds_dwordx4 v[210:211], off
	s_setprio 1
	s_waitcnt vmcnt(8) lgkmcnt(0)
	s_barrier
	v_mfma_f32_16x16x32_bf16 v[126:129], v[130:133], v[162:165], 0
	v_mfma_f32_16x16x32_bf16 v[122:125], v[138:141], v[162:165], 0
	v_mfma_f32_16x16x32_bf16 v[110:113], v[130:133], v[170:173], 0
	v_mfma_f32_16x16x32_bf16 v[106:109], v[138:141], v[170:173], 0
	v_mfma_f32_16x16x32_bf16 v[98:101], v[130:133], v[178:181], 0
	v_mfma_f32_16x16x32_bf16 v[90:93], v[138:141], v[178:181], 0
	v_mfma_f32_16x16x32_bf16 v[82:85], v[130:133], v[186:189], 0
	v_mfma_f32_16x16x32_bf16 v[74:77], v[138:141], v[186:189], 0
	v_mfma_f32_16x16x32_bf16 v[126:129], v[134:137], v[166:169], v[126:129]
	v_mfma_f32_16x16x32_bf16 v[122:125], v[142:145], v[166:169], v[122:125]
	v_mfma_f32_16x16x32_bf16 v[110:113], v[134:137], v[174:177], v[110:113]
	v_mfma_f32_16x16x32_bf16 v[106:109], v[142:145], v[174:177], v[106:109]
	v_mfma_f32_16x16x32_bf16 v[98:101], v[134:137], v[182:185], v[98:101]
	v_mfma_f32_16x16x32_bf16 v[90:93], v[142:145], v[182:185], v[90:93]
	v_mfma_f32_16x16x32_bf16 v[82:85], v[134:137], v[196:199], v[82:85]
	v_mfma_f32_16x16x32_bf16 v[74:77], v[142:145], v[196:199], v[74:77]
	s_setprio 0
	s_setprio 1
	v_mfma_f32_16x16x32_bf16 v[118:121], v[146:149], v[162:165], 0
	v_mfma_f32_16x16x32_bf16 v[114:117], v[154:157], v[162:165], 0
	v_mfma_f32_16x16x32_bf16 v[102:105], v[146:149], v[170:173], 0
	v_mfma_f32_16x16x32_bf16 v[94:97], v[154:157], v[170:173], 0
	v_mfma_f32_16x16x32_bf16 v[86:89], v[146:149], v[178:181], 0
	v_mfma_f32_16x16x32_bf16 v[78:81], v[154:157], v[178:181], 0
	v_mfma_f32_16x16x32_bf16 v[70:73], v[146:149], v[186:189], 0
	v_mfma_f32_16x16x32_bf16 v[66:69], v[154:157], v[186:189], 0
	v_mfma_f32_16x16x32_bf16 v[118:121], v[150:153], v[166:169], v[118:121]
	v_mfma_f32_16x16x32_bf16 v[114:117], v[158:161], v[166:169], v[114:117]
	v_mfma_f32_16x16x32_bf16 v[102:105], v[150:153], v[174:177], v[102:105]
	v_mfma_f32_16x16x32_bf16 v[94:97], v[158:161], v[174:177], v[94:97]
	v_mfma_f32_16x16x32_bf16 v[86:89], v[150:153], v[182:185], v[86:89]
	v_mfma_f32_16x16x32_bf16 v[78:81], v[158:161], v[182:185], v[78:81]
	v_mfma_f32_16x16x32_bf16 v[70:73], v[150:153], v[196:199], v[70:73]
	v_mfma_f32_16x16x32_bf16 v[66:69], v[158:161], v[196:199], v[66:69]
	s_barrier
	s_setprio 0
	s_add_i32 s56, s56, s34
	v_lshl_add_u64 v[210:211], s[26:27], 0, v[190:191]
	s_mov_b32 m0, s56
	ds_read_b128 v[162:165], v240 offset:16384
	ds_read_b128 v[166:169], v240 offset:17408
	ds_read_b128 v[170:173], v240 offset:18432
	ds_read_b128 v[174:177], v240 offset:19456
	ds_read_b128 v[178:181], v240 offset:20480
	ds_read_b128 v[182:185], v240 offset:21504
	ds_read_b128 v[186:189], v240 offset:22528
	ds_read_b128 v[196:199], v240 offset:23552
	global_load_lds_dwordx4 v[210:211], off
	s_add_i32 m0, s56, 0x2000
	s_add_u32 s56, s26, 0x80000
	v_lshl_add_u64 v[212:213], s[26:27], 0, v[204:205]
	s_addc_u32 s57, s27, 0
	s_add_i32 s60, s60, s34
	global_load_lds_dwordx4 v[212:213], off
	v_lshl_add_u64 v[214:215], s[56:57], 0, v[190:191]
	s_mov_b32 m0, s60
	v_lshl_add_u64 v[216:217], s[28:29], 0, v[202:203]
	global_load_lds_dwordx4 v[214:215], off
	s_add_i32 m0, s60, 0x2000
	v_lshl_add_u64 v[214:215], s[56:57], 0, v[204:205]
	global_load_lds_dwordx4 v[214:215], off
	s_mov_b32 m0, s23
	v_lshl_add_u64 v[214:215], s[28:29], 0, v[200:201]
	global_load_lds_dwordx4 v[214:215], off
	s_mov_b32 m0, s35
	s_nop 0
	global_load_lds_dwordx4 v[216:217], off
	s_setprio 1
	s_waitcnt vmcnt(8) lgkmcnt(0)
	s_barrier
	v_mfma_f32_16x16x32_bf16 v[62:65], v[130:133], v[162:165], 0
	v_mfma_f32_16x16x32_bf16 v[58:61], v[138:141], v[162:165], 0
	v_mfma_f32_16x16x32_bf16 v[50:53], v[130:133], v[170:173], 0
	v_mfma_f32_16x16x32_bf16 v[42:45], v[138:141], v[170:173], 0
	v_mfma_f32_16x16x32_bf16 v[34:37], v[130:133], v[178:181], 0
	v_mfma_f32_16x16x32_bf16 v[26:29], v[138:141], v[178:181], 0
	v_mfma_f32_16x16x32_bf16 v[18:21], v[130:133], v[186:189], 0
	v_mfma_f32_16x16x32_bf16 v[10:13], v[138:141], v[186:189], 0
	v_mfma_f32_16x16x32_bf16 v[62:65], v[134:137], v[166:169], v[62:65]
	v_mfma_f32_16x16x32_bf16 v[58:61], v[142:145], v[166:169], v[58:61]
	v_mfma_f32_16x16x32_bf16 v[50:53], v[134:137], v[174:177], v[50:53]
	v_mfma_f32_16x16x32_bf16 v[42:45], v[142:145], v[174:177], v[42:45]
	v_mfma_f32_16x16x32_bf16 v[34:37], v[134:137], v[182:185], v[34:37]
	v_mfma_f32_16x16x32_bf16 v[26:29], v[142:145], v[182:185], v[26:29]
	v_mfma_f32_16x16x32_bf16 v[18:21], v[134:137], v[196:199], v[18:21]
	v_mfma_f32_16x16x32_bf16 v[10:13], v[142:145], v[196:199], v[10:13]
	s_setprio 0
	s_setprio 1
	v_mfma_f32_16x16x32_bf16 v[54:57], v[146:149], v[162:165], 0
	v_mfma_f32_16x16x32_bf16 v[46:49], v[154:157], v[162:165], 0
	v_mfma_f32_16x16x32_bf16 v[38:41], v[146:149], v[170:173], 0
	v_mfma_f32_16x16x32_bf16 v[30:33], v[154:157], v[170:173], 0
	v_mfma_f32_16x16x32_bf16 v[22:25], v[146:149], v[178:181], 0
	v_mfma_f32_16x16x32_bf16 v[14:17], v[154:157], v[178:181], 0
	v_mfma_f32_16x16x32_bf16 v[6:9], v[146:149], v[186:189], 0
	v_mfma_f32_16x16x32_bf16 v[2:5], v[154:157], v[186:189], 0
	v_mfma_f32_16x16x32_bf16 v[54:57], v[150:153], v[166:169], v[54:57]
	v_mfma_f32_16x16x32_bf16 v[46:49], v[158:161], v[166:169], v[46:49]
	v_mfma_f32_16x16x32_bf16 v[38:41], v[150:153], v[174:177], v[38:41]
	v_mfma_f32_16x16x32_bf16 v[30:33], v[158:161], v[174:177], v[30:33]
	v_mfma_f32_16x16x32_bf16 v[22:25], v[150:153], v[182:185], v[22:25]
	v_mfma_f32_16x16x32_bf16 v[14:17], v[158:161], v[182:185], v[14:17]
	v_mfma_f32_16x16x32_bf16 v[6:9], v[150:153], v[196:199], v[6:9]
	v_mfma_f32_16x16x32_bf16 v[2:5], v[158:161], v[196:199], v[2:5]
	s_barrier
	s_setprio 0
	s_add_i32 s56, 0, 0x18000
	s_add_i32 s57, 0, 0x1c000
	v_add_u32_e32 v142, s56, v238
	v_add_u32_e32 v158, s57, v238
	ds_read_b128 v[130:133], v142
	ds_read_b128 v[134:137], v142 offset:1024
	ds_read_b128 v[138:141], v142 offset:2048
	ds_read_b128 v[142:145], v142 offset:3072
	ds_read_b128 v[146:149], v158
	ds_read_b128 v[150:153], v158 offset:1024
	ds_read_b128 v[154:157], v158 offset:2048
	ds_read_b128 v[158:161], v158 offset:3072
	s_add_u32 s28, s28, 0x80000
	s_addc_u32 s29, s29, 0
	s_mov_b32 m0, s41
	v_lshl_add_u64 v[218:219], s[28:29], 0, v[200:201]
	ds_read_b128 v[162:165], v240 offset:32768
	ds_read_b128 v[166:169], v240 offset:33792
	ds_read_b128 v[170:173], v240 offset:34816
	ds_read_b128 v[174:177], v240 offset:35840
	ds_read_b128 v[178:181], v240 offset:36864
	ds_read_b128 v[182:185], v240 offset:37888
	ds_read_b128 v[186:189], v240 offset:38912
	ds_read_b128 v[196:199], v240 offset:39936
	global_load_lds_dwordx4 v[218:219], off
	s_mov_b32 m0, s42
	v_lshl_add_u64 v[218:219], s[28:29], 0, v[202:203]
	global_load_lds_dwordx4 v[218:219], off
	s_setprio 1
	s_waitcnt vmcnt(8) lgkmcnt(0)
	s_barrier
	v_mfma_f32_16x16x32_bf16 v[126:129], v[130:133], v[162:165], v[126:129]
	v_mfma_f32_16x16x32_bf16 v[122:125], v[138:141], v[162:165], v[122:125]
	v_mfma_f32_16x16x32_bf16 v[110:113], v[130:133], v[170:173], v[110:113]
	v_mfma_f32_16x16x32_bf16 v[106:109], v[138:141], v[170:173], v[106:109]
	v_mfma_f32_16x16x32_bf16 v[98:101], v[130:133], v[178:181], v[98:101]
	v_mfma_f32_16x16x32_bf16 v[90:93], v[138:141], v[178:181], v[90:93]
	v_mfma_f32_16x16x32_bf16 v[82:85], v[130:133], v[186:189], v[82:85]
	v_mfma_f32_16x16x32_bf16 v[74:77], v[138:141], v[186:189], v[74:77]
	v_mfma_f32_16x16x32_bf16 v[126:129], v[134:137], v[166:169], v[126:129]
	v_mfma_f32_16x16x32_bf16 v[122:125], v[142:145], v[166:169], v[122:125]
	v_mfma_f32_16x16x32_bf16 v[110:113], v[134:137], v[174:177], v[110:113]
	v_mfma_f32_16x16x32_bf16 v[106:109], v[142:145], v[174:177], v[106:109]
	v_mfma_f32_16x16x32_bf16 v[98:101], v[134:137], v[182:185], v[98:101]
	v_mfma_f32_16x16x32_bf16 v[90:93], v[142:145], v[182:185], v[90:93]
	v_mfma_f32_16x16x32_bf16 v[82:85], v[134:137], v[196:199], v[82:85]
	v_mfma_f32_16x16x32_bf16 v[74:77], v[142:145], v[196:199], v[74:77]
	s_setprio 0
	s_setprio 1
	v_mfma_f32_16x16x32_bf16 v[118:121], v[146:149], v[162:165], v[118:121]
	v_mfma_f32_16x16x32_bf16 v[114:117], v[154:157], v[162:165], v[114:117]
	v_mfma_f32_16x16x32_bf16 v[102:105], v[146:149], v[170:173], v[102:105]
	v_mfma_f32_16x16x32_bf16 v[94:97], v[154:157], v[170:173], v[94:97]
	v_mfma_f32_16x16x32_bf16 v[86:89], v[146:149], v[178:181], v[86:89]
	v_mfma_f32_16x16x32_bf16 v[78:81], v[154:157], v[178:181], v[78:81]
	v_mfma_f32_16x16x32_bf16 v[70:73], v[146:149], v[186:189], v[70:73]
	v_mfma_f32_16x16x32_bf16 v[66:69], v[154:157], v[186:189], v[66:69]
	v_mfma_f32_16x16x32_bf16 v[118:121], v[150:153], v[166:169], v[118:121]
	v_mfma_f32_16x16x32_bf16 v[114:117], v[158:161], v[166:169], v[114:117]
	v_mfma_f32_16x16x32_bf16 v[102:105], v[150:153], v[174:177], v[102:105]
	v_mfma_f32_16x16x32_bf16 v[94:97], v[158:161], v[174:177], v[94:97]
	v_mfma_f32_16x16x32_bf16 v[86:89], v[150:153], v[182:185], v[86:89]
	v_mfma_f32_16x16x32_bf16 v[78:81], v[158:161], v[182:185], v[78:81]
	v_mfma_f32_16x16x32_bf16 v[70:73], v[150:153], v[196:199], v[70:73]
	v_mfma_f32_16x16x32_bf16 v[66:69], v[158:161], v[196:199], v[66:69]
	s_barrier
	s_setprio 0
	s_add_i32 s28, s56, s34
	v_lshl_add_u64 v[210:211], v[210:211], 0, s[58:59]
	s_mov_b32 m0, s28
	ds_read_b128 v[162:165], v240 offset:49152
	ds_read_b128 v[166:169], v240 offset:50176
	ds_read_b128 v[170:173], v240 offset:51200
	ds_read_b128 v[174:177], v240 offset:52224
	ds_read_b128 v[178:181], v240 offset:53248
	ds_read_b128 v[182:185], v240 offset:54272
	ds_read_b128 v[186:189], v240 offset:55296
	ds_read_b128 v[196:199], v240 offset:56320
	global_load_lds_dwordx4 v[210:211], off
	s_add_i32 m0, s28, 0x2000
	s_add_u32 s26, s26, 0x80080
	v_lshl_add_u64 v[210:211], v[212:213], 0, s[58:59]
	s_addc_u32 s27, s27, 0
	s_add_i32 s28, s57, s34
	global_load_lds_dwordx4 v[210:211], off
	s_mov_b32 m0, s28
	v_lshl_add_u64 v[210:211], s[26:27], 0, v[190:191]
	global_load_lds_dwordx4 v[210:211], off
	s_add_i32 m0, s28, 0x2000
	v_lshl_add_u64 v[210:211], s[26:27], 0, v[204:205]
	global_load_lds_dwordx4 v[210:211], off
	s_mov_b32 m0, s43
	v_lshl_add_u64 v[210:211], v[214:215], 0, s[58:59]
	global_load_lds_dwordx4 v[210:211], off
	s_mov_b32 m0, s46
	v_lshl_add_u64 v[210:211], v[216:217], 0, s[58:59]
	global_load_lds_dwordx4 v[210:211], off
	s_setprio 1
	s_waitcnt vmcnt(8) lgkmcnt(0)
	s_barrier
	v_mfma_f32_16x16x32_bf16 v[62:65], v[130:133], v[162:165], v[62:65]
	v_mfma_f32_16x16x32_bf16 v[58:61], v[138:141], v[162:165], v[58:61]
	v_mfma_f32_16x16x32_bf16 v[50:53], v[130:133], v[170:173], v[50:53]
	v_mfma_f32_16x16x32_bf16 v[42:45], v[138:141], v[170:173], v[42:45]
	v_mfma_f32_16x16x32_bf16 v[34:37], v[130:133], v[178:181], v[34:37]
	v_mfma_f32_16x16x32_bf16 v[26:29], v[138:141], v[178:181], v[26:29]
	v_mfma_f32_16x16x32_bf16 v[18:21], v[130:133], v[186:189], v[18:21]
	v_mfma_f32_16x16x32_bf16 v[10:13], v[138:141], v[186:189], v[10:13]
	v_mfma_f32_16x16x32_bf16 v[62:65], v[134:137], v[166:169], v[62:65]
	v_mfma_f32_16x16x32_bf16 v[58:61], v[142:145], v[166:169], v[58:61]
	v_mfma_f32_16x16x32_bf16 v[50:53], v[134:137], v[174:177], v[50:53]
	v_mfma_f32_16x16x32_bf16 v[42:45], v[142:145], v[174:177], v[42:45]
	v_mfma_f32_16x16x32_bf16 v[34:37], v[134:137], v[182:185], v[34:37]
	v_mfma_f32_16x16x32_bf16 v[26:29], v[142:145], v[182:185], v[26:29]
	v_mfma_f32_16x16x32_bf16 v[18:21], v[134:137], v[196:199], v[18:21]
	v_mfma_f32_16x16x32_bf16 v[10:13], v[142:145], v[196:199], v[10:13]
	s_setprio 0
	s_setprio 1
	v_mfma_f32_16x16x32_bf16 v[54:57], v[146:149], v[162:165], v[54:57]
	v_mfma_f32_16x16x32_bf16 v[46:49], v[154:157], v[162:165], v[46:49]
	v_mfma_f32_16x16x32_bf16 v[38:41], v[146:149], v[170:173], v[38:41]
	v_mfma_f32_16x16x32_bf16 v[30:33], v[154:157], v[170:173], v[30:33]
	v_mfma_f32_16x16x32_bf16 v[22:25], v[146:149], v[178:181], v[22:25]
	v_mfma_f32_16x16x32_bf16 v[14:17], v[154:157], v[178:181], v[14:17]
	v_mfma_f32_16x16x32_bf16 v[6:9], v[146:149], v[186:189], v[6:9]
	v_mfma_f32_16x16x32_bf16 v[2:5], v[154:157], v[186:189], v[2:5]
	v_mfma_f32_16x16x32_bf16 v[54:57], v[150:153], v[166:169], v[54:57]
	v_mfma_f32_16x16x32_bf16 v[46:49], v[158:161], v[166:169], v[46:49]
	v_mfma_f32_16x16x32_bf16 v[38:41], v[150:153], v[174:177], v[38:41]
	v_mfma_f32_16x16x32_bf16 v[30:33], v[158:161], v[174:177], v[30:33]
	v_mfma_f32_16x16x32_bf16 v[22:25], v[150:153], v[182:185], v[22:25]
	v_mfma_f32_16x16x32_bf16 v[14:17], v[158:161], v[182:185], v[14:17]
	v_mfma_f32_16x16x32_bf16 v[6:9], v[150:153], v[196:199], v[6:9]
	v_mfma_f32_16x16x32_bf16 v[2:5], v[158:161], v[196:199], v[2:5]
	s_barrier
	s_setprio 0
	s_add_i32 s55, s55, 2
	s_add_u32 s24, s24, 0x100
	s_addc_u32 s25, s25, 0
	s_add_u32 s52, s52, 0x100
	s_addc_u32 s53, s53, 0
	s_cmp_gt_u32 s55, 29
	s_cbranch_scc1 .Lpeel_done_4
.LBB0_800:
	s_add_u32 s26, s24, 0xfff80080
	s_addc_u32 s27, s25, -1
	s_add_i32 s56, 0, 0x10000
	s_cmp_eq_u32 s55, 28
	s_cselect_b32 s29, s11, s27
	s_cselect_b32 s28, s21, s26
	s_cselect_b32 s27, s9, s53
	s_cselect_b32 s26, s47, s52
	s_add_i32 s60, 0, 0x14000
	v_add_u32_e32 v142, s56, v238
	v_add_u32_e32 v158, s60, v238
	ds_read_b128 v[130:133], v142
	ds_read_b128 v[134:137], v142 offset:1024
	ds_read_b128 v[138:141], v142 offset:2048
	ds_read_b128 v[142:145], v142 offset:3072
	ds_read_b128 v[146:149], v158
	ds_read_b128 v[150:153], v158 offset:1024
	ds_read_b128 v[154:157], v158 offset:2048
	ds_read_b128 v[158:161], v158 offset:3072
	v_lshl_add_u64 v[210:211], s[24:25], 0, v[206:207]
	s_add_i32 m0, s23, 0xc000
	ds_read_b128 v[162:165], v240
	ds_read_b128 v[166:169], v240 offset:1024
	ds_read_b128 v[170:173], v240 offset:2048
	ds_read_b128 v[174:177], v240 offset:3072
	ds_read_b128 v[178:181], v240 offset:4096
	ds_read_b128 v[182:185], v240 offset:5120
	ds_read_b128 v[186:189], v240 offset:6144
	ds_read_b128 v[196:199], v240 offset:7168
	global_load_lds_dwordx4 v[210:211], off
	s_add_i32 m0, s23, 0xe000
	v_lshl_add_u64 v[210:211], s[24:25], 0, v[208:209]
	global_load_lds_dwordx4 v[210:211], off
	s_setprio 1
	s_waitcnt vmcnt(8) lgkmcnt(0)
	s_barrier
	v_mfma_f32_16x16x32_bf16 v[126:129], v[130:133], v[162:165], v[126:129]
	v_mfma_f32_16x16x32_bf16 v[122:125], v[138:141], v[162:165], v[122:125]
	v_mfma_f32_16x16x32_bf16 v[110:113], v[130:133], v[170:173], v[110:113]
	v_mfma_f32_16x16x32_bf16 v[106:109], v[138:141], v[170:173], v[106:109]
	v_mfma_f32_16x16x32_bf16 v[98:101], v[130:133], v[178:181], v[98:101]
	v_mfma_f32_16x16x32_bf16 v[90:93], v[138:141], v[178:181], v[90:93]
	v_mfma_f32_16x16x32_bf16 v[82:85], v[130:133], v[186:189], v[82:85]
	v_mfma_f32_16x16x32_bf16 v[74:77], v[138:141], v[186:189], v[74:77]
	v_mfma_f32_16x16x32_bf16 v[126:129], v[134:137], v[166:169], v[126:129]
	v_mfma_f32_16x16x32_bf16 v[122:125], v[142:145], v[166:169], v[122:125]
	v_mfma_f32_16x16x32_bf16 v[110:113], v[134:137], v[174:177], v[110:113]
	v_mfma_f32_16x16x32_bf16 v[106:109], v[142:145], v[174:177], v[106:109]
	v_mfma_f32_16x16x32_bf16 v[98:101], v[134:137], v[182:185], v[98:101]
	v_mfma_f32_16x16x32_bf16 v[90:93], v[142:145], v[182:185], v[90:93]
	v_mfma_f32_16x16x32_bf16 v[82:85], v[134:137], v[196:199], v[82:85]
	v_mfma_f32_16x16x32_bf16 v[74:77], v[142:145], v[196:199], v[74:77]
	s_setprio 0
	s_setprio 1
	v_mfma_f32_16x16x32_bf16 v[118:121], v[146:149], v[162:165], v[118:121]
	v_mfma_f32_16x16x32_bf16 v[114:117], v[154:157], v[162:165], v[114:117]
	v_mfma_f32_16x16x32_bf16 v[102:105], v[146:149], v[170:173], v[102:105]
	v_mfma_f32_16x16x32_bf16 v[94:97], v[154:157], v[170:173], v[94:97]
	v_mfma_f32_16x16x32_bf16 v[86:89], v[146:149], v[178:181], v[86:89]
	v_mfma_f32_16x16x32_bf16 v[78:81], v[154:157], v[178:181], v[78:81]
	v_mfma_f32_16x16x32_bf16 v[70:73], v[146:149], v[186:189], v[70:73]
	v_mfma_f32_16x16x32_bf16 v[66:69], v[154:157], v[186:189], v[66:69]
	v_mfma_f32_16x16x32_bf16 v[118:121], v[150:153], v[166:169], v[118:121]
	v_mfma_f32_16x16x32_bf16 v[114:117], v[158:161], v[166:169], v[114:117]
	v_mfma_f32_16x16x32_bf16 v[102:105], v[150:153], v[174:177], v[102:105]
	v_mfma_f32_16x16x32_bf16 v[94:97], v[158:161], v[174:177], v[94:97]
	v_mfma_f32_16x16x32_bf16 v[86:89], v[150:153], v[182:185], v[86:89]
	v_mfma_f32_16x16x32_bf16 v[78:81], v[158:161], v[182:185], v[78:81]
	v_mfma_f32_16x16x32_bf16 v[70:73], v[150:153], v[196:199], v[70:73]
	v_mfma_f32_16x16x32_bf16 v[66:69], v[158:161], v[196:199], v[66:69]
	s_setprio 0
	s_barrier
	s_add_i32 s56, s56, s34
	v_lshl_add_u64 v[210:211], s[26:27], 0, v[190:191]
	s_mov_b32 m0, s56
	ds_read_b128 v[162:165], v240 offset:16384
	ds_read_b128 v[166:169], v240 offset:17408
	ds_read_b128 v[170:173], v240 offset:18432
	ds_read_b128 v[174:177], v240 offset:19456
	ds_read_b128 v[178:181], v240 offset:20480
	ds_read_b128 v[182:185], v240 offset:21504
	ds_read_b128 v[186:189], v240 offset:22528
	ds_read_b128 v[196:199], v240 offset:23552
	global_load_lds_dwordx4 v[210:211], off
	s_add_i32 m0, s56, 0x2000
	s_add_u32 s56, s26, 0x80000
	v_lshl_add_u64 v[212:213], s[26:27], 0, v[204:205]
	s_addc_u32 s57, s27, 0
	s_add_i32 s60, s60, s34
	global_load_lds_dwordx4 v[212:213], off
	v_lshl_add_u64 v[214:215], s[56:57], 0, v[190:191]
	s_mov_b32 m0, s60
	v_lshl_add_u64 v[216:217], s[28:29], 0, v[202:203]
	global_load_lds_dwordx4 v[214:215], off
	s_add_i32 m0, s60, 0x2000
	v_lshl_add_u64 v[214:215], s[56:57], 0, v[204:205]
	global_load_lds_dwordx4 v[214:215], off
	s_mov_b32 m0, s23
	v_lshl_add_u64 v[214:215], s[28:29], 0, v[200:201]
	global_load_lds_dwordx4 v[214:215], off
	s_mov_b32 m0, s35
	s_nop 0
	global_load_lds_dwordx4 v[216:217], off
	s_setprio 1
	s_waitcnt vmcnt(8) lgkmcnt(0)
	s_barrier
	v_mfma_f32_16x16x32_bf16 v[62:65], v[130:133], v[162:165], v[62:65]
	v_mfma_f32_16x16x32_bf16 v[58:61], v[138:141], v[162:165], v[58:61]
	v_mfma_f32_16x16x32_bf16 v[50:53], v[130:133], v[170:173], v[50:53]
	v_mfma_f32_16x16x32_bf16 v[42:45], v[138:141], v[170:173], v[42:45]
	v_mfma_f32_16x16x32_bf16 v[34:37], v[130:133], v[178:181], v[34:37]
	v_mfma_f32_16x16x32_bf16 v[26:29], v[138:141], v[178:181], v[26:29]
	v_mfma_f32_16x16x32_bf16 v[18:21], v[130:133], v[186:189], v[18:21]
	v_mfma_f32_16x16x32_bf16 v[10:13], v[138:141], v[186:189], v[10:13]
	v_mfma_f32_16x16x32_bf16 v[62:65], v[134:137], v[166:169], v[62:65]
	v_mfma_f32_16x16x32_bf16 v[58:61], v[142:145], v[166:169], v[58:61]
	v_mfma_f32_16x16x32_bf16 v[50:53], v[134:137], v[174:177], v[50:53]
	v_mfma_f32_16x16x32_bf16 v[42:45], v[142:145], v[174:177], v[42:45]
	v_mfma_f32_16x16x32_bf16 v[34:37], v[134:137], v[182:185], v[34:37]
	v_mfma_f32_16x16x32_bf16 v[26:29], v[142:145], v[182:185], v[26:29]
	v_mfma_f32_16x16x32_bf16 v[18:21], v[134:137], v[196:199], v[18:21]
	v_mfma_f32_16x16x32_bf16 v[10:13], v[142:145], v[196:199], v[10:13]
	s_setprio 0
	s_setprio 1
	v_mfma_f32_16x16x32_bf16 v[54:57], v[146:149], v[162:165], v[54:57]
	v_mfma_f32_16x16x32_bf16 v[46:49], v[154:157], v[162:165], v[46:49]
	v_mfma_f32_16x16x32_bf16 v[38:41], v[146:149], v[170:173], v[38:41]
	v_mfma_f32_16x16x32_bf16 v[30:33], v[154:157], v[170:173], v[30:33]
	v_mfma_f32_16x16x32_bf16 v[22:25], v[146:149], v[178:181], v[22:25]
	v_mfma_f32_16x16x32_bf16 v[14:17], v[154:157], v[178:181], v[14:17]
	v_mfma_f32_16x16x32_bf16 v[6:9], v[146:149], v[186:189], v[6:9]
	v_mfma_f32_16x16x32_bf16 v[2:5], v[154:157], v[186:189], v[2:5]
	v_mfma_f32_16x16x32_bf16 v[54:57], v[150:153], v[166:169], v[54:57]
	v_mfma_f32_16x16x32_bf16 v[46:49], v[158:161], v[166:169], v[46:49]
	v_mfma_f32_16x16x32_bf16 v[38:41], v[150:153], v[174:177], v[38:41]
	v_mfma_f32_16x16x32_bf16 v[30:33], v[158:161], v[174:177], v[30:33]
	v_mfma_f32_16x16x32_bf16 v[22:25], v[150:153], v[182:185], v[22:25]
	v_mfma_f32_16x16x32_bf16 v[14:17], v[158:161], v[182:185], v[14:17]
	v_mfma_f32_16x16x32_bf16 v[6:9], v[150:153], v[196:199], v[6:9]
	v_mfma_f32_16x16x32_bf16 v[2:5], v[158:161], v[196:199], v[2:5]
	s_setprio 0
	s_barrier
	s_add_i32 s56, 0, 0x18000
	s_add_i32 s57, 0, 0x1c000
	v_add_u32_e32 v142, s56, v238
	v_add_u32_e32 v158, s57, v238
	ds_read_b128 v[130:133], v142
	ds_read_b128 v[134:137], v142 offset:1024
	ds_read_b128 v[138:141], v142 offset:2048
	ds_read_b128 v[142:145], v142 offset:3072
	ds_read_b128 v[146:149], v158
	ds_read_b128 v[150:153], v158 offset:1024
	ds_read_b128 v[154:157], v158 offset:2048
	ds_read_b128 v[158:161], v158 offset:3072
	s_add_u32 s28, s28, 0x80000
	s_addc_u32 s29, s29, 0
	s_mov_b32 m0, s41
	v_lshl_add_u64 v[218:219], s[28:29], 0, v[200:201]
	ds_read_b128 v[162:165], v240 offset:32768
	ds_read_b128 v[166:169], v240 offset:33792
	ds_read_b128 v[170:173], v240 offset:34816
	ds_read_b128 v[174:177], v240 offset:35840
	ds_read_b128 v[178:181], v240 offset:36864
	ds_read_b128 v[182:185], v240 offset:37888
	ds_read_b128 v[186:189], v240 offset:38912
	ds_read_b128 v[196:199], v240 offset:39936
	global_load_lds_dwordx4 v[218:219], off
	s_mov_b32 m0, s42
	v_lshl_add_u64 v[218:219], s[28:29], 0, v[202:203]
	global_load_lds_dwordx4 v[218:219], off
	s_setprio 1
	s_waitcnt vmcnt(8) lgkmcnt(0)
	s_barrier
	v_mfma_f32_16x16x32_bf16 v[126:129], v[130:133], v[162:165], v[126:129]
	v_mfma_f32_16x16x32_bf16 v[122:125], v[138:141], v[162:165], v[122:125]
	v_mfma_f32_16x16x32_bf16 v[110:113], v[130:133], v[170:173], v[110:113]
	v_mfma_f32_16x16x32_bf16 v[106:109], v[138:141], v[170:173], v[106:109]
	v_mfma_f32_16x16x32_bf16 v[98:101], v[130:133], v[178:181], v[98:101]
	v_mfma_f32_16x16x32_bf16 v[90:93], v[138:141], v[178:181], v[90:93]
	v_mfma_f32_16x16x32_bf16 v[82:85], v[130:133], v[186:189], v[82:85]
	v_mfma_f32_16x16x32_bf16 v[74:77], v[138:141], v[186:189], v[74:77]
	v_mfma_f32_16x16x32_bf16 v[126:129], v[134:137], v[166:169], v[126:129]
	v_mfma_f32_16x16x32_bf16 v[122:125], v[142:145], v[166:169], v[122:125]
	v_mfma_f32_16x16x32_bf16 v[110:113], v[134:137], v[174:177], v[110:113]
	v_mfma_f32_16x16x32_bf16 v[106:109], v[142:145], v[174:177], v[106:109]
	v_mfma_f32_16x16x32_bf16 v[98:101], v[134:137], v[182:185], v[98:101]
	v_mfma_f32_16x16x32_bf16 v[90:93], v[142:145], v[182:185], v[90:93]
	v_mfma_f32_16x16x32_bf16 v[82:85], v[134:137], v[196:199], v[82:85]
	v_mfma_f32_16x16x32_bf16 v[74:77], v[142:145], v[196:199], v[74:77]
	s_setprio 0
	s_setprio 1
	v_mfma_f32_16x16x32_bf16 v[118:121], v[146:149], v[162:165], v[118:121]
	v_mfma_f32_16x16x32_bf16 v[114:117], v[154:157], v[162:165], v[114:117]
	v_mfma_f32_16x16x32_bf16 v[102:105], v[146:149], v[170:173], v[102:105]
	v_mfma_f32_16x16x32_bf16 v[94:97], v[154:157], v[170:173], v[94:97]
	v_mfma_f32_16x16x32_bf16 v[86:89], v[146:149], v[178:181], v[86:89]
	v_mfma_f32_16x16x32_bf16 v[78:81], v[154:157], v[178:181], v[78:81]
	v_mfma_f32_16x16x32_bf16 v[70:73], v[146:149], v[186:189], v[70:73]
	v_mfma_f32_16x16x32_bf16 v[66:69], v[154:157], v[186:189], v[66:69]
	v_mfma_f32_16x16x32_bf16 v[118:121], v[150:153], v[166:169], v[118:121]
	v_mfma_f32_16x16x32_bf16 v[114:117], v[158:161], v[166:169], v[114:117]
	v_mfma_f32_16x16x32_bf16 v[102:105], v[150:153], v[174:177], v[102:105]
	v_mfma_f32_16x16x32_bf16 v[94:97], v[158:161], v[174:177], v[94:97]
	v_mfma_f32_16x16x32_bf16 v[86:89], v[150:153], v[182:185], v[86:89]
	v_mfma_f32_16x16x32_bf16 v[78:81], v[158:161], v[182:185], v[78:81]
	v_mfma_f32_16x16x32_bf16 v[70:73], v[150:153], v[196:199], v[70:73]
	v_mfma_f32_16x16x32_bf16 v[66:69], v[158:161], v[196:199], v[66:69]
	s_setprio 0
	s_barrier
	s_add_i32 s28, s56, s34
	v_lshl_add_u64 v[210:211], v[210:211], 0, s[58:59]
	s_mov_b32 m0, s28
	ds_read_b128 v[162:165], v240 offset:49152
	ds_read_b128 v[166:169], v240 offset:50176
	ds_read_b128 v[170:173], v240 offset:51200
	ds_read_b128 v[174:177], v240 offset:52224
	ds_read_b128 v[178:181], v240 offset:53248
	ds_read_b128 v[182:185], v240 offset:54272
	ds_read_b128 v[186:189], v240 offset:55296
	ds_read_b128 v[196:199], v240 offset:56320
	global_load_lds_dwordx4 v[210:211], off
	s_add_i32 m0, s28, 0x2000
	s_add_u32 s26, s26, 0x80080
	v_lshl_add_u64 v[210:211], v[212:213], 0, s[58:59]
	s_addc_u32 s27, s27, 0
	s_add_i32 s28, s57, s34
	global_load_lds_dwordx4 v[210:211], off
	s_mov_b32 m0, s28
	v_lshl_add_u64 v[210:211], s[26:27], 0, v[190:191]
	global_load_lds_dwordx4 v[210:211], off
	s_add_i32 m0, s28, 0x2000
	v_lshl_add_u64 v[210:211], s[26:27], 0, v[204:205]
	global_load_lds_dwordx4 v[210:211], off
	s_mov_b32 m0, s43
	v_lshl_add_u64 v[210:211], v[214:215], 0, s[58:59]
	global_load_lds_dwordx4 v[210:211], off
	s_mov_b32 m0, s46
	v_lshl_add_u64 v[210:211], v[216:217], 0, s[58:59]
	global_load_lds_dwordx4 v[210:211], off
	s_setprio 1
	s_waitcnt vmcnt(8) lgkmcnt(0)
	s_barrier
	v_mfma_f32_16x16x32_bf16 v[62:65], v[130:133], v[162:165], v[62:65]
	v_mfma_f32_16x16x32_bf16 v[58:61], v[138:141], v[162:165], v[58:61]
	v_mfma_f32_16x16x32_bf16 v[50:53], v[130:133], v[170:173], v[50:53]
	v_mfma_f32_16x16x32_bf16 v[42:45], v[138:141], v[170:173], v[42:45]
	v_mfma_f32_16x16x32_bf16 v[34:37], v[130:133], v[178:181], v[34:37]
	v_mfma_f32_16x16x32_bf16 v[26:29], v[138:141], v[178:181], v[26:29]
	v_mfma_f32_16x16x32_bf16 v[18:21], v[130:133], v[186:189], v[18:21]
	v_mfma_f32_16x16x32_bf16 v[10:13], v[138:141], v[186:189], v[10:13]
	v_mfma_f32_16x16x32_bf16 v[62:65], v[134:137], v[166:169], v[62:65]
	v_mfma_f32_16x16x32_bf16 v[58:61], v[142:145], v[166:169], v[58:61]
	v_mfma_f32_16x16x32_bf16 v[50:53], v[134:137], v[174:177], v[50:53]
	v_mfma_f32_16x16x32_bf16 v[42:45], v[142:145], v[174:177], v[42:45]
	v_mfma_f32_16x16x32_bf16 v[34:37], v[134:137], v[182:185], v[34:37]
	v_mfma_f32_16x16x32_bf16 v[26:29], v[142:145], v[182:185], v[26:29]
	v_mfma_f32_16x16x32_bf16 v[18:21], v[134:137], v[196:199], v[18:21]
	v_mfma_f32_16x16x32_bf16 v[10:13], v[142:145], v[196:199], v[10:13]
	s_setprio 0
	s_setprio 1
	v_mfma_f32_16x16x32_bf16 v[54:57], v[146:149], v[162:165], v[54:57]
	v_mfma_f32_16x16x32_bf16 v[46:49], v[154:157], v[162:165], v[46:49]
	v_mfma_f32_16x16x32_bf16 v[38:41], v[146:149], v[170:173], v[38:41]
	v_mfma_f32_16x16x32_bf16 v[30:33], v[154:157], v[170:173], v[30:33]
	v_mfma_f32_16x16x32_bf16 v[22:25], v[146:149], v[178:181], v[22:25]
	v_mfma_f32_16x16x32_bf16 v[14:17], v[154:157], v[178:181], v[14:17]
	v_mfma_f32_16x16x32_bf16 v[6:9], v[146:149], v[186:189], v[6:9]
	v_mfma_f32_16x16x32_bf16 v[2:5], v[154:157], v[186:189], v[2:5]
	v_mfma_f32_16x16x32_bf16 v[54:57], v[150:153], v[166:169], v[54:57]
	v_mfma_f32_16x16x32_bf16 v[46:49], v[158:161], v[166:169], v[46:49]
	v_mfma_f32_16x16x32_bf16 v[38:41], v[150:153], v[174:177], v[38:41]
	v_mfma_f32_16x16x32_bf16 v[30:33], v[158:161], v[174:177], v[30:33]
	v_mfma_f32_16x16x32_bf16 v[22:25], v[150:153], v[182:185], v[22:25]
	v_mfma_f32_16x16x32_bf16 v[14:17], v[158:161], v[182:185], v[14:17]
	v_mfma_f32_16x16x32_bf16 v[6:9], v[150:153], v[196:199], v[6:9]
	v_mfma_f32_16x16x32_bf16 v[2:5], v[158:161], v[196:199], v[2:5]
	s_setprio 0
	s_barrier
	s_add_i32 s55, s55, 2
	s_add_u32 s24, s24, 0x100
	s_addc_u32 s25, s25, 0
	s_add_u32 s52, s52, 0x100
	s_addc_u32 s53, s53, 0
	s_cmp_gt_u32 s55, 29
	s_cbranch_scc0 .LBB0_800

.LBB0_822:
	s_ashr_i32 s17, s16, 31
	s_lshl_b64 s[22:23], s[16:17], 20
	v_readlane_b32 s0, v254, 60
	s_add_u32 s22, s0, s22
	v_readlane_b32 s0, v254, 61
	s_addc_u32 s23, s0, s23
	s_and_b64 s[24:25], s[20:21], exec
	s_cselect_b32 s17, s23, s31
	s_cselect_b32 s27, s22, s30
	s_ashr_i32 s15, s14, 31
	s_lshl_b64 s[24:25], s[14:15], 20
	v_readlane_b32 s0, v254, 40
	v_readlane_b32 s1, v254, 41
	s_add_u32 s24, s0, s24
	s_addc_u32 s25, s1, s25
	s_and_b64 s[52:53], s[20:21], exec
	s_cselect_b32 s15, s25, s35
	s_cselect_b32 s29, s24, s34
	s_add_u32 s30, s30, 0x80080
	s_addc_u32 s31, s31, 0
	s_add_u32 s81, s34, 0x100
	s_addc_u32 s88, s35, 0
	s_mov_b32 s89, -2
	v_readlane_b32 s90, v255, 49
	s_nop 3
	s_cmp_eq_u32 s90, 6
	v_writelane_b32 v255, 6, 49
	s_cbranch_scc0 .Ltrip0_strict_5
	s_add_u32 s34, s30, 0xfff80080
	s_addc_u32 s35, s31, -1
	s_add_i32 s90, 0, 0x10000
	s_cmp_eq_u32 s89, 28
	s_cselect_b32 s53, s17, s35
	s_cselect_b32 s52, s27, s34
	s_cselect_b32 s35, s15, s88
	s_cselect_b32 s34, s29, s81
	s_add_i32 s96, 0, 0x14000
	v_add_u32_e32 v142, s90, v220
	v_add_u32_e32 v158, s96, v220
	ds_read_b128 v[130:133], v142
	ds_read_b128 v[134:137], v142 offset:1024
	ds_read_b128 v[138:141], v142 offset:2048
	ds_read_b128 v[142:145], v142 offset:3072
	ds_read_b128 v[146:149], v158
	ds_read_b128 v[150:153], v158 offset:1024
	ds_read_b128 v[154:157], v158 offset:2048
	ds_read_b128 v[158:161], v158 offset:3072
	v_lshl_add_u64 v[210:211], s[30:31], 0, v[202:203]
	s_add_i32 m0, s55, 0xc000
	ds_read_b128 v[162:165], v222
	ds_read_b128 v[166:169], v222 offset:1024
	ds_read_b128 v[170:173], v222 offset:2048
	ds_read_b128 v[174:177], v222 offset:3072
	ds_read_b128 v[178:181], v222 offset:4096
	ds_read_b128 v[182:185], v222 offset:5120
	ds_read_b128 v[196:199], v222 offset:6144
	ds_read_b128 v[206:209], v222 offset:7168
	global_load_lds_dwordx4 v[210:211], off
	s_add_i32 m0, s55, 0xe000
	v_lshl_add_u64 v[210:211], s[30:31], 0, v[204:205]
	global_load_lds_dwordx4 v[210:211], off
	s_setprio 1
	s_waitcnt vmcnt(24) lgkmcnt(0)
	s_barrier
	v_mfma_f32_16x16x32_bf16 v[126:129], v[130:133], v[162:165], 0
	v_mfma_f32_16x16x32_bf16 v[122:125], v[138:141], v[162:165], 0
	v_mfma_f32_16x16x32_bf16 v[110:113], v[130:133], v[170:173], 0
	v_mfma_f32_16x16x32_bf16 v[106:109], v[138:141], v[170:173], 0
	v_mfma_f32_16x16x32_bf16 v[94:97], v[130:133], v[178:181], 0
	v_mfma_f32_16x16x32_bf16 v[90:93], v[138:141], v[178:181], 0
	v_mfma_f32_16x16x32_bf16 v[78:81], v[130:133], v[196:199], 0
	v_mfma_f32_16x16x32_bf16 v[74:77], v[138:141], v[196:199], 0
	v_mfma_f32_16x16x32_bf16 v[126:129], v[134:137], v[166:169], v[126:129]
	v_mfma_f32_16x16x32_bf16 v[122:125], v[142:145], v[166:169], v[122:125]
	v_mfma_f32_16x16x32_bf16 v[110:113], v[134:137], v[174:177], v[110:113]
	v_mfma_f32_16x16x32_bf16 v[106:109], v[142:145], v[174:177], v[106:109]
	v_mfma_f32_16x16x32_bf16 v[94:97], v[134:137], v[182:185], v[94:97]
	v_mfma_f32_16x16x32_bf16 v[90:93], v[142:145], v[182:185], v[90:93]
	v_mfma_f32_16x16x32_bf16 v[78:81], v[134:137], v[206:209], v[78:81]
	v_mfma_f32_16x16x32_bf16 v[74:77], v[142:145], v[206:209], v[74:77]
	s_setprio 0
	s_setprio 1
	v_mfma_f32_16x16x32_bf16 v[118:121], v[146:149], v[162:165], 0
	v_mfma_f32_16x16x32_bf16 v[114:117], v[154:157], v[162:165], 0
	v_mfma_f32_16x16x32_bf16 v[102:105], v[146:149], v[170:173], 0
	v_mfma_f32_16x16x32_bf16 v[98:101], v[154:157], v[170:173], 0
	v_mfma_f32_16x16x32_bf16 v[86:89], v[146:149], v[178:181], 0
	v_mfma_f32_16x16x32_bf16 v[82:85], v[154:157], v[178:181], 0
	v_mfma_f32_16x16x32_bf16 v[70:73], v[146:149], v[196:199], 0
	v_mfma_f32_16x16x32_bf16 v[66:69], v[154:157], v[196:199], 0
	v_mfma_f32_16x16x32_bf16 v[118:121], v[150:153], v[166:169], v[118:121]
	v_mfma_f32_16x16x32_bf16 v[114:117], v[158:161], v[166:169], v[114:117]
	v_mfma_f32_16x16x32_bf16 v[102:105], v[150:153], v[174:177], v[102:105]
	v_mfma_f32_16x16x32_bf16 v[98:101], v[158:161], v[174:177], v[98:101]
	v_mfma_f32_16x16x32_bf16 v[86:89], v[150:153], v[182:185], v[86:89]
	v_mfma_f32_16x16x32_bf16 v[82:85], v[158:161], v[182:185], v[82:85]
	v_mfma_f32_16x16x32_bf16 v[70:73], v[150:153], v[206:209], v[70:73]
	v_mfma_f32_16x16x32_bf16 v[66:69], v[158:161], v[206:209], v[66:69]
	s_barrier
	s_setprio 0
	s_add_i32 s90, s90, s47
	v_lshl_add_u64 v[210:211], s[34:35], 0, v[190:191]
	s_mov_b32 m0, s90
	ds_read_b128 v[162:165], v222 offset:16384
	ds_read_b128 v[166:169], v222 offset:17408
	ds_read_b128 v[170:173], v222 offset:18432
	ds_read_b128 v[174:177], v222 offset:19456
	ds_read_b128 v[178:181], v222 offset:20480
	ds_read_b128 v[182:185], v222 offset:21504
	ds_read_b128 v[196:199], v222 offset:22528
	ds_read_b128 v[206:209], v222 offset:23552
	global_load_lds_dwordx4 v[210:211], off
	s_add_i32 m0, s90, 0x2000
	s_add_u32 s90, s34, 0x80000
	v_lshl_add_u64 v[212:213], s[34:35], 0, v[200:201]
	s_addc_u32 s91, s35, 0
	s_add_i32 s96, s96, s47
	global_load_lds_dwordx4 v[212:213], off
	v_lshl_add_u64 v[214:215], s[90:91], 0, v[190:191]
	s_mov_b32 m0, s96
	v_lshl_add_u64 v[216:217], s[52:53], 0, v[188:189]
	global_load_lds_dwordx4 v[214:215], off
	s_add_i32 m0, s96, 0x2000
	v_lshl_add_u64 v[214:215], s[90:91], 0, v[200:201]
	global_load_lds_dwordx4 v[214:215], off
	s_mov_b32 m0, s55
	v_lshl_add_u64 v[214:215], s[52:53], 0, v[186:187]
	global_load_lds_dwordx4 v[214:215], off
	s_mov_b32 m0, s56
	s_nop 0
	global_load_lds_dwordx4 v[216:217], off
	s_setprio 1
	s_waitcnt vmcnt(24) lgkmcnt(0)
	s_barrier
	v_mfma_f32_16x16x32_bf16 v[62:65], v[130:133], v[162:165], 0
	v_mfma_f32_16x16x32_bf16 v[58:61], v[138:141], v[162:165], 0
	v_mfma_f32_16x16x32_bf16 v[46:49], v[130:133], v[170:173], 0
	v_mfma_f32_16x16x32_bf16 v[42:45], v[138:141], v[170:173], 0
	v_mfma_f32_16x16x32_bf16 v[30:33], v[130:133], v[178:181], 0
	v_mfma_f32_16x16x32_bf16 v[26:29], v[138:141], v[178:181], 0
	v_mfma_f32_16x16x32_bf16 v[14:17], v[130:133], v[196:199], 0
	v_mfma_f32_16x16x32_bf16 v[10:13], v[138:141], v[196:199], 0
	v_mfma_f32_16x16x32_bf16 v[62:65], v[134:137], v[166:169], v[62:65]
	v_mfma_f32_16x16x32_bf16 v[58:61], v[142:145], v[166:169], v[58:61]
	v_mfma_f32_16x16x32_bf16 v[46:49], v[134:137], v[174:177], v[46:49]
	v_mfma_f32_16x16x32_bf16 v[42:45], v[142:145], v[174:177], v[42:45]
	v_mfma_f32_16x16x32_bf16 v[30:33], v[134:137], v[182:185], v[30:33]
	v_mfma_f32_16x16x32_bf16 v[26:29], v[142:145], v[182:185], v[26:29]
	v_mfma_f32_16x16x32_bf16 v[14:17], v[134:137], v[206:209], v[14:17]
	v_mfma_f32_16x16x32_bf16 v[10:13], v[142:145], v[206:209], v[10:13]
	s_setprio 0
	s_setprio 1
	v_mfma_f32_16x16x32_bf16 v[54:57], v[146:149], v[162:165], 0
	v_mfma_f32_16x16x32_bf16 v[50:53], v[154:157], v[162:165], 0
	v_mfma_f32_16x16x32_bf16 v[38:41], v[146:149], v[170:173], 0
	v_mfma_f32_16x16x32_bf16 v[34:37], v[154:157], v[170:173], 0
	v_mfma_f32_16x16x32_bf16 v[22:25], v[146:149], v[178:181], 0
	v_mfma_f32_16x16x32_bf16 v[18:21], v[154:157], v[178:181], 0
	v_mfma_f32_16x16x32_bf16 v[6:9], v[146:149], v[196:199], 0
	v_mfma_f32_16x16x32_bf16 v[2:5], v[154:157], v[196:199], 0
	v_mfma_f32_16x16x32_bf16 v[54:57], v[150:153], v[166:169], v[54:57]
	v_mfma_f32_16x16x32_bf16 v[50:53], v[158:161], v[166:169], v[50:53]
	v_mfma_f32_16x16x32_bf16 v[38:41], v[150:153], v[174:177], v[38:41]
	v_mfma_f32_16x16x32_bf16 v[34:37], v[158:161], v[174:177], v[34:37]
	v_mfma_f32_16x16x32_bf16 v[22:25], v[150:153], v[182:185], v[22:25]
	v_mfma_f32_16x16x32_bf16 v[18:21], v[158:161], v[182:185], v[18:21]
	v_mfma_f32_16x16x32_bf16 v[6:9], v[150:153], v[206:209], v[6:9]
	v_mfma_f32_16x16x32_bf16 v[2:5], v[158:161], v[206:209], v[2:5]
	s_barrier
	s_setprio 0
	s_add_i32 s90, 0, 0x18000
	s_add_i32 s91, 0, 0x1c000
	v_add_u32_e32 v142, s90, v220
	v_add_u32_e32 v158, s91, v220
	ds_read_b128 v[130:133], v142
	ds_read_b128 v[134:137], v142 offset:1024
	ds_read_b128 v[138:141], v142 offset:2048
	ds_read_b128 v[142:145], v142 offset:3072
	ds_read_b128 v[146:149], v158
	ds_read_b128 v[150:153], v158 offset:1024
	ds_read_b128 v[154:157], v158 offset:2048
	ds_read_b128 v[158:161], v158 offset:3072
	s_add_u32 s52, s52, 0x80000
	s_addc_u32 s53, s53, 0
	s_mov_b32 m0, s57
	v_lshl_add_u64 v[218:219], s[52:53], 0, v[186:187]
	ds_read_b128 v[162:165], v222 offset:32768
	ds_read_b128 v[166:169], v222 offset:33792
	ds_read_b128 v[170:173], v222 offset:34816
	ds_read_b128 v[174:177], v222 offset:35840
	ds_read_b128 v[178:181], v222 offset:36864
	ds_read_b128 v[182:185], v222 offset:37888
	ds_read_b128 v[196:199], v222 offset:38912
	ds_read_b128 v[206:209], v222 offset:39936
	global_load_lds_dwordx4 v[218:219], off
	s_mov_b32 m0, s60
	v_lshl_add_u64 v[218:219], s[52:53], 0, v[188:189]
	global_load_lds_dwordx4 v[218:219], off
	s_setprio 1
	s_waitcnt vmcnt(8) lgkmcnt(0)
	s_barrier
	v_mfma_f32_16x16x32_bf16 v[126:129], v[130:133], v[162:165], v[126:129]
	v_mfma_f32_16x16x32_bf16 v[122:125], v[138:141], v[162:165], v[122:125]
	v_mfma_f32_16x16x32_bf16 v[110:113], v[130:133], v[170:173], v[110:113]
	v_mfma_f32_16x16x32_bf16 v[106:109], v[138:141], v[170:173], v[106:109]
	v_mfma_f32_16x16x32_bf16 v[94:97], v[130:133], v[178:181], v[94:97]
	v_mfma_f32_16x16x32_bf16 v[90:93], v[138:141], v[178:181], v[90:93]
	v_mfma_f32_16x16x32_bf16 v[78:81], v[130:133], v[196:199], v[78:81]
	v_mfma_f32_16x16x32_bf16 v[74:77], v[138:141], v[196:199], v[74:77]
	v_mfma_f32_16x16x32_bf16 v[126:129], v[134:137], v[166:169], v[126:129]
	v_mfma_f32_16x16x32_bf16 v[122:125], v[142:145], v[166:169], v[122:125]
	v_mfma_f32_16x16x32_bf16 v[110:113], v[134:137], v[174:177], v[110:113]
	v_mfma_f32_16x16x32_bf16 v[106:109], v[142:145], v[174:177], v[106:109]
	v_mfma_f32_16x16x32_bf16 v[94:97], v[134:137], v[182:185], v[94:97]
	v_mfma_f32_16x16x32_bf16 v[90:93], v[142:145], v[182:185], v[90:93]
	v_mfma_f32_16x16x32_bf16 v[78:81], v[134:137], v[206:209], v[78:81]
	v_mfma_f32_16x16x32_bf16 v[74:77], v[142:145], v[206:209], v[74:77]
	s_setprio 0
	s_setprio 1
	v_mfma_f32_16x16x32_bf16 v[118:121], v[146:149], v[162:165], v[118:121]
	v_mfma_f32_16x16x32_bf16 v[114:117], v[154:157], v[162:165], v[114:117]
	v_mfma_f32_16x16x32_bf16 v[102:105], v[146:149], v[170:173], v[102:105]
	v_mfma_f32_16x16x32_bf16 v[98:101], v[154:157], v[170:173], v[98:101]
	v_mfma_f32_16x16x32_bf16 v[86:89], v[146:149], v[178:181], v[86:89]
	v_mfma_f32_16x16x32_bf16 v[82:85], v[154:157], v[178:181], v[82:85]
	v_mfma_f32_16x16x32_bf16 v[70:73], v[146:149], v[196:199], v[70:73]
	v_mfma_f32_16x16x32_bf16 v[66:69], v[154:157], v[196:199], v[66:69]
	v_mfma_f32_16x16x32_bf16 v[118:121], v[150:153], v[166:169], v[118:121]
	v_mfma_f32_16x16x32_bf16 v[114:117], v[158:161], v[166:169], v[114:117]
	v_mfma_f32_16x16x32_bf16 v[102:105], v[150:153], v[174:177], v[102:105]
	v_mfma_f32_16x16x32_bf16 v[98:101], v[158:161], v[174:177], v[98:101]
	v_mfma_f32_16x16x32_bf16 v[86:89], v[150:153], v[182:185], v[86:89]
	v_mfma_f32_16x16x32_bf16 v[82:85], v[158:161], v[182:185], v[82:85]
	v_mfma_f32_16x16x32_bf16 v[70:73], v[150:153], v[206:209], v[70:73]
	v_mfma_f32_16x16x32_bf16 v[66:69], v[158:161], v[206:209], v[66:69]
	s_barrier
	s_setprio 0
	s_add_i32 s52, s90, s47
	v_lshl_add_u64 v[210:211], v[210:211], 0, s[58:59]
	s_mov_b32 m0, s52
	ds_read_b128 v[162:165], v222 offset:49152
	ds_read_b128 v[166:169], v222 offset:50176
	ds_read_b128 v[170:173], v222 offset:51200
	ds_read_b128 v[174:177], v222 offset:52224
	ds_read_b128 v[178:181], v222 offset:53248
	ds_read_b128 v[182:185], v222 offset:54272
	ds_read_b128 v[196:199], v222 offset:55296
	ds_read_b128 v[206:209], v222 offset:56320
	global_load_lds_dwordx4 v[210:211], off
	s_add_i32 m0, s52, 0x2000
	s_add_u32 s34, s34, 0x80080
	v_lshl_add_u64 v[210:211], v[212:213], 0, s[58:59]
	s_addc_u32 s35, s35, 0
	s_add_i32 s52, s91, s47
	global_load_lds_dwordx4 v[210:211], off
	s_mov_b32 m0, s52
	v_lshl_add_u64 v[210:211], s[34:35], 0, v[190:191]
	global_load_lds_dwordx4 v[210:211], off
	s_add_i32 m0, s52, 0x2000
	v_lshl_add_u64 v[210:211], s[34:35], 0, v[200:201]
	global_load_lds_dwordx4 v[210:211], off
	s_mov_b32 m0, s61
	v_lshl_add_u64 v[210:211], v[214:215], 0, s[58:59]
	global_load_lds_dwordx4 v[210:211], off
	s_mov_b32 m0, s69
	v_lshl_add_u64 v[210:211], v[216:217], 0, s[58:59]
	global_load_lds_dwordx4 v[210:211], off
	s_setprio 1
	s_waitcnt vmcnt(8) lgkmcnt(0)
	s_barrier
	v_mfma_f32_16x16x32_bf16 v[62:65], v[130:133], v[162:165], v[62:65]
	v_mfma_f32_16x16x32_bf16 v[58:61], v[138:141], v[162:165], v[58:61]
	v_mfma_f32_16x16x32_bf16 v[46:49], v[130:133], v[170:173], v[46:49]
	v_mfma_f32_16x16x32_bf16 v[42:45], v[138:141], v[170:173], v[42:45]
	v_mfma_f32_16x16x32_bf16 v[30:33], v[130:133], v[178:181], v[30:33]
	v_mfma_f32_16x16x32_bf16 v[26:29], v[138:141], v[178:181], v[26:29]
	v_mfma_f32_16x16x32_bf16 v[14:17], v[130:133], v[196:199], v[14:17]
	v_mfma_f32_16x16x32_bf16 v[10:13], v[138:141], v[196:199], v[10:13]
	v_mfma_f32_16x16x32_bf16 v[62:65], v[134:137], v[166:169], v[62:65]
	v_mfma_f32_16x16x32_bf16 v[58:61], v[142:145], v[166:169], v[58:61]
	v_mfma_f32_16x16x32_bf16 v[46:49], v[134:137], v[174:177], v[46:49]
	v_mfma_f32_16x16x32_bf16 v[42:45], v[142:145], v[174:177], v[42:45]
	v_mfma_f32_16x16x32_bf16 v[30:33], v[134:137], v[182:185], v[30:33]
	v_mfma_f32_16x16x32_bf16 v[26:29], v[142:145], v[182:185], v[26:29]
	v_mfma_f32_16x16x32_bf16 v[14:17], v[134:137], v[206:209], v[14:17]
	v_mfma_f32_16x16x32_bf16 v[10:13], v[142:145], v[206:209], v[10:13]
	s_setprio 0
	s_setprio 1
	v_mfma_f32_16x16x32_bf16 v[54:57], v[146:149], v[162:165], v[54:57]
	v_mfma_f32_16x16x32_bf16 v[50:53], v[154:157], v[162:165], v[50:53]
	v_mfma_f32_16x16x32_bf16 v[38:41], v[146:149], v[170:173], v[38:41]
	v_mfma_f32_16x16x32_bf16 v[34:37], v[154:157], v[170:173], v[34:37]
	v_mfma_f32_16x16x32_bf16 v[22:25], v[146:149], v[178:181], v[22:25]
	v_mfma_f32_16x16x32_bf16 v[18:21], v[154:157], v[178:181], v[18:21]
	v_mfma_f32_16x16x32_bf16 v[6:9], v[146:149], v[196:199], v[6:9]
	v_mfma_f32_16x16x32_bf16 v[2:5], v[154:157], v[196:199], v[2:5]
	v_mfma_f32_16x16x32_bf16 v[54:57], v[150:153], v[166:169], v[54:57]
	v_mfma_f32_16x16x32_bf16 v[50:53], v[158:161], v[166:169], v[50:53]
	v_mfma_f32_16x16x32_bf16 v[38:41], v[150:153], v[174:177], v[38:41]
	v_mfma_f32_16x16x32_bf16 v[34:37], v[158:161], v[174:177], v[34:37]
	v_mfma_f32_16x16x32_bf16 v[22:25], v[150:153], v[182:185], v[22:25]
	v_mfma_f32_16x16x32_bf16 v[18:21], v[158:161], v[182:185], v[18:21]
	v_mfma_f32_16x16x32_bf16 v[6:9], v[150:153], v[206:209], v[6:9]
	v_mfma_f32_16x16x32_bf16 v[2:5], v[158:161], v[206:209], v[2:5]
	s_barrier
	s_setprio 0
	s_add_i32 s89, s89, 2
	s_add_u32 s30, s30, 0x100
	s_addc_u32 s31, s31, 0
	s_add_u32 s81, s81, 0x100
	s_addc_u32 s88, s88, 0
	s_cmp_gt_u32 s89, 29
	s_cbranch_scc1 .Lpeel_done_5
	s_branch .LBB0_823
.Ltrip0_strict_5:
	s_add_u32 s34, s30, 0xfff80080
	s_addc_u32 s35, s31, -1
	s_add_i32 s90, 0, 0x10000
	s_cmp_eq_u32 s89, 28
	s_cselect_b32 s53, s17, s35
	s_cselect_b32 s52, s27, s34
	s_cselect_b32 s35, s15, s88
	s_cselect_b32 s34, s29, s81
	s_add_i32 s96, 0, 0x14000
	v_add_u32_e32 v142, s90, v220
	v_add_u32_e32 v158, s96, v220
	ds_read_b128 v[130:133], v142
	ds_read_b128 v[134:137], v142 offset:1024
	ds_read_b128 v[138:141], v142 offset:2048
	ds_read_b128 v[142:145], v142 offset:3072
	ds_read_b128 v[146:149], v158
	ds_read_b128 v[150:153], v158 offset:1024
	ds_read_b128 v[154:157], v158 offset:2048
	ds_read_b128 v[158:161], v158 offset:3072
	v_lshl_add_u64 v[210:211], s[30:31], 0, v[202:203]
	s_add_i32 m0, s55, 0xc000
	ds_read_b128 v[162:165], v222
	ds_read_b128 v[166:169], v222 offset:1024
	ds_read_b128 v[170:173], v222 offset:2048
	ds_read_b128 v[174:177], v222 offset:3072
	ds_read_b128 v[178:181], v222 offset:4096
	ds_read_b128 v[182:185], v222 offset:5120
	ds_read_b128 v[196:199], v222 offset:6144
	ds_read_b128 v[206:209], v222 offset:7168
	global_load_lds_dwordx4 v[210:211], off
	s_add_i32 m0, s55, 0xe000
	v_lshl_add_u64 v[210:211], s[30:31], 0, v[204:205]
	global_load_lds_dwordx4 v[210:211], off
	s_setprio 1
	s_waitcnt vmcnt(8) lgkmcnt(0)
	s_barrier
	v_mfma_f32_16x16x32_bf16 v[126:129], v[130:133], v[162:165], 0
	v_mfma_f32_16x16x32_bf16 v[122:125], v[138:141], v[162:165], 0
	v_mfma_f32_16x16x32_bf16 v[110:113], v[130:133], v[170:173], 0
	v_mfma_f32_16x16x32_bf16 v[106:109], v[138:141], v[170:173], 0
	v_mfma_f32_16x16x32_bf16 v[94:97], v[130:133], v[178:181], 0
	v_mfma_f32_16x16x32_bf16 v[90:93], v[138:141], v[178:181], 0
	v_mfma_f32_16x16x32_bf16 v[78:81], v[130:133], v[196:199], 0
	v_mfma_f32_16x16x32_bf16 v[74:77], v[138:141], v[196:199], 0
	v_mfma_f32_16x16x32_bf16 v[126:129], v[134:137], v[166:169], v[126:129]
	v_mfma_f32_16x16x32_bf16 v[122:125], v[142:145], v[166:169], v[122:125]
	v_mfma_f32_16x16x32_bf16 v[110:113], v[134:137], v[174:177], v[110:113]
	v_mfma_f32_16x16x32_bf16 v[106:109], v[142:145], v[174:177], v[106:109]
	v_mfma_f32_16x16x32_bf16 v[94:97], v[134:137], v[182:185], v[94:97]
	v_mfma_f32_16x16x32_bf16 v[90:93], v[142:145], v[182:185], v[90:93]
	v_mfma_f32_16x16x32_bf16 v[78:81], v[134:137], v[206:209], v[78:81]
	v_mfma_f32_16x16x32_bf16 v[74:77], v[142:145], v[206:209], v[74:77]
	s_setprio 0
	s_setprio 1
	v_mfma_f32_16x16x32_bf16 v[118:121], v[146:149], v[162:165], 0
	v_mfma_f32_16x16x32_bf16 v[114:117], v[154:157], v[162:165], 0
	v_mfma_f32_16x16x32_bf16 v[102:105], v[146:149], v[170:173], 0
	v_mfma_f32_16x16x32_bf16 v[98:101], v[154:157], v[170:173], 0
	v_mfma_f32_16x16x32_bf16 v[86:89], v[146:149], v[178:181], 0
	v_mfma_f32_16x16x32_bf16 v[82:85], v[154:157], v[178:181], 0
	v_mfma_f32_16x16x32_bf16 v[70:73], v[146:149], v[196:199], 0
	v_mfma_f32_16x16x32_bf16 v[66:69], v[154:157], v[196:199], 0
	v_mfma_f32_16x16x32_bf16 v[118:121], v[150:153], v[166:169], v[118:121]
	v_mfma_f32_16x16x32_bf16 v[114:117], v[158:161], v[166:169], v[114:117]
	v_mfma_f32_16x16x32_bf16 v[102:105], v[150:153], v[174:177], v[102:105]
	v_mfma_f32_16x16x32_bf16 v[98:101], v[158:161], v[174:177], v[98:101]
	v_mfma_f32_16x16x32_bf16 v[86:89], v[150:153], v[182:185], v[86:89]
	v_mfma_f32_16x16x32_bf16 v[82:85], v[158:161], v[182:185], v[82:85]
	v_mfma_f32_16x16x32_bf16 v[70:73], v[150:153], v[206:209], v[70:73]
	v_mfma_f32_16x16x32_bf16 v[66:69], v[158:161], v[206:209], v[66:69]
	s_barrier
	s_setprio 0
	s_add_i32 s90, s90, s47
	v_lshl_add_u64 v[210:211], s[34:35], 0, v[190:191]
	s_mov_b32 m0, s90
	ds_read_b128 v[162:165], v222 offset:16384
	ds_read_b128 v[166:169], v222 offset:17408
	ds_read_b128 v[170:173], v222 offset:18432
	ds_read_b128 v[174:177], v222 offset:19456
	ds_read_b128 v[178:181], v222 offset:20480
	ds_read_b128 v[182:185], v222 offset:21504
	ds_read_b128 v[196:199], v222 offset:22528
	ds_read_b128 v[206:209], v222 offset:23552
	global_load_lds_dwordx4 v[210:211], off
	s_add_i32 m0, s90, 0x2000
	s_add_u32 s90, s34, 0x80000
	v_lshl_add_u64 v[212:213], s[34:35], 0, v[200:201]
	s_addc_u32 s91, s35, 0
	s_add_i32 s96, s96, s47
	global_load_lds_dwordx4 v[212:213], off
	v_lshl_add_u64 v[214:215], s[90:91], 0, v[190:191]
	s_mov_b32 m0, s96
	v_lshl_add_u64 v[216:217], s[52:53], 0, v[188:189]
	global_load_lds_dwordx4 v[214:215], off
	s_add_i32 m0, s96, 0x2000
	v_lshl_add_u64 v[214:215], s[90:91], 0, v[200:201]
	global_load_lds_dwordx4 v[214:215], off
	s_mov_b32 m0, s55
	v_lshl_add_u64 v[214:215], s[52:53], 0, v[186:187]
	global_load_lds_dwordx4 v[214:215], off
	s_mov_b32 m0, s56
	s_nop 0
	global_load_lds_dwordx4 v[216:217], off
	s_setprio 1
	s_waitcnt vmcnt(8) lgkmcnt(0)
	s_barrier
	v_mfma_f32_16x16x32_bf16 v[62:65], v[130:133], v[162:165], 0
	v_mfma_f32_16x16x32_bf16 v[58:61], v[138:141], v[162:165], 0
	v_mfma_f32_16x16x32_bf16 v[46:49], v[130:133], v[170:173], 0
	v_mfma_f32_16x16x32_bf16 v[42:45], v[138:141], v[170:173], 0
	v_mfma_f32_16x16x32_bf16 v[30:33], v[130:133], v[178:181], 0
	v_mfma_f32_16x16x32_bf16 v[26:29], v[138:141], v[178:181], 0
	v_mfma_f32_16x16x32_bf16 v[14:17], v[130:133], v[196:199], 0
	v_mfma_f32_16x16x32_bf16 v[10:13], v[138:141], v[196:199], 0
	v_mfma_f32_16x16x32_bf16 v[62:65], v[134:137], v[166:169], v[62:65]
	v_mfma_f32_16x16x32_bf16 v[58:61], v[142:145], v[166:169], v[58:61]
	v_mfma_f32_16x16x32_bf16 v[46:49], v[134:137], v[174:177], v[46:49]
	v_mfma_f32_16x16x32_bf16 v[42:45], v[142:145], v[174:177], v[42:45]
	v_mfma_f32_16x16x32_bf16 v[30:33], v[134:137], v[182:185], v[30:33]
	v_mfma_f32_16x16x32_bf16 v[26:29], v[142:145], v[182:185], v[26:29]
	v_mfma_f32_16x16x32_bf16 v[14:17], v[134:137], v[206:209], v[14:17]
	v_mfma_f32_16x16x32_bf16 v[10:13], v[142:145], v[206:209], v[10:13]
	s_setprio 0
	s_setprio 1
	v_mfma_f32_16x16x32_bf16 v[54:57], v[146:149], v[162:165], 0
	v_mfma_f32_16x16x32_bf16 v[50:53], v[154:157], v[162:165], 0
	v_mfma_f32_16x16x32_bf16 v[38:41], v[146:149], v[170:173], 0
	v_mfma_f32_16x16x32_bf16 v[34:37], v[154:157], v[170:173], 0
	v_mfma_f32_16x16x32_bf16 v[22:25], v[146:149], v[178:181], 0
	v_mfma_f32_16x16x32_bf16 v[18:21], v[154:157], v[178:181], 0
	v_mfma_f32_16x16x32_bf16 v[6:9], v[146:149], v[196:199], 0
	v_mfma_f32_16x16x32_bf16 v[2:5], v[154:157], v[196:199], 0
	v_mfma_f32_16x16x32_bf16 v[54:57], v[150:153], v[166:169], v[54:57]
	v_mfma_f32_16x16x32_bf16 v[50:53], v[158:161], v[166:169], v[50:53]
	v_mfma_f32_16x16x32_bf16 v[38:41], v[150:153], v[174:177], v[38:41]
	v_mfma_f32_16x16x32_bf16 v[34:37], v[158:161], v[174:177], v[34:37]
	v_mfma_f32_16x16x32_bf16 v[22:25], v[150:153], v[182:185], v[22:25]
	v_mfma_f32_16x16x32_bf16 v[18:21], v[158:161], v[182:185], v[18:21]
	v_mfma_f32_16x16x32_bf16 v[6:9], v[150:153], v[206:209], v[6:9]
	v_mfma_f32_16x16x32_bf16 v[2:5], v[158:161], v[206:209], v[2:5]
	s_barrier
	s_setprio 0
	s_add_i32 s90, 0, 0x18000
	s_add_i32 s91, 0, 0x1c000
	v_add_u32_e32 v142, s90, v220
	v_add_u32_e32 v158, s91, v220
	ds_read_b128 v[130:133], v142
	ds_read_b128 v[134:137], v142 offset:1024
	ds_read_b128 v[138:141], v142 offset:2048
	ds_read_b128 v[142:145], v142 offset:3072
	ds_read_b128 v[146:149], v158
	ds_read_b128 v[150:153], v158 offset:1024
	ds_read_b128 v[154:157], v158 offset:2048
	ds_read_b128 v[158:161], v158 offset:3072
	s_add_u32 s52, s52, 0x80000
	s_addc_u32 s53, s53, 0
	s_mov_b32 m0, s57
	v_lshl_add_u64 v[218:219], s[52:53], 0, v[186:187]
	ds_read_b128 v[162:165], v222 offset:32768
	ds_read_b128 v[166:169], v222 offset:33792
	ds_read_b128 v[170:173], v222 offset:34816
	ds_read_b128 v[174:177], v222 offset:35840
	ds_read_b128 v[178:181], v222 offset:36864
	ds_read_b128 v[182:185], v222 offset:37888
	ds_read_b128 v[196:199], v222 offset:38912
	ds_read_b128 v[206:209], v222 offset:39936
	global_load_lds_dwordx4 v[218:219], off
	s_mov_b32 m0, s60
	v_lshl_add_u64 v[218:219], s[52:53], 0, v[188:189]
	global_load_lds_dwordx4 v[218:219], off
	s_setprio 1
	s_waitcnt vmcnt(8) lgkmcnt(0)
	s_barrier
	v_mfma_f32_16x16x32_bf16 v[126:129], v[130:133], v[162:165], v[126:129]
	v_mfma_f32_16x16x32_bf16 v[122:125], v[138:141], v[162:165], v[122:125]
	v_mfma_f32_16x16x32_bf16 v[110:113], v[130:133], v[170:173], v[110:113]
	v_mfma_f32_16x16x32_bf16 v[106:109], v[138:141], v[170:173], v[106:109]
	v_mfma_f32_16x16x32_bf16 v[94:97], v[130:133], v[178:181], v[94:97]
	v_mfma_f32_16x16x32_bf16 v[90:93], v[138:141], v[178:181], v[90:93]
	v_mfma_f32_16x16x32_bf16 v[78:81], v[130:133], v[196:199], v[78:81]
	v_mfma_f32_16x16x32_bf16 v[74:77], v[138:141], v[196:199], v[74:77]
	v_mfma_f32_16x16x32_bf16 v[126:129], v[134:137], v[166:169], v[126:129]
	v_mfma_f32_16x16x32_bf16 v[122:125], v[142:145], v[166:169], v[122:125]
	v_mfma_f32_16x16x32_bf16 v[110:113], v[134:137], v[174:177], v[110:113]
	v_mfma_f32_16x16x32_bf16 v[106:109], v[142:145], v[174:177], v[106:109]
	v_mfma_f32_16x16x32_bf16 v[94:97], v[134:137], v[182:185], v[94:97]
	v_mfma_f32_16x16x32_bf16 v[90:93], v[142:145], v[182:185], v[90:93]
	v_mfma_f32_16x16x32_bf16 v[78:81], v[134:137], v[206:209], v[78:81]
	v_mfma_f32_16x16x32_bf16 v[74:77], v[142:145], v[206:209], v[74:77]
	s_setprio 0
	s_setprio 1
	v_mfma_f32_16x16x32_bf16 v[118:121], v[146:149], v[162:165], v[118:121]
	v_mfma_f32_16x16x32_bf16 v[114:117], v[154:157], v[162:165], v[114:117]
	v_mfma_f32_16x16x32_bf16 v[102:105], v[146:149], v[170:173], v[102:105]
	v_mfma_f32_16x16x32_bf16 v[98:101], v[154:157], v[170:173], v[98:101]
	v_mfma_f32_16x16x32_bf16 v[86:89], v[146:149], v[178:181], v[86:89]
	v_mfma_f32_16x16x32_bf16 v[82:85], v[154:157], v[178:181], v[82:85]
	v_mfma_f32_16x16x32_bf16 v[70:73], v[146:149], v[196:199], v[70:73]
	v_mfma_f32_16x16x32_bf16 v[66:69], v[154:157], v[196:199], v[66:69]
	v_mfma_f32_16x16x32_bf16 v[118:121], v[150:153], v[166:169], v[118:121]
	v_mfma_f32_16x16x32_bf16 v[114:117], v[158:161], v[166:169], v[114:117]
	v_mfma_f32_16x16x32_bf16 v[102:105], v[150:153], v[174:177], v[102:105]
	v_mfma_f32_16x16x32_bf16 v[98:101], v[158:161], v[174:177], v[98:101]
	v_mfma_f32_16x16x32_bf16 v[86:89], v[150:153], v[182:185], v[86:89]
	v_mfma_f32_16x16x32_bf16 v[82:85], v[158:161], v[182:185], v[82:85]
	v_mfma_f32_16x16x32_bf16 v[70:73], v[150:153], v[206:209], v[70:73]
	v_mfma_f32_16x16x32_bf16 v[66:69], v[158:161], v[206:209], v[66:69]
	s_barrier
	s_setprio 0
	s_add_i32 s52, s90, s47
	v_lshl_add_u64 v[210:211], v[210:211], 0, s[58:59]
	s_mov_b32 m0, s52
	ds_read_b128 v[162:165], v222 offset:49152
	ds_read_b128 v[166:169], v222 offset:50176
	ds_read_b128 v[170:173], v222 offset:51200
	ds_read_b128 v[174:177], v222 offset:52224
	ds_read_b128 v[178:181], v222 offset:53248
	ds_read_b128 v[182:185], v222 offset:54272
	ds_read_b128 v[196:199], v222 offset:55296
	ds_read_b128 v[206:209], v222 offset:56320
	global_load_lds_dwordx4 v[210:211], off
	s_add_i32 m0, s52, 0x2000
	s_add_u32 s34, s34, 0x80080
	v_lshl_add_u64 v[210:211], v[212:213], 0, s[58:59]
	s_addc_u32 s35, s35, 0
	s_add_i32 s52, s91, s47
	global_load_lds_dwordx4 v[210:211], off
	s_mov_b32 m0, s52
	v_lshl_add_u64 v[210:211], s[34:35], 0, v[190:191]
	global_load_lds_dwordx4 v[210:211], off
	s_add_i32 m0, s52, 0x2000
	v_lshl_add_u64 v[210:211], s[34:35], 0, v[200:201]
	global_load_lds_dwordx4 v[210:211], off
	s_mov_b32 m0, s61
	v_lshl_add_u64 v[210:211], v[214:215], 0, s[58:59]
	global_load_lds_dwordx4 v[210:211], off
	s_mov_b32 m0, s69
	v_lshl_add_u64 v[210:211], v[216:217], 0, s[58:59]
	global_load_lds_dwordx4 v[210:211], off
	s_setprio 1
	s_waitcnt vmcnt(8) lgkmcnt(0)
	s_barrier
	v_mfma_f32_16x16x32_bf16 v[62:65], v[130:133], v[162:165], v[62:65]
	v_mfma_f32_16x16x32_bf16 v[58:61], v[138:141], v[162:165], v[58:61]
	v_mfma_f32_16x16x32_bf16 v[46:49], v[130:133], v[170:173], v[46:49]
	v_mfma_f32_16x16x32_bf16 v[42:45], v[138:141], v[170:173], v[42:45]
	v_mfma_f32_16x16x32_bf16 v[30:33], v[130:133], v[178:181], v[30:33]
	v_mfma_f32_16x16x32_bf16 v[26:29], v[138:141], v[178:181], v[26:29]
	v_mfma_f32_16x16x32_bf16 v[14:17], v[130:133], v[196:199], v[14:17]
	v_mfma_f32_16x16x32_bf16 v[10:13], v[138:141], v[196:199], v[10:13]
	v_mfma_f32_16x16x32_bf16 v[62:65], v[134:137], v[166:169], v[62:65]
	v_mfma_f32_16x16x32_bf16 v[58:61], v[142:145], v[166:169], v[58:61]
	v_mfma_f32_16x16x32_bf16 v[46:49], v[134:137], v[174:177], v[46:49]
	v_mfma_f32_16x16x32_bf16 v[42:45], v[142:145], v[174:177], v[42:45]
	v_mfma_f32_16x16x32_bf16 v[30:33], v[134:137], v[182:185], v[30:33]
	v_mfma_f32_16x16x32_bf16 v[26:29], v[142:145], v[182:185], v[26:29]
	v_mfma_f32_16x16x32_bf16 v[14:17], v[134:137], v[206:209], v[14:17]
	v_mfma_f32_16x16x32_bf16 v[10:13], v[142:145], v[206:209], v[10:13]
	s_setprio 0
	s_setprio 1
	v_mfma_f32_16x16x32_bf16 v[54:57], v[146:149], v[162:165], v[54:57]
	v_mfma_f32_16x16x32_bf16 v[50:53], v[154:157], v[162:165], v[50:53]
	v_mfma_f32_16x16x32_bf16 v[38:41], v[146:149], v[170:173], v[38:41]
	v_mfma_f32_16x16x32_bf16 v[34:37], v[154:157], v[170:173], v[34:37]
	v_mfma_f32_16x16x32_bf16 v[22:25], v[146:149], v[178:181], v[22:25]
	v_mfma_f32_16x16x32_bf16 v[18:21], v[154:157], v[178:181], v[18:21]
	v_mfma_f32_16x16x32_bf16 v[6:9], v[146:149], v[196:199], v[6:9]
	v_mfma_f32_16x16x32_bf16 v[2:5], v[154:157], v[196:199], v[2:5]
	v_mfma_f32_16x16x32_bf16 v[54:57], v[150:153], v[166:169], v[54:57]
	v_mfma_f32_16x16x32_bf16 v[50:53], v[158:161], v[166:169], v[50:53]
	v_mfma_f32_16x16x32_bf16 v[38:41], v[150:153], v[174:177], v[38:41]
	v_mfma_f32_16x16x32_bf16 v[34:37], v[158:161], v[174:177], v[34:37]
	v_mfma_f32_16x16x32_bf16 v[22:25], v[150:153], v[182:185], v[22:25]
	v_mfma_f32_16x16x32_bf16 v[18:21], v[158:161], v[182:185], v[18:21]
	v_mfma_f32_16x16x32_bf16 v[6:9], v[150:153], v[206:209], v[6:9]
	v_mfma_f32_16x16x32_bf16 v[2:5], v[158:161], v[206:209], v[2:5]
	s_barrier
	s_setprio 0
	s_add_i32 s89, s89, 2
	s_add_u32 s30, s30, 0x100
	s_addc_u32 s31, s31, 0
	s_add_u32 s81, s81, 0x100
	s_addc_u32 s88, s88, 0
	s_cmp_gt_u32 s89, 29
	s_cbranch_scc1 .Lpeel_done_5
.LBB0_823:
	s_add_u32 s34, s30, 0xfff80080
	s_addc_u32 s35, s31, -1
	s_add_i32 s90, 0, 0x10000
	s_cmp_eq_u32 s89, 28
	s_cselect_b32 s53, s17, s35
	s_cselect_b32 s52, s27, s34
	s_cselect_b32 s35, s15, s88
	s_cselect_b32 s34, s29, s81
	s_add_i32 s96, 0, 0x14000
	v_add_u32_e32 v142, s90, v220
	v_add_u32_e32 v158, s96, v220
	ds_read_b128 v[130:133], v142
	ds_read_b128 v[134:137], v142 offset:1024
	ds_read_b128 v[138:141], v142 offset:2048
	ds_read_b128 v[142:145], v142 offset:3072
	ds_read_b128 v[146:149], v158
	ds_read_b128 v[150:153], v158 offset:1024
	ds_read_b128 v[154:157], v158 offset:2048
	ds_read_b128 v[158:161], v158 offset:3072
	v_lshl_add_u64 v[210:211], s[30:31], 0, v[202:203]
	s_add_i32 m0, s55, 0xc000
	ds_read_b128 v[162:165], v222
	ds_read_b128 v[166:169], v222 offset:1024
	ds_read_b128 v[170:173], v222 offset:2048
	ds_read_b128 v[174:177], v222 offset:3072
	ds_read_b128 v[178:181], v222 offset:4096
	ds_read_b128 v[182:185], v222 offset:5120
	ds_read_b128 v[196:199], v222 offset:6144
	ds_read_b128 v[206:209], v222 offset:7168
	global_load_lds_dwordx4 v[210:211], off
	s_add_i32 m0, s55, 0xe000
	v_lshl_add_u64 v[210:211], s[30:31], 0, v[204:205]
	global_load_lds_dwordx4 v[210:211], off
	s_setprio 1
	s_waitcnt vmcnt(8) lgkmcnt(0)
	s_barrier
	v_mfma_f32_16x16x32_bf16 v[126:129], v[130:133], v[162:165], v[126:129]
	v_mfma_f32_16x16x32_bf16 v[122:125], v[138:141], v[162:165], v[122:125]
	v_mfma_f32_16x16x32_bf16 v[110:113], v[130:133], v[170:173], v[110:113]
	v_mfma_f32_16x16x32_bf16 v[106:109], v[138:141], v[170:173], v[106:109]
	v_mfma_f32_16x16x32_bf16 v[94:97], v[130:133], v[178:181], v[94:97]
	v_mfma_f32_16x16x32_bf16 v[90:93], v[138:141], v[178:181], v[90:93]
	v_mfma_f32_16x16x32_bf16 v[78:81], v[130:133], v[196:199], v[78:81]
	v_mfma_f32_16x16x32_bf16 v[74:77], v[138:141], v[196:199], v[74:77]
	v_mfma_f32_16x16x32_bf16 v[126:129], v[134:137], v[166:169], v[126:129]
	v_mfma_f32_16x16x32_bf16 v[122:125], v[142:145], v[166:169], v[122:125]
	v_mfma_f32_16x16x32_bf16 v[110:113], v[134:137], v[174:177], v[110:113]
	v_mfma_f32_16x16x32_bf16 v[106:109], v[142:145], v[174:177], v[106:109]
	v_mfma_f32_16x16x32_bf16 v[94:97], v[134:137], v[182:185], v[94:97]
	v_mfma_f32_16x16x32_bf16 v[90:93], v[142:145], v[182:185], v[90:93]
	v_mfma_f32_16x16x32_bf16 v[78:81], v[134:137], v[206:209], v[78:81]
	v_mfma_f32_16x16x32_bf16 v[74:77], v[142:145], v[206:209], v[74:77]
	s_setprio 0
	s_setprio 1
	v_mfma_f32_16x16x32_bf16 v[118:121], v[146:149], v[162:165], v[118:121]
	v_mfma_f32_16x16x32_bf16 v[114:117], v[154:157], v[162:165], v[114:117]
	v_mfma_f32_16x16x32_bf16 v[102:105], v[146:149], v[170:173], v[102:105]
	v_mfma_f32_16x16x32_bf16 v[98:101], v[154:157], v[170:173], v[98:101]
	v_mfma_f32_16x16x32_bf16 v[86:89], v[146:149], v[178:181], v[86:89]
	v_mfma_f32_16x16x32_bf16 v[82:85], v[154:157], v[178:181], v[82:85]
	v_mfma_f32_16x16x32_bf16 v[70:73], v[146:149], v[196:199], v[70:73]
	v_mfma_f32_16x16x32_bf16 v[66:69], v[154:157], v[196:199], v[66:69]
	v_mfma_f32_16x16x32_bf16 v[118:121], v[150:153], v[166:169], v[118:121]
	v_mfma_f32_16x16x32_bf16 v[114:117], v[158:161], v[166:169], v[114:117]
	v_mfma_f32_16x16x32_bf16 v[102:105], v[150:153], v[174:177], v[102:105]
	v_mfma_f32_16x16x32_bf16 v[98:101], v[158:161], v[174:177], v[98:101]
	v_mfma_f32_16x16x32_bf16 v[86:89], v[150:153], v[182:185], v[86:89]
	v_mfma_f32_16x16x32_bf16 v[82:85], v[158:161], v[182:185], v[82:85]
	v_mfma_f32_16x16x32_bf16 v[70:73], v[150:153], v[206:209], v[70:73]
	v_mfma_f32_16x16x32_bf16 v[66:69], v[158:161], v[206:209], v[66:69]
	s_setprio 0
	s_barrier
	s_add_i32 s90, s90, s47
	v_lshl_add_u64 v[210:211], s[34:35], 0, v[190:191]
	s_mov_b32 m0, s90
	ds_read_b128 v[162:165], v222 offset:16384
	ds_read_b128 v[166:169], v222 offset:17408
	ds_read_b128 v[170:173], v222 offset:18432
	ds_read_b128 v[174:177], v222 offset:19456
	ds_read_b128 v[178:181], v222 offset:20480
	ds_read_b128 v[182:185], v222 offset:21504
	ds_read_b128 v[196:199], v222 offset:22528
	ds_read_b128 v[206:209], v222 offset:23552
	global_load_lds_dwordx4 v[210:211], off
	s_add_i32 m0, s90, 0x2000
	s_add_u32 s90, s34, 0x80000
	v_lshl_add_u64 v[212:213], s[34:35], 0, v[200:201]
	s_addc_u32 s91, s35, 0
	s_add_i32 s96, s96, s47
	global_load_lds_dwordx4 v[212:213], off
	v_lshl_add_u64 v[214:215], s[90:91], 0, v[190:191]
	s_mov_b32 m0, s96
	v_lshl_add_u64 v[216:217], s[52:53], 0, v[188:189]
	global_load_lds_dwordx4 v[214:215], off
	s_add_i32 m0, s96, 0x2000
	v_lshl_add_u64 v[214:215], s[90:91], 0, v[200:201]
	global_load_lds_dwordx4 v[214:215], off
	s_mov_b32 m0, s55
	v_lshl_add_u64 v[214:215], s[52:53], 0, v[186:187]
	global_load_lds_dwordx4 v[214:215], off
	s_mov_b32 m0, s56
	s_nop 0
	global_load_lds_dwordx4 v[216:217], off
	s_setprio 1
	s_waitcnt vmcnt(8) lgkmcnt(0)
	s_barrier
	v_mfma_f32_16x16x32_bf16 v[62:65], v[130:133], v[162:165], v[62:65]
	v_mfma_f32_16x16x32_bf16 v[58:61], v[138:141], v[162:165], v[58:61]
	v_mfma_f32_16x16x32_bf16 v[46:49], v[130:133], v[170:173], v[46:49]
	v_mfma_f32_16x16x32_bf16 v[42:45], v[138:141], v[170:173], v[42:45]
	v_mfma_f32_16x16x32_bf16 v[30:33], v[130:133], v[178:181], v[30:33]
	v_mfma_f32_16x16x32_bf16 v[26:29], v[138:141], v[178:181], v[26:29]
	v_mfma_f32_16x16x32_bf16 v[14:17], v[130:133], v[196:199], v[14:17]
	v_mfma_f32_16x16x32_bf16 v[10:13], v[138:141], v[196:199], v[10:13]
	v_mfma_f32_16x16x32_bf16 v[62:65], v[134:137], v[166:169], v[62:65]
	v_mfma_f32_16x16x32_bf16 v[58:61], v[142:145], v[166:169], v[58:61]
	v_mfma_f32_16x16x32_bf16 v[46:49], v[134:137], v[174:177], v[46:49]
	v_mfma_f32_16x16x32_bf16 v[42:45], v[142:145], v[174:177], v[42:45]
	v_mfma_f32_16x16x32_bf16 v[30:33], v[134:137], v[182:185], v[30:33]
	v_mfma_f32_16x16x32_bf16 v[26:29], v[142:145], v[182:185], v[26:29]
	v_mfma_f32_16x16x32_bf16 v[14:17], v[134:137], v[206:209], v[14:17]
	v_mfma_f32_16x16x32_bf16 v[10:13], v[142:145], v[206:209], v[10:13]
	s_setprio 0
	s_setprio 1
	v_mfma_f32_16x16x32_bf16 v[54:57], v[146:149], v[162:165], v[54:57]
	v_mfma_f32_16x16x32_bf16 v[50:53], v[154:157], v[162:165], v[50:53]
	v_mfma_f32_16x16x32_bf16 v[38:41], v[146:149], v[170:173], v[38:41]
	v_mfma_f32_16x16x32_bf16 v[34:37], v[154:157], v[170:173], v[34:37]
	v_mfma_f32_16x16x32_bf16 v[22:25], v[146:149], v[178:181], v[22:25]
	v_mfma_f32_16x16x32_bf16 v[18:21], v[154:157], v[178:181], v[18:21]
	v_mfma_f32_16x16x32_bf16 v[6:9], v[146:149], v[196:199], v[6:9]
	v_mfma_f32_16x16x32_bf16 v[2:5], v[154:157], v[196:199], v[2:5]
	v_mfma_f32_16x16x32_bf16 v[54:57], v[150:153], v[166:169], v[54:57]
	v_mfma_f32_16x16x32_bf16 v[50:53], v[158:161], v[166:169], v[50:53]
	v_mfma_f32_16x16x32_bf16 v[38:41], v[150:153], v[174:177], v[38:41]
	v_mfma_f32_16x16x32_bf16 v[34:37], v[158:161], v[174:177], v[34:37]
	v_mfma_f32_16x16x32_bf16 v[22:25], v[150:153], v[182:185], v[22:25]
	v_mfma_f32_16x16x32_bf16 v[18:21], v[158:161], v[182:185], v[18:21]
	v_mfma_f32_16x16x32_bf16 v[6:9], v[150:153], v[206:209], v[6:9]
	v_mfma_f32_16x16x32_bf16 v[2:5], v[158:161], v[206:209], v[2:5]
	s_setprio 0
	s_barrier
	s_add_i32 s90, 0, 0x18000
	s_add_i32 s91, 0, 0x1c000
	v_add_u32_e32 v142, s90, v220
	v_add_u32_e32 v158, s91, v220
	ds_read_b128 v[130:133], v142
	ds_read_b128 v[134:137], v142 offset:1024
	ds_read_b128 v[138:141], v142 offset:2048
	ds_read_b128 v[142:145], v142 offset:3072
	ds_read_b128 v[146:149], v158
	ds_read_b128 v[150:153], v158 offset:1024
	ds_read_b128 v[154:157], v158 offset:2048
	ds_read_b128 v[158:161], v158 offset:3072
	s_add_u32 s52, s52, 0x80000
	s_addc_u32 s53, s53, 0
	s_mov_b32 m0, s57
	v_lshl_add_u64 v[218:219], s[52:53], 0, v[186:187]
	ds_read_b128 v[162:165], v222 offset:32768
	ds_read_b128 v[166:169], v222 offset:33792
	ds_read_b128 v[170:173], v222 offset:34816
	ds_read_b128 v[174:177], v222 offset:35840
	ds_read_b128 v[178:181], v222 offset:36864
	ds_read_b128 v[182:185], v222 offset:37888
	ds_read_b128 v[196:199], v222 offset:38912
	ds_read_b128 v[206:209], v222 offset:39936
	global_load_lds_dwordx4 v[218:219], off
	s_mov_b32 m0, s60
	v_lshl_add_u64 v[218:219], s[52:53], 0, v[188:189]
	global_load_lds_dwordx4 v[218:219], off
	s_setprio 1
	s_waitcnt vmcnt(8) lgkmcnt(0)
	s_barrier
	v_mfma_f32_16x16x32_bf16 v[126:129], v[130:133], v[162:165], v[126:129]
	v_mfma_f32_16x16x32_bf16 v[122:125], v[138:141], v[162:165], v[122:125]
	v_mfma_f32_16x16x32_bf16 v[110:113], v[130:133], v[170:173], v[110:113]
	v_mfma_f32_16x16x32_bf16 v[106:109], v[138:141], v[170:173], v[106:109]
	v_mfma_f32_16x16x32_bf16 v[94:97], v[130:133], v[178:181], v[94:97]
	v_mfma_f32_16x16x32_bf16 v[90:93], v[138:141], v[178:181], v[90:93]
	v_mfma_f32_16x16x32_bf16 v[78:81], v[130:133], v[196:199], v[78:81]
	v_mfma_f32_16x16x32_bf16 v[74:77], v[138:141], v[196:199], v[74:77]
	v_mfma_f32_16x16x32_bf16 v[126:129], v[134:137], v[166:169], v[126:129]
	v_mfma_f32_16x16x32_bf16 v[122:125], v[142:145], v[166:169], v[122:125]
	v_mfma_f32_16x16x32_bf16 v[110:113], v[134:137], v[174:177], v[110:113]
	v_mfma_f32_16x16x32_bf16 v[106:109], v[142:145], v[174:177], v[106:109]
	v_mfma_f32_16x16x32_bf16 v[94:97], v[134:137], v[182:185], v[94:97]
	v_mfma_f32_16x16x32_bf16 v[90:93], v[142:145], v[182:185], v[90:93]
	v_mfma_f32_16x16x32_bf16 v[78:81], v[134:137], v[206:209], v[78:81]
	v_mfma_f32_16x16x32_bf16 v[74:77], v[142:145], v[206:209], v[74:77]
	s_setprio 0
	s_setprio 1
	v_mfma_f32_16x16x32_bf16 v[118:121], v[146:149], v[162:165], v[118:121]
	v_mfma_f32_16x16x32_bf16 v[114:117], v[154:157], v[162:165], v[114:117]
	v_mfma_f32_16x16x32_bf16 v[102:105], v[146:149], v[170:173], v[102:105]
	v_mfma_f32_16x16x32_bf16 v[98:101], v[154:157], v[170:173], v[98:101]
	v_mfma_f32_16x16x32_bf16 v[86:89], v[146:149], v[178:181], v[86:89]
	v_mfma_f32_16x16x32_bf16 v[82:85], v[154:157], v[178:181], v[82:85]
	v_mfma_f32_16x16x32_bf16 v[70:73], v[146:149], v[196:199], v[70:73]
	v_mfma_f32_16x16x32_bf16 v[66:69], v[154:157], v[196:199], v[66:69]
	v_mfma_f32_16x16x32_bf16 v[118:121], v[150:153], v[166:169], v[118:121]
	v_mfma_f32_16x16x32_bf16 v[114:117], v[158:161], v[166:169], v[114:117]
	v_mfma_f32_16x16x32_bf16 v[102:105], v[150:153], v[174:177], v[102:105]
	v_mfma_f32_16x16x32_bf16 v[98:101], v[158:161], v[174:177], v[98:101]
	v_mfma_f32_16x16x32_bf16 v[86:89], v[150:153], v[182:185], v[86:89]
	v_mfma_f32_16x16x32_bf16 v[82:85], v[158:161], v[182:185], v[82:85]
	v_mfma_f32_16x16x32_bf16 v[70:73], v[150:153], v[206:209], v[70:73]
	v_mfma_f32_16x16x32_bf16 v[66:69], v[158:161], v[206:209], v[66:69]
	s_setprio 0
	s_barrier
	s_add_i32 s52, s90, s47
	v_lshl_add_u64 v[210:211], v[210:211], 0, s[58:59]
	s_mov_b32 m0, s52
	ds_read_b128 v[162:165], v222 offset:49152
	ds_read_b128 v[166:169], v222 offset:50176
	ds_read_b128 v[170:173], v222 offset:51200
	ds_read_b128 v[174:177], v222 offset:52224
	ds_read_b128 v[178:181], v222 offset:53248
	ds_read_b128 v[182:185], v222 offset:54272
	ds_read_b128 v[196:199], v222 offset:55296
	ds_read_b128 v[206:209], v222 offset:56320
	global_load_lds_dwordx4 v[210:211], off
	s_add_i32 m0, s52, 0x2000
	s_add_u32 s34, s34, 0x80080
	v_lshl_add_u64 v[210:211], v[212:213], 0, s[58:59]
	s_addc_u32 s35, s35, 0
	s_add_i32 s52, s91, s47
	global_load_lds_dwordx4 v[210:211], off
	s_mov_b32 m0, s52
	v_lshl_add_u64 v[210:211], s[34:35], 0, v[190:191]
	global_load_lds_dwordx4 v[210:211], off
	s_add_i32 m0, s52, 0x2000
	v_lshl_add_u64 v[210:211], s[34:35], 0, v[200:201]
	global_load_lds_dwordx4 v[210:211], off
	s_mov_b32 m0, s61
	v_lshl_add_u64 v[210:211], v[214:215], 0, s[58:59]
	global_load_lds_dwordx4 v[210:211], off
	s_mov_b32 m0, s69
	v_lshl_add_u64 v[210:211], v[216:217], 0, s[58:59]
	global_load_lds_dwordx4 v[210:211], off
	s_setprio 1
	s_waitcnt vmcnt(8) lgkmcnt(0)
	s_barrier
	v_mfma_f32_16x16x32_bf16 v[62:65], v[130:133], v[162:165], v[62:65]
	v_mfma_f32_16x16x32_bf16 v[58:61], v[138:141], v[162:165], v[58:61]
	v_mfma_f32_16x16x32_bf16 v[46:49], v[130:133], v[170:173], v[46:49]
	v_mfma_f32_16x16x32_bf16 v[42:45], v[138:141], v[170:173], v[42:45]
	v_mfma_f32_16x16x32_bf16 v[30:33], v[130:133], v[178:181], v[30:33]
	v_mfma_f32_16x16x32_bf16 v[26:29], v[138:141], v[178:181], v[26:29]
	v_mfma_f32_16x16x32_bf16 v[14:17], v[130:133], v[196:199], v[14:17]
	v_mfma_f32_16x16x32_bf16 v[10:13], v[138:141], v[196:199], v[10:13]
	v_mfma_f32_16x16x32_bf16 v[62:65], v[134:137], v[166:169], v[62:65]
	v_mfma_f32_16x16x32_bf16 v[58:61], v[142:145], v[166:169], v[58:61]
	v_mfma_f32_16x16x32_bf16 v[46:49], v[134:137], v[174:177], v[46:49]
	v_mfma_f32_16x16x32_bf16 v[42:45], v[142:145], v[174:177], v[42:45]
	v_mfma_f32_16x16x32_bf16 v[30:33], v[134:137], v[182:185], v[30:33]
	v_mfma_f32_16x16x32_bf16 v[26:29], v[142:145], v[182:185], v[26:29]
	v_mfma_f32_16x16x32_bf16 v[14:17], v[134:137], v[206:209], v[14:17]
	v_mfma_f32_16x16x32_bf16 v[10:13], v[142:145], v[206:209], v[10:13]
	s_setprio 0
	s_setprio 1
	v_mfma_f32_16x16x32_bf16 v[54:57], v[146:149], v[162:165], v[54:57]
	v_mfma_f32_16x16x32_bf16 v[50:53], v[154:157], v[162:165], v[50:53]
	v_mfma_f32_16x16x32_bf16 v[38:41], v[146:149], v[170:173], v[38:41]
	v_mfma_f32_16x16x32_bf16 v[34:37], v[154:157], v[170:173], v[34:37]
	v_mfma_f32_16x16x32_bf16 v[22:25], v[146:149], v[178:181], v[22:25]
	v_mfma_f32_16x16x32_bf16 v[18:21], v[154:157], v[178:181], v[18:21]
	v_mfma_f32_16x16x32_bf16 v[6:9], v[146:149], v[196:199], v[6:9]
	v_mfma_f32_16x16x32_bf16 v[2:5], v[154:157], v[196:199], v[2:5]
	v_mfma_f32_16x16x32_bf16 v[54:57], v[150:153], v[166:169], v[54:57]
	v_mfma_f32_16x16x32_bf16 v[50:53], v[158:161], v[166:169], v[50:53]
	v_mfma_f32_16x16x32_bf16 v[38:41], v[150:153], v[174:177], v[38:41]
	v_mfma_f32_16x16x32_bf16 v[34:37], v[158:161], v[174:177], v[34:37]
	v_mfma_f32_16x16x32_bf16 v[22:25], v[150:153], v[182:185], v[22:25]
	v_mfma_f32_16x16x32_bf16 v[18:21], v[158:161], v[182:185], v[18:21]
	v_mfma_f32_16x16x32_bf16 v[6:9], v[150:153], v[206:209], v[6:9]
	v_mfma_f32_16x16x32_bf16 v[2:5], v[158:161], v[206:209], v[2:5]
	s_setprio 0
	s_barrier
	s_add_i32 s89, s89, 2
	s_add_u32 s30, s30, 0x100
	s_addc_u32 s31, s31, 0
	s_add_u32 s81, s81, 0x100
	s_addc_u32 s88, s88, 0
	s_cmp_gt_u32 s89, 29
	s_cbranch_scc0 .LBB0_823

.LBB0_937:
	s_ashr_i32 s23, s22, 31
	s_lshl_b64 s[4:5], s[22:23], 20
	s_add_u32 s4, s86, s4
	s_addc_u32 s5, s87, s5
	s_and_b64 s[26:27], s[24:25], exec
	s_cselect_b32 s11, s5, s29
	s_cselect_b32 s23, s4, s28
	s_ashr_i32 s21, s20, 31
	s_lshl_b64 s[26:27], s[20:21], 20
	v_readlane_b32 s0, v254, 38
	v_readlane_b32 s1, v254, 39
	s_add_u32 s26, s0, s26
	s_addc_u32 s27, s1, s27
	s_and_b64 s[34:35], s[24:25], exec
	s_cselect_b32 s21, s27, s31
	s_cselect_b32 s53, s26, s30
	s_add_u32 s28, s28, 0x80080
	s_addc_u32 s29, s29, 0
	s_add_u32 s55, s30, 0x100
	s_addc_u32 s56, s31, 0
	s_mov_b32 s57, -2
	v_readlane_b32 s60, v255, 49
	s_nop 3
	s_cmp_eq_u32 s60, 7
	v_writelane_b32 v255, 7, 49
	s_cbranch_scc0 .Ltrip0_strict_6
	s_add_u32 s30, s28, 0xfff80080
	s_addc_u32 s31, s29, -1
	s_add_i32 s60, 0, 0x10000
	s_cmp_eq_u32 s57, 28
	s_cselect_b32 s35, s11, s31
	s_cselect_b32 s34, s23, s30
	s_cselect_b32 s31, s21, s56
	s_cselect_b32 s30, s53, s55
	s_add_i32 s66, 0, 0x14000
	v_add_u32_e32 v154, s60, v139
	v_add_u32_e32 v170, s66, v139
	ds_read_b128 v[142:145], v154
	ds_read_b128 v[146:149], v154 offset:1024
	ds_read_b128 v[150:153], v154 offset:2048
	ds_read_b128 v[154:157], v154 offset:3072
	ds_read_b128 v[158:161], v170
	ds_read_b128 v[162:165], v170 offset:1024
	ds_read_b128 v[166:169], v170 offset:2048
	ds_read_b128 v[170:173], v170 offset:3072
	v_lshl_add_u64 v[186:187], s[28:29], 0, v[134:135]
	s_add_i32 m0, s13, 0xc000
	ds_read_b128 v[174:177], v141
	ds_read_b128 v[178:181], v141 offset:1024
	ds_read_b128 v[182:185], v141 offset:2048
	ds_read_b128 v[196:199], v141 offset:3072
	ds_read_b128 v[200:203], v141 offset:4096
	ds_read_b128 v[204:207], v141 offset:5120
	ds_read_b128 v[208:211], v141 offset:6144
	ds_read_b128 v[212:215], v141 offset:7168
	global_load_lds_dwordx4 v[186:187], off
	s_add_i32 m0, s13, 0xe000
	v_lshl_add_u64 v[186:187], s[28:29], 0, v[136:137]
	global_load_lds_dwordx4 v[186:187], off
	s_setprio 1
	s_waitcnt vmcnt(24) lgkmcnt(0)
	s_barrier
	v_mfma_f32_16x16x32_bf16 v[124:127], v[142:145], v[174:177], 0
	v_mfma_f32_16x16x32_bf16 v[120:123], v[150:153], v[174:177], 0
	v_mfma_f32_16x16x32_bf16 v[116:119], v[142:145], v[182:185], 0
	v_mfma_f32_16x16x32_bf16 v[112:115], v[150:153], v[182:185], 0
	v_mfma_f32_16x16x32_bf16 v[100:103], v[142:145], v[200:203], 0
	v_mfma_f32_16x16x32_bf16 v[96:99], v[150:153], v[200:203], 0
	v_mfma_f32_16x16x32_bf16 v[84:87], v[142:145], v[208:211], 0
	v_mfma_f32_16x16x32_bf16 v[80:83], v[150:153], v[208:211], 0
	v_mfma_f32_16x16x32_bf16 v[124:127], v[146:149], v[178:181], v[124:127]
	v_mfma_f32_16x16x32_bf16 v[120:123], v[154:157], v[178:181], v[120:123]
	v_mfma_f32_16x16x32_bf16 v[116:119], v[146:149], v[196:199], v[116:119]
	v_mfma_f32_16x16x32_bf16 v[112:115], v[154:157], v[196:199], v[112:115]
	v_mfma_f32_16x16x32_bf16 v[100:103], v[146:149], v[204:207], v[100:103]
	v_mfma_f32_16x16x32_bf16 v[96:99], v[154:157], v[204:207], v[96:99]
	v_mfma_f32_16x16x32_bf16 v[84:87], v[146:149], v[212:215], v[84:87]
	v_mfma_f32_16x16x32_bf16 v[80:83], v[154:157], v[212:215], v[80:83]
	s_setprio 0
	s_setprio 1
	v_mfma_f32_16x16x32_bf16 v[108:111], v[158:161], v[174:177], 0
	v_mfma_f32_16x16x32_bf16 v[104:107], v[166:169], v[174:177], 0
	v_mfma_f32_16x16x32_bf16 v[92:95], v[158:161], v[182:185], 0
	v_mfma_f32_16x16x32_bf16 v[88:91], v[166:169], v[182:185], 0
	v_mfma_f32_16x16x32_bf16 v[76:79], v[158:161], v[200:203], 0
	v_mfma_f32_16x16x32_bf16 v[72:75], v[166:169], v[200:203], 0
	v_mfma_f32_16x16x32_bf16 v[68:71], v[158:161], v[208:211], 0
	v_mfma_f32_16x16x32_bf16 v[64:67], v[166:169], v[208:211], 0
	v_mfma_f32_16x16x32_bf16 v[108:111], v[162:165], v[178:181], v[108:111]
	v_mfma_f32_16x16x32_bf16 v[104:107], v[170:173], v[178:181], v[104:107]
	v_mfma_f32_16x16x32_bf16 v[92:95], v[162:165], v[196:199], v[92:95]
	v_mfma_f32_16x16x32_bf16 v[88:91], v[170:173], v[196:199], v[88:91]
	v_mfma_f32_16x16x32_bf16 v[76:79], v[162:165], v[204:207], v[76:79]
	v_mfma_f32_16x16x32_bf16 v[72:75], v[170:173], v[204:207], v[72:75]
	v_mfma_f32_16x16x32_bf16 v[68:71], v[162:165], v[212:215], v[68:71]
	v_mfma_f32_16x16x32_bf16 v[64:67], v[170:173], v[212:215], v[64:67]
	s_barrier
	s_setprio 0
	s_add_i32 s60, s60, s38
	v_lshl_add_u64 v[186:187], s[30:31], 0, v[190:191]
	s_mov_b32 m0, s60
	ds_read_b128 v[174:177], v141 offset:16384
	ds_read_b128 v[178:181], v141 offset:17408
	ds_read_b128 v[182:185], v141 offset:18432
	ds_read_b128 v[196:199], v141 offset:19456
	ds_read_b128 v[200:203], v141 offset:20480
	ds_read_b128 v[204:207], v141 offset:21504
	ds_read_b128 v[208:211], v141 offset:22528
	ds_read_b128 v[212:215], v141 offset:23552
	global_load_lds_dwordx4 v[186:187], off
	s_add_i32 m0, s60, 0x2000
	s_add_u32 s60, s30, 0x80000
	v_lshl_add_u64 v[216:217], s[30:31], 0, v[132:133]
	s_addc_u32 s61, s31, 0
	s_add_i32 s66, s66, s38
	global_load_lds_dwordx4 v[216:217], off
	v_lshl_add_u64 v[218:219], s[60:61], 0, v[190:191]
	s_mov_b32 m0, s66
	v_lshl_add_u64 v[220:221], s[34:35], 0, v[130:131]
	global_load_lds_dwordx4 v[218:219], off
	s_add_i32 m0, s66, 0x2000
	v_lshl_add_u64 v[218:219], s[60:61], 0, v[132:133]
	global_load_lds_dwordx4 v[218:219], off
	s_mov_b32 m0, s13
	v_lshl_add_u64 v[218:219], s[34:35], 0, v[128:129]
	global_load_lds_dwordx4 v[218:219], off
	s_mov_b32 m0, s39
	s_nop 0
	global_load_lds_dwordx4 v[220:221], off
	s_setprio 1
	s_waitcnt vmcnt(24) lgkmcnt(0)
	s_barrier
	v_mfma_f32_16x16x32_bf16 v[60:63], v[142:145], v[174:177], 0
	v_mfma_f32_16x16x32_bf16 v[56:59], v[150:153], v[174:177], 0
	v_mfma_f32_16x16x32_bf16 v[52:55], v[142:145], v[182:185], 0
	v_mfma_f32_16x16x32_bf16 v[48:51], v[150:153], v[182:185], 0
	v_mfma_f32_16x16x32_bf16 v[36:39], v[142:145], v[200:203], 0
	v_mfma_f32_16x16x32_bf16 v[32:35], v[150:153], v[200:203], 0
	v_mfma_f32_16x16x32_bf16 v[20:23], v[142:145], v[208:211], 0
	v_mfma_f32_16x16x32_bf16 v[16:19], v[150:153], v[208:211], 0
	v_mfma_f32_16x16x32_bf16 v[60:63], v[146:149], v[178:181], v[60:63]
	v_mfma_f32_16x16x32_bf16 v[56:59], v[154:157], v[178:181], v[56:59]
	v_mfma_f32_16x16x32_bf16 v[52:55], v[146:149], v[196:199], v[52:55]
	v_mfma_f32_16x16x32_bf16 v[48:51], v[154:157], v[196:199], v[48:51]
	v_mfma_f32_16x16x32_bf16 v[36:39], v[146:149], v[204:207], v[36:39]
	v_mfma_f32_16x16x32_bf16 v[32:35], v[154:157], v[204:207], v[32:35]
	v_mfma_f32_16x16x32_bf16 v[20:23], v[146:149], v[212:215], v[20:23]
	v_mfma_f32_16x16x32_bf16 v[16:19], v[154:157], v[212:215], v[16:19]
	s_setprio 0
	s_setprio 1
	v_mfma_f32_16x16x32_bf16 v[44:47], v[158:161], v[174:177], 0
	v_mfma_f32_16x16x32_bf16 v[40:43], v[166:169], v[174:177], 0
	v_mfma_f32_16x16x32_bf16 v[28:31], v[158:161], v[182:185], 0
	v_mfma_f32_16x16x32_bf16 v[24:27], v[166:169], v[182:185], 0
	v_mfma_f32_16x16x32_bf16 v[12:15], v[158:161], v[200:203], 0
	v_mfma_f32_16x16x32_bf16 v[8:11], v[166:169], v[200:203], 0
	v_mfma_f32_16x16x32_bf16 v[4:7], v[158:161], v[208:211], 0
	v_mfma_f32_16x16x32_bf16 v[0:3], v[166:169], v[208:211], 0
	v_mfma_f32_16x16x32_bf16 v[44:47], v[162:165], v[178:181], v[44:47]
	v_mfma_f32_16x16x32_bf16 v[40:43], v[170:173], v[178:181], v[40:43]
	v_mfma_f32_16x16x32_bf16 v[28:31], v[162:165], v[196:199], v[28:31]
	v_mfma_f32_16x16x32_bf16 v[24:27], v[170:173], v[196:199], v[24:27]
	v_mfma_f32_16x16x32_bf16 v[12:15], v[162:165], v[204:207], v[12:15]
	v_mfma_f32_16x16x32_bf16 v[8:11], v[170:173], v[204:207], v[8:11]
	v_mfma_f32_16x16x32_bf16 v[4:7], v[162:165], v[212:215], v[4:7]
	v_mfma_f32_16x16x32_bf16 v[0:3], v[170:173], v[212:215], v[0:3]
	s_barrier
	s_setprio 0
	s_add_i32 s60, 0, 0x18000
	s_add_i32 s61, 0, 0x1c000
	v_add_u32_e32 v154, s60, v139
	v_add_u32_e32 v170, s61, v139
	ds_read_b128 v[142:145], v154
	ds_read_b128 v[146:149], v154 offset:1024
	ds_read_b128 v[150:153], v154 offset:2048
	ds_read_b128 v[154:157], v154 offset:3072
	ds_read_b128 v[158:161], v170
	ds_read_b128 v[162:165], v170 offset:1024
	ds_read_b128 v[166:169], v170 offset:2048
	ds_read_b128 v[170:173], v170 offset:3072
	s_add_u32 s34, s34, 0x80000
	s_addc_u32 s35, s35, 0
	s_mov_b32 m0, s41
	v_lshl_add_u64 v[222:223], s[34:35], 0, v[128:129]
	ds_read_b128 v[174:177], v141 offset:32768
	ds_read_b128 v[178:181], v141 offset:33792
	ds_read_b128 v[182:185], v141 offset:34816
	ds_read_b128 v[196:199], v141 offset:35840
	ds_read_b128 v[200:203], v141 offset:36864
	ds_read_b128 v[204:207], v141 offset:37888
	ds_read_b128 v[208:211], v141 offset:38912
	ds_read_b128 v[212:215], v141 offset:39936
	global_load_lds_dwordx4 v[222:223], off
	s_mov_b32 m0, s42
	v_lshl_add_u64 v[222:223], s[34:35], 0, v[130:131]
	global_load_lds_dwordx4 v[222:223], off
	s_setprio 1
	s_waitcnt vmcnt(8) lgkmcnt(0)
	s_barrier
	v_mfma_f32_16x16x32_bf16 v[124:127], v[142:145], v[174:177], v[124:127]
	v_mfma_f32_16x16x32_bf16 v[120:123], v[150:153], v[174:177], v[120:123]
	v_mfma_f32_16x16x32_bf16 v[116:119], v[142:145], v[182:185], v[116:119]
	v_mfma_f32_16x16x32_bf16 v[112:115], v[150:153], v[182:185], v[112:115]
	v_mfma_f32_16x16x32_bf16 v[100:103], v[142:145], v[200:203], v[100:103]
	v_mfma_f32_16x16x32_bf16 v[96:99], v[150:153], v[200:203], v[96:99]
	v_mfma_f32_16x16x32_bf16 v[84:87], v[142:145], v[208:211], v[84:87]
	v_mfma_f32_16x16x32_bf16 v[80:83], v[150:153], v[208:211], v[80:83]
	v_mfma_f32_16x16x32_bf16 v[124:127], v[146:149], v[178:181], v[124:127]
	v_mfma_f32_16x16x32_bf16 v[120:123], v[154:157], v[178:181], v[120:123]
	v_mfma_f32_16x16x32_bf16 v[116:119], v[146:149], v[196:199], v[116:119]
	v_mfma_f32_16x16x32_bf16 v[112:115], v[154:157], v[196:199], v[112:115]
	v_mfma_f32_16x16x32_bf16 v[100:103], v[146:149], v[204:207], v[100:103]
	v_mfma_f32_16x16x32_bf16 v[96:99], v[154:157], v[204:207], v[96:99]
	v_mfma_f32_16x16x32_bf16 v[84:87], v[146:149], v[212:215], v[84:87]
	v_mfma_f32_16x16x32_bf16 v[80:83], v[154:157], v[212:215], v[80:83]
	s_setprio 0
	s_setprio 1
	v_mfma_f32_16x16x32_bf16 v[108:111], v[158:161], v[174:177], v[108:111]
	v_mfma_f32_16x16x32_bf16 v[104:107], v[166:169], v[174:177], v[104:107]
	v_mfma_f32_16x16x32_bf16 v[92:95], v[158:161], v[182:185], v[92:95]
	v_mfma_f32_16x16x32_bf16 v[88:91], v[166:169], v[182:185], v[88:91]
	v_mfma_f32_16x16x32_bf16 v[76:79], v[158:161], v[200:203], v[76:79]
	v_mfma_f32_16x16x32_bf16 v[72:75], v[166:169], v[200:203], v[72:75]
	v_mfma_f32_16x16x32_bf16 v[68:71], v[158:161], v[208:211], v[68:71]
	v_mfma_f32_16x16x32_bf16 v[64:67], v[166:169], v[208:211], v[64:67]
	v_mfma_f32_16x16x32_bf16 v[108:111], v[162:165], v[178:181], v[108:111]
	v_mfma_f32_16x16x32_bf16 v[104:107], v[170:173], v[178:181], v[104:107]
	v_mfma_f32_16x16x32_bf16 v[92:95], v[162:165], v[196:199], v[92:95]
	v_mfma_f32_16x16x32_bf16 v[88:91], v[170:173], v[196:199], v[88:91]
	v_mfma_f32_16x16x32_bf16 v[76:79], v[162:165], v[204:207], v[76:79]
	v_mfma_f32_16x16x32_bf16 v[72:75], v[170:173], v[204:207], v[72:75]
	v_mfma_f32_16x16x32_bf16 v[68:71], v[162:165], v[212:215], v[68:71]
	v_mfma_f32_16x16x32_bf16 v[64:67], v[170:173], v[212:215], v[64:67]
	s_barrier
	s_setprio 0
	s_add_i32 s34, s60, s38
	v_lshl_add_u64 v[186:187], v[186:187], 0, s[58:59]
	s_mov_b32 m0, s34
	ds_read_b128 v[174:177], v141 offset:49152
	ds_read_b128 v[178:181], v141 offset:50176
	ds_read_b128 v[182:185], v141 offset:51200
	ds_read_b128 v[196:199], v141 offset:52224
	ds_read_b128 v[200:203], v141 offset:53248
	ds_read_b128 v[204:207], v141 offset:54272
	ds_read_b128 v[208:211], v141 offset:55296
	ds_read_b128 v[212:215], v141 offset:56320
	global_load_lds_dwordx4 v[186:187], off
	s_add_i32 m0, s34, 0x2000
	s_add_u32 s30, s30, 0x80080
	v_lshl_add_u64 v[186:187], v[216:217], 0, s[58:59]
	s_addc_u32 s31, s31, 0
	s_add_i32 s34, s61, s38
	global_load_lds_dwordx4 v[186:187], off
	s_mov_b32 m0, s34
	v_lshl_add_u64 v[186:187], s[30:31], 0, v[190:191]
	global_load_lds_dwordx4 v[186:187], off
	s_add_i32 m0, s34, 0x2000
	v_lshl_add_u64 v[186:187], s[30:31], 0, v[132:133]
	global_load_lds_dwordx4 v[186:187], off
	s_mov_b32 m0, s43
	v_lshl_add_u64 v[186:187], v[218:219], 0, s[58:59]
	global_load_lds_dwordx4 v[186:187], off
	s_mov_b32 m0, s47
	v_lshl_add_u64 v[186:187], v[220:221], 0, s[58:59]
	global_load_lds_dwordx4 v[186:187], off
	s_setprio 1
	s_waitcnt vmcnt(8) lgkmcnt(0)
	s_barrier
	v_mfma_f32_16x16x32_bf16 v[60:63], v[142:145], v[174:177], v[60:63]
	v_mfma_f32_16x16x32_bf16 v[56:59], v[150:153], v[174:177], v[56:59]
	v_mfma_f32_16x16x32_bf16 v[52:55], v[142:145], v[182:185], v[52:55]
	v_mfma_f32_16x16x32_bf16 v[48:51], v[150:153], v[182:185], v[48:51]
	v_mfma_f32_16x16x32_bf16 v[36:39], v[142:145], v[200:203], v[36:39]
	v_mfma_f32_16x16x32_bf16 v[32:35], v[150:153], v[200:203], v[32:35]
	v_mfma_f32_16x16x32_bf16 v[20:23], v[142:145], v[208:211], v[20:23]
	v_mfma_f32_16x16x32_bf16 v[16:19], v[150:153], v[208:211], v[16:19]
	v_mfma_f32_16x16x32_bf16 v[60:63], v[146:149], v[178:181], v[60:63]
	v_mfma_f32_16x16x32_bf16 v[56:59], v[154:157], v[178:181], v[56:59]
	v_mfma_f32_16x16x32_bf16 v[52:55], v[146:149], v[196:199], v[52:55]
	v_mfma_f32_16x16x32_bf16 v[48:51], v[154:157], v[196:199], v[48:51]
	v_mfma_f32_16x16x32_bf16 v[36:39], v[146:149], v[204:207], v[36:39]
	v_mfma_f32_16x16x32_bf16 v[32:35], v[154:157], v[204:207], v[32:35]
	v_mfma_f32_16x16x32_bf16 v[20:23], v[146:149], v[212:215], v[20:23]
	v_mfma_f32_16x16x32_bf16 v[16:19], v[154:157], v[212:215], v[16:19]
	s_setprio 0
	s_setprio 1
	v_mfma_f32_16x16x32_bf16 v[44:47], v[158:161], v[174:177], v[44:47]
	v_mfma_f32_16x16x32_bf16 v[40:43], v[166:169], v[174:177], v[40:43]
	v_mfma_f32_16x16x32_bf16 v[28:31], v[158:161], v[182:185], v[28:31]
	v_mfma_f32_16x16x32_bf16 v[24:27], v[166:169], v[182:185], v[24:27]
	v_mfma_f32_16x16x32_bf16 v[12:15], v[158:161], v[200:203], v[12:15]
	v_mfma_f32_16x16x32_bf16 v[8:11], v[166:169], v[200:203], v[8:11]
	v_mfma_f32_16x16x32_bf16 v[4:7], v[158:161], v[208:211], v[4:7]
	v_mfma_f32_16x16x32_bf16 v[0:3], v[166:169], v[208:211], v[0:3]
	v_mfma_f32_16x16x32_bf16 v[44:47], v[162:165], v[178:181], v[44:47]
	v_mfma_f32_16x16x32_bf16 v[40:43], v[170:173], v[178:181], v[40:43]
	v_mfma_f32_16x16x32_bf16 v[28:31], v[162:165], v[196:199], v[28:31]
	v_mfma_f32_16x16x32_bf16 v[24:27], v[170:173], v[196:199], v[24:27]
	v_mfma_f32_16x16x32_bf16 v[12:15], v[162:165], v[204:207], v[12:15]
	v_mfma_f32_16x16x32_bf16 v[8:11], v[170:173], v[204:207], v[8:11]
	v_mfma_f32_16x16x32_bf16 v[4:7], v[162:165], v[212:215], v[4:7]
	v_mfma_f32_16x16x32_bf16 v[0:3], v[170:173], v[212:215], v[0:3]
	s_barrier
	s_setprio 0
	s_add_i32 s57, s57, 2
	s_add_u32 s28, s28, 0x100
	s_addc_u32 s29, s29, 0
	s_add_u32 s55, s55, 0x100
	s_addc_u32 s56, s56, 0
	s_cmp_gt_u32 s57, 29
	s_cbranch_scc1 .Lpeel_done_6
	s_branch .LBB0_938
.Ltrip0_strict_6:
	s_add_u32 s30, s28, 0xfff80080
	s_addc_u32 s31, s29, -1
	s_add_i32 s60, 0, 0x10000
	s_cmp_eq_u32 s57, 28
	s_cselect_b32 s35, s11, s31
	s_cselect_b32 s34, s23, s30
	s_cselect_b32 s31, s21, s56
	s_cselect_b32 s30, s53, s55
	s_add_i32 s66, 0, 0x14000
	v_add_u32_e32 v154, s60, v139
	v_add_u32_e32 v170, s66, v139
	ds_read_b128 v[142:145], v154
	ds_read_b128 v[146:149], v154 offset:1024
	ds_read_b128 v[150:153], v154 offset:2048
	ds_read_b128 v[154:157], v154 offset:3072
	ds_read_b128 v[158:161], v170
	ds_read_b128 v[162:165], v170 offset:1024
	ds_read_b128 v[166:169], v170 offset:2048
	ds_read_b128 v[170:173], v170 offset:3072
	v_lshl_add_u64 v[186:187], s[28:29], 0, v[134:135]
	s_add_i32 m0, s13, 0xc000
	ds_read_b128 v[174:177], v141
	ds_read_b128 v[178:181], v141 offset:1024
	ds_read_b128 v[182:185], v141 offset:2048
	ds_read_b128 v[196:199], v141 offset:3072
	ds_read_b128 v[200:203], v141 offset:4096
	ds_read_b128 v[204:207], v141 offset:5120
	ds_read_b128 v[208:211], v141 offset:6144
	ds_read_b128 v[212:215], v141 offset:7168
	global_load_lds_dwordx4 v[186:187], off
	s_add_i32 m0, s13, 0xe000
	v_lshl_add_u64 v[186:187], s[28:29], 0, v[136:137]
	global_load_lds_dwordx4 v[186:187], off
	s_setprio 1
	s_waitcnt vmcnt(8) lgkmcnt(0)
	s_barrier
	v_mfma_f32_16x16x32_bf16 v[124:127], v[142:145], v[174:177], 0
	v_mfma_f32_16x16x32_bf16 v[120:123], v[150:153], v[174:177], 0
	v_mfma_f32_16x16x32_bf16 v[116:119], v[142:145], v[182:185], 0
	v_mfma_f32_16x16x32_bf16 v[112:115], v[150:153], v[182:185], 0
	v_mfma_f32_16x16x32_bf16 v[100:103], v[142:145], v[200:203], 0
	v_mfma_f32_16x16x32_bf16 v[96:99], v[150:153], v[200:203], 0
	v_mfma_f32_16x16x32_bf16 v[84:87], v[142:145], v[208:211], 0
	v_mfma_f32_16x16x32_bf16 v[80:83], v[150:153], v[208:211], 0
	v_mfma_f32_16x16x32_bf16 v[124:127], v[146:149], v[178:181], v[124:127]
	v_mfma_f32_16x16x32_bf16 v[120:123], v[154:157], v[178:181], v[120:123]
	v_mfma_f32_16x16x32_bf16 v[116:119], v[146:149], v[196:199], v[116:119]
	v_mfma_f32_16x16x32_bf16 v[112:115], v[154:157], v[196:199], v[112:115]
	v_mfma_f32_16x16x32_bf16 v[100:103], v[146:149], v[204:207], v[100:103]
	v_mfma_f32_16x16x32_bf16 v[96:99], v[154:157], v[204:207], v[96:99]
	v_mfma_f32_16x16x32_bf16 v[84:87], v[146:149], v[212:215], v[84:87]
	v_mfma_f32_16x16x32_bf16 v[80:83], v[154:157], v[212:215], v[80:83]
	s_setprio 0
	s_setprio 1
	v_mfma_f32_16x16x32_bf16 v[108:111], v[158:161], v[174:177], 0
	v_mfma_f32_16x16x32_bf16 v[104:107], v[166:169], v[174:177], 0
	v_mfma_f32_16x16x32_bf16 v[92:95], v[158:161], v[182:185], 0
	v_mfma_f32_16x16x32_bf16 v[88:91], v[166:169], v[182:185], 0
	v_mfma_f32_16x16x32_bf16 v[76:79], v[158:161], v[200:203], 0
	v_mfma_f32_16x16x32_bf16 v[72:75], v[166:169], v[200:203], 0
	v_mfma_f32_16x16x32_bf16 v[68:71], v[158:161], v[208:211], 0
	v_mfma_f32_16x16x32_bf16 v[64:67], v[166:169], v[208:211], 0
	v_mfma_f32_16x16x32_bf16 v[108:111], v[162:165], v[178:181], v[108:111]
	v_mfma_f32_16x16x32_bf16 v[104:107], v[170:173], v[178:181], v[104:107]
	v_mfma_f32_16x16x32_bf16 v[92:95], v[162:165], v[196:199], v[92:95]
	v_mfma_f32_16x16x32_bf16 v[88:91], v[170:173], v[196:199], v[88:91]
	v_mfma_f32_16x16x32_bf16 v[76:79], v[162:165], v[204:207], v[76:79]
	v_mfma_f32_16x16x32_bf16 v[72:75], v[170:173], v[204:207], v[72:75]
	v_mfma_f32_16x16x32_bf16 v[68:71], v[162:165], v[212:215], v[68:71]
	v_mfma_f32_16x16x32_bf16 v[64:67], v[170:173], v[212:215], v[64:67]
	s_barrier
	s_setprio 0
	s_add_i32 s60, s60, s38
	v_lshl_add_u64 v[186:187], s[30:31], 0, v[190:191]
	s_mov_b32 m0, s60
	ds_read_b128 v[174:177], v141 offset:16384
	ds_read_b128 v[178:181], v141 offset:17408
	ds_read_b128 v[182:185], v141 offset:18432
	ds_read_b128 v[196:199], v141 offset:19456
	ds_read_b128 v[200:203], v141 offset:20480
	ds_read_b128 v[204:207], v141 offset:21504
	ds_read_b128 v[208:211], v141 offset:22528
	ds_read_b128 v[212:215], v141 offset:23552
	global_load_lds_dwordx4 v[186:187], off
	s_add_i32 m0, s60, 0x2000
	s_add_u32 s60, s30, 0x80000
	v_lshl_add_u64 v[216:217], s[30:31], 0, v[132:133]
	s_addc_u32 s61, s31, 0
	s_add_i32 s66, s66, s38
	global_load_lds_dwordx4 v[216:217], off
	v_lshl_add_u64 v[218:219], s[60:61], 0, v[190:191]
	s_mov_b32 m0, s66
	v_lshl_add_u64 v[220:221], s[34:35], 0, v[130:131]
	global_load_lds_dwordx4 v[218:219], off
	s_add_i32 m0, s66, 0x2000
	v_lshl_add_u64 v[218:219], s[60:61], 0, v[132:133]
	global_load_lds_dwordx4 v[218:219], off
	s_mov_b32 m0, s13
	v_lshl_add_u64 v[218:219], s[34:35], 0, v[128:129]
	global_load_lds_dwordx4 v[218:219], off
	s_mov_b32 m0, s39
	s_nop 0
	global_load_lds_dwordx4 v[220:221], off
	s_setprio 1
	s_waitcnt vmcnt(8) lgkmcnt(0)
	s_barrier
	v_mfma_f32_16x16x32_bf16 v[60:63], v[142:145], v[174:177], 0
	v_mfma_f32_16x16x32_bf16 v[56:59], v[150:153], v[174:177], 0
	v_mfma_f32_16x16x32_bf16 v[52:55], v[142:145], v[182:185], 0
	v_mfma_f32_16x16x32_bf16 v[48:51], v[150:153], v[182:185], 0
	v_mfma_f32_16x16x32_bf16 v[36:39], v[142:145], v[200:203], 0
	v_mfma_f32_16x16x32_bf16 v[32:35], v[150:153], v[200:203], 0
	v_mfma_f32_16x16x32_bf16 v[20:23], v[142:145], v[208:211], 0
	v_mfma_f32_16x16x32_bf16 v[16:19], v[150:153], v[208:211], 0
	v_mfma_f32_16x16x32_bf16 v[60:63], v[146:149], v[178:181], v[60:63]
	v_mfma_f32_16x16x32_bf16 v[56:59], v[154:157], v[178:181], v[56:59]
	v_mfma_f32_16x16x32_bf16 v[52:55], v[146:149], v[196:199], v[52:55]
	v_mfma_f32_16x16x32_bf16 v[48:51], v[154:157], v[196:199], v[48:51]
	v_mfma_f32_16x16x32_bf16 v[36:39], v[146:149], v[204:207], v[36:39]
	v_mfma_f32_16x16x32_bf16 v[32:35], v[154:157], v[204:207], v[32:35]
	v_mfma_f32_16x16x32_bf16 v[20:23], v[146:149], v[212:215], v[20:23]
	v_mfma_f32_16x16x32_bf16 v[16:19], v[154:157], v[212:215], v[16:19]
	s_setprio 0
	s_setprio 1
	v_mfma_f32_16x16x32_bf16 v[44:47], v[158:161], v[174:177], 0
	v_mfma_f32_16x16x32_bf16 v[40:43], v[166:169], v[174:177], 0
	v_mfma_f32_16x16x32_bf16 v[28:31], v[158:161], v[182:185], 0
	v_mfma_f32_16x16x32_bf16 v[24:27], v[166:169], v[182:185], 0
	v_mfma_f32_16x16x32_bf16 v[12:15], v[158:161], v[200:203], 0
	v_mfma_f32_16x16x32_bf16 v[8:11], v[166:169], v[200:203], 0
	v_mfma_f32_16x16x32_bf16 v[4:7], v[158:161], v[208:211], 0
	v_mfma_f32_16x16x32_bf16 v[0:3], v[166:169], v[208:211], 0
	v_mfma_f32_16x16x32_bf16 v[44:47], v[162:165], v[178:181], v[44:47]
	v_mfma_f32_16x16x32_bf16 v[40:43], v[170:173], v[178:181], v[40:43]
	v_mfma_f32_16x16x32_bf16 v[28:31], v[162:165], v[196:199], v[28:31]
	v_mfma_f32_16x16x32_bf16 v[24:27], v[170:173], v[196:199], v[24:27]
	v_mfma_f32_16x16x32_bf16 v[12:15], v[162:165], v[204:207], v[12:15]
	v_mfma_f32_16x16x32_bf16 v[8:11], v[170:173], v[204:207], v[8:11]
	v_mfma_f32_16x16x32_bf16 v[4:7], v[162:165], v[212:215], v[4:7]
	v_mfma_f32_16x16x32_bf16 v[0:3], v[170:173], v[212:215], v[0:3]
	s_barrier
	s_setprio 0
	s_add_i32 s60, 0, 0x18000
	s_add_i32 s61, 0, 0x1c000
	v_add_u32_e32 v154, s60, v139
	v_add_u32_e32 v170, s61, v139
	ds_read_b128 v[142:145], v154
	ds_read_b128 v[146:149], v154 offset:1024
	ds_read_b128 v[150:153], v154 offset:2048
	ds_read_b128 v[154:157], v154 offset:3072
	ds_read_b128 v[158:161], v170
	ds_read_b128 v[162:165], v170 offset:1024
	ds_read_b128 v[166:169], v170 offset:2048
	ds_read_b128 v[170:173], v170 offset:3072
	s_add_u32 s34, s34, 0x80000
	s_addc_u32 s35, s35, 0
	s_mov_b32 m0, s41
	v_lshl_add_u64 v[222:223], s[34:35], 0, v[128:129]
	ds_read_b128 v[174:177], v141 offset:32768
	ds_read_b128 v[178:181], v141 offset:33792
	ds_read_b128 v[182:185], v141 offset:34816
	ds_read_b128 v[196:199], v141 offset:35840
	ds_read_b128 v[200:203], v141 offset:36864
	ds_read_b128 v[204:207], v141 offset:37888
	ds_read_b128 v[208:211], v141 offset:38912
	ds_read_b128 v[212:215], v141 offset:39936
	global_load_lds_dwordx4 v[222:223], off
	s_mov_b32 m0, s42
	v_lshl_add_u64 v[222:223], s[34:35], 0, v[130:131]
	global_load_lds_dwordx4 v[222:223], off
	s_setprio 1
	s_waitcnt vmcnt(8) lgkmcnt(0)
	s_barrier
	v_mfma_f32_16x16x32_bf16 v[124:127], v[142:145], v[174:177], v[124:127]
	v_mfma_f32_16x16x32_bf16 v[120:123], v[150:153], v[174:177], v[120:123]
	v_mfma_f32_16x16x32_bf16 v[116:119], v[142:145], v[182:185], v[116:119]
	v_mfma_f32_16x16x32_bf16 v[112:115], v[150:153], v[182:185], v[112:115]
	v_mfma_f32_16x16x32_bf16 v[100:103], v[142:145], v[200:203], v[100:103]
	v_mfma_f32_16x16x32_bf16 v[96:99], v[150:153], v[200:203], v[96:99]
	v_mfma_f32_16x16x32_bf16 v[84:87], v[142:145], v[208:211], v[84:87]
	v_mfma_f32_16x16x32_bf16 v[80:83], v[150:153], v[208:211], v[80:83]
	v_mfma_f32_16x16x32_bf16 v[124:127], v[146:149], v[178:181], v[124:127]
	v_mfma_f32_16x16x32_bf16 v[120:123], v[154:157], v[178:181], v[120:123]
	v_mfma_f32_16x16x32_bf16 v[116:119], v[146:149], v[196:199], v[116:119]
	v_mfma_f32_16x16x32_bf16 v[112:115], v[154:157], v[196:199], v[112:115]
	v_mfma_f32_16x16x32_bf16 v[100:103], v[146:149], v[204:207], v[100:103]
	v_mfma_f32_16x16x32_bf16 v[96:99], v[154:157], v[204:207], v[96:99]
	v_mfma_f32_16x16x32_bf16 v[84:87], v[146:149], v[212:215], v[84:87]
	v_mfma_f32_16x16x32_bf16 v[80:83], v[154:157], v[212:215], v[80:83]
	s_setprio 0
	s_setprio 1
	v_mfma_f32_16x16x32_bf16 v[108:111], v[158:161], v[174:177], v[108:111]
	v_mfma_f32_16x16x32_bf16 v[104:107], v[166:169], v[174:177], v[104:107]
	v_mfma_f32_16x16x32_bf16 v[92:95], v[158:161], v[182:185], v[92:95]
	v_mfma_f32_16x16x32_bf16 v[88:91], v[166:169], v[182:185], v[88:91]
	v_mfma_f32_16x16x32_bf16 v[76:79], v[158:161], v[200:203], v[76:79]
	v_mfma_f32_16x16x32_bf16 v[72:75], v[166:169], v[200:203], v[72:75]
	v_mfma_f32_16x16x32_bf16 v[68:71], v[158:161], v[208:211], v[68:71]
	v_mfma_f32_16x16x32_bf16 v[64:67], v[166:169], v[208:211], v[64:67]
	v_mfma_f32_16x16x32_bf16 v[108:111], v[162:165], v[178:181], v[108:111]
	v_mfma_f32_16x16x32_bf16 v[104:107], v[170:173], v[178:181], v[104:107]
	v_mfma_f32_16x16x32_bf16 v[92:95], v[162:165], v[196:199], v[92:95]
	v_mfma_f32_16x16x32_bf16 v[88:91], v[170:173], v[196:199], v[88:91]
	v_mfma_f32_16x16x32_bf16 v[76:79], v[162:165], v[204:207], v[76:79]
	v_mfma_f32_16x16x32_bf16 v[72:75], v[170:173], v[204:207], v[72:75]
	v_mfma_f32_16x16x32_bf16 v[68:71], v[162:165], v[212:215], v[68:71]
	v_mfma_f32_16x16x32_bf16 v[64:67], v[170:173], v[212:215], v[64:67]
	s_barrier
	s_setprio 0
	s_add_i32 s34, s60, s38
	v_lshl_add_u64 v[186:187], v[186:187], 0, s[58:59]
	s_mov_b32 m0, s34
	ds_read_b128 v[174:177], v141 offset:49152
	ds_read_b128 v[178:181], v141 offset:50176
	ds_read_b128 v[182:185], v141 offset:51200
	ds_read_b128 v[196:199], v141 offset:52224
	ds_read_b128 v[200:203], v141 offset:53248
	ds_read_b128 v[204:207], v141 offset:54272
	ds_read_b128 v[208:211], v141 offset:55296
	ds_read_b128 v[212:215], v141 offset:56320
	global_load_lds_dwordx4 v[186:187], off
	s_add_i32 m0, s34, 0x2000
	s_add_u32 s30, s30, 0x80080
	v_lshl_add_u64 v[186:187], v[216:217], 0, s[58:59]
	s_addc_u32 s31, s31, 0
	s_add_i32 s34, s61, s38
	global_load_lds_dwordx4 v[186:187], off
	s_mov_b32 m0, s34
	v_lshl_add_u64 v[186:187], s[30:31], 0, v[190:191]
	global_load_lds_dwordx4 v[186:187], off
	s_add_i32 m0, s34, 0x2000
	v_lshl_add_u64 v[186:187], s[30:31], 0, v[132:133]
	global_load_lds_dwordx4 v[186:187], off
	s_mov_b32 m0, s43
	v_lshl_add_u64 v[186:187], v[218:219], 0, s[58:59]
	global_load_lds_dwordx4 v[186:187], off
	s_mov_b32 m0, s47
	v_lshl_add_u64 v[186:187], v[220:221], 0, s[58:59]
	global_load_lds_dwordx4 v[186:187], off
	s_setprio 1
	s_waitcnt vmcnt(8) lgkmcnt(0)
	s_barrier
	v_mfma_f32_16x16x32_bf16 v[60:63], v[142:145], v[174:177], v[60:63]
	v_mfma_f32_16x16x32_bf16 v[56:59], v[150:153], v[174:177], v[56:59]
	v_mfma_f32_16x16x32_bf16 v[52:55], v[142:145], v[182:185], v[52:55]
	v_mfma_f32_16x16x32_bf16 v[48:51], v[150:153], v[182:185], v[48:51]
	v_mfma_f32_16x16x32_bf16 v[36:39], v[142:145], v[200:203], v[36:39]
	v_mfma_f32_16x16x32_bf16 v[32:35], v[150:153], v[200:203], v[32:35]
	v_mfma_f32_16x16x32_bf16 v[20:23], v[142:145], v[208:211], v[20:23]
	v_mfma_f32_16x16x32_bf16 v[16:19], v[150:153], v[208:211], v[16:19]
	v_mfma_f32_16x16x32_bf16 v[60:63], v[146:149], v[178:181], v[60:63]
	v_mfma_f32_16x16x32_bf16 v[56:59], v[154:157], v[178:181], v[56:59]
	v_mfma_f32_16x16x32_bf16 v[52:55], v[146:149], v[196:199], v[52:55]
	v_mfma_f32_16x16x32_bf16 v[48:51], v[154:157], v[196:199], v[48:51]
	v_mfma_f32_16x16x32_bf16 v[36:39], v[146:149], v[204:207], v[36:39]
	v_mfma_f32_16x16x32_bf16 v[32:35], v[154:157], v[204:207], v[32:35]
	v_mfma_f32_16x16x32_bf16 v[20:23], v[146:149], v[212:215], v[20:23]
	v_mfma_f32_16x16x32_bf16 v[16:19], v[154:157], v[212:215], v[16:19]
	s_setprio 0
	s_setprio 1
	v_mfma_f32_16x16x32_bf16 v[44:47], v[158:161], v[174:177], v[44:47]
	v_mfma_f32_16x16x32_bf16 v[40:43], v[166:169], v[174:177], v[40:43]
	v_mfma_f32_16x16x32_bf16 v[28:31], v[158:161], v[182:185], v[28:31]
	v_mfma_f32_16x16x32_bf16 v[24:27], v[166:169], v[182:185], v[24:27]
	v_mfma_f32_16x16x32_bf16 v[12:15], v[158:161], v[200:203], v[12:15]
	v_mfma_f32_16x16x32_bf16 v[8:11], v[166:169], v[200:203], v[8:11]
	v_mfma_f32_16x16x32_bf16 v[4:7], v[158:161], v[208:211], v[4:7]
	v_mfma_f32_16x16x32_bf16 v[0:3], v[166:169], v[208:211], v[0:3]
	v_mfma_f32_16x16x32_bf16 v[44:47], v[162:165], v[178:181], v[44:47]
	v_mfma_f32_16x16x32_bf16 v[40:43], v[170:173], v[178:181], v[40:43]
	v_mfma_f32_16x16x32_bf16 v[28:31], v[162:165], v[196:199], v[28:31]
	v_mfma_f32_16x16x32_bf16 v[24:27], v[170:173], v[196:199], v[24:27]
	v_mfma_f32_16x16x32_bf16 v[12:15], v[162:165], v[204:207], v[12:15]
	v_mfma_f32_16x16x32_bf16 v[8:11], v[170:173], v[204:207], v[8:11]
	v_mfma_f32_16x16x32_bf16 v[4:7], v[162:165], v[212:215], v[4:7]
	v_mfma_f32_16x16x32_bf16 v[0:3], v[170:173], v[212:215], v[0:3]
	s_barrier
	s_setprio 0
	s_add_i32 s57, s57, 2
	s_add_u32 s28, s28, 0x100
	s_addc_u32 s29, s29, 0
	s_add_u32 s55, s55, 0x100
	s_addc_u32 s56, s56, 0
	s_cmp_gt_u32 s57, 29
	s_cbranch_scc1 .Lpeel_done_6
.LBB0_938:
	s_add_u32 s30, s28, 0xfff80080
	s_addc_u32 s31, s29, -1
	s_add_i32 s60, 0, 0x10000
	s_cmp_eq_u32 s57, 28
	s_cselect_b32 s35, s11, s31
	s_cselect_b32 s34, s23, s30
	s_cselect_b32 s31, s21, s56
	s_cselect_b32 s30, s53, s55
	s_add_i32 s66, 0, 0x14000
	v_add_u32_e32 v154, s60, v139
	v_add_u32_e32 v170, s66, v139
	ds_read_b128 v[142:145], v154
	ds_read_b128 v[146:149], v154 offset:1024
	ds_read_b128 v[150:153], v154 offset:2048
	ds_read_b128 v[154:157], v154 offset:3072
	ds_read_b128 v[158:161], v170
	ds_read_b128 v[162:165], v170 offset:1024
	ds_read_b128 v[166:169], v170 offset:2048
	ds_read_b128 v[170:173], v170 offset:3072
	v_lshl_add_u64 v[186:187], s[28:29], 0, v[134:135]
	s_add_i32 m0, s13, 0xc000
	ds_read_b128 v[174:177], v141
	ds_read_b128 v[178:181], v141 offset:1024
	ds_read_b128 v[182:185], v141 offset:2048
	ds_read_b128 v[196:199], v141 offset:3072
	ds_read_b128 v[200:203], v141 offset:4096
	ds_read_b128 v[204:207], v141 offset:5120
	ds_read_b128 v[208:211], v141 offset:6144
	ds_read_b128 v[212:215], v141 offset:7168
	global_load_lds_dwordx4 v[186:187], off
	s_add_i32 m0, s13, 0xe000
	v_lshl_add_u64 v[186:187], s[28:29], 0, v[136:137]
	global_load_lds_dwordx4 v[186:187], off
	s_setprio 1
	s_waitcnt vmcnt(8) lgkmcnt(0)
	s_barrier
	v_mfma_f32_16x16x32_bf16 v[124:127], v[142:145], v[174:177], v[124:127]
	v_mfma_f32_16x16x32_bf16 v[120:123], v[150:153], v[174:177], v[120:123]
	v_mfma_f32_16x16x32_bf16 v[116:119], v[142:145], v[182:185], v[116:119]
	v_mfma_f32_16x16x32_bf16 v[112:115], v[150:153], v[182:185], v[112:115]
	v_mfma_f32_16x16x32_bf16 v[100:103], v[142:145], v[200:203], v[100:103]
	v_mfma_f32_16x16x32_bf16 v[96:99], v[150:153], v[200:203], v[96:99]
	v_mfma_f32_16x16x32_bf16 v[84:87], v[142:145], v[208:211], v[84:87]
	v_mfma_f32_16x16x32_bf16 v[80:83], v[150:153], v[208:211], v[80:83]
	v_mfma_f32_16x16x32_bf16 v[124:127], v[146:149], v[178:181], v[124:127]
	v_mfma_f32_16x16x32_bf16 v[120:123], v[154:157], v[178:181], v[120:123]
	v_mfma_f32_16x16x32_bf16 v[116:119], v[146:149], v[196:199], v[116:119]
	v_mfma_f32_16x16x32_bf16 v[112:115], v[154:157], v[196:199], v[112:115]
	v_mfma_f32_16x16x32_bf16 v[100:103], v[146:149], v[204:207], v[100:103]
	v_mfma_f32_16x16x32_bf16 v[96:99], v[154:157], v[204:207], v[96:99]
	v_mfma_f32_16x16x32_bf16 v[84:87], v[146:149], v[212:215], v[84:87]
	v_mfma_f32_16x16x32_bf16 v[80:83], v[154:157], v[212:215], v[80:83]
	s_setprio 0
	s_setprio 1
	v_mfma_f32_16x16x32_bf16 v[108:111], v[158:161], v[174:177], v[108:111]
	v_mfma_f32_16x16x32_bf16 v[104:107], v[166:169], v[174:177], v[104:107]
	v_mfma_f32_16x16x32_bf16 v[92:95], v[158:161], v[182:185], v[92:95]
	v_mfma_f32_16x16x32_bf16 v[88:91], v[166:169], v[182:185], v[88:91]
	v_mfma_f32_16x16x32_bf16 v[76:79], v[158:161], v[200:203], v[76:79]
	v_mfma_f32_16x16x32_bf16 v[72:75], v[166:169], v[200:203], v[72:75]
	v_mfma_f32_16x16x32_bf16 v[68:71], v[158:161], v[208:211], v[68:71]
	v_mfma_f32_16x16x32_bf16 v[64:67], v[166:169], v[208:211], v[64:67]
	v_mfma_f32_16x16x32_bf16 v[108:111], v[162:165], v[178:181], v[108:111]
	v_mfma_f32_16x16x32_bf16 v[104:107], v[170:173], v[178:181], v[104:107]
	v_mfma_f32_16x16x32_bf16 v[92:95], v[162:165], v[196:199], v[92:95]
	v_mfma_f32_16x16x32_bf16 v[88:91], v[170:173], v[196:199], v[88:91]
	v_mfma_f32_16x16x32_bf16 v[76:79], v[162:165], v[204:207], v[76:79]
	v_mfma_f32_16x16x32_bf16 v[72:75], v[170:173], v[204:207], v[72:75]
	v_mfma_f32_16x16x32_bf16 v[68:71], v[162:165], v[212:215], v[68:71]
	v_mfma_f32_16x16x32_bf16 v[64:67], v[170:173], v[212:215], v[64:67]
	s_setprio 0
	s_barrier
	s_add_i32 s60, s60, s38
	v_lshl_add_u64 v[186:187], s[30:31], 0, v[190:191]
	s_mov_b32 m0, s60
	ds_read_b128 v[174:177], v141 offset:16384
	ds_read_b128 v[178:181], v141 offset:17408
	ds_read_b128 v[182:185], v141 offset:18432
	ds_read_b128 v[196:199], v141 offset:19456
	ds_read_b128 v[200:203], v141 offset:20480
	ds_read_b128 v[204:207], v141 offset:21504
	ds_read_b128 v[208:211], v141 offset:22528
	ds_read_b128 v[212:215], v141 offset:23552
	global_load_lds_dwordx4 v[186:187], off
	s_add_i32 m0, s60, 0x2000
	s_add_u32 s60, s30, 0x80000
	v_lshl_add_u64 v[216:217], s[30:31], 0, v[132:133]
	s_addc_u32 s61, s31, 0
	s_add_i32 s66, s66, s38
	global_load_lds_dwordx4 v[216:217], off
	v_lshl_add_u64 v[218:219], s[60:61], 0, v[190:191]
	s_mov_b32 m0, s66
	v_lshl_add_u64 v[220:221], s[34:35], 0, v[130:131]
	global_load_lds_dwordx4 v[218:219], off
	s_add_i32 m0, s66, 0x2000
	v_lshl_add_u64 v[218:219], s[60:61], 0, v[132:133]
	global_load_lds_dwordx4 v[218:219], off
	s_mov_b32 m0, s13
	v_lshl_add_u64 v[218:219], s[34:35], 0, v[128:129]
	global_load_lds_dwordx4 v[218:219], off
	s_mov_b32 m0, s39
	s_nop 0
	global_load_lds_dwordx4 v[220:221], off
	s_setprio 1
	s_waitcnt vmcnt(8) lgkmcnt(0)
	s_barrier
	v_mfma_f32_16x16x32_bf16 v[60:63], v[142:145], v[174:177], v[60:63]
	v_mfma_f32_16x16x32_bf16 v[56:59], v[150:153], v[174:177], v[56:59]
	v_mfma_f32_16x16x32_bf16 v[52:55], v[142:145], v[182:185], v[52:55]
	v_mfma_f32_16x16x32_bf16 v[48:51], v[150:153], v[182:185], v[48:51]
	v_mfma_f32_16x16x32_bf16 v[36:39], v[142:145], v[200:203], v[36:39]
	v_mfma_f32_16x16x32_bf16 v[32:35], v[150:153], v[200:203], v[32:35]
	v_mfma_f32_16x16x32_bf16 v[20:23], v[142:145], v[208:211], v[20:23]
	v_mfma_f32_16x16x32_bf16 v[16:19], v[150:153], v[208:211], v[16:19]
	v_mfma_f32_16x16x32_bf16 v[60:63], v[146:149], v[178:181], v[60:63]
	v_mfma_f32_16x16x32_bf16 v[56:59], v[154:157], v[178:181], v[56:59]
	v_mfma_f32_16x16x32_bf16 v[52:55], v[146:149], v[196:199], v[52:55]
	v_mfma_f32_16x16x32_bf16 v[48:51], v[154:157], v[196:199], v[48:51]
	v_mfma_f32_16x16x32_bf16 v[36:39], v[146:149], v[204:207], v[36:39]
	v_mfma_f32_16x16x32_bf16 v[32:35], v[154:157], v[204:207], v[32:35]
	v_mfma_f32_16x16x32_bf16 v[20:23], v[146:149], v[212:215], v[20:23]
	v_mfma_f32_16x16x32_bf16 v[16:19], v[154:157], v[212:215], v[16:19]
	s_setprio 0
	s_setprio 1
	v_mfma_f32_16x16x32_bf16 v[44:47], v[158:161], v[174:177], v[44:47]
	v_mfma_f32_16x16x32_bf16 v[40:43], v[166:169], v[174:177], v[40:43]
	v_mfma_f32_16x16x32_bf16 v[28:31], v[158:161], v[182:185], v[28:31]
	v_mfma_f32_16x16x32_bf16 v[24:27], v[166:169], v[182:185], v[24:27]
	v_mfma_f32_16x16x32_bf16 v[12:15], v[158:161], v[200:203], v[12:15]
	v_mfma_f32_16x16x32_bf16 v[8:11], v[166:169], v[200:203], v[8:11]
	v_mfma_f32_16x16x32_bf16 v[4:7], v[158:161], v[208:211], v[4:7]
	v_mfma_f32_16x16x32_bf16 v[0:3], v[166:169], v[208:211], v[0:3]
	v_mfma_f32_16x16x32_bf16 v[44:47], v[162:165], v[178:181], v[44:47]
	v_mfma_f32_16x16x32_bf16 v[40:43], v[170:173], v[178:181], v[40:43]
	v_mfma_f32_16x16x32_bf16 v[28:31], v[162:165], v[196:199], v[28:31]
	v_mfma_f32_16x16x32_bf16 v[24:27], v[170:173], v[196:199], v[24:27]
	v_mfma_f32_16x16x32_bf16 v[12:15], v[162:165], v[204:207], v[12:15]
	v_mfma_f32_16x16x32_bf16 v[8:11], v[170:173], v[204:207], v[8:11]
	v_mfma_f32_16x16x32_bf16 v[4:7], v[162:165], v[212:215], v[4:7]
	v_mfma_f32_16x16x32_bf16 v[0:3], v[170:173], v[212:215], v[0:3]
	s_setprio 0
	s_barrier
	s_add_i32 s60, 0, 0x18000
	s_add_i32 s61, 0, 0x1c000
	v_add_u32_e32 v154, s60, v139
	v_add_u32_e32 v170, s61, v139
	ds_read_b128 v[142:145], v154
	ds_read_b128 v[146:149], v154 offset:1024
	ds_read_b128 v[150:153], v154 offset:2048
	ds_read_b128 v[154:157], v154 offset:3072
	ds_read_b128 v[158:161], v170
	ds_read_b128 v[162:165], v170 offset:1024
	ds_read_b128 v[166:169], v170 offset:2048
	ds_read_b128 v[170:173], v170 offset:3072
	s_add_u32 s34, s34, 0x80000
	s_addc_u32 s35, s35, 0
	s_mov_b32 m0, s41
	v_lshl_add_u64 v[222:223], s[34:35], 0, v[128:129]
	ds_read_b128 v[174:177], v141 offset:32768
	ds_read_b128 v[178:181], v141 offset:33792
	ds_read_b128 v[182:185], v141 offset:34816
	ds_read_b128 v[196:199], v141 offset:35840
	ds_read_b128 v[200:203], v141 offset:36864
	ds_read_b128 v[204:207], v141 offset:37888
	ds_read_b128 v[208:211], v141 offset:38912
	ds_read_b128 v[212:215], v141 offset:39936
	global_load_lds_dwordx4 v[222:223], off
	s_mov_b32 m0, s42
	v_lshl_add_u64 v[222:223], s[34:35], 0, v[130:131]
	global_load_lds_dwordx4 v[222:223], off
	s_setprio 1
	s_waitcnt vmcnt(8) lgkmcnt(0)
	s_barrier
	v_mfma_f32_16x16x32_bf16 v[124:127], v[142:145], v[174:177], v[124:127]
	v_mfma_f32_16x16x32_bf16 v[120:123], v[150:153], v[174:177], v[120:123]
	v_mfma_f32_16x16x32_bf16 v[116:119], v[142:145], v[182:185], v[116:119]
	v_mfma_f32_16x16x32_bf16 v[112:115], v[150:153], v[182:185], v[112:115]
	v_mfma_f32_16x16x32_bf16 v[100:103], v[142:145], v[200:203], v[100:103]
	v_mfma_f32_16x16x32_bf16 v[96:99], v[150:153], v[200:203], v[96:99]
	v_mfma_f32_16x16x32_bf16 v[84:87], v[142:145], v[208:211], v[84:87]
	v_mfma_f32_16x16x32_bf16 v[80:83], v[150:153], v[208:211], v[80:83]
	v_mfma_f32_16x16x32_bf16 v[124:127], v[146:149], v[178:181], v[124:127]
	v_mfma_f32_16x16x32_bf16 v[120:123], v[154:157], v[178:181], v[120:123]
	v_mfma_f32_16x16x32_bf16 v[116:119], v[146:149], v[196:199], v[116:119]
	v_mfma_f32_16x16x32_bf16 v[112:115], v[154:157], v[196:199], v[112:115]
	v_mfma_f32_16x16x32_bf16 v[100:103], v[146:149], v[204:207], v[100:103]
	v_mfma_f32_16x16x32_bf16 v[96:99], v[154:157], v[204:207], v[96:99]
	v_mfma_f32_16x16x32_bf16 v[84:87], v[146:149], v[212:215], v[84:87]
	v_mfma_f32_16x16x32_bf16 v[80:83], v[154:157], v[212:215], v[80:83]
	s_setprio 0
	s_setprio 1
	v_mfma_f32_16x16x32_bf16 v[108:111], v[158:161], v[174:177], v[108:111]
	v_mfma_f32_16x16x32_bf16 v[104:107], v[166:169], v[174:177], v[104:107]
	v_mfma_f32_16x16x32_bf16 v[92:95], v[158:161], v[182:185], v[92:95]
	v_mfma_f32_16x16x32_bf16 v[88:91], v[166:169], v[182:185], v[88:91]
	v_mfma_f32_16x16x32_bf16 v[76:79], v[158:161], v[200:203], v[76:79]
	v_mfma_f32_16x16x32_bf16 v[72:75], v[166:169], v[200:203], v[72:75]
	v_mfma_f32_16x16x32_bf16 v[68:71], v[158:161], v[208:211], v[68:71]
	v_mfma_f32_16x16x32_bf16 v[64:67], v[166:169], v[208:211], v[64:67]
	v_mfma_f32_16x16x32_bf16 v[108:111], v[162:165], v[178:181], v[108:111]
	v_mfma_f32_16x16x32_bf16 v[104:107], v[170:173], v[178:181], v[104:107]
	v_mfma_f32_16x16x32_bf16 v[92:95], v[162:165], v[196:199], v[92:95]
	v_mfma_f32_16x16x32_bf16 v[88:91], v[170:173], v[196:199], v[88:91]
	v_mfma_f32_16x16x32_bf16 v[76:79], v[162:165], v[204:207], v[76:79]
	v_mfma_f32_16x16x32_bf16 v[72:75], v[170:173], v[204:207], v[72:75]
	v_mfma_f32_16x16x32_bf16 v[68:71], v[162:165], v[212:215], v[68:71]
	v_mfma_f32_16x16x32_bf16 v[64:67], v[170:173], v[212:215], v[64:67]
	s_setprio 0
	s_barrier
	s_add_i32 s34, s60, s38
	v_lshl_add_u64 v[186:187], v[186:187], 0, s[58:59]
	s_mov_b32 m0, s34
	ds_read_b128 v[174:177], v141 offset:49152
	ds_read_b128 v[178:181], v141 offset:50176
	ds_read_b128 v[182:185], v141 offset:51200
	ds_read_b128 v[196:199], v141 offset:52224
	ds_read_b128 v[200:203], v141 offset:53248
	ds_read_b128 v[204:207], v141 offset:54272
	ds_read_b128 v[208:211], v141 offset:55296
	ds_read_b128 v[212:215], v141 offset:56320
	global_load_lds_dwordx4 v[186:187], off
	s_add_i32 m0, s34, 0x2000
	s_add_u32 s30, s30, 0x80080
	v_lshl_add_u64 v[186:187], v[216:217], 0, s[58:59]
	s_addc_u32 s31, s31, 0
	s_add_i32 s34, s61, s38
	global_load_lds_dwordx4 v[186:187], off
	s_mov_b32 m0, s34
	v_lshl_add_u64 v[186:187], s[30:31], 0, v[190:191]
	global_load_lds_dwordx4 v[186:187], off
	s_add_i32 m0, s34, 0x2000
	v_lshl_add_u64 v[186:187], s[30:31], 0, v[132:133]
	global_load_lds_dwordx4 v[186:187], off
	s_mov_b32 m0, s43
	v_lshl_add_u64 v[186:187], v[218:219], 0, s[58:59]
	global_load_lds_dwordx4 v[186:187], off
	s_mov_b32 m0, s47
	v_lshl_add_u64 v[186:187], v[220:221], 0, s[58:59]
	global_load_lds_dwordx4 v[186:187], off
	s_setprio 1
	s_waitcnt vmcnt(8) lgkmcnt(0)
	s_barrier
	v_mfma_f32_16x16x32_bf16 v[60:63], v[142:145], v[174:177], v[60:63]
	v_mfma_f32_16x16x32_bf16 v[56:59], v[150:153], v[174:177], v[56:59]
	v_mfma_f32_16x16x32_bf16 v[52:55], v[142:145], v[182:185], v[52:55]
	v_mfma_f32_16x16x32_bf16 v[48:51], v[150:153], v[182:185], v[48:51]
	v_mfma_f32_16x16x32_bf16 v[36:39], v[142:145], v[200:203], v[36:39]
	v_mfma_f32_16x16x32_bf16 v[32:35], v[150:153], v[200:203], v[32:35]
	v_mfma_f32_16x16x32_bf16 v[20:23], v[142:145], v[208:211], v[20:23]
	v_mfma_f32_16x16x32_bf16 v[16:19], v[150:153], v[208:211], v[16:19]
	v_mfma_f32_16x16x32_bf16 v[60:63], v[146:149], v[178:181], v[60:63]
	v_mfma_f32_16x16x32_bf16 v[56:59], v[154:157], v[178:181], v[56:59]
	v_mfma_f32_16x16x32_bf16 v[52:55], v[146:149], v[196:199], v[52:55]
	v_mfma_f32_16x16x32_bf16 v[48:51], v[154:157], v[196:199], v[48:51]
	v_mfma_f32_16x16x32_bf16 v[36:39], v[146:149], v[204:207], v[36:39]
	v_mfma_f32_16x16x32_bf16 v[32:35], v[154:157], v[204:207], v[32:35]
	v_mfma_f32_16x16x32_bf16 v[20:23], v[146:149], v[212:215], v[20:23]
	v_mfma_f32_16x16x32_bf16 v[16:19], v[154:157], v[212:215], v[16:19]
	s_setprio 0
	s_setprio 1
	v_mfma_f32_16x16x32_bf16 v[44:47], v[158:161], v[174:177], v[44:47]
	v_mfma_f32_16x16x32_bf16 v[40:43], v[166:169], v[174:177], v[40:43]
	v_mfma_f32_16x16x32_bf16 v[28:31], v[158:161], v[182:185], v[28:31]
	v_mfma_f32_16x16x32_bf16 v[24:27], v[166:169], v[182:185], v[24:27]
	v_mfma_f32_16x16x32_bf16 v[12:15], v[158:161], v[200:203], v[12:15]
	v_mfma_f32_16x16x32_bf16 v[8:11], v[166:169], v[200:203], v[8:11]
	v_mfma_f32_16x16x32_bf16 v[4:7], v[158:161], v[208:211], v[4:7]
	v_mfma_f32_16x16x32_bf16 v[0:3], v[166:169], v[208:211], v[0:3]
	v_mfma_f32_16x16x32_bf16 v[44:47], v[162:165], v[178:181], v[44:47]
	v_mfma_f32_16x16x32_bf16 v[40:43], v[170:173], v[178:181], v[40:43]
	v_mfma_f32_16x16x32_bf16 v[28:31], v[162:165], v[196:199], v[28:31]
	v_mfma_f32_16x16x32_bf16 v[24:27], v[170:173], v[196:199], v[24:27]
	v_mfma_f32_16x16x32_bf16 v[12:15], v[162:165], v[204:207], v[12:15]
	v_mfma_f32_16x16x32_bf16 v[8:11], v[170:173], v[204:207], v[8:11]
	v_mfma_f32_16x16x32_bf16 v[4:7], v[162:165], v[212:215], v[4:7]
	v_mfma_f32_16x16x32_bf16 v[0:3], v[170:173], v[212:215], v[0:3]
	s_setprio 0
	s_barrier
	s_add_i32 s57, s57, 2
	s_add_u32 s28, s28, 0x100
	s_addc_u32 s29, s29, 0
	s_add_u32 s55, s55, 0x100
	s_addc_u32 s56, s56, 0
	s_cmp_gt_u32 s57, 29
	s_cbranch_scc0 .LBB0_938

.LBB0_1104:
	s_ashr_i32 s61, s60, 31
	s_lshl_b64 s[52:53], s[60:61], 20
	v_readlane_b32 s0, v254, 17
	v_readlane_b32 s1, v254, 18
	s_add_u32 s88, s0, s52
	s_addc_u32 s89, s1, s53
	s_and_b64 s[52:53], s[8:9], exec
	s_cselect_b32 s13, s89, s11
	s_cselect_b32 s15, s88, s10
	s_ashr_i32 s57, s56, 31
	s_lshl_b64 s[52:53], s[56:57], 20
	v_readlane_b32 s0, v254, 36
	v_readlane_b32 s1, v254, 37
	s_add_u32 s90, s0, s52
	s_addc_u32 s91, s1, s53
	s_and_b64 s[52:53], s[8:9], exec
	s_cselect_b32 s57, s91, s17
	s_cselect_b32 s61, s90, s16
	s_add_u32 s66, s16, 0x100
	s_addc_u32 s67, s17, 0
	s_mov_b32 vcc_lo, -2
	v_readlane_b32 s0, v255, 49
	s_nop 3
	s_cmp_eq_u32 s0, 8
	v_writelane_b32 v255, 8, 49
	s_cbranch_scc0 .Ltrip0_strict_7
	s_add_u32 s16, s10, 0x100
	s_addc_u32 s17, s11, 0
	s_add_i32 vcc_hi, 0, 0x10000
	s_cmp_eq_u32 vcc_lo, 28
	s_cselect_b32 s69, s13, s17
	s_cselect_b32 s68, s15, s16
	s_cselect_b32 s53, s57, s67
	s_cselect_b32 s52, s61, s66
	s_add_i32 s0, 0, 0x14000
	v_add_u32_e32 v140, vcc_hi, v200
	v_add_u32_e32 v156, s0, v200
	ds_read_b128 v[128:131], v140
	ds_read_b128 v[132:135], v140 offset:1024
	ds_read_b128 v[136:139], v140 offset:2048
	ds_read_b128 v[140:143], v140 offset:3072
	ds_read_b128 v[144:147], v156
	ds_read_b128 v[148:151], v156 offset:1024
	ds_read_b128 v[152:155], v156 offset:2048
	ds_read_b128 v[156:159], v156 offset:3072
	v_lshl_add_u64 v[186:187], s[10:11], 0, v[182:183]
	s_add_i32 m0, s40, 0xc000
	ds_read_b128 v[160:163], v206
	ds_read_b128 v[164:167], v206 offset:1024
	ds_read_b128 v[168:171], v206 offset:2048
	ds_read_b128 v[172:175], v206 offset:3072
	ds_read_b128 v[196:199], v206 offset:4096
	ds_read_b128 v[208:211], v206 offset:5120
	ds_read_b128 v[212:215], v206 offset:6144
	ds_read_b128 v[216:219], v206 offset:7168
	global_load_lds_dwordx4 v[186:187], off
	s_add_i32 m0, s40, 0xe000
	v_lshl_add_u64 v[186:187], s[10:11], 0, v[184:185]
	global_load_lds_dwordx4 v[186:187], off
	s_setprio 1
	s_waitcnt vmcnt(24) lgkmcnt(0)
	s_barrier
	v_mfma_f32_16x16x32_bf16 v[120:123], v[128:131], v[160:163], 0
	v_mfma_f32_16x16x32_bf16 v[48:51], v[136:139], v[160:163], 0
	v_mfma_f32_16x16x32_bf16 v[124:127], v[128:131], v[168:171], 0
	v_mfma_f32_16x16x32_bf16 v[60:63], v[136:139], v[168:171], 0
	v_mfma_f32_16x16x32_bf16 v[112:115], v[128:131], v[196:199], 0
	v_mfma_f32_16x16x32_bf16 v[52:55], v[136:139], v[196:199], 0
	v_mfma_f32_16x16x32_bf16 v[108:111], v[128:131], v[212:215], 0
	v_mfma_f32_16x16x32_bf16 v[36:39], v[136:139], v[212:215], 0
	v_mfma_f32_16x16x32_bf16 v[120:123], v[132:135], v[164:167], v[120:123]
	v_mfma_f32_16x16x32_bf16 v[48:51], v[140:143], v[164:167], v[48:51]
	v_mfma_f32_16x16x32_bf16 v[124:127], v[132:135], v[172:175], v[124:127]
	v_mfma_f32_16x16x32_bf16 v[60:63], v[140:143], v[172:175], v[60:63]
	v_mfma_f32_16x16x32_bf16 v[112:115], v[132:135], v[208:211], v[112:115]
	v_mfma_f32_16x16x32_bf16 v[52:55], v[140:143], v[208:211], v[52:55]
	v_mfma_f32_16x16x32_bf16 v[108:111], v[132:135], v[216:219], v[108:111]
	v_mfma_f32_16x16x32_bf16 v[36:39], v[140:143], v[216:219], v[36:39]
	s_setprio 0
	s_setprio 1
	v_mfma_f32_16x16x32_bf16 v[100:103], v[144:147], v[160:163], 0
	v_mfma_f32_16x16x32_bf16 v[40:43], v[152:155], v[160:163], 0
	v_mfma_f32_16x16x32_bf16 v[116:119], v[144:147], v[168:171], 0
	v_mfma_f32_16x16x32_bf16 v[56:59], v[152:155], v[168:171], 0
	v_mfma_f32_16x16x32_bf16 v[104:107], v[144:147], v[196:199], 0
	v_mfma_f32_16x16x32_bf16 v[44:47], v[152:155], v[196:199], 0
	v_mfma_f32_16x16x32_bf16 v[96:99], v[144:147], v[212:215], 0
	v_mfma_f32_16x16x32_bf16 v[32:35], v[152:155], v[212:215], 0
	v_mfma_f32_16x16x32_bf16 v[100:103], v[148:151], v[164:167], v[100:103]
	v_mfma_f32_16x16x32_bf16 v[40:43], v[156:159], v[164:167], v[40:43]
	v_mfma_f32_16x16x32_bf16 v[116:119], v[148:151], v[172:175], v[116:119]
	v_mfma_f32_16x16x32_bf16 v[56:59], v[156:159], v[172:175], v[56:59]
	v_mfma_f32_16x16x32_bf16 v[104:107], v[148:151], v[208:211], v[104:107]
	v_mfma_f32_16x16x32_bf16 v[44:47], v[156:159], v[208:211], v[44:47]
	v_mfma_f32_16x16x32_bf16 v[96:99], v[148:151], v[216:219], v[96:99]
	v_mfma_f32_16x16x32_bf16 v[32:35], v[156:159], v[216:219], v[32:35]
	s_barrier
	s_setprio 0
	s_add_i32 s1, vcc_hi, s33
	v_lshl_add_u64 v[186:187], s[52:53], 0, v[190:191]
	s_mov_b32 m0, s1
	ds_read_b128 v[160:163], v206 offset:16384
	ds_read_b128 v[164:167], v206 offset:17408
	ds_read_b128 v[168:171], v206 offset:18432
	ds_read_b128 v[172:175], v206 offset:19456
	ds_read_b128 v[196:199], v206 offset:20480
	ds_read_b128 v[208:211], v206 offset:21504
	ds_read_b128 v[212:215], v206 offset:22528
	ds_read_b128 v[216:219], v206 offset:23552
	global_load_lds_dwordx4 v[186:187], off
	s_add_i32 m0, s1, 0x2000
	s_add_u32 s10, s52, 0x80000
	v_lshl_add_u64 v[220:221], s[52:53], 0, v[180:181]
	s_addc_u32 s11, s53, 0
	s_add_i32 s0, s0, s33
	global_load_lds_dwordx4 v[220:221], off
	v_lshl_add_u64 v[222:223], s[10:11], 0, v[190:191]
	s_mov_b32 m0, s0
	v_lshl_add_u64 v[224:225], s[68:69], 0, v[178:179]
	global_load_lds_dwordx4 v[222:223], off
	s_add_i32 m0, s0, 0x2000
	v_lshl_add_u64 v[222:223], s[10:11], 0, v[180:181]
	global_load_lds_dwordx4 v[222:223], off
	s_mov_b32 m0, s40
	v_lshl_add_u64 v[222:223], s[68:69], 0, v[176:177]
	global_load_lds_dwordx4 v[222:223], off
	s_mov_b32 m0, s41
	s_nop 0
	global_load_lds_dwordx4 v[224:225], off
	s_setprio 1
	s_waitcnt vmcnt(24) lgkmcnt(0)
	s_barrier
	v_mfma_f32_16x16x32_bf16 v[88:91], v[128:131], v[160:163], 0
	v_mfma_f32_16x16x32_bf16 v[20:23], v[136:139], v[160:163], 0
	v_mfma_f32_16x16x32_bf16 v[92:95], v[128:131], v[168:171], 0
	v_mfma_f32_16x16x32_bf16 v[28:31], v[136:139], v[168:171], 0
	v_mfma_f32_16x16x32_bf16 v[80:83], v[128:131], v[196:199], 0
	v_mfma_f32_16x16x32_bf16 v[16:19], v[136:139], v[196:199], 0
	v_mfma_f32_16x16x32_bf16 v[76:79], v[128:131], v[212:215], 0
	v_mfma_f32_16x16x32_bf16 v[12:15], v[136:139], v[212:215], 0
	v_mfma_f32_16x16x32_bf16 v[88:91], v[132:135], v[164:167], v[88:91]
	v_mfma_f32_16x16x32_bf16 v[20:23], v[140:143], v[164:167], v[20:23]
	v_mfma_f32_16x16x32_bf16 v[92:95], v[132:135], v[172:175], v[92:95]
	v_mfma_f32_16x16x32_bf16 v[28:31], v[140:143], v[172:175], v[28:31]
	v_mfma_f32_16x16x32_bf16 v[80:83], v[132:135], v[208:211], v[80:83]
	v_mfma_f32_16x16x32_bf16 v[16:19], v[140:143], v[208:211], v[16:19]
	v_mfma_f32_16x16x32_bf16 v[76:79], v[132:135], v[216:219], v[76:79]
	v_mfma_f32_16x16x32_bf16 v[12:15], v[140:143], v[216:219], v[12:15]
	s_setprio 0
	s_setprio 1
	v_mfma_f32_16x16x32_bf16 v[68:71], v[144:147], v[160:163], 0
	v_mfma_f32_16x16x32_bf16 v[4:7], v[152:155], v[160:163], 0
	v_mfma_f32_16x16x32_bf16 v[84:87], v[144:147], v[168:171], 0
	v_mfma_f32_16x16x32_bf16 v[24:27], v[152:155], v[168:171], 0
	v_mfma_f32_16x16x32_bf16 v[72:75], v[144:147], v[196:199], 0
	v_mfma_f32_16x16x32_bf16 v[8:11], v[152:155], v[196:199], 0
	v_mfma_f32_16x16x32_bf16 v[64:67], v[144:147], v[212:215], 0
	v_mfma_f32_16x16x32_bf16 v[0:3], v[152:155], v[212:215], 0
	v_mfma_f32_16x16x32_bf16 v[68:71], v[148:151], v[164:167], v[68:71]
	v_mfma_f32_16x16x32_bf16 v[4:7], v[156:159], v[164:167], v[4:7]
	v_mfma_f32_16x16x32_bf16 v[84:87], v[148:151], v[172:175], v[84:87]
	v_mfma_f32_16x16x32_bf16 v[24:27], v[156:159], v[172:175], v[24:27]
	v_mfma_f32_16x16x32_bf16 v[72:75], v[148:151], v[208:211], v[72:75]
	v_mfma_f32_16x16x32_bf16 v[8:11], v[156:159], v[208:211], v[8:11]
	v_mfma_f32_16x16x32_bf16 v[64:67], v[148:151], v[216:219], v[64:67]
	v_mfma_f32_16x16x32_bf16 v[0:3], v[156:159], v[216:219], v[0:3]
	s_barrier
	s_setprio 0
	s_add_i32 s0, 0, 0x18000
	s_add_i32 s1, 0, 0x1c000
	v_add_u32_e32 v140, s0, v200
	v_add_u32_e32 v156, s1, v200
	ds_read_b128 v[128:131], v140
	ds_read_b128 v[132:135], v140 offset:1024
	ds_read_b128 v[136:139], v140 offset:2048
	ds_read_b128 v[140:143], v140 offset:3072
	ds_read_b128 v[144:147], v156
	ds_read_b128 v[148:151], v156 offset:1024
	ds_read_b128 v[152:155], v156 offset:2048
	ds_read_b128 v[156:159], v156 offset:3072
	s_add_u32 s10, s68, 0x80000
	s_addc_u32 s11, s69, 0
	s_mov_b32 m0, s42
	v_lshl_add_u64 v[226:227], s[10:11], 0, v[176:177]
	ds_read_b128 v[160:163], v206 offset:32768
	ds_read_b128 v[164:167], v206 offset:33792
	ds_read_b128 v[168:171], v206 offset:34816
	ds_read_b128 v[172:175], v206 offset:35840
	ds_read_b128 v[196:199], v206 offset:36864
	ds_read_b128 v[208:211], v206 offset:37888
	ds_read_b128 v[212:215], v206 offset:38912
	ds_read_b128 v[216:219], v206 offset:39936
	global_load_lds_dwordx4 v[226:227], off
	s_mov_b32 m0, s43
	v_lshl_add_u64 v[226:227], s[10:11], 0, v[178:179]
	global_load_lds_dwordx4 v[226:227], off
	s_setprio 1
	s_waitcnt vmcnt(8) lgkmcnt(0)
	s_barrier
	v_mfma_f32_16x16x32_bf16 v[120:123], v[128:131], v[160:163], v[120:123]
	v_mfma_f32_16x16x32_bf16 v[48:51], v[136:139], v[160:163], v[48:51]
	v_mfma_f32_16x16x32_bf16 v[124:127], v[128:131], v[168:171], v[124:127]
	v_mfma_f32_16x16x32_bf16 v[60:63], v[136:139], v[168:171], v[60:63]
	v_mfma_f32_16x16x32_bf16 v[112:115], v[128:131], v[196:199], v[112:115]
	v_mfma_f32_16x16x32_bf16 v[52:55], v[136:139], v[196:199], v[52:55]
	v_mfma_f32_16x16x32_bf16 v[108:111], v[128:131], v[212:215], v[108:111]
	v_mfma_f32_16x16x32_bf16 v[36:39], v[136:139], v[212:215], v[36:39]
	v_mfma_f32_16x16x32_bf16 v[120:123], v[132:135], v[164:167], v[120:123]
	v_mfma_f32_16x16x32_bf16 v[48:51], v[140:143], v[164:167], v[48:51]
	v_mfma_f32_16x16x32_bf16 v[124:127], v[132:135], v[172:175], v[124:127]
	v_mfma_f32_16x16x32_bf16 v[60:63], v[140:143], v[172:175], v[60:63]
	v_mfma_f32_16x16x32_bf16 v[112:115], v[132:135], v[208:211], v[112:115]
	v_mfma_f32_16x16x32_bf16 v[52:55], v[140:143], v[208:211], v[52:55]
	v_mfma_f32_16x16x32_bf16 v[108:111], v[132:135], v[216:219], v[108:111]
	v_mfma_f32_16x16x32_bf16 v[36:39], v[140:143], v[216:219], v[36:39]
	s_setprio 0
	s_setprio 1
	v_mfma_f32_16x16x32_bf16 v[100:103], v[144:147], v[160:163], v[100:103]
	v_mfma_f32_16x16x32_bf16 v[40:43], v[152:155], v[160:163], v[40:43]
	v_mfma_f32_16x16x32_bf16 v[116:119], v[144:147], v[168:171], v[116:119]
	v_mfma_f32_16x16x32_bf16 v[56:59], v[152:155], v[168:171], v[56:59]
	v_mfma_f32_16x16x32_bf16 v[104:107], v[144:147], v[196:199], v[104:107]
	v_mfma_f32_16x16x32_bf16 v[44:47], v[152:155], v[196:199], v[44:47]
	v_mfma_f32_16x16x32_bf16 v[96:99], v[144:147], v[212:215], v[96:99]
	v_mfma_f32_16x16x32_bf16 v[32:35], v[152:155], v[212:215], v[32:35]
	v_mfma_f32_16x16x32_bf16 v[100:103], v[148:151], v[164:167], v[100:103]
	v_mfma_f32_16x16x32_bf16 v[40:43], v[156:159], v[164:167], v[40:43]
	v_mfma_f32_16x16x32_bf16 v[116:119], v[148:151], v[172:175], v[116:119]
	v_mfma_f32_16x16x32_bf16 v[56:59], v[156:159], v[172:175], v[56:59]
	v_mfma_f32_16x16x32_bf16 v[104:107], v[148:151], v[208:211], v[104:107]
	v_mfma_f32_16x16x32_bf16 v[44:47], v[156:159], v[208:211], v[44:47]
	v_mfma_f32_16x16x32_bf16 v[96:99], v[148:151], v[216:219], v[96:99]
	v_mfma_f32_16x16x32_bf16 v[32:35], v[156:159], v[216:219], v[32:35]
	s_barrier
	s_setprio 0
	s_add_i32 s0, s0, s33
	v_lshl_add_u64 v[186:187], v[186:187], 0, s[58:59]
	s_mov_b32 m0, s0
	ds_read_b128 v[160:163], v206 offset:49152
	ds_read_b128 v[164:167], v206 offset:50176
	ds_read_b128 v[168:171], v206 offset:51200
	ds_read_b128 v[172:175], v206 offset:52224
	ds_read_b128 v[196:199], v206 offset:53248
	ds_read_b128 v[208:211], v206 offset:54272
	ds_read_b128 v[212:215], v206 offset:55296
	ds_read_b128 v[216:219], v206 offset:56320
	global_load_lds_dwordx4 v[186:187], off
	s_add_i32 m0, s0, 0x2000
	s_add_u32 s10, s52, 0x80080
	v_lshl_add_u64 v[186:187], v[220:221], 0, s[58:59]
	s_addc_u32 s11, s53, 0
	s_add_i32 s0, s1, s33
	global_load_lds_dwordx4 v[186:187], off
	s_mov_b32 m0, s0
	v_lshl_add_u64 v[186:187], s[10:11], 0, v[190:191]
	global_load_lds_dwordx4 v[186:187], off
	s_add_i32 m0, s0, 0x2000
	v_lshl_add_u64 v[186:187], s[10:11], 0, v[180:181]
	global_load_lds_dwordx4 v[186:187], off
	s_mov_b32 m0, s55
	v_lshl_add_u64 v[186:187], v[222:223], 0, s[58:59]
	global_load_lds_dwordx4 v[186:187], off
	s_mov_b32 m0, s77
	v_lshl_add_u64 v[186:187], v[224:225], 0, s[58:59]
	global_load_lds_dwordx4 v[186:187], off
	s_setprio 1
	s_waitcnt vmcnt(8) lgkmcnt(0)
	s_barrier
	v_mfma_f32_16x16x32_bf16 v[88:91], v[128:131], v[160:163], v[88:91]
	v_mfma_f32_16x16x32_bf16 v[20:23], v[136:139], v[160:163], v[20:23]
	v_mfma_f32_16x16x32_bf16 v[92:95], v[128:131], v[168:171], v[92:95]
	v_mfma_f32_16x16x32_bf16 v[28:31], v[136:139], v[168:171], v[28:31]
	v_mfma_f32_16x16x32_bf16 v[80:83], v[128:131], v[196:199], v[80:83]
	v_mfma_f32_16x16x32_bf16 v[16:19], v[136:139], v[196:199], v[16:19]
	v_mfma_f32_16x16x32_bf16 v[76:79], v[128:131], v[212:215], v[76:79]
	v_mfma_f32_16x16x32_bf16 v[12:15], v[136:139], v[212:215], v[12:15]
	v_mfma_f32_16x16x32_bf16 v[88:91], v[132:135], v[164:167], v[88:91]
	v_mfma_f32_16x16x32_bf16 v[20:23], v[140:143], v[164:167], v[20:23]
	v_mfma_f32_16x16x32_bf16 v[92:95], v[132:135], v[172:175], v[92:95]
	v_mfma_f32_16x16x32_bf16 v[28:31], v[140:143], v[172:175], v[28:31]
	v_mfma_f32_16x16x32_bf16 v[80:83], v[132:135], v[208:211], v[80:83]
	v_mfma_f32_16x16x32_bf16 v[16:19], v[140:143], v[208:211], v[16:19]
	v_mfma_f32_16x16x32_bf16 v[76:79], v[132:135], v[216:219], v[76:79]
	v_mfma_f32_16x16x32_bf16 v[12:15], v[140:143], v[216:219], v[12:15]
	s_setprio 0
	s_setprio 1
	v_mfma_f32_16x16x32_bf16 v[68:71], v[144:147], v[160:163], v[68:71]
	v_mfma_f32_16x16x32_bf16 v[4:7], v[152:155], v[160:163], v[4:7]
	v_mfma_f32_16x16x32_bf16 v[84:87], v[144:147], v[168:171], v[84:87]
	v_mfma_f32_16x16x32_bf16 v[24:27], v[152:155], v[168:171], v[24:27]
	v_mfma_f32_16x16x32_bf16 v[72:75], v[144:147], v[196:199], v[72:75]
	v_mfma_f32_16x16x32_bf16 v[8:11], v[152:155], v[196:199], v[8:11]
	v_mfma_f32_16x16x32_bf16 v[64:67], v[144:147], v[212:215], v[64:67]
	v_mfma_f32_16x16x32_bf16 v[0:3], v[152:155], v[212:215], v[0:3]
	v_mfma_f32_16x16x32_bf16 v[68:71], v[148:151], v[164:167], v[68:71]
	v_mfma_f32_16x16x32_bf16 v[4:7], v[156:159], v[164:167], v[4:7]
	v_mfma_f32_16x16x32_bf16 v[84:87], v[148:151], v[172:175], v[84:87]
	v_mfma_f32_16x16x32_bf16 v[24:27], v[156:159], v[172:175], v[24:27]
	v_mfma_f32_16x16x32_bf16 v[72:75], v[148:151], v[208:211], v[72:75]
	v_mfma_f32_16x16x32_bf16 v[8:11], v[156:159], v[208:211], v[8:11]
	v_mfma_f32_16x16x32_bf16 v[64:67], v[148:151], v[216:219], v[64:67]
	v_mfma_f32_16x16x32_bf16 v[0:3], v[156:159], v[216:219], v[0:3]
	s_barrier
	s_setprio 0
	s_add_i32 vcc_lo, vcc_lo, 2
	s_add_u32 s66, s66, 0x100
	s_addc_u32 s67, s67, 0
	s_cmp_gt_u32 vcc_lo, 29
	s_mov_b64 s[10:11], s[16:17]
	s_cbranch_scc1 .Lpeel_done_7
	s_branch .LBB0_1105
.Ltrip0_strict_7:
	s_add_u32 s16, s10, 0x100
	s_addc_u32 s17, s11, 0
	s_add_i32 vcc_hi, 0, 0x10000
	s_cmp_eq_u32 vcc_lo, 28
	s_cselect_b32 s69, s13, s17
	s_cselect_b32 s68, s15, s16
	s_cselect_b32 s53, s57, s67
	s_cselect_b32 s52, s61, s66
	s_add_i32 s0, 0, 0x14000
	v_add_u32_e32 v140, vcc_hi, v200
	v_add_u32_e32 v156, s0, v200
	ds_read_b128 v[128:131], v140
	ds_read_b128 v[132:135], v140 offset:1024
	ds_read_b128 v[136:139], v140 offset:2048
	ds_read_b128 v[140:143], v140 offset:3072
	ds_read_b128 v[144:147], v156
	ds_read_b128 v[148:151], v156 offset:1024
	ds_read_b128 v[152:155], v156 offset:2048
	ds_read_b128 v[156:159], v156 offset:3072
	v_lshl_add_u64 v[186:187], s[10:11], 0, v[182:183]
	s_add_i32 m0, s40, 0xc000
	ds_read_b128 v[160:163], v206
	ds_read_b128 v[164:167], v206 offset:1024
	ds_read_b128 v[168:171], v206 offset:2048
	ds_read_b128 v[172:175], v206 offset:3072
	ds_read_b128 v[196:199], v206 offset:4096
	ds_read_b128 v[208:211], v206 offset:5120
	ds_read_b128 v[212:215], v206 offset:6144
	ds_read_b128 v[216:219], v206 offset:7168
	global_load_lds_dwordx4 v[186:187], off
	s_add_i32 m0, s40, 0xe000
	v_lshl_add_u64 v[186:187], s[10:11], 0, v[184:185]
	global_load_lds_dwordx4 v[186:187], off
	s_setprio 1
	s_waitcnt vmcnt(8) lgkmcnt(0)
	s_barrier
	v_mfma_f32_16x16x32_bf16 v[120:123], v[128:131], v[160:163], 0
	v_mfma_f32_16x16x32_bf16 v[48:51], v[136:139], v[160:163], 0
	v_mfma_f32_16x16x32_bf16 v[124:127], v[128:131], v[168:171], 0
	v_mfma_f32_16x16x32_bf16 v[60:63], v[136:139], v[168:171], 0
	v_mfma_f32_16x16x32_bf16 v[112:115], v[128:131], v[196:199], 0
	v_mfma_f32_16x16x32_bf16 v[52:55], v[136:139], v[196:199], 0
	v_mfma_f32_16x16x32_bf16 v[108:111], v[128:131], v[212:215], 0
	v_mfma_f32_16x16x32_bf16 v[36:39], v[136:139], v[212:215], 0
	v_mfma_f32_16x16x32_bf16 v[120:123], v[132:135], v[164:167], v[120:123]
	v_mfma_f32_16x16x32_bf16 v[48:51], v[140:143], v[164:167], v[48:51]
	v_mfma_f32_16x16x32_bf16 v[124:127], v[132:135], v[172:175], v[124:127]
	v_mfma_f32_16x16x32_bf16 v[60:63], v[140:143], v[172:175], v[60:63]
	v_mfma_f32_16x16x32_bf16 v[112:115], v[132:135], v[208:211], v[112:115]
	v_mfma_f32_16x16x32_bf16 v[52:55], v[140:143], v[208:211], v[52:55]
	v_mfma_f32_16x16x32_bf16 v[108:111], v[132:135], v[216:219], v[108:111]
	v_mfma_f32_16x16x32_bf16 v[36:39], v[140:143], v[216:219], v[36:39]
	s_setprio 0
	s_setprio 1
	v_mfma_f32_16x16x32_bf16 v[100:103], v[144:147], v[160:163], 0
	v_mfma_f32_16x16x32_bf16 v[40:43], v[152:155], v[160:163], 0
	v_mfma_f32_16x16x32_bf16 v[116:119], v[144:147], v[168:171], 0
	v_mfma_f32_16x16x32_bf16 v[56:59], v[152:155], v[168:171], 0
	v_mfma_f32_16x16x32_bf16 v[104:107], v[144:147], v[196:199], 0
	v_mfma_f32_16x16x32_bf16 v[44:47], v[152:155], v[196:199], 0
	v_mfma_f32_16x16x32_bf16 v[96:99], v[144:147], v[212:215], 0
	v_mfma_f32_16x16x32_bf16 v[32:35], v[152:155], v[212:215], 0
	v_mfma_f32_16x16x32_bf16 v[100:103], v[148:151], v[164:167], v[100:103]
	v_mfma_f32_16x16x32_bf16 v[40:43], v[156:159], v[164:167], v[40:43]
	v_mfma_f32_16x16x32_bf16 v[116:119], v[148:151], v[172:175], v[116:119]
	v_mfma_f32_16x16x32_bf16 v[56:59], v[156:159], v[172:175], v[56:59]
	v_mfma_f32_16x16x32_bf16 v[104:107], v[148:151], v[208:211], v[104:107]
	v_mfma_f32_16x16x32_bf16 v[44:47], v[156:159], v[208:211], v[44:47]
	v_mfma_f32_16x16x32_bf16 v[96:99], v[148:151], v[216:219], v[96:99]
	v_mfma_f32_16x16x32_bf16 v[32:35], v[156:159], v[216:219], v[32:35]
	s_barrier
	s_setprio 0
	s_add_i32 s1, vcc_hi, s33
	v_lshl_add_u64 v[186:187], s[52:53], 0, v[190:191]
	s_mov_b32 m0, s1
	ds_read_b128 v[160:163], v206 offset:16384
	ds_read_b128 v[164:167], v206 offset:17408
	ds_read_b128 v[168:171], v206 offset:18432
	ds_read_b128 v[172:175], v206 offset:19456
	ds_read_b128 v[196:199], v206 offset:20480
	ds_read_b128 v[208:211], v206 offset:21504
	ds_read_b128 v[212:215], v206 offset:22528
	ds_read_b128 v[216:219], v206 offset:23552
	global_load_lds_dwordx4 v[186:187], off
	s_add_i32 m0, s1, 0x2000
	s_add_u32 s10, s52, 0x80000
	v_lshl_add_u64 v[220:221], s[52:53], 0, v[180:181]
	s_addc_u32 s11, s53, 0
	s_add_i32 s0, s0, s33
	global_load_lds_dwordx4 v[220:221], off
	v_lshl_add_u64 v[222:223], s[10:11], 0, v[190:191]
	s_mov_b32 m0, s0
	v_lshl_add_u64 v[224:225], s[68:69], 0, v[178:179]
	global_load_lds_dwordx4 v[222:223], off
	s_add_i32 m0, s0, 0x2000
	v_lshl_add_u64 v[222:223], s[10:11], 0, v[180:181]
	global_load_lds_dwordx4 v[222:223], off
	s_mov_b32 m0, s40
	v_lshl_add_u64 v[222:223], s[68:69], 0, v[176:177]
	global_load_lds_dwordx4 v[222:223], off
	s_mov_b32 m0, s41
	s_nop 0
	global_load_lds_dwordx4 v[224:225], off
	s_setprio 1
	s_waitcnt vmcnt(8) lgkmcnt(0)
	s_barrier
	v_mfma_f32_16x16x32_bf16 v[88:91], v[128:131], v[160:163], 0
	v_mfma_f32_16x16x32_bf16 v[20:23], v[136:139], v[160:163], 0
	v_mfma_f32_16x16x32_bf16 v[92:95], v[128:131], v[168:171], 0
	v_mfma_f32_16x16x32_bf16 v[28:31], v[136:139], v[168:171], 0
	v_mfma_f32_16x16x32_bf16 v[80:83], v[128:131], v[196:199], 0
	v_mfma_f32_16x16x32_bf16 v[16:19], v[136:139], v[196:199], 0
	v_mfma_f32_16x16x32_bf16 v[76:79], v[128:131], v[212:215], 0
	v_mfma_f32_16x16x32_bf16 v[12:15], v[136:139], v[212:215], 0
	v_mfma_f32_16x16x32_bf16 v[88:91], v[132:135], v[164:167], v[88:91]
	v_mfma_f32_16x16x32_bf16 v[20:23], v[140:143], v[164:167], v[20:23]
	v_mfma_f32_16x16x32_bf16 v[92:95], v[132:135], v[172:175], v[92:95]
	v_mfma_f32_16x16x32_bf16 v[28:31], v[140:143], v[172:175], v[28:31]
	v_mfma_f32_16x16x32_bf16 v[80:83], v[132:135], v[208:211], v[80:83]
	v_mfma_f32_16x16x32_bf16 v[16:19], v[140:143], v[208:211], v[16:19]
	v_mfma_f32_16x16x32_bf16 v[76:79], v[132:135], v[216:219], v[76:79]
	v_mfma_f32_16x16x32_bf16 v[12:15], v[140:143], v[216:219], v[12:15]
	s_setprio 0
	s_setprio 1
	v_mfma_f32_16x16x32_bf16 v[68:71], v[144:147], v[160:163], 0
	v_mfma_f32_16x16x32_bf16 v[4:7], v[152:155], v[160:163], 0
	v_mfma_f32_16x16x32_bf16 v[84:87], v[144:147], v[168:171], 0
	v_mfma_f32_16x16x32_bf16 v[24:27], v[152:155], v[168:171], 0
	v_mfma_f32_16x16x32_bf16 v[72:75], v[144:147], v[196:199], 0
	v_mfma_f32_16x16x32_bf16 v[8:11], v[152:155], v[196:199], 0
	v_mfma_f32_16x16x32_bf16 v[64:67], v[144:147], v[212:215], 0
	v_mfma_f32_16x16x32_bf16 v[0:3], v[152:155], v[212:215], 0
	v_mfma_f32_16x16x32_bf16 v[68:71], v[148:151], v[164:167], v[68:71]
	v_mfma_f32_16x16x32_bf16 v[4:7], v[156:159], v[164:167], v[4:7]
	v_mfma_f32_16x16x32_bf16 v[84:87], v[148:151], v[172:175], v[84:87]
	v_mfma_f32_16x16x32_bf16 v[24:27], v[156:159], v[172:175], v[24:27]
	v_mfma_f32_16x16x32_bf16 v[72:75], v[148:151], v[208:211], v[72:75]
	v_mfma_f32_16x16x32_bf16 v[8:11], v[156:159], v[208:211], v[8:11]
	v_mfma_f32_16x16x32_bf16 v[64:67], v[148:151], v[216:219], v[64:67]
	v_mfma_f32_16x16x32_bf16 v[0:3], v[156:159], v[216:219], v[0:3]
	s_barrier
	s_setprio 0
	s_add_i32 s0, 0, 0x18000
	s_add_i32 s1, 0, 0x1c000
	v_add_u32_e32 v140, s0, v200
	v_add_u32_e32 v156, s1, v200
	ds_read_b128 v[128:131], v140
	ds_read_b128 v[132:135], v140 offset:1024
	ds_read_b128 v[136:139], v140 offset:2048
	ds_read_b128 v[140:143], v140 offset:3072
	ds_read_b128 v[144:147], v156
	ds_read_b128 v[148:151], v156 offset:1024
	ds_read_b128 v[152:155], v156 offset:2048
	ds_read_b128 v[156:159], v156 offset:3072
	s_add_u32 s10, s68, 0x80000
	s_addc_u32 s11, s69, 0
	s_mov_b32 m0, s42
	v_lshl_add_u64 v[226:227], s[10:11], 0, v[176:177]
	ds_read_b128 v[160:163], v206 offset:32768
	ds_read_b128 v[164:167], v206 offset:33792
	ds_read_b128 v[168:171], v206 offset:34816
	ds_read_b128 v[172:175], v206 offset:35840
	ds_read_b128 v[196:199], v206 offset:36864
	ds_read_b128 v[208:211], v206 offset:37888
	ds_read_b128 v[212:215], v206 offset:38912
	ds_read_b128 v[216:219], v206 offset:39936
	global_load_lds_dwordx4 v[226:227], off
	s_mov_b32 m0, s43
	v_lshl_add_u64 v[226:227], s[10:11], 0, v[178:179]
	global_load_lds_dwordx4 v[226:227], off
	s_setprio 1
	s_waitcnt vmcnt(8) lgkmcnt(0)
	s_barrier
	v_mfma_f32_16x16x32_bf16 v[120:123], v[128:131], v[160:163], v[120:123]
	v_mfma_f32_16x16x32_bf16 v[48:51], v[136:139], v[160:163], v[48:51]
	v_mfma_f32_16x16x32_bf16 v[124:127], v[128:131], v[168:171], v[124:127]
	v_mfma_f32_16x16x32_bf16 v[60:63], v[136:139], v[168:171], v[60:63]
	v_mfma_f32_16x16x32_bf16 v[112:115], v[128:131], v[196:199], v[112:115]
	v_mfma_f32_16x16x32_bf16 v[52:55], v[136:139], v[196:199], v[52:55]
	v_mfma_f32_16x16x32_bf16 v[108:111], v[128:131], v[212:215], v[108:111]
	v_mfma_f32_16x16x32_bf16 v[36:39], v[136:139], v[212:215], v[36:39]
	v_mfma_f32_16x16x32_bf16 v[120:123], v[132:135], v[164:167], v[120:123]
	v_mfma_f32_16x16x32_bf16 v[48:51], v[140:143], v[164:167], v[48:51]
	v_mfma_f32_16x16x32_bf16 v[124:127], v[132:135], v[172:175], v[124:127]
	v_mfma_f32_16x16x32_bf16 v[60:63], v[140:143], v[172:175], v[60:63]
	v_mfma_f32_16x16x32_bf16 v[112:115], v[132:135], v[208:211], v[112:115]
	v_mfma_f32_16x16x32_bf16 v[52:55], v[140:143], v[208:211], v[52:55]
	v_mfma_f32_16x16x32_bf16 v[108:111], v[132:135], v[216:219], v[108:111]
	v_mfma_f32_16x16x32_bf16 v[36:39], v[140:143], v[216:219], v[36:39]
	s_setprio 0
	s_setprio 1
	v_mfma_f32_16x16x32_bf16 v[100:103], v[144:147], v[160:163], v[100:103]
	v_mfma_f32_16x16x32_bf16 v[40:43], v[152:155], v[160:163], v[40:43]
	v_mfma_f32_16x16x32_bf16 v[116:119], v[144:147], v[168:171], v[116:119]
	v_mfma_f32_16x16x32_bf16 v[56:59], v[152:155], v[168:171], v[56:59]
	v_mfma_f32_16x16x32_bf16 v[104:107], v[144:147], v[196:199], v[104:107]
	v_mfma_f32_16x16x32_bf16 v[44:47], v[152:155], v[196:199], v[44:47]
	v_mfma_f32_16x16x32_bf16 v[96:99], v[144:147], v[212:215], v[96:99]
	v_mfma_f32_16x16x32_bf16 v[32:35], v[152:155], v[212:215], v[32:35]
	v_mfma_f32_16x16x32_bf16 v[100:103], v[148:151], v[164:167], v[100:103]
	v_mfma_f32_16x16x32_bf16 v[40:43], v[156:159], v[164:167], v[40:43]
	v_mfma_f32_16x16x32_bf16 v[116:119], v[148:151], v[172:175], v[116:119]
	v_mfma_f32_16x16x32_bf16 v[56:59], v[156:159], v[172:175], v[56:59]
	v_mfma_f32_16x16x32_bf16 v[104:107], v[148:151], v[208:211], v[104:107]
	v_mfma_f32_16x16x32_bf16 v[44:47], v[156:159], v[208:211], v[44:47]
	v_mfma_f32_16x16x32_bf16 v[96:99], v[148:151], v[216:219], v[96:99]
	v_mfma_f32_16x16x32_bf16 v[32:35], v[156:159], v[216:219], v[32:35]
	s_barrier
	s_setprio 0
	s_add_i32 s0, s0, s33
	v_lshl_add_u64 v[186:187], v[186:187], 0, s[58:59]
	s_mov_b32 m0, s0
	ds_read_b128 v[160:163], v206 offset:49152
	ds_read_b128 v[164:167], v206 offset:50176
	ds_read_b128 v[168:171], v206 offset:51200
	ds_read_b128 v[172:175], v206 offset:52224
	ds_read_b128 v[196:199], v206 offset:53248
	ds_read_b128 v[208:211], v206 offset:54272
	ds_read_b128 v[212:215], v206 offset:55296
	ds_read_b128 v[216:219], v206 offset:56320
	global_load_lds_dwordx4 v[186:187], off
	s_add_i32 m0, s0, 0x2000
	s_add_u32 s10, s52, 0x80080
	v_lshl_add_u64 v[186:187], v[220:221], 0, s[58:59]
	s_addc_u32 s11, s53, 0
	s_add_i32 s0, s1, s33
	global_load_lds_dwordx4 v[186:187], off
	s_mov_b32 m0, s0
	v_lshl_add_u64 v[186:187], s[10:11], 0, v[190:191]
	global_load_lds_dwordx4 v[186:187], off
	s_add_i32 m0, s0, 0x2000
	v_lshl_add_u64 v[186:187], s[10:11], 0, v[180:181]
	global_load_lds_dwordx4 v[186:187], off
	s_mov_b32 m0, s55
	v_lshl_add_u64 v[186:187], v[222:223], 0, s[58:59]
	global_load_lds_dwordx4 v[186:187], off
	s_mov_b32 m0, s77
	v_lshl_add_u64 v[186:187], v[224:225], 0, s[58:59]
	global_load_lds_dwordx4 v[186:187], off
	s_setprio 1
	s_waitcnt vmcnt(8) lgkmcnt(0)
	s_barrier
	v_mfma_f32_16x16x32_bf16 v[88:91], v[128:131], v[160:163], v[88:91]
	v_mfma_f32_16x16x32_bf16 v[20:23], v[136:139], v[160:163], v[20:23]
	v_mfma_f32_16x16x32_bf16 v[92:95], v[128:131], v[168:171], v[92:95]
	v_mfma_f32_16x16x32_bf16 v[28:31], v[136:139], v[168:171], v[28:31]
	v_mfma_f32_16x16x32_bf16 v[80:83], v[128:131], v[196:199], v[80:83]
	v_mfma_f32_16x16x32_bf16 v[16:19], v[136:139], v[196:199], v[16:19]
	v_mfma_f32_16x16x32_bf16 v[76:79], v[128:131], v[212:215], v[76:79]
	v_mfma_f32_16x16x32_bf16 v[12:15], v[136:139], v[212:215], v[12:15]
	v_mfma_f32_16x16x32_bf16 v[88:91], v[132:135], v[164:167], v[88:91]
	v_mfma_f32_16x16x32_bf16 v[20:23], v[140:143], v[164:167], v[20:23]
	v_mfma_f32_16x16x32_bf16 v[92:95], v[132:135], v[172:175], v[92:95]
	v_mfma_f32_16x16x32_bf16 v[28:31], v[140:143], v[172:175], v[28:31]
	v_mfma_f32_16x16x32_bf16 v[80:83], v[132:135], v[208:211], v[80:83]
	v_mfma_f32_16x16x32_bf16 v[16:19], v[140:143], v[208:211], v[16:19]
	v_mfma_f32_16x16x32_bf16 v[76:79], v[132:135], v[216:219], v[76:79]
	v_mfma_f32_16x16x32_bf16 v[12:15], v[140:143], v[216:219], v[12:15]
	s_setprio 0
	s_setprio 1
	v_mfma_f32_16x16x32_bf16 v[68:71], v[144:147], v[160:163], v[68:71]
	v_mfma_f32_16x16x32_bf16 v[4:7], v[152:155], v[160:163], v[4:7]
	v_mfma_f32_16x16x32_bf16 v[84:87], v[144:147], v[168:171], v[84:87]
	v_mfma_f32_16x16x32_bf16 v[24:27], v[152:155], v[168:171], v[24:27]
	v_mfma_f32_16x16x32_bf16 v[72:75], v[144:147], v[196:199], v[72:75]
	v_mfma_f32_16x16x32_bf16 v[8:11], v[152:155], v[196:199], v[8:11]
	v_mfma_f32_16x16x32_bf16 v[64:67], v[144:147], v[212:215], v[64:67]
	v_mfma_f32_16x16x32_bf16 v[0:3], v[152:155], v[212:215], v[0:3]
	v_mfma_f32_16x16x32_bf16 v[68:71], v[148:151], v[164:167], v[68:71]
	v_mfma_f32_16x16x32_bf16 v[4:7], v[156:159], v[164:167], v[4:7]
	v_mfma_f32_16x16x32_bf16 v[84:87], v[148:151], v[172:175], v[84:87]
	v_mfma_f32_16x16x32_bf16 v[24:27], v[156:159], v[172:175], v[24:27]
	v_mfma_f32_16x16x32_bf16 v[72:75], v[148:151], v[208:211], v[72:75]
	v_mfma_f32_16x16x32_bf16 v[8:11], v[156:159], v[208:211], v[8:11]
	v_mfma_f32_16x16x32_bf16 v[64:67], v[148:151], v[216:219], v[64:67]
	v_mfma_f32_16x16x32_bf16 v[0:3], v[156:159], v[216:219], v[0:3]
	s_barrier
	s_setprio 0
	s_add_i32 vcc_lo, vcc_lo, 2
	s_add_u32 s66, s66, 0x100
	s_addc_u32 s67, s67, 0
	s_cmp_gt_u32 vcc_lo, 29
	s_mov_b64 s[10:11], s[16:17]
	s_cbranch_scc1 .Lpeel_done_7
.LBB0_1105:
	s_add_u32 s16, s10, 0x100
	s_addc_u32 s17, s11, 0
	s_add_i32 vcc_hi, 0, 0x10000
	s_cmp_eq_u32 vcc_lo, 28
	s_cselect_b32 s69, s13, s17
	s_cselect_b32 s68, s15, s16
	s_cselect_b32 s53, s57, s67
	s_cselect_b32 s52, s61, s66
	s_add_i32 s0, 0, 0x14000
	v_add_u32_e32 v140, vcc_hi, v200
	v_add_u32_e32 v156, s0, v200
	ds_read_b128 v[128:131], v140
	ds_read_b128 v[132:135], v140 offset:1024
	ds_read_b128 v[136:139], v140 offset:2048
	ds_read_b128 v[140:143], v140 offset:3072
	ds_read_b128 v[144:147], v156
	ds_read_b128 v[148:151], v156 offset:1024
	ds_read_b128 v[152:155], v156 offset:2048
	ds_read_b128 v[156:159], v156 offset:3072
	v_lshl_add_u64 v[186:187], s[10:11], 0, v[182:183]
	s_add_i32 m0, s40, 0xc000
	ds_read_b128 v[160:163], v206
	ds_read_b128 v[164:167], v206 offset:1024
	ds_read_b128 v[168:171], v206 offset:2048
	ds_read_b128 v[172:175], v206 offset:3072
	ds_read_b128 v[196:199], v206 offset:4096
	ds_read_b128 v[208:211], v206 offset:5120
	ds_read_b128 v[212:215], v206 offset:6144
	ds_read_b128 v[216:219], v206 offset:7168
	global_load_lds_dwordx4 v[186:187], off
	s_add_i32 m0, s40, 0xe000
	v_lshl_add_u64 v[186:187], s[10:11], 0, v[184:185]
	global_load_lds_dwordx4 v[186:187], off
	s_setprio 1
	s_waitcnt vmcnt(8) lgkmcnt(0)
	s_barrier
	v_mfma_f32_16x16x32_bf16 v[120:123], v[128:131], v[160:163], v[120:123]
	v_mfma_f32_16x16x32_bf16 v[48:51], v[136:139], v[160:163], v[48:51]
	v_mfma_f32_16x16x32_bf16 v[124:127], v[128:131], v[168:171], v[124:127]
	v_mfma_f32_16x16x32_bf16 v[60:63], v[136:139], v[168:171], v[60:63]
	v_mfma_f32_16x16x32_bf16 v[112:115], v[128:131], v[196:199], v[112:115]
	v_mfma_f32_16x16x32_bf16 v[52:55], v[136:139], v[196:199], v[52:55]
	v_mfma_f32_16x16x32_bf16 v[108:111], v[128:131], v[212:215], v[108:111]
	v_mfma_f32_16x16x32_bf16 v[36:39], v[136:139], v[212:215], v[36:39]
	v_mfma_f32_16x16x32_bf16 v[120:123], v[132:135], v[164:167], v[120:123]
	v_mfma_f32_16x16x32_bf16 v[48:51], v[140:143], v[164:167], v[48:51]
	v_mfma_f32_16x16x32_bf16 v[124:127], v[132:135], v[172:175], v[124:127]
	v_mfma_f32_16x16x32_bf16 v[60:63], v[140:143], v[172:175], v[60:63]
	v_mfma_f32_16x16x32_bf16 v[112:115], v[132:135], v[208:211], v[112:115]
	v_mfma_f32_16x16x32_bf16 v[52:55], v[140:143], v[208:211], v[52:55]
	v_mfma_f32_16x16x32_bf16 v[108:111], v[132:135], v[216:219], v[108:111]
	v_mfma_f32_16x16x32_bf16 v[36:39], v[140:143], v[216:219], v[36:39]
	s_setprio 0
	s_setprio 1
	v_mfma_f32_16x16x32_bf16 v[100:103], v[144:147], v[160:163], v[100:103]
	v_mfma_f32_16x16x32_bf16 v[40:43], v[152:155], v[160:163], v[40:43]
	v_mfma_f32_16x16x32_bf16 v[116:119], v[144:147], v[168:171], v[116:119]
	v_mfma_f32_16x16x32_bf16 v[56:59], v[152:155], v[168:171], v[56:59]
	v_mfma_f32_16x16x32_bf16 v[104:107], v[144:147], v[196:199], v[104:107]
	v_mfma_f32_16x16x32_bf16 v[44:47], v[152:155], v[196:199], v[44:47]
	v_mfma_f32_16x16x32_bf16 v[96:99], v[144:147], v[212:215], v[96:99]
	v_mfma_f32_16x16x32_bf16 v[32:35], v[152:155], v[212:215], v[32:35]
	v_mfma_f32_16x16x32_bf16 v[100:103], v[148:151], v[164:167], v[100:103]
	v_mfma_f32_16x16x32_bf16 v[40:43], v[156:159], v[164:167], v[40:43]
	v_mfma_f32_16x16x32_bf16 v[116:119], v[148:151], v[172:175], v[116:119]
	v_mfma_f32_16x16x32_bf16 v[56:59], v[156:159], v[172:175], v[56:59]
	v_mfma_f32_16x16x32_bf16 v[104:107], v[148:151], v[208:211], v[104:107]
	v_mfma_f32_16x16x32_bf16 v[44:47], v[156:159], v[208:211], v[44:47]
	v_mfma_f32_16x16x32_bf16 v[96:99], v[148:151], v[216:219], v[96:99]
	v_mfma_f32_16x16x32_bf16 v[32:35], v[156:159], v[216:219], v[32:35]
	s_setprio 0
	s_barrier
	s_add_i32 s1, vcc_hi, s33
	v_lshl_add_u64 v[186:187], s[52:53], 0, v[190:191]
	s_mov_b32 m0, s1
	ds_read_b128 v[160:163], v206 offset:16384
	ds_read_b128 v[164:167], v206 offset:17408
	ds_read_b128 v[168:171], v206 offset:18432
	ds_read_b128 v[172:175], v206 offset:19456
	ds_read_b128 v[196:199], v206 offset:20480
	ds_read_b128 v[208:211], v206 offset:21504
	ds_read_b128 v[212:215], v206 offset:22528
	ds_read_b128 v[216:219], v206 offset:23552
	global_load_lds_dwordx4 v[186:187], off
	s_add_i32 m0, s1, 0x2000
	s_add_u32 s10, s52, 0x80000
	v_lshl_add_u64 v[220:221], s[52:53], 0, v[180:181]
	s_addc_u32 s11, s53, 0
	s_add_i32 s0, s0, s33
	global_load_lds_dwordx4 v[220:221], off
	v_lshl_add_u64 v[222:223], s[10:11], 0, v[190:191]
	s_mov_b32 m0, s0
	v_lshl_add_u64 v[224:225], s[68:69], 0, v[178:179]
	global_load_lds_dwordx4 v[222:223], off
	s_add_i32 m0, s0, 0x2000
	v_lshl_add_u64 v[222:223], s[10:11], 0, v[180:181]
	global_load_lds_dwordx4 v[222:223], off
	s_mov_b32 m0, s40
	v_lshl_add_u64 v[222:223], s[68:69], 0, v[176:177]
	global_load_lds_dwordx4 v[222:223], off
	s_mov_b32 m0, s41
	s_nop 0
	global_load_lds_dwordx4 v[224:225], off
	s_setprio 1
	s_waitcnt vmcnt(8) lgkmcnt(0)
	s_barrier
	v_mfma_f32_16x16x32_bf16 v[88:91], v[128:131], v[160:163], v[88:91]
	v_mfma_f32_16x16x32_bf16 v[20:23], v[136:139], v[160:163], v[20:23]
	v_mfma_f32_16x16x32_bf16 v[92:95], v[128:131], v[168:171], v[92:95]
	v_mfma_f32_16x16x32_bf16 v[28:31], v[136:139], v[168:171], v[28:31]
	v_mfma_f32_16x16x32_bf16 v[80:83], v[128:131], v[196:199], v[80:83]
	v_mfma_f32_16x16x32_bf16 v[16:19], v[136:139], v[196:199], v[16:19]
	v_mfma_f32_16x16x32_bf16 v[76:79], v[128:131], v[212:215], v[76:79]
	v_mfma_f32_16x16x32_bf16 v[12:15], v[136:139], v[212:215], v[12:15]
	v_mfma_f32_16x16x32_bf16 v[88:91], v[132:135], v[164:167], v[88:91]
	v_mfma_f32_16x16x32_bf16 v[20:23], v[140:143], v[164:167], v[20:23]
	v_mfma_f32_16x16x32_bf16 v[92:95], v[132:135], v[172:175], v[92:95]
	v_mfma_f32_16x16x32_bf16 v[28:31], v[140:143], v[172:175], v[28:31]
	v_mfma_f32_16x16x32_bf16 v[80:83], v[132:135], v[208:211], v[80:83]
	v_mfma_f32_16x16x32_bf16 v[16:19], v[140:143], v[208:211], v[16:19]
	v_mfma_f32_16x16x32_bf16 v[76:79], v[132:135], v[216:219], v[76:79]
	v_mfma_f32_16x16x32_bf16 v[12:15], v[140:143], v[216:219], v[12:15]
	s_setprio 0
	s_setprio 1
	v_mfma_f32_16x16x32_bf16 v[68:71], v[144:147], v[160:163], v[68:71]
	v_mfma_f32_16x16x32_bf16 v[4:7], v[152:155], v[160:163], v[4:7]
	v_mfma_f32_16x16x32_bf16 v[84:87], v[144:147], v[168:171], v[84:87]
	v_mfma_f32_16x16x32_bf16 v[24:27], v[152:155], v[168:171], v[24:27]
	v_mfma_f32_16x16x32_bf16 v[72:75], v[144:147], v[196:199], v[72:75]
	v_mfma_f32_16x16x32_bf16 v[8:11], v[152:155], v[196:199], v[8:11]
	v_mfma_f32_16x16x32_bf16 v[64:67], v[144:147], v[212:215], v[64:67]
	v_mfma_f32_16x16x32_bf16 v[0:3], v[152:155], v[212:215], v[0:3]
	v_mfma_f32_16x16x32_bf16 v[68:71], v[148:151], v[164:167], v[68:71]
	v_mfma_f32_16x16x32_bf16 v[4:7], v[156:159], v[164:167], v[4:7]
	v_mfma_f32_16x16x32_bf16 v[84:87], v[148:151], v[172:175], v[84:87]
	v_mfma_f32_16x16x32_bf16 v[24:27], v[156:159], v[172:175], v[24:27]
	v_mfma_f32_16x16x32_bf16 v[72:75], v[148:151], v[208:211], v[72:75]
	v_mfma_f32_16x16x32_bf16 v[8:11], v[156:159], v[208:211], v[8:11]
	v_mfma_f32_16x16x32_bf16 v[64:67], v[148:151], v[216:219], v[64:67]
	v_mfma_f32_16x16x32_bf16 v[0:3], v[156:159], v[216:219], v[0:3]
	s_setprio 0
	s_barrier
	s_add_i32 s0, 0, 0x18000
	s_add_i32 s1, 0, 0x1c000
	v_add_u32_e32 v140, s0, v200
	v_add_u32_e32 v156, s1, v200
	ds_read_b128 v[128:131], v140
	ds_read_b128 v[132:135], v140 offset:1024
	ds_read_b128 v[136:139], v140 offset:2048
	ds_read_b128 v[140:143], v140 offset:3072
	ds_read_b128 v[144:147], v156
	ds_read_b128 v[148:151], v156 offset:1024
	ds_read_b128 v[152:155], v156 offset:2048
	ds_read_b128 v[156:159], v156 offset:3072
	s_add_u32 s10, s68, 0x80000
	s_addc_u32 s11, s69, 0
	s_mov_b32 m0, s42
	v_lshl_add_u64 v[226:227], s[10:11], 0, v[176:177]
	ds_read_b128 v[160:163], v206 offset:32768
	ds_read_b128 v[164:167], v206 offset:33792
	ds_read_b128 v[168:171], v206 offset:34816
	ds_read_b128 v[172:175], v206 offset:35840
	ds_read_b128 v[196:199], v206 offset:36864
	ds_read_b128 v[208:211], v206 offset:37888
	ds_read_b128 v[212:215], v206 offset:38912
	ds_read_b128 v[216:219], v206 offset:39936
	global_load_lds_dwordx4 v[226:227], off
	s_mov_b32 m0, s43
	v_lshl_add_u64 v[226:227], s[10:11], 0, v[178:179]
	global_load_lds_dwordx4 v[226:227], off
	s_setprio 1
	s_waitcnt vmcnt(8) lgkmcnt(0)
	s_barrier
	v_mfma_f32_16x16x32_bf16 v[120:123], v[128:131], v[160:163], v[120:123]
	v_mfma_f32_16x16x32_bf16 v[48:51], v[136:139], v[160:163], v[48:51]
	v_mfma_f32_16x16x32_bf16 v[124:127], v[128:131], v[168:171], v[124:127]
	v_mfma_f32_16x16x32_bf16 v[60:63], v[136:139], v[168:171], v[60:63]
	v_mfma_f32_16x16x32_bf16 v[112:115], v[128:131], v[196:199], v[112:115]
	v_mfma_f32_16x16x32_bf16 v[52:55], v[136:139], v[196:199], v[52:55]
	v_mfma_f32_16x16x32_bf16 v[108:111], v[128:131], v[212:215], v[108:111]
	v_mfma_f32_16x16x32_bf16 v[36:39], v[136:139], v[212:215], v[36:39]
	v_mfma_f32_16x16x32_bf16 v[120:123], v[132:135], v[164:167], v[120:123]
	v_mfma_f32_16x16x32_bf16 v[48:51], v[140:143], v[164:167], v[48:51]
	v_mfma_f32_16x16x32_bf16 v[124:127], v[132:135], v[172:175], v[124:127]
	v_mfma_f32_16x16x32_bf16 v[60:63], v[140:143], v[172:175], v[60:63]
	v_mfma_f32_16x16x32_bf16 v[112:115], v[132:135], v[208:211], v[112:115]
	v_mfma_f32_16x16x32_bf16 v[52:55], v[140:143], v[208:211], v[52:55]
	v_mfma_f32_16x16x32_bf16 v[108:111], v[132:135], v[216:219], v[108:111]
	v_mfma_f32_16x16x32_bf16 v[36:39], v[140:143], v[216:219], v[36:39]
	s_setprio 0
	s_setprio 1
	v_mfma_f32_16x16x32_bf16 v[100:103], v[144:147], v[160:163], v[100:103]
	v_mfma_f32_16x16x32_bf16 v[40:43], v[152:155], v[160:163], v[40:43]
	v_mfma_f32_16x16x32_bf16 v[116:119], v[144:147], v[168:171], v[116:119]
	v_mfma_f32_16x16x32_bf16 v[56:59], v[152:155], v[168:171], v[56:59]
	v_mfma_f32_16x16x32_bf16 v[104:107], v[144:147], v[196:199], v[104:107]
	v_mfma_f32_16x16x32_bf16 v[44:47], v[152:155], v[196:199], v[44:47]
	v_mfma_f32_16x16x32_bf16 v[96:99], v[144:147], v[212:215], v[96:99]
	v_mfma_f32_16x16x32_bf16 v[32:35], v[152:155], v[212:215], v[32:35]
	v_mfma_f32_16x16x32_bf16 v[100:103], v[148:151], v[164:167], v[100:103]
	v_mfma_f32_16x16x32_bf16 v[40:43], v[156:159], v[164:167], v[40:43]
	v_mfma_f32_16x16x32_bf16 v[116:119], v[148:151], v[172:175], v[116:119]
	v_mfma_f32_16x16x32_bf16 v[56:59], v[156:159], v[172:175], v[56:59]
	v_mfma_f32_16x16x32_bf16 v[104:107], v[148:151], v[208:211], v[104:107]
	v_mfma_f32_16x16x32_bf16 v[44:47], v[156:159], v[208:211], v[44:47]
	v_mfma_f32_16x16x32_bf16 v[96:99], v[148:151], v[216:219], v[96:99]
	v_mfma_f32_16x16x32_bf16 v[32:35], v[156:159], v[216:219], v[32:35]
	s_setprio 0
	s_barrier
	s_add_i32 s0, s0, s33
	v_lshl_add_u64 v[186:187], v[186:187], 0, s[58:59]
	s_mov_b32 m0, s0
	ds_read_b128 v[160:163], v206 offset:49152
	ds_read_b128 v[164:167], v206 offset:50176
	ds_read_b128 v[168:171], v206 offset:51200
	ds_read_b128 v[172:175], v206 offset:52224
	ds_read_b128 v[196:199], v206 offset:53248
	ds_read_b128 v[208:211], v206 offset:54272
	ds_read_b128 v[212:215], v206 offset:55296
	ds_read_b128 v[216:219], v206 offset:56320
	global_load_lds_dwordx4 v[186:187], off
	s_add_i32 m0, s0, 0x2000
	s_add_u32 s10, s52, 0x80080
	v_lshl_add_u64 v[186:187], v[220:221], 0, s[58:59]
	s_addc_u32 s11, s53, 0
	s_add_i32 s0, s1, s33
	global_load_lds_dwordx4 v[186:187], off
	s_mov_b32 m0, s0
	v_lshl_add_u64 v[186:187], s[10:11], 0, v[190:191]
	global_load_lds_dwordx4 v[186:187], off
	s_add_i32 m0, s0, 0x2000
	v_lshl_add_u64 v[186:187], s[10:11], 0, v[180:181]
	global_load_lds_dwordx4 v[186:187], off
	s_mov_b32 m0, s55
	v_lshl_add_u64 v[186:187], v[222:223], 0, s[58:59]
	global_load_lds_dwordx4 v[186:187], off
	s_mov_b32 m0, s77
	v_lshl_add_u64 v[186:187], v[224:225], 0, s[58:59]
	global_load_lds_dwordx4 v[186:187], off
	s_setprio 1
	s_waitcnt vmcnt(8) lgkmcnt(0)
	s_barrier
	v_mfma_f32_16x16x32_bf16 v[88:91], v[128:131], v[160:163], v[88:91]
	v_mfma_f32_16x16x32_bf16 v[20:23], v[136:139], v[160:163], v[20:23]
	v_mfma_f32_16x16x32_bf16 v[92:95], v[128:131], v[168:171], v[92:95]
	v_mfma_f32_16x16x32_bf16 v[28:31], v[136:139], v[168:171], v[28:31]
	v_mfma_f32_16x16x32_bf16 v[80:83], v[128:131], v[196:199], v[80:83]
	v_mfma_f32_16x16x32_bf16 v[16:19], v[136:139], v[196:199], v[16:19]
	v_mfma_f32_16x16x32_bf16 v[76:79], v[128:131], v[212:215], v[76:79]
	v_mfma_f32_16x16x32_bf16 v[12:15], v[136:139], v[212:215], v[12:15]
	v_mfma_f32_16x16x32_bf16 v[88:91], v[132:135], v[164:167], v[88:91]
	v_mfma_f32_16x16x32_bf16 v[20:23], v[140:143], v[164:167], v[20:23]
	v_mfma_f32_16x16x32_bf16 v[92:95], v[132:135], v[172:175], v[92:95]
	v_mfma_f32_16x16x32_bf16 v[28:31], v[140:143], v[172:175], v[28:31]
	v_mfma_f32_16x16x32_bf16 v[80:83], v[132:135], v[208:211], v[80:83]
	v_mfma_f32_16x16x32_bf16 v[16:19], v[140:143], v[208:211], v[16:19]
	v_mfma_f32_16x16x32_bf16 v[76:79], v[132:135], v[216:219], v[76:79]
	v_mfma_f32_16x16x32_bf16 v[12:15], v[140:143], v[216:219], v[12:15]
	s_setprio 0
	s_setprio 1
	v_mfma_f32_16x16x32_bf16 v[68:71], v[144:147], v[160:163], v[68:71]
	v_mfma_f32_16x16x32_bf16 v[4:7], v[152:155], v[160:163], v[4:7]
	v_mfma_f32_16x16x32_bf16 v[84:87], v[144:147], v[168:171], v[84:87]
	v_mfma_f32_16x16x32_bf16 v[24:27], v[152:155], v[168:171], v[24:27]
	v_mfma_f32_16x16x32_bf16 v[72:75], v[144:147], v[196:199], v[72:75]
	v_mfma_f32_16x16x32_bf16 v[8:11], v[152:155], v[196:199], v[8:11]
	v_mfma_f32_16x16x32_bf16 v[64:67], v[144:147], v[212:215], v[64:67]
	v_mfma_f32_16x16x32_bf16 v[0:3], v[152:155], v[212:215], v[0:3]
	v_mfma_f32_16x16x32_bf16 v[68:71], v[148:151], v[164:167], v[68:71]
	v_mfma_f32_16x16x32_bf16 v[4:7], v[156:159], v[164:167], v[4:7]
	v_mfma_f32_16x16x32_bf16 v[84:87], v[148:151], v[172:175], v[84:87]
	v_mfma_f32_16x16x32_bf16 v[24:27], v[156:159], v[172:175], v[24:27]
	v_mfma_f32_16x16x32_bf16 v[72:75], v[148:151], v[208:211], v[72:75]
	v_mfma_f32_16x16x32_bf16 v[8:11], v[156:159], v[208:211], v[8:11]
	v_mfma_f32_16x16x32_bf16 v[64:67], v[148:151], v[216:219], v[64:67]
	v_mfma_f32_16x16x32_bf16 v[0:3], v[156:159], v[216:219], v[0:3]
	s_setprio 0
	s_barrier
	s_add_i32 vcc_lo, vcc_lo, 2
	s_add_u32 s66, s66, 0x100
	s_addc_u32 s67, s67, 0
	s_cmp_gt_u32 vcc_lo, 29
	s_mov_b64 s[10:11], s[16:17]
	s_cbranch_scc0 .LBB0_1105

.LBB0_1349:
	s_add_u32 s47, s20, 0x100
	s_addc_u32 s52, s21, 0
	s_mov_b32 s53, -2
	v_readlane_b32 s0, v255, 49
	s_nop 3
	s_cmp_eq_u32 s0, 9
	v_writelane_b32 v255, 9, 49
	s_cbranch_scc0 .Ltrip0_strict_8
	s_add_u32 s20, s16, 0x100
	s_addc_u32 s21, s17, 0
	s_add_i32 s0, 0, 0x10000
	s_cmpk_eq_i32 s53, 0x54
	s_cselect_b32 s25, s13, s21
	s_cselect_b32 s24, s12, s20
	s_cselect_b32 s23, s15, s52
	s_cselect_b32 s22, s14, s47
	s_add_i32 s1, 0, 0x14000
	v_add_u32_e32 v154, s0, v139
	v_add_u32_e32 v170, s1, v139
	ds_read_b128 v[142:145], v154
	ds_read_b128 v[146:149], v154 offset:1024
	ds_read_b128 v[150:153], v154 offset:2048
	ds_read_b128 v[154:157], v154 offset:3072
	ds_read_b128 v[158:161], v170
	ds_read_b128 v[162:165], v170 offset:1024
	ds_read_b128 v[166:169], v170 offset:2048
	ds_read_b128 v[170:173], v170 offset:3072
	v_lshl_add_u64 v[186:187], s[16:17], 0, v[134:135]
	s_add_i32 m0, s29, 0xc000
	ds_read_b128 v[174:177], v141
	ds_read_b128 v[178:181], v141 offset:1024
	ds_read_b128 v[182:185], v141 offset:2048
	ds_read_b128 v[196:199], v141 offset:3072
	ds_read_b128 v[200:203], v141 offset:4096
	ds_read_b128 v[204:207], v141 offset:5120
	ds_read_b128 v[208:211], v141 offset:6144
	ds_read_b128 v[212:215], v141 offset:7168
	global_load_lds_dwordx4 v[186:187], off
	s_add_i32 m0, s29, 0xe000
	v_lshl_add_u64 v[186:187], s[16:17], 0, v[136:137]
	global_load_lds_dwordx4 v[186:187], off
	s_setprio 1
	s_waitcnt vmcnt(24) lgkmcnt(0)
	s_barrier
	v_mfma_f32_16x16x32_bf16 v[124:127], v[142:145], v[174:177], 0
	v_mfma_f32_16x16x32_bf16 v[120:123], v[150:153], v[174:177], 0
	v_mfma_f32_16x16x32_bf16 v[116:119], v[142:145], v[182:185], 0
	v_mfma_f32_16x16x32_bf16 v[112:115], v[150:153], v[182:185], 0
	v_mfma_f32_16x16x32_bf16 v[100:103], v[142:145], v[200:203], 0
	v_mfma_f32_16x16x32_bf16 v[96:99], v[150:153], v[200:203], 0
	v_mfma_f32_16x16x32_bf16 v[84:87], v[142:145], v[208:211], 0
	v_mfma_f32_16x16x32_bf16 v[80:83], v[150:153], v[208:211], 0
	v_mfma_f32_16x16x32_bf16 v[124:127], v[146:149], v[178:181], v[124:127]
	v_mfma_f32_16x16x32_bf16 v[120:123], v[154:157], v[178:181], v[120:123]
	v_mfma_f32_16x16x32_bf16 v[116:119], v[146:149], v[196:199], v[116:119]
	v_mfma_f32_16x16x32_bf16 v[112:115], v[154:157], v[196:199], v[112:115]
	v_mfma_f32_16x16x32_bf16 v[100:103], v[146:149], v[204:207], v[100:103]
	v_mfma_f32_16x16x32_bf16 v[96:99], v[154:157], v[204:207], v[96:99]
	v_mfma_f32_16x16x32_bf16 v[84:87], v[146:149], v[212:215], v[84:87]
	v_mfma_f32_16x16x32_bf16 v[80:83], v[154:157], v[212:215], v[80:83]
	s_setprio 0
	s_setprio 1
	v_mfma_f32_16x16x32_bf16 v[108:111], v[158:161], v[174:177], 0
	v_mfma_f32_16x16x32_bf16 v[104:107], v[166:169], v[174:177], 0
	v_mfma_f32_16x16x32_bf16 v[92:95], v[158:161], v[182:185], 0
	v_mfma_f32_16x16x32_bf16 v[88:91], v[166:169], v[182:185], 0
	v_mfma_f32_16x16x32_bf16 v[76:79], v[158:161], v[200:203], 0
	v_mfma_f32_16x16x32_bf16 v[72:75], v[166:169], v[200:203], 0
	v_mfma_f32_16x16x32_bf16 v[68:71], v[158:161], v[208:211], 0
	v_mfma_f32_16x16x32_bf16 v[64:67], v[166:169], v[208:211], 0
	v_mfma_f32_16x16x32_bf16 v[108:111], v[162:165], v[178:181], v[108:111]
	v_mfma_f32_16x16x32_bf16 v[104:107], v[170:173], v[178:181], v[104:107]
	v_mfma_f32_16x16x32_bf16 v[92:95], v[162:165], v[196:199], v[92:95]
	v_mfma_f32_16x16x32_bf16 v[88:91], v[170:173], v[196:199], v[88:91]
	v_mfma_f32_16x16x32_bf16 v[76:79], v[162:165], v[204:207], v[76:79]
	v_mfma_f32_16x16x32_bf16 v[72:75], v[170:173], v[204:207], v[72:75]
	v_mfma_f32_16x16x32_bf16 v[68:71], v[162:165], v[212:215], v[68:71]
	v_mfma_f32_16x16x32_bf16 v[64:67], v[170:173], v[212:215], v[64:67]
	s_barrier
	s_setprio 0
	s_add_i32 s0, s0, s28
	v_lshl_add_u64 v[186:187], s[22:23], 0, v[190:191]
	s_mov_b32 m0, s0
	ds_read_b128 v[174:177], v141 offset:16384
	ds_read_b128 v[178:181], v141 offset:17408
	ds_read_b128 v[182:185], v141 offset:18432
	ds_read_b128 v[196:199], v141 offset:19456
	ds_read_b128 v[200:203], v141 offset:20480
	ds_read_b128 v[204:207], v141 offset:21504
	ds_read_b128 v[208:211], v141 offset:22528
	ds_read_b128 v[212:215], v141 offset:23552
	global_load_lds_dwordx4 v[186:187], off
	s_add_i32 m0, s0, 0x2000
	s_add_u32 s16, s22, 0x160000
	v_lshl_add_u64 v[216:217], s[22:23], 0, v[132:133]
	s_addc_u32 s17, s23, 0
	s_add_i32 s0, s1, s28
	global_load_lds_dwordx4 v[216:217], off
	v_lshl_add_u64 v[218:219], s[16:17], 0, v[190:191]
	s_mov_b32 m0, s0
	v_lshl_add_u64 v[220:221], s[24:25], 0, v[130:131]
	global_load_lds_dwordx4 v[218:219], off
	s_add_i32 m0, s0, 0x2000
	v_lshl_add_u64 v[218:219], s[16:17], 0, v[132:133]
	global_load_lds_dwordx4 v[218:219], off
	s_mov_b32 m0, s29
	v_lshl_add_u64 v[218:219], s[24:25], 0, v[128:129]
	global_load_lds_dwordx4 v[218:219], off
	s_mov_b32 m0, s30
	s_nop 0
	global_load_lds_dwordx4 v[220:221], off
	s_setprio 1
	s_waitcnt vmcnt(24) lgkmcnt(0)
	s_barrier
	v_mfma_f32_16x16x32_bf16 v[60:63], v[142:145], v[174:177], 0
	v_mfma_f32_16x16x32_bf16 v[56:59], v[150:153], v[174:177], 0
	v_mfma_f32_16x16x32_bf16 v[52:55], v[142:145], v[182:185], 0
	v_mfma_f32_16x16x32_bf16 v[48:51], v[150:153], v[182:185], 0
	v_mfma_f32_16x16x32_bf16 v[36:39], v[142:145], v[200:203], 0
	v_mfma_f32_16x16x32_bf16 v[32:35], v[150:153], v[200:203], 0
	v_mfma_f32_16x16x32_bf16 v[20:23], v[142:145], v[208:211], 0
	v_mfma_f32_16x16x32_bf16 v[16:19], v[150:153], v[208:211], 0
	v_mfma_f32_16x16x32_bf16 v[60:63], v[146:149], v[178:181], v[60:63]
	v_mfma_f32_16x16x32_bf16 v[56:59], v[154:157], v[178:181], v[56:59]
	v_mfma_f32_16x16x32_bf16 v[52:55], v[146:149], v[196:199], v[52:55]
	v_mfma_f32_16x16x32_bf16 v[48:51], v[154:157], v[196:199], v[48:51]
	v_mfma_f32_16x16x32_bf16 v[36:39], v[146:149], v[204:207], v[36:39]
	v_mfma_f32_16x16x32_bf16 v[32:35], v[154:157], v[204:207], v[32:35]
	v_mfma_f32_16x16x32_bf16 v[20:23], v[146:149], v[212:215], v[20:23]
	v_mfma_f32_16x16x32_bf16 v[16:19], v[154:157], v[212:215], v[16:19]
	s_setprio 0
	s_setprio 1
	v_mfma_f32_16x16x32_bf16 v[44:47], v[158:161], v[174:177], 0
	v_mfma_f32_16x16x32_bf16 v[40:43], v[166:169], v[174:177], 0
	v_mfma_f32_16x16x32_bf16 v[28:31], v[158:161], v[182:185], 0
	v_mfma_f32_16x16x32_bf16 v[24:27], v[166:169], v[182:185], 0
	v_mfma_f32_16x16x32_bf16 v[12:15], v[158:161], v[200:203], 0
	v_mfma_f32_16x16x32_bf16 v[8:11], v[166:169], v[200:203], 0
	v_mfma_f32_16x16x32_bf16 v[4:7], v[158:161], v[208:211], 0
	v_mfma_f32_16x16x32_bf16 v[0:3], v[166:169], v[208:211], 0
	v_mfma_f32_16x16x32_bf16 v[44:47], v[162:165], v[178:181], v[44:47]
	v_mfma_f32_16x16x32_bf16 v[40:43], v[170:173], v[178:181], v[40:43]
	v_mfma_f32_16x16x32_bf16 v[28:31], v[162:165], v[196:199], v[28:31]
	v_mfma_f32_16x16x32_bf16 v[24:27], v[170:173], v[196:199], v[24:27]
	v_mfma_f32_16x16x32_bf16 v[12:15], v[162:165], v[204:207], v[12:15]
	v_mfma_f32_16x16x32_bf16 v[8:11], v[170:173], v[204:207], v[8:11]
	v_mfma_f32_16x16x32_bf16 v[4:7], v[162:165], v[212:215], v[4:7]
	v_mfma_f32_16x16x32_bf16 v[0:3], v[170:173], v[212:215], v[0:3]
	s_barrier
	s_setprio 0
	s_add_i32 s0, 0, 0x18000
	s_add_i32 s1, 0, 0x1c000
	v_add_u32_e32 v154, s0, v139
	v_add_u32_e32 v170, s1, v139
	ds_read_b128 v[142:145], v154
	ds_read_b128 v[146:149], v154 offset:1024
	ds_read_b128 v[150:153], v154 offset:2048
	ds_read_b128 v[154:157], v154 offset:3072
	ds_read_b128 v[158:161], v170
	ds_read_b128 v[162:165], v170 offset:1024
	ds_read_b128 v[166:169], v170 offset:2048
	ds_read_b128 v[170:173], v170 offset:3072
	s_add_u32 s16, s24, 0x160000
	s_addc_u32 s17, s25, 0
	s_mov_b32 m0, s31
	v_lshl_add_u64 v[222:223], s[16:17], 0, v[128:129]
	ds_read_b128 v[174:177], v141 offset:32768
	ds_read_b128 v[178:181], v141 offset:33792
	ds_read_b128 v[182:185], v141 offset:34816
	ds_read_b128 v[196:199], v141 offset:35840
	ds_read_b128 v[200:203], v141 offset:36864
	ds_read_b128 v[204:207], v141 offset:37888
	ds_read_b128 v[208:211], v141 offset:38912
	ds_read_b128 v[212:215], v141 offset:39936
	global_load_lds_dwordx4 v[222:223], off
	s_mov_b32 m0, s33
	v_lshl_add_u64 v[222:223], s[16:17], 0, v[130:131]
	global_load_lds_dwordx4 v[222:223], off
	s_setprio 1
	s_waitcnt vmcnt(8) lgkmcnt(0)
	s_barrier
	v_mfma_f32_16x16x32_bf16 v[124:127], v[142:145], v[174:177], v[124:127]
	v_mfma_f32_16x16x32_bf16 v[120:123], v[150:153], v[174:177], v[120:123]
	v_mfma_f32_16x16x32_bf16 v[116:119], v[142:145], v[182:185], v[116:119]
	v_mfma_f32_16x16x32_bf16 v[112:115], v[150:153], v[182:185], v[112:115]
	v_mfma_f32_16x16x32_bf16 v[100:103], v[142:145], v[200:203], v[100:103]
	v_mfma_f32_16x16x32_bf16 v[96:99], v[150:153], v[200:203], v[96:99]
	v_mfma_f32_16x16x32_bf16 v[84:87], v[142:145], v[208:211], v[84:87]
	v_mfma_f32_16x16x32_bf16 v[80:83], v[150:153], v[208:211], v[80:83]
	v_mfma_f32_16x16x32_bf16 v[124:127], v[146:149], v[178:181], v[124:127]
	v_mfma_f32_16x16x32_bf16 v[120:123], v[154:157], v[178:181], v[120:123]
	v_mfma_f32_16x16x32_bf16 v[116:119], v[146:149], v[196:199], v[116:119]
	v_mfma_f32_16x16x32_bf16 v[112:115], v[154:157], v[196:199], v[112:115]
	v_mfma_f32_16x16x32_bf16 v[100:103], v[146:149], v[204:207], v[100:103]
	v_mfma_f32_16x16x32_bf16 v[96:99], v[154:157], v[204:207], v[96:99]
	v_mfma_f32_16x16x32_bf16 v[84:87], v[146:149], v[212:215], v[84:87]
	v_mfma_f32_16x16x32_bf16 v[80:83], v[154:157], v[212:215], v[80:83]
	s_setprio 0
	s_setprio 1
	v_mfma_f32_16x16x32_bf16 v[108:111], v[158:161], v[174:177], v[108:111]
	v_mfma_f32_16x16x32_bf16 v[104:107], v[166:169], v[174:177], v[104:107]
	v_mfma_f32_16x16x32_bf16 v[92:95], v[158:161], v[182:185], v[92:95]
	v_mfma_f32_16x16x32_bf16 v[88:91], v[166:169], v[182:185], v[88:91]
	v_mfma_f32_16x16x32_bf16 v[76:79], v[158:161], v[200:203], v[76:79]
	v_mfma_f32_16x16x32_bf16 v[72:75], v[166:169], v[200:203], v[72:75]
	v_mfma_f32_16x16x32_bf16 v[68:71], v[158:161], v[208:211], v[68:71]
	v_mfma_f32_16x16x32_bf16 v[64:67], v[166:169], v[208:211], v[64:67]
	v_mfma_f32_16x16x32_bf16 v[108:111], v[162:165], v[178:181], v[108:111]
	v_mfma_f32_16x16x32_bf16 v[104:107], v[170:173], v[178:181], v[104:107]
	v_mfma_f32_16x16x32_bf16 v[92:95], v[162:165], v[196:199], v[92:95]
	v_mfma_f32_16x16x32_bf16 v[88:91], v[170:173], v[196:199], v[88:91]
	v_mfma_f32_16x16x32_bf16 v[76:79], v[162:165], v[204:207], v[76:79]
	v_mfma_f32_16x16x32_bf16 v[72:75], v[170:173], v[204:207], v[72:75]
	v_mfma_f32_16x16x32_bf16 v[68:71], v[162:165], v[212:215], v[68:71]
	v_mfma_f32_16x16x32_bf16 v[64:67], v[170:173], v[212:215], v[64:67]
	s_barrier
	s_setprio 0
	s_add_i32 s0, s0, s28
	v_lshl_add_u64 v[186:187], v[186:187], 0, s[58:59]
	s_mov_b32 m0, s0
	ds_read_b128 v[174:177], v141 offset:49152
	ds_read_b128 v[178:181], v141 offset:50176
	ds_read_b128 v[182:185], v141 offset:51200
	ds_read_b128 v[196:199], v141 offset:52224
	ds_read_b128 v[200:203], v141 offset:53248
	ds_read_b128 v[204:207], v141 offset:54272
	ds_read_b128 v[208:211], v141 offset:55296
	ds_read_b128 v[212:215], v141 offset:56320
	global_load_lds_dwordx4 v[186:187], off
	s_add_i32 m0, s0, 0x2000
	s_add_u32 s16, s22, 0x160080
	v_lshl_add_u64 v[186:187], v[216:217], 0, s[58:59]
	s_addc_u32 s17, s23, 0
	s_add_i32 s0, s1, s28
	global_load_lds_dwordx4 v[186:187], off
	s_mov_b32 m0, s0
	v_lshl_add_u64 v[186:187], s[16:17], 0, v[190:191]
	global_load_lds_dwordx4 v[186:187], off
	s_add_i32 m0, s0, 0x2000
	v_lshl_add_u64 v[186:187], s[16:17], 0, v[132:133]
	global_load_lds_dwordx4 v[186:187], off
	s_mov_b32 m0, s37
	v_lshl_add_u64 v[186:187], v[218:219], 0, s[58:59]
	global_load_lds_dwordx4 v[186:187], off
	s_mov_b32 m0, s38
	v_lshl_add_u64 v[186:187], v[220:221], 0, s[58:59]
	global_load_lds_dwordx4 v[186:187], off
	s_setprio 1
	s_waitcnt vmcnt(8) lgkmcnt(0)
	s_barrier
	v_mfma_f32_16x16x32_bf16 v[60:63], v[142:145], v[174:177], v[60:63]
	v_mfma_f32_16x16x32_bf16 v[56:59], v[150:153], v[174:177], v[56:59]
	v_mfma_f32_16x16x32_bf16 v[52:55], v[142:145], v[182:185], v[52:55]
	v_mfma_f32_16x16x32_bf16 v[48:51], v[150:153], v[182:185], v[48:51]
	v_mfma_f32_16x16x32_bf16 v[36:39], v[142:145], v[200:203], v[36:39]
	v_mfma_f32_16x16x32_bf16 v[32:35], v[150:153], v[200:203], v[32:35]
	v_mfma_f32_16x16x32_bf16 v[20:23], v[142:145], v[208:211], v[20:23]
	v_mfma_f32_16x16x32_bf16 v[16:19], v[150:153], v[208:211], v[16:19]
	v_mfma_f32_16x16x32_bf16 v[60:63], v[146:149], v[178:181], v[60:63]
	v_mfma_f32_16x16x32_bf16 v[56:59], v[154:157], v[178:181], v[56:59]
	v_mfma_f32_16x16x32_bf16 v[52:55], v[146:149], v[196:199], v[52:55]
	v_mfma_f32_16x16x32_bf16 v[48:51], v[154:157], v[196:199], v[48:51]
	v_mfma_f32_16x16x32_bf16 v[36:39], v[146:149], v[204:207], v[36:39]
	v_mfma_f32_16x16x32_bf16 v[32:35], v[154:157], v[204:207], v[32:35]
	v_mfma_f32_16x16x32_bf16 v[20:23], v[146:149], v[212:215], v[20:23]
	v_mfma_f32_16x16x32_bf16 v[16:19], v[154:157], v[212:215], v[16:19]
	s_setprio 0
	s_setprio 1
	v_mfma_f32_16x16x32_bf16 v[44:47], v[158:161], v[174:177], v[44:47]
	v_mfma_f32_16x16x32_bf16 v[40:43], v[166:169], v[174:177], v[40:43]
	v_mfma_f32_16x16x32_bf16 v[28:31], v[158:161], v[182:185], v[28:31]
	v_mfma_f32_16x16x32_bf16 v[24:27], v[166:169], v[182:185], v[24:27]
	v_mfma_f32_16x16x32_bf16 v[12:15], v[158:161], v[200:203], v[12:15]
	v_mfma_f32_16x16x32_bf16 v[8:11], v[166:169], v[200:203], v[8:11]
	v_mfma_f32_16x16x32_bf16 v[4:7], v[158:161], v[208:211], v[4:7]
	v_mfma_f32_16x16x32_bf16 v[0:3], v[166:169], v[208:211], v[0:3]
	v_mfma_f32_16x16x32_bf16 v[44:47], v[162:165], v[178:181], v[44:47]
	v_mfma_f32_16x16x32_bf16 v[40:43], v[170:173], v[178:181], v[40:43]
	v_mfma_f32_16x16x32_bf16 v[28:31], v[162:165], v[196:199], v[28:31]
	v_mfma_f32_16x16x32_bf16 v[24:27], v[170:173], v[196:199], v[24:27]
	v_mfma_f32_16x16x32_bf16 v[12:15], v[162:165], v[204:207], v[12:15]
	v_mfma_f32_16x16x32_bf16 v[8:11], v[170:173], v[204:207], v[8:11]
	v_mfma_f32_16x16x32_bf16 v[4:7], v[162:165], v[212:215], v[4:7]
	v_mfma_f32_16x16x32_bf16 v[0:3], v[170:173], v[212:215], v[0:3]
	s_barrier
	s_setprio 0
	s_add_i32 s53, s53, 2
	s_add_u32 s47, s47, 0x100
	s_addc_u32 s52, s52, 0
	s_cmpk_gt_u32 s53, 0x55
	s_mov_b64 s[16:17], s[20:21]
	s_cbranch_scc1 .Lpeel_done_8
	s_branch .LBB0_1350
.Ltrip0_strict_8:
	s_add_u32 s20, s16, 0x100
	s_addc_u32 s21, s17, 0
	s_add_i32 s0, 0, 0x10000
	s_cmpk_eq_i32 s53, 0x54
	s_cselect_b32 s25, s13, s21
	s_cselect_b32 s24, s12, s20
	s_cselect_b32 s23, s15, s52
	s_cselect_b32 s22, s14, s47
	s_add_i32 s1, 0, 0x14000
	v_add_u32_e32 v154, s0, v139
	v_add_u32_e32 v170, s1, v139
	ds_read_b128 v[142:145], v154
	ds_read_b128 v[146:149], v154 offset:1024
	ds_read_b128 v[150:153], v154 offset:2048
	ds_read_b128 v[154:157], v154 offset:3072
	ds_read_b128 v[158:161], v170
	ds_read_b128 v[162:165], v170 offset:1024
	ds_read_b128 v[166:169], v170 offset:2048
	ds_read_b128 v[170:173], v170 offset:3072
	v_lshl_add_u64 v[186:187], s[16:17], 0, v[134:135]
	s_add_i32 m0, s29, 0xc000
	ds_read_b128 v[174:177], v141
	ds_read_b128 v[178:181], v141 offset:1024
	ds_read_b128 v[182:185], v141 offset:2048
	ds_read_b128 v[196:199], v141 offset:3072
	ds_read_b128 v[200:203], v141 offset:4096
	ds_read_b128 v[204:207], v141 offset:5120
	ds_read_b128 v[208:211], v141 offset:6144
	ds_read_b128 v[212:215], v141 offset:7168
	global_load_lds_dwordx4 v[186:187], off
	s_add_i32 m0, s29, 0xe000
	v_lshl_add_u64 v[186:187], s[16:17], 0, v[136:137]
	global_load_lds_dwordx4 v[186:187], off
	s_setprio 1
	s_waitcnt vmcnt(8) lgkmcnt(0)
	s_barrier
	v_mfma_f32_16x16x32_bf16 v[124:127], v[142:145], v[174:177], 0
	v_mfma_f32_16x16x32_bf16 v[120:123], v[150:153], v[174:177], 0
	v_mfma_f32_16x16x32_bf16 v[116:119], v[142:145], v[182:185], 0
	v_mfma_f32_16x16x32_bf16 v[112:115], v[150:153], v[182:185], 0
	v_mfma_f32_16x16x32_bf16 v[100:103], v[142:145], v[200:203], 0
	v_mfma_f32_16x16x32_bf16 v[96:99], v[150:153], v[200:203], 0
	v_mfma_f32_16x16x32_bf16 v[84:87], v[142:145], v[208:211], 0
	v_mfma_f32_16x16x32_bf16 v[80:83], v[150:153], v[208:211], 0
	v_mfma_f32_16x16x32_bf16 v[124:127], v[146:149], v[178:181], v[124:127]
	v_mfma_f32_16x16x32_bf16 v[120:123], v[154:157], v[178:181], v[120:123]
	v_mfma_f32_16x16x32_bf16 v[116:119], v[146:149], v[196:199], v[116:119]
	v_mfma_f32_16x16x32_bf16 v[112:115], v[154:157], v[196:199], v[112:115]
	v_mfma_f32_16x16x32_bf16 v[100:103], v[146:149], v[204:207], v[100:103]
	v_mfma_f32_16x16x32_bf16 v[96:99], v[154:157], v[204:207], v[96:99]
	v_mfma_f32_16x16x32_bf16 v[84:87], v[146:149], v[212:215], v[84:87]
	v_mfma_f32_16x16x32_bf16 v[80:83], v[154:157], v[212:215], v[80:83]
	s_setprio 0
	s_setprio 1
	v_mfma_f32_16x16x32_bf16 v[108:111], v[158:161], v[174:177], 0
	v_mfma_f32_16x16x32_bf16 v[104:107], v[166:169], v[174:177], 0
	v_mfma_f32_16x16x32_bf16 v[92:95], v[158:161], v[182:185], 0
	v_mfma_f32_16x16x32_bf16 v[88:91], v[166:169], v[182:185], 0
	v_mfma_f32_16x16x32_bf16 v[76:79], v[158:161], v[200:203], 0
	v_mfma_f32_16x16x32_bf16 v[72:75], v[166:169], v[200:203], 0
	v_mfma_f32_16x16x32_bf16 v[68:71], v[158:161], v[208:211], 0
	v_mfma_f32_16x16x32_bf16 v[64:67], v[166:169], v[208:211], 0
	v_mfma_f32_16x16x32_bf16 v[108:111], v[162:165], v[178:181], v[108:111]
	v_mfma_f32_16x16x32_bf16 v[104:107], v[170:173], v[178:181], v[104:107]
	v_mfma_f32_16x16x32_bf16 v[92:95], v[162:165], v[196:199], v[92:95]
	v_mfma_f32_16x16x32_bf16 v[88:91], v[170:173], v[196:199], v[88:91]
	v_mfma_f32_16x16x32_bf16 v[76:79], v[162:165], v[204:207], v[76:79]
	v_mfma_f32_16x16x32_bf16 v[72:75], v[170:173], v[204:207], v[72:75]
	v_mfma_f32_16x16x32_bf16 v[68:71], v[162:165], v[212:215], v[68:71]
	v_mfma_f32_16x16x32_bf16 v[64:67], v[170:173], v[212:215], v[64:67]
	s_barrier
	s_setprio 0
	s_add_i32 s0, s0, s28
	v_lshl_add_u64 v[186:187], s[22:23], 0, v[190:191]
	s_mov_b32 m0, s0
	ds_read_b128 v[174:177], v141 offset:16384
	ds_read_b128 v[178:181], v141 offset:17408
	ds_read_b128 v[182:185], v141 offset:18432
	ds_read_b128 v[196:199], v141 offset:19456
	ds_read_b128 v[200:203], v141 offset:20480
	ds_read_b128 v[204:207], v141 offset:21504
	ds_read_b128 v[208:211], v141 offset:22528
	ds_read_b128 v[212:215], v141 offset:23552
	global_load_lds_dwordx4 v[186:187], off
	s_add_i32 m0, s0, 0x2000
	s_add_u32 s16, s22, 0x160000
	v_lshl_add_u64 v[216:217], s[22:23], 0, v[132:133]
	s_addc_u32 s17, s23, 0
	s_add_i32 s0, s1, s28
	global_load_lds_dwordx4 v[216:217], off
	v_lshl_add_u64 v[218:219], s[16:17], 0, v[190:191]
	s_mov_b32 m0, s0
	v_lshl_add_u64 v[220:221], s[24:25], 0, v[130:131]
	global_load_lds_dwordx4 v[218:219], off
	s_add_i32 m0, s0, 0x2000
	v_lshl_add_u64 v[218:219], s[16:17], 0, v[132:133]
	global_load_lds_dwordx4 v[218:219], off
	s_mov_b32 m0, s29
	v_lshl_add_u64 v[218:219], s[24:25], 0, v[128:129]
	global_load_lds_dwordx4 v[218:219], off
	s_mov_b32 m0, s30
	s_nop 0
	global_load_lds_dwordx4 v[220:221], off
	s_setprio 1
	s_waitcnt vmcnt(8) lgkmcnt(0)
	s_barrier
	v_mfma_f32_16x16x32_bf16 v[60:63], v[142:145], v[174:177], 0
	v_mfma_f32_16x16x32_bf16 v[56:59], v[150:153], v[174:177], 0
	v_mfma_f32_16x16x32_bf16 v[52:55], v[142:145], v[182:185], 0
	v_mfma_f32_16x16x32_bf16 v[48:51], v[150:153], v[182:185], 0
	v_mfma_f32_16x16x32_bf16 v[36:39], v[142:145], v[200:203], 0
	v_mfma_f32_16x16x32_bf16 v[32:35], v[150:153], v[200:203], 0
	v_mfma_f32_16x16x32_bf16 v[20:23], v[142:145], v[208:211], 0
	v_mfma_f32_16x16x32_bf16 v[16:19], v[150:153], v[208:211], 0
	v_mfma_f32_16x16x32_bf16 v[60:63], v[146:149], v[178:181], v[60:63]
	v_mfma_f32_16x16x32_bf16 v[56:59], v[154:157], v[178:181], v[56:59]
	v_mfma_f32_16x16x32_bf16 v[52:55], v[146:149], v[196:199], v[52:55]
	v_mfma_f32_16x16x32_bf16 v[48:51], v[154:157], v[196:199], v[48:51]
	v_mfma_f32_16x16x32_bf16 v[36:39], v[146:149], v[204:207], v[36:39]
	v_mfma_f32_16x16x32_bf16 v[32:35], v[154:157], v[204:207], v[32:35]
	v_mfma_f32_16x16x32_bf16 v[20:23], v[146:149], v[212:215], v[20:23]
	v_mfma_f32_16x16x32_bf16 v[16:19], v[154:157], v[212:215], v[16:19]
	s_setprio 0
	s_setprio 1
	v_mfma_f32_16x16x32_bf16 v[44:47], v[158:161], v[174:177], 0
	v_mfma_f32_16x16x32_bf16 v[40:43], v[166:169], v[174:177], 0
	v_mfma_f32_16x16x32_bf16 v[28:31], v[158:161], v[182:185], 0
	v_mfma_f32_16x16x32_bf16 v[24:27], v[166:169], v[182:185], 0
	v_mfma_f32_16x16x32_bf16 v[12:15], v[158:161], v[200:203], 0
	v_mfma_f32_16x16x32_bf16 v[8:11], v[166:169], v[200:203], 0
	v_mfma_f32_16x16x32_bf16 v[4:7], v[158:161], v[208:211], 0
	v_mfma_f32_16x16x32_bf16 v[0:3], v[166:169], v[208:211], 0
	v_mfma_f32_16x16x32_bf16 v[44:47], v[162:165], v[178:181], v[44:47]
	v_mfma_f32_16x16x32_bf16 v[40:43], v[170:173], v[178:181], v[40:43]
	v_mfma_f32_16x16x32_bf16 v[28:31], v[162:165], v[196:199], v[28:31]
	v_mfma_f32_16x16x32_bf16 v[24:27], v[170:173], v[196:199], v[24:27]
	v_mfma_f32_16x16x32_bf16 v[12:15], v[162:165], v[204:207], v[12:15]
	v_mfma_f32_16x16x32_bf16 v[8:11], v[170:173], v[204:207], v[8:11]
	v_mfma_f32_16x16x32_bf16 v[4:7], v[162:165], v[212:215], v[4:7]
	v_mfma_f32_16x16x32_bf16 v[0:3], v[170:173], v[212:215], v[0:3]
	s_barrier
	s_setprio 0
	s_add_i32 s0, 0, 0x18000
	s_add_i32 s1, 0, 0x1c000
	v_add_u32_e32 v154, s0, v139
	v_add_u32_e32 v170, s1, v139
	ds_read_b128 v[142:145], v154
	ds_read_b128 v[146:149], v154 offset:1024
	ds_read_b128 v[150:153], v154 offset:2048
	ds_read_b128 v[154:157], v154 offset:3072
	ds_read_b128 v[158:161], v170
	ds_read_b128 v[162:165], v170 offset:1024
	ds_read_b128 v[166:169], v170 offset:2048
	ds_read_b128 v[170:173], v170 offset:3072
	s_add_u32 s16, s24, 0x160000
	s_addc_u32 s17, s25, 0
	s_mov_b32 m0, s31
	v_lshl_add_u64 v[222:223], s[16:17], 0, v[128:129]
	ds_read_b128 v[174:177], v141 offset:32768
	ds_read_b128 v[178:181], v141 offset:33792
	ds_read_b128 v[182:185], v141 offset:34816
	ds_read_b128 v[196:199], v141 offset:35840
	ds_read_b128 v[200:203], v141 offset:36864
	ds_read_b128 v[204:207], v141 offset:37888
	ds_read_b128 v[208:211], v141 offset:38912
	ds_read_b128 v[212:215], v141 offset:39936
	global_load_lds_dwordx4 v[222:223], off
	s_mov_b32 m0, s33
	v_lshl_add_u64 v[222:223], s[16:17], 0, v[130:131]
	global_load_lds_dwordx4 v[222:223], off
	s_setprio 1
	s_waitcnt vmcnt(8) lgkmcnt(0)
	s_barrier
	v_mfma_f32_16x16x32_bf16 v[124:127], v[142:145], v[174:177], v[124:127]
	v_mfma_f32_16x16x32_bf16 v[120:123], v[150:153], v[174:177], v[120:123]
	v_mfma_f32_16x16x32_bf16 v[116:119], v[142:145], v[182:185], v[116:119]
	v_mfma_f32_16x16x32_bf16 v[112:115], v[150:153], v[182:185], v[112:115]
	v_mfma_f32_16x16x32_bf16 v[100:103], v[142:145], v[200:203], v[100:103]
	v_mfma_f32_16x16x32_bf16 v[96:99], v[150:153], v[200:203], v[96:99]
	v_mfma_f32_16x16x32_bf16 v[84:87], v[142:145], v[208:211], v[84:87]
	v_mfma_f32_16x16x32_bf16 v[80:83], v[150:153], v[208:211], v[80:83]
	v_mfma_f32_16x16x32_bf16 v[124:127], v[146:149], v[178:181], v[124:127]
	v_mfma_f32_16x16x32_bf16 v[120:123], v[154:157], v[178:181], v[120:123]
	v_mfma_f32_16x16x32_bf16 v[116:119], v[146:149], v[196:199], v[116:119]
	v_mfma_f32_16x16x32_bf16 v[112:115], v[154:157], v[196:199], v[112:115]
	v_mfma_f32_16x16x32_bf16 v[100:103], v[146:149], v[204:207], v[100:103]
	v_mfma_f32_16x16x32_bf16 v[96:99], v[154:157], v[204:207], v[96:99]
	v_mfma_f32_16x16x32_bf16 v[84:87], v[146:149], v[212:215], v[84:87]
	v_mfma_f32_16x16x32_bf16 v[80:83], v[154:157], v[212:215], v[80:83]
	s_setprio 0
	s_setprio 1
	v_mfma_f32_16x16x32_bf16 v[108:111], v[158:161], v[174:177], v[108:111]
	v_mfma_f32_16x16x32_bf16 v[104:107], v[166:169], v[174:177], v[104:107]
	v_mfma_f32_16x16x32_bf16 v[92:95], v[158:161], v[182:185], v[92:95]
	v_mfma_f32_16x16x32_bf16 v[88:91], v[166:169], v[182:185], v[88:91]
	v_mfma_f32_16x16x32_bf16 v[76:79], v[158:161], v[200:203], v[76:79]
	v_mfma_f32_16x16x32_bf16 v[72:75], v[166:169], v[200:203], v[72:75]
	v_mfma_f32_16x16x32_bf16 v[68:71], v[158:161], v[208:211], v[68:71]
	v_mfma_f32_16x16x32_bf16 v[64:67], v[166:169], v[208:211], v[64:67]
	v_mfma_f32_16x16x32_bf16 v[108:111], v[162:165], v[178:181], v[108:111]
	v_mfma_f32_16x16x32_bf16 v[104:107], v[170:173], v[178:181], v[104:107]
	v_mfma_f32_16x16x32_bf16 v[92:95], v[162:165], v[196:199], v[92:95]
	v_mfma_f32_16x16x32_bf16 v[88:91], v[170:173], v[196:199], v[88:91]
	v_mfma_f32_16x16x32_bf16 v[76:79], v[162:165], v[204:207], v[76:79]
	v_mfma_f32_16x16x32_bf16 v[72:75], v[170:173], v[204:207], v[72:75]
	v_mfma_f32_16x16x32_bf16 v[68:71], v[162:165], v[212:215], v[68:71]
	v_mfma_f32_16x16x32_bf16 v[64:67], v[170:173], v[212:215], v[64:67]
	s_barrier
	s_setprio 0
	s_add_i32 s0, s0, s28
	v_lshl_add_u64 v[186:187], v[186:187], 0, s[58:59]
	s_mov_b32 m0, s0
	ds_read_b128 v[174:177], v141 offset:49152
	ds_read_b128 v[178:181], v141 offset:50176
	ds_read_b128 v[182:185], v141 offset:51200
	ds_read_b128 v[196:199], v141 offset:52224
	ds_read_b128 v[200:203], v141 offset:53248
	ds_read_b128 v[204:207], v141 offset:54272
	ds_read_b128 v[208:211], v141 offset:55296
	ds_read_b128 v[212:215], v141 offset:56320
	global_load_lds_dwordx4 v[186:187], off
	s_add_i32 m0, s0, 0x2000
	s_add_u32 s16, s22, 0x160080
	v_lshl_add_u64 v[186:187], v[216:217], 0, s[58:59]
	s_addc_u32 s17, s23, 0
	s_add_i32 s0, s1, s28
	global_load_lds_dwordx4 v[186:187], off
	s_mov_b32 m0, s0
	v_lshl_add_u64 v[186:187], s[16:17], 0, v[190:191]
	global_load_lds_dwordx4 v[186:187], off
	s_add_i32 m0, s0, 0x2000
	v_lshl_add_u64 v[186:187], s[16:17], 0, v[132:133]
	global_load_lds_dwordx4 v[186:187], off
	s_mov_b32 m0, s37
	v_lshl_add_u64 v[186:187], v[218:219], 0, s[58:59]
	global_load_lds_dwordx4 v[186:187], off
	s_mov_b32 m0, s38
	v_lshl_add_u64 v[186:187], v[220:221], 0, s[58:59]
	global_load_lds_dwordx4 v[186:187], off
	s_setprio 1
	s_waitcnt vmcnt(8) lgkmcnt(0)
	s_barrier
	v_mfma_f32_16x16x32_bf16 v[60:63], v[142:145], v[174:177], v[60:63]
	v_mfma_f32_16x16x32_bf16 v[56:59], v[150:153], v[174:177], v[56:59]
	v_mfma_f32_16x16x32_bf16 v[52:55], v[142:145], v[182:185], v[52:55]
	v_mfma_f32_16x16x32_bf16 v[48:51], v[150:153], v[182:185], v[48:51]
	v_mfma_f32_16x16x32_bf16 v[36:39], v[142:145], v[200:203], v[36:39]
	v_mfma_f32_16x16x32_bf16 v[32:35], v[150:153], v[200:203], v[32:35]
	v_mfma_f32_16x16x32_bf16 v[20:23], v[142:145], v[208:211], v[20:23]
	v_mfma_f32_16x16x32_bf16 v[16:19], v[150:153], v[208:211], v[16:19]
	v_mfma_f32_16x16x32_bf16 v[60:63], v[146:149], v[178:181], v[60:63]
	v_mfma_f32_16x16x32_bf16 v[56:59], v[154:157], v[178:181], v[56:59]
	v_mfma_f32_16x16x32_bf16 v[52:55], v[146:149], v[196:199], v[52:55]
	v_mfma_f32_16x16x32_bf16 v[48:51], v[154:157], v[196:199], v[48:51]
	v_mfma_f32_16x16x32_bf16 v[36:39], v[146:149], v[204:207], v[36:39]
	v_mfma_f32_16x16x32_bf16 v[32:35], v[154:157], v[204:207], v[32:35]
	v_mfma_f32_16x16x32_bf16 v[20:23], v[146:149], v[212:215], v[20:23]
	v_mfma_f32_16x16x32_bf16 v[16:19], v[154:157], v[212:215], v[16:19]
	s_setprio 0
	s_setprio 1
	v_mfma_f32_16x16x32_bf16 v[44:47], v[158:161], v[174:177], v[44:47]
	v_mfma_f32_16x16x32_bf16 v[40:43], v[166:169], v[174:177], v[40:43]
	v_mfma_f32_16x16x32_bf16 v[28:31], v[158:161], v[182:185], v[28:31]
	v_mfma_f32_16x16x32_bf16 v[24:27], v[166:169], v[182:185], v[24:27]
	v_mfma_f32_16x16x32_bf16 v[12:15], v[158:161], v[200:203], v[12:15]
	v_mfma_f32_16x16x32_bf16 v[8:11], v[166:169], v[200:203], v[8:11]
	v_mfma_f32_16x16x32_bf16 v[4:7], v[158:161], v[208:211], v[4:7]
	v_mfma_f32_16x16x32_bf16 v[0:3], v[166:169], v[208:211], v[0:3]
	v_mfma_f32_16x16x32_bf16 v[44:47], v[162:165], v[178:181], v[44:47]
	v_mfma_f32_16x16x32_bf16 v[40:43], v[170:173], v[178:181], v[40:43]
	v_mfma_f32_16x16x32_bf16 v[28:31], v[162:165], v[196:199], v[28:31]
	v_mfma_f32_16x16x32_bf16 v[24:27], v[170:173], v[196:199], v[24:27]
	v_mfma_f32_16x16x32_bf16 v[12:15], v[162:165], v[204:207], v[12:15]
	v_mfma_f32_16x16x32_bf16 v[8:11], v[170:173], v[204:207], v[8:11]
	v_mfma_f32_16x16x32_bf16 v[4:7], v[162:165], v[212:215], v[4:7]
	v_mfma_f32_16x16x32_bf16 v[0:3], v[170:173], v[212:215], v[0:3]
	s_barrier
	s_setprio 0
	s_add_i32 s53, s53, 2
	s_add_u32 s47, s47, 0x100
	s_addc_u32 s52, s52, 0
	s_cmpk_gt_u32 s53, 0x55
	s_mov_b64 s[16:17], s[20:21]
	s_cbranch_scc1 .Lpeel_done_8
.LBB0_1350:
	s_add_u32 s20, s16, 0x100
	s_addc_u32 s21, s17, 0
	s_add_i32 s0, 0, 0x10000
	s_cmpk_eq_i32 s53, 0x54
	s_cselect_b32 s25, s13, s21
	s_cselect_b32 s24, s12, s20
	s_cselect_b32 s23, s15, s52
	s_cselect_b32 s22, s14, s47
	s_add_i32 s1, 0, 0x14000
	v_add_u32_e32 v154, s0, v139
	v_add_u32_e32 v170, s1, v139
	ds_read_b128 v[142:145], v154
	ds_read_b128 v[146:149], v154 offset:1024
	ds_read_b128 v[150:153], v154 offset:2048
	ds_read_b128 v[154:157], v154 offset:3072
	ds_read_b128 v[158:161], v170
	ds_read_b128 v[162:165], v170 offset:1024
	ds_read_b128 v[166:169], v170 offset:2048
	ds_read_b128 v[170:173], v170 offset:3072
	v_lshl_add_u64 v[186:187], s[16:17], 0, v[134:135]
	s_add_i32 m0, s29, 0xc000
	ds_read_b128 v[174:177], v141
	ds_read_b128 v[178:181], v141 offset:1024
	ds_read_b128 v[182:185], v141 offset:2048
	ds_read_b128 v[196:199], v141 offset:3072
	ds_read_b128 v[200:203], v141 offset:4096
	ds_read_b128 v[204:207], v141 offset:5120
	ds_read_b128 v[208:211], v141 offset:6144
	ds_read_b128 v[212:215], v141 offset:7168
	global_load_lds_dwordx4 v[186:187], off
	s_add_i32 m0, s29, 0xe000
	v_lshl_add_u64 v[186:187], s[16:17], 0, v[136:137]
	global_load_lds_dwordx4 v[186:187], off
	s_setprio 1
	s_waitcnt vmcnt(8) lgkmcnt(0)
	s_barrier
	v_mfma_f32_16x16x32_bf16 v[124:127], v[142:145], v[174:177], v[124:127]
	v_mfma_f32_16x16x32_bf16 v[120:123], v[150:153], v[174:177], v[120:123]
	v_mfma_f32_16x16x32_bf16 v[116:119], v[142:145], v[182:185], v[116:119]
	v_mfma_f32_16x16x32_bf16 v[112:115], v[150:153], v[182:185], v[112:115]
	v_mfma_f32_16x16x32_bf16 v[100:103], v[142:145], v[200:203], v[100:103]
	v_mfma_f32_16x16x32_bf16 v[96:99], v[150:153], v[200:203], v[96:99]
	v_mfma_f32_16x16x32_bf16 v[84:87], v[142:145], v[208:211], v[84:87]
	v_mfma_f32_16x16x32_bf16 v[80:83], v[150:153], v[208:211], v[80:83]
	v_mfma_f32_16x16x32_bf16 v[124:127], v[146:149], v[178:181], v[124:127]
	v_mfma_f32_16x16x32_bf16 v[120:123], v[154:157], v[178:181], v[120:123]
	v_mfma_f32_16x16x32_bf16 v[116:119], v[146:149], v[196:199], v[116:119]
	v_mfma_f32_16x16x32_bf16 v[112:115], v[154:157], v[196:199], v[112:115]
	v_mfma_f32_16x16x32_bf16 v[100:103], v[146:149], v[204:207], v[100:103]
	v_mfma_f32_16x16x32_bf16 v[96:99], v[154:157], v[204:207], v[96:99]
	v_mfma_f32_16x16x32_bf16 v[84:87], v[146:149], v[212:215], v[84:87]
	v_mfma_f32_16x16x32_bf16 v[80:83], v[154:157], v[212:215], v[80:83]
	s_setprio 0
	s_setprio 1
	v_mfma_f32_16x16x32_bf16 v[108:111], v[158:161], v[174:177], v[108:111]
	v_mfma_f32_16x16x32_bf16 v[104:107], v[166:169], v[174:177], v[104:107]
	v_mfma_f32_16x16x32_bf16 v[92:95], v[158:161], v[182:185], v[92:95]
	v_mfma_f32_16x16x32_bf16 v[88:91], v[166:169], v[182:185], v[88:91]
	v_mfma_f32_16x16x32_bf16 v[76:79], v[158:161], v[200:203], v[76:79]
	v_mfma_f32_16x16x32_bf16 v[72:75], v[166:169], v[200:203], v[72:75]
	v_mfma_f32_16x16x32_bf16 v[68:71], v[158:161], v[208:211], v[68:71]
	v_mfma_f32_16x16x32_bf16 v[64:67], v[166:169], v[208:211], v[64:67]
	v_mfma_f32_16x16x32_bf16 v[108:111], v[162:165], v[178:181], v[108:111]
	v_mfma_f32_16x16x32_bf16 v[104:107], v[170:173], v[178:181], v[104:107]
	v_mfma_f32_16x16x32_bf16 v[92:95], v[162:165], v[196:199], v[92:95]
	v_mfma_f32_16x16x32_bf16 v[88:91], v[170:173], v[196:199], v[88:91]
	v_mfma_f32_16x16x32_bf16 v[76:79], v[162:165], v[204:207], v[76:79]
	v_mfma_f32_16x16x32_bf16 v[72:75], v[170:173], v[204:207], v[72:75]
	v_mfma_f32_16x16x32_bf16 v[68:71], v[162:165], v[212:215], v[68:71]
	v_mfma_f32_16x16x32_bf16 v[64:67], v[170:173], v[212:215], v[64:67]
	s_setprio 0
	s_barrier
	s_add_i32 s0, s0, s28
	v_lshl_add_u64 v[186:187], s[22:23], 0, v[190:191]
	s_mov_b32 m0, s0
	ds_read_b128 v[174:177], v141 offset:16384
	ds_read_b128 v[178:181], v141 offset:17408
	ds_read_b128 v[182:185], v141 offset:18432
	ds_read_b128 v[196:199], v141 offset:19456
	ds_read_b128 v[200:203], v141 offset:20480
	ds_read_b128 v[204:207], v141 offset:21504
	ds_read_b128 v[208:211], v141 offset:22528
	ds_read_b128 v[212:215], v141 offset:23552
	global_load_lds_dwordx4 v[186:187], off
	s_add_i32 m0, s0, 0x2000
	s_add_u32 s16, s22, 0x160000
	v_lshl_add_u64 v[216:217], s[22:23], 0, v[132:133]
	s_addc_u32 s17, s23, 0
	s_add_i32 s0, s1, s28
	global_load_lds_dwordx4 v[216:217], off
	v_lshl_add_u64 v[218:219], s[16:17], 0, v[190:191]
	s_mov_b32 m0, s0
	v_lshl_add_u64 v[220:221], s[24:25], 0, v[130:131]
	global_load_lds_dwordx4 v[218:219], off
	s_add_i32 m0, s0, 0x2000
	v_lshl_add_u64 v[218:219], s[16:17], 0, v[132:133]
	global_load_lds_dwordx4 v[218:219], off
	s_mov_b32 m0, s29
	v_lshl_add_u64 v[218:219], s[24:25], 0, v[128:129]
	global_load_lds_dwordx4 v[218:219], off
	s_mov_b32 m0, s30
	s_nop 0
	global_load_lds_dwordx4 v[220:221], off
	s_setprio 1
	s_waitcnt vmcnt(8) lgkmcnt(0)
	s_barrier
	v_mfma_f32_16x16x32_bf16 v[60:63], v[142:145], v[174:177], v[60:63]
	v_mfma_f32_16x16x32_bf16 v[56:59], v[150:153], v[174:177], v[56:59]
	v_mfma_f32_16x16x32_bf16 v[52:55], v[142:145], v[182:185], v[52:55]
	v_mfma_f32_16x16x32_bf16 v[48:51], v[150:153], v[182:185], v[48:51]
	v_mfma_f32_16x16x32_bf16 v[36:39], v[142:145], v[200:203], v[36:39]
	v_mfma_f32_16x16x32_bf16 v[32:35], v[150:153], v[200:203], v[32:35]
	v_mfma_f32_16x16x32_bf16 v[20:23], v[142:145], v[208:211], v[20:23]
	v_mfma_f32_16x16x32_bf16 v[16:19], v[150:153], v[208:211], v[16:19]
	v_mfma_f32_16x16x32_bf16 v[60:63], v[146:149], v[178:181], v[60:63]
	v_mfma_f32_16x16x32_bf16 v[56:59], v[154:157], v[178:181], v[56:59]
	v_mfma_f32_16x16x32_bf16 v[52:55], v[146:149], v[196:199], v[52:55]
	v_mfma_f32_16x16x32_bf16 v[48:51], v[154:157], v[196:199], v[48:51]
	v_mfma_f32_16x16x32_bf16 v[36:39], v[146:149], v[204:207], v[36:39]
	v_mfma_f32_16x16x32_bf16 v[32:35], v[154:157], v[204:207], v[32:35]
	v_mfma_f32_16x16x32_bf16 v[20:23], v[146:149], v[212:215], v[20:23]
	v_mfma_f32_16x16x32_bf16 v[16:19], v[154:157], v[212:215], v[16:19]
	s_setprio 0
	s_setprio 1
	v_mfma_f32_16x16x32_bf16 v[44:47], v[158:161], v[174:177], v[44:47]
	v_mfma_f32_16x16x32_bf16 v[40:43], v[166:169], v[174:177], v[40:43]
	v_mfma_f32_16x16x32_bf16 v[28:31], v[158:161], v[182:185], v[28:31]
	v_mfma_f32_16x16x32_bf16 v[24:27], v[166:169], v[182:185], v[24:27]
	v_mfma_f32_16x16x32_bf16 v[12:15], v[158:161], v[200:203], v[12:15]
	v_mfma_f32_16x16x32_bf16 v[8:11], v[166:169], v[200:203], v[8:11]
	v_mfma_f32_16x16x32_bf16 v[4:7], v[158:161], v[208:211], v[4:7]
	v_mfma_f32_16x16x32_bf16 v[0:3], v[166:169], v[208:211], v[0:3]
	v_mfma_f32_16x16x32_bf16 v[44:47], v[162:165], v[178:181], v[44:47]
	v_mfma_f32_16x16x32_bf16 v[40:43], v[170:173], v[178:181], v[40:43]
	v_mfma_f32_16x16x32_bf16 v[28:31], v[162:165], v[196:199], v[28:31]
	v_mfma_f32_16x16x32_bf16 v[24:27], v[170:173], v[196:199], v[24:27]
	v_mfma_f32_16x16x32_bf16 v[12:15], v[162:165], v[204:207], v[12:15]
	v_mfma_f32_16x16x32_bf16 v[8:11], v[170:173], v[204:207], v[8:11]
	v_mfma_f32_16x16x32_bf16 v[4:7], v[162:165], v[212:215], v[4:7]
	v_mfma_f32_16x16x32_bf16 v[0:3], v[170:173], v[212:215], v[0:3]
	s_setprio 0
	s_barrier
	s_add_i32 s0, 0, 0x18000
	s_add_i32 s1, 0, 0x1c000
	v_add_u32_e32 v154, s0, v139
	v_add_u32_e32 v170, s1, v139
	ds_read_b128 v[142:145], v154
	ds_read_b128 v[146:149], v154 offset:1024
	ds_read_b128 v[150:153], v154 offset:2048
	ds_read_b128 v[154:157], v154 offset:3072
	ds_read_b128 v[158:161], v170
	ds_read_b128 v[162:165], v170 offset:1024
	ds_read_b128 v[166:169], v170 offset:2048
	ds_read_b128 v[170:173], v170 offset:3072
	s_add_u32 s16, s24, 0x160000
	s_addc_u32 s17, s25, 0
	s_mov_b32 m0, s31
	v_lshl_add_u64 v[222:223], s[16:17], 0, v[128:129]
	ds_read_b128 v[174:177], v141 offset:32768
	ds_read_b128 v[178:181], v141 offset:33792
	ds_read_b128 v[182:185], v141 offset:34816
	ds_read_b128 v[196:199], v141 offset:35840
	ds_read_b128 v[200:203], v141 offset:36864
	ds_read_b128 v[204:207], v141 offset:37888
	ds_read_b128 v[208:211], v141 offset:38912
	ds_read_b128 v[212:215], v141 offset:39936
	global_load_lds_dwordx4 v[222:223], off
	s_mov_b32 m0, s33
	v_lshl_add_u64 v[222:223], s[16:17], 0, v[130:131]
	global_load_lds_dwordx4 v[222:223], off
	s_setprio 1
	s_waitcnt vmcnt(8) lgkmcnt(0)
	s_barrier
	v_mfma_f32_16x16x32_bf16 v[124:127], v[142:145], v[174:177], v[124:127]
	v_mfma_f32_16x16x32_bf16 v[120:123], v[150:153], v[174:177], v[120:123]
	v_mfma_f32_16x16x32_bf16 v[116:119], v[142:145], v[182:185], v[116:119]
	v_mfma_f32_16x16x32_bf16 v[112:115], v[150:153], v[182:185], v[112:115]
	v_mfma_f32_16x16x32_bf16 v[100:103], v[142:145], v[200:203], v[100:103]
	v_mfma_f32_16x16x32_bf16 v[96:99], v[150:153], v[200:203], v[96:99]
	v_mfma_f32_16x16x32_bf16 v[84:87], v[142:145], v[208:211], v[84:87]
	v_mfma_f32_16x16x32_bf16 v[80:83], v[150:153], v[208:211], v[80:83]
	v_mfma_f32_16x16x32_bf16 v[124:127], v[146:149], v[178:181], v[124:127]
	v_mfma_f32_16x16x32_bf16 v[120:123], v[154:157], v[178:181], v[120:123]
	v_mfma_f32_16x16x32_bf16 v[116:119], v[146:149], v[196:199], v[116:119]
	v_mfma_f32_16x16x32_bf16 v[112:115], v[154:157], v[196:199], v[112:115]
	v_mfma_f32_16x16x32_bf16 v[100:103], v[146:149], v[204:207], v[100:103]
	v_mfma_f32_16x16x32_bf16 v[96:99], v[154:157], v[204:207], v[96:99]
	v_mfma_f32_16x16x32_bf16 v[84:87], v[146:149], v[212:215], v[84:87]
	v_mfma_f32_16x16x32_bf16 v[80:83], v[154:157], v[212:215], v[80:83]
	s_setprio 0
	s_setprio 1
	v_mfma_f32_16x16x32_bf16 v[108:111], v[158:161], v[174:177], v[108:111]
	v_mfma_f32_16x16x32_bf16 v[104:107], v[166:169], v[174:177], v[104:107]
	v_mfma_f32_16x16x32_bf16 v[92:95], v[158:161], v[182:185], v[92:95]
	v_mfma_f32_16x16x32_bf16 v[88:91], v[166:169], v[182:185], v[88:91]
	v_mfma_f32_16x16x32_bf16 v[76:79], v[158:161], v[200:203], v[76:79]
	v_mfma_f32_16x16x32_bf16 v[72:75], v[166:169], v[200:203], v[72:75]
	v_mfma_f32_16x16x32_bf16 v[68:71], v[158:161], v[208:211], v[68:71]
	v_mfma_f32_16x16x32_bf16 v[64:67], v[166:169], v[208:211], v[64:67]
	v_mfma_f32_16x16x32_bf16 v[108:111], v[162:165], v[178:181], v[108:111]
	v_mfma_f32_16x16x32_bf16 v[104:107], v[170:173], v[178:181], v[104:107]
	v_mfma_f32_16x16x32_bf16 v[92:95], v[162:165], v[196:199], v[92:95]
	v_mfma_f32_16x16x32_bf16 v[88:91], v[170:173], v[196:199], v[88:91]
	v_mfma_f32_16x16x32_bf16 v[76:79], v[162:165], v[204:207], v[76:79]
	v_mfma_f32_16x16x32_bf16 v[72:75], v[170:173], v[204:207], v[72:75]
	v_mfma_f32_16x16x32_bf16 v[68:71], v[162:165], v[212:215], v[68:71]
	v_mfma_f32_16x16x32_bf16 v[64:67], v[170:173], v[212:215], v[64:67]
	s_setprio 0
	s_barrier
	s_add_i32 s0, s0, s28
	v_lshl_add_u64 v[186:187], v[186:187], 0, s[58:59]
	s_mov_b32 m0, s0
	ds_read_b128 v[174:177], v141 offset:49152
	ds_read_b128 v[178:181], v141 offset:50176
	ds_read_b128 v[182:185], v141 offset:51200
	ds_read_b128 v[196:199], v141 offset:52224
	ds_read_b128 v[200:203], v141 offset:53248
	ds_read_b128 v[204:207], v141 offset:54272
	ds_read_b128 v[208:211], v141 offset:55296
	ds_read_b128 v[212:215], v141 offset:56320
	global_load_lds_dwordx4 v[186:187], off
	s_add_i32 m0, s0, 0x2000
	s_add_u32 s16, s22, 0x160080
	v_lshl_add_u64 v[186:187], v[216:217], 0, s[58:59]
	s_addc_u32 s17, s23, 0
	s_add_i32 s0, s1, s28
	global_load_lds_dwordx4 v[186:187], off
	s_mov_b32 m0, s0
	v_lshl_add_u64 v[186:187], s[16:17], 0, v[190:191]
	global_load_lds_dwordx4 v[186:187], off
	s_add_i32 m0, s0, 0x2000
	v_lshl_add_u64 v[186:187], s[16:17], 0, v[132:133]
	global_load_lds_dwordx4 v[186:187], off
	s_mov_b32 m0, s37
	v_lshl_add_u64 v[186:187], v[218:219], 0, s[58:59]
	global_load_lds_dwordx4 v[186:187], off
	s_mov_b32 m0, s38
	v_lshl_add_u64 v[186:187], v[220:221], 0, s[58:59]
	global_load_lds_dwordx4 v[186:187], off
	s_setprio 1
	s_waitcnt vmcnt(8) lgkmcnt(0)
	s_barrier
	v_mfma_f32_16x16x32_bf16 v[60:63], v[142:145], v[174:177], v[60:63]
	v_mfma_f32_16x16x32_bf16 v[56:59], v[150:153], v[174:177], v[56:59]
	v_mfma_f32_16x16x32_bf16 v[52:55], v[142:145], v[182:185], v[52:55]
	v_mfma_f32_16x16x32_bf16 v[48:51], v[150:153], v[182:185], v[48:51]
	v_mfma_f32_16x16x32_bf16 v[36:39], v[142:145], v[200:203], v[36:39]
	v_mfma_f32_16x16x32_bf16 v[32:35], v[150:153], v[200:203], v[32:35]
	v_mfma_f32_16x16x32_bf16 v[20:23], v[142:145], v[208:211], v[20:23]
	v_mfma_f32_16x16x32_bf16 v[16:19], v[150:153], v[208:211], v[16:19]
	v_mfma_f32_16x16x32_bf16 v[60:63], v[146:149], v[178:181], v[60:63]
	v_mfma_f32_16x16x32_bf16 v[56:59], v[154:157], v[178:181], v[56:59]
	v_mfma_f32_16x16x32_bf16 v[52:55], v[146:149], v[196:199], v[52:55]
	v_mfma_f32_16x16x32_bf16 v[48:51], v[154:157], v[196:199], v[48:51]
	v_mfma_f32_16x16x32_bf16 v[36:39], v[146:149], v[204:207], v[36:39]
	v_mfma_f32_16x16x32_bf16 v[32:35], v[154:157], v[204:207], v[32:35]
	v_mfma_f32_16x16x32_bf16 v[20:23], v[146:149], v[212:215], v[20:23]
	v_mfma_f32_16x16x32_bf16 v[16:19], v[154:157], v[212:215], v[16:19]
	s_setprio 0
	s_setprio 1
	v_mfma_f32_16x16x32_bf16 v[44:47], v[158:161], v[174:177], v[44:47]
	v_mfma_f32_16x16x32_bf16 v[40:43], v[166:169], v[174:177], v[40:43]
	v_mfma_f32_16x16x32_bf16 v[28:31], v[158:161], v[182:185], v[28:31]
	v_mfma_f32_16x16x32_bf16 v[24:27], v[166:169], v[182:185], v[24:27]
	v_mfma_f32_16x16x32_bf16 v[12:15], v[158:161], v[200:203], v[12:15]
	v_mfma_f32_16x16x32_bf16 v[8:11], v[166:169], v[200:203], v[8:11]
	v_mfma_f32_16x16x32_bf16 v[4:7], v[158:161], v[208:211], v[4:7]
	v_mfma_f32_16x16x32_bf16 v[0:3], v[166:169], v[208:211], v[0:3]
	v_mfma_f32_16x16x32_bf16 v[44:47], v[162:165], v[178:181], v[44:47]
	v_mfma_f32_16x16x32_bf16 v[40:43], v[170:173], v[178:181], v[40:43]
	v_mfma_f32_16x16x32_bf16 v[28:31], v[162:165], v[196:199], v[28:31]
	v_mfma_f32_16x16x32_bf16 v[24:27], v[170:173], v[196:199], v[24:27]
	v_mfma_f32_16x16x32_bf16 v[12:15], v[162:165], v[204:207], v[12:15]
	v_mfma_f32_16x16x32_bf16 v[8:11], v[170:173], v[204:207], v[8:11]
	v_mfma_f32_16x16x32_bf16 v[4:7], v[162:165], v[212:215], v[4:7]
	v_mfma_f32_16x16x32_bf16 v[0:3], v[170:173], v[212:215], v[0:3]
	s_setprio 0
	s_barrier
	s_add_i32 s53, s53, 2
	s_add_u32 s47, s47, 0x100
	s_addc_u32 s52, s52, 0
	s_cmpk_gt_u32 s53, 0x55
	s_mov_b64 s[16:17], s[20:21]
	s_cbranch_scc0 .LBB0_1350
